# gspace
# baseline (speedup 1.0000x reference)
; #define STAGE(P, BASE, LD, br, kt) do { const char* _g = (const char*)((BASE) + (size_t)(br) * (LD) + (size_t)(kt) * 64); \
;     for (int _i = 0; _i < 2; ++_i) { int _b = tidx * 16 + _i * 8192; int _r, _c; stage_rc(_b, _r, _c); \
;       __builtin_amdgcn_global_load_lds((const unsigned*)(_g + (unsigned)((_r * (LD) + _c) * 2)), (unsigned*)((char*)(P) + _b), 16, 0, 0); } } while (0)
; #define LDA(dst, b, h) for (int m = 0; m < 4; ++m) for (int k = 0; k < 2; ++k) \
;     dst[m][k] = *reinterpret_cast<const bf16x8*>((char*)SA(b, h) + lds_byte(wr * 64 + m * 16 + fr, k * 32 + fq * 8))
; #define LDB(dst, b, h) for (int n = 0; n < 2; ++n) for (int k = 0; k < 2; ++k) \
;     dst[n][k] = *reinterpret_cast<const bf16x8*>((char*)SB(b, h) + lds_byte(wc * 32 + n * 16 + fr, k * 32 + fq * 8))
; #define MMA(ai, bj, At_, Bt_) do { __builtin_amdgcn_s_setprio(1); \
;     for (int k = 0; k < 2; ++k) for (int m = 0; m < 4; ++m) for (int n = 0; n < 2; ++n) \
;       acc[ai][bj][m][n] = __builtin_amdgcn_mfma_f32_16x16x32_bf16(At_[m][k], Bt_[n][k], acc[ai][bj][m][n], 0, 0, 0); \
;     __builtin_amdgcn_s_setprio(0); } while (0)
; #define WAIT_L(n) asm volatile("s_waitcnt lgkmcnt(" #n ")" ::: "memory")
; #define BAR __builtin_amdgcn_s_barrier()
; #define SCHED __builtin_amdgcn_sched_barrier(0)
; template <int EPI, int lda, int ldb, int N, int K>
; __device__ __forceinline__ void gemm_phase(const u16* __restrict__ A, const u16* __restrict__ Bt, const GemmEpi ep, int wv) {
;     ...
;     for (int t = 0; t < nt - 2; t += 2) {
;       LDB(B0, 0, 0); SCHED; LDA(At, 0, 0); STAGE(SA(1, 1), Ab, lda, brow + HALF, t + 1);
;       WAIT_L(8); BAR; WAIT_L(0); MMA(0, 0, At, B0); BAR; SCHED;
;       LDB(B1, 0, 1); STAGE(SB(0, 0), Bt, ldb, bcol, t + 2);
;       BAR; WAIT_L(0); MMA(0, 1, At, B1); BAR;
;       LDA(At, 0, 1); STAGE(SA(0, 0), Ab, lda, brow, t + 2);
;       BAR; WAIT_L(0); MMA(1, 0, At, B0); BAR; SCHED;
.LBB0_53:
	ds_read_b128 v[172:175], v161
	ds_read_b128 v[176:179], v161 offset:1024
	ds_read_b128 v[180:183], v161 offset:2048
	ds_read_b128 v[184:187], v161 offset:3072
	v_add_u32_e32 v169, 0xc000, v148
	v_lshl_add_u64 v[236:237], v[136:137], 0, s[42:43]
	v_readfirstlane_b32 s45, v169
	v_add_u32_e32 v170, 0xe000, v148
	v_lshl_add_u64 v[162:163], v[236:237], 0, s[14:15]
	s_mov_b32 m0, s45
	v_lshl_add_u64 v[238:239], v[134:135], 0, s[42:43]
	v_readfirstlane_b32 s45, v170
	ds_read_b128 v[164:167], v152
	ds_read_b128 v[188:191], v152 offset:1024
	ds_read_b128 v[192:195], v151
	ds_read_b128 v[196:199], v151 offset:1024
	ds_read_b128 v[200:203], v150
	ds_read_b128 v[204:207], v150 offset:1024
	ds_read_b128 v[208:211], v149
	ds_read_b128 v[212:215], v149 offset:1024
	global_load_lds_dwordx4 v[162:163], off
	s_nop 1
	v_lshl_add_u64 v[162:163], v[238:239], 0, s[14:15]
	s_mov_b32 m0, s45
	s_nop 0
	global_load_lds_dwordx4 v[162:163], off
	s_waitcnt lgkmcnt(8)
	s_barrier
	s_waitcnt lgkmcnt(0)
	s_waitcnt lgkmcnt(0)
	v_mfma_f32_16x16x32_bf16 v[124:127], v[172:175], v[164:167], v[124:127]
	v_mfma_f32_16x16x32_bf16 v[120:123], v[180:183], v[164:167], v[120:123]
	v_mfma_f32_16x16x32_bf16 v[116:119], v[172:175], v[192:195], v[116:119]
	v_mfma_f32_16x16x32_bf16 v[112:115], v[180:183], v[192:195], v[112:115]
	v_mfma_f32_16x16x32_bf16 v[108:111], v[172:175], v[200:203], v[108:111]
	v_mfma_f32_16x16x32_bf16 v[104:107], v[180:183], v[200:203], v[104:107]
	v_mfma_f32_16x16x32_bf16 v[100:103], v[172:175], v[208:211], v[100:103]
	v_mfma_f32_16x16x32_bf16 v[96:99], v[180:183], v[208:211], v[96:99]
	v_mfma_f32_16x16x32_bf16 v[124:127], v[176:179], v[188:191], v[124:127]
	v_mfma_f32_16x16x32_bf16 v[120:123], v[184:187], v[188:191], v[120:123]
	v_mfma_f32_16x16x32_bf16 v[116:119], v[176:179], v[196:199], v[116:119]
	v_mfma_f32_16x16x32_bf16 v[112:115], v[184:187], v[196:199], v[112:115]
	v_mfma_f32_16x16x32_bf16 v[108:111], v[176:179], v[204:207], v[108:111]
	v_mfma_f32_16x16x32_bf16 v[104:107], v[184:187], v[204:207], v[104:107]
	v_mfma_f32_16x16x32_bf16 v[100:103], v[176:179], v[212:215], v[100:103]
	v_mfma_f32_16x16x32_bf16 v[96:99], v[184:187], v[212:215], v[96:99]
	s_barrier
	v_add_u32_e32 v162, s54, v153
	v_lshl_add_u64 v[240:241], v[140:141], 0, s[42:43]
	v_readfirstlane_b32 s45, v162
	v_add_u32_e32 v163, 0x2000, v162
	v_lshl_add_u64 v[232:233], v[240:241], 0, s[16:17]
	s_mov_b32 m0, s45
	v_lshl_add_u64 v[242:243], v[138:139], 0, s[42:43]
	v_readfirstlane_b32 s45, v163
	ds_read_b128 v[216:219], v160
	ds_read_b128 v[220:223], v160 offset:1024
	ds_read_b128 v[224:227], v160 offset:2048
	ds_read_b128 v[228:231], v160 offset:3072
	global_load_lds_dwordx4 v[232:233], off
	s_nop 1
	v_lshl_add_u64 v[232:233], v[242:243], 0, s[16:17]
	s_mov_b32 m0, s45
	s_nop 0
	global_load_lds_dwordx4 v[232:233], off
	s_barrier
	s_waitcnt lgkmcnt(0)
	s_waitcnt lgkmcnt(0)
	v_mfma_f32_16x16x32_bf16 v[92:95], v[216:219], v[164:167], v[92:95]
	v_mfma_f32_16x16x32_bf16 v[88:91], v[224:227], v[164:167], v[88:91]
	v_mfma_f32_16x16x32_bf16 v[84:87], v[216:219], v[192:195], v[84:87]
	v_mfma_f32_16x16x32_bf16 v[80:83], v[224:227], v[192:195], v[80:83]
	v_mfma_f32_16x16x32_bf16 v[76:79], v[216:219], v[200:203], v[76:79]
	v_mfma_f32_16x16x32_bf16 v[72:75], v[224:227], v[200:203], v[72:75]
	v_mfma_f32_16x16x32_bf16 v[68:71], v[216:219], v[208:211], v[68:71]
	v_mfma_f32_16x16x32_bf16 v[64:67], v[224:227], v[208:211], v[64:67]
	v_mfma_f32_16x16x32_bf16 v[92:95], v[220:223], v[188:191], v[92:95]
	v_mfma_f32_16x16x32_bf16 v[88:91], v[228:231], v[188:191], v[88:91]
	v_mfma_f32_16x16x32_bf16 v[84:87], v[220:223], v[196:199], v[84:87]
	v_mfma_f32_16x16x32_bf16 v[80:83], v[228:231], v[196:199], v[80:83]
	v_mfma_f32_16x16x32_bf16 v[76:79], v[220:223], v[204:207], v[76:79]
	v_mfma_f32_16x16x32_bf16 v[72:75], v[228:231], v[204:207], v[72:75]
	v_mfma_f32_16x16x32_bf16 v[68:71], v[220:223], v[212:215], v[68:71]
	v_mfma_f32_16x16x32_bf16 v[64:67], v[228:231], v[212:215], v[64:67]
	v_readfirstlane_b32 s45, v148
	v_lshl_add_u64 v[164:165], v[236:237], 0, s[18:19]
	s_mov_b32 m0, s45
	s_barrier
	ds_read_b128 v[188:191], v152 offset:16384
	ds_read_b128 v[192:195], v152 offset:17408
	ds_read_b128 v[196:199], v151 offset:16384
	ds_read_b128 v[200:203], v151 offset:17408
	ds_read_b128 v[204:207], v150 offset:16384
	ds_read_b128 v[208:211], v150 offset:17408
	ds_read_b128 v[212:215], v149 offset:16384
	ds_read_b128 v[232:235], v149 offset:17408
	global_load_lds_dwordx4 v[164:165], off
	s_nop 1
	v_add_u32_e32 v164, 0x2000, v148
	v_lshl_add_u64 v[166:167], v[238:239], 0, s[18:19]
	v_readfirstlane_b32 s45, v164
	s_mov_b32 m0, s45
	s_nop 0
	global_load_lds_dwordx4 v[166:167], off
	s_barrier
	s_waitcnt lgkmcnt(0)
	s_waitcnt lgkmcnt(0)
	v_mfma_f32_16x16x32_bf16 v[60:63], v[172:175], v[188:191], v[60:63]
	v_mfma_f32_16x16x32_bf16 v[56:59], v[180:183], v[188:191], v[56:59]
	v_mfma_f32_16x16x32_bf16 v[52:55], v[172:175], v[196:199], v[52:55]
	v_mfma_f32_16x16x32_bf16 v[48:51], v[180:183], v[196:199], v[48:51]
	v_mfma_f32_16x16x32_bf16 v[44:47], v[172:175], v[204:207], v[44:47]
	v_mfma_f32_16x16x32_bf16 v[40:43], v[180:183], v[204:207], v[40:43]
	v_mfma_f32_16x16x32_bf16 v[36:39], v[172:175], v[212:215], v[36:39]
	v_mfma_f32_16x16x32_bf16 v[32:35], v[180:183], v[212:215], v[32:35]
	v_mfma_f32_16x16x32_bf16 v[60:63], v[176:179], v[192:195], v[60:63]
	v_mfma_f32_16x16x32_bf16 v[56:59], v[184:187], v[192:195], v[56:59]
	v_mfma_f32_16x16x32_bf16 v[52:55], v[176:179], v[200:203], v[52:55]
	v_mfma_f32_16x16x32_bf16 v[48:51], v[184:187], v[200:203], v[48:51]
	v_mfma_f32_16x16x32_bf16 v[44:47], v[176:179], v[208:211], v[44:47]
	v_mfma_f32_16x16x32_bf16 v[40:43], v[184:187], v[208:211], v[40:43]
	v_mfma_f32_16x16x32_bf16 v[36:39], v[176:179], v[232:235], v[36:39]
	v_mfma_f32_16x16x32_bf16 v[32:35], v[184:187], v[232:235], v[32:35]
	s_barrier
; #define STAGE(P, BASE, LD, br, kt) do { const char* _g = (const char*)((BASE) + (size_t)(br) * (LD) + (size_t)(kt) * 64); \
;     for (int _i = 0; _i < 2; ++_i) { int _b = tidx * 16 + _i * 8192; int _r, _c; stage_rc(_b, _r, _c); \
;       __builtin_amdgcn_global_load_lds((const unsigned*)(_g + (unsigned)((_r * (LD) + _c) * 2)), (unsigned*)((char*)(P) + _b), 16, 0, 0); } } while (0)
; #define LDA(dst, b, h) for (int m = 0; m < 4; ++m) for (int k = 0; k < 2; ++k) \
;     dst[m][k] = *reinterpret_cast<const bf16x8*>((char*)SA(b, h) + lds_byte(wr * 64 + m * 16 + fr, k * 32 + fq * 8))
; #define LDB(dst, b, h) for (int n = 0; n < 2; ++n) for (int k = 0; k < 2; ++k) \
;     dst[n][k] = *reinterpret_cast<const bf16x8*>((char*)SB(b, h) + lds_byte(wc * 32 + n * 16 + fr, k * 32 + fq * 8))
; #define MMA(ai, bj, At_, Bt_) do { __builtin_amdgcn_s_setprio(1); \
;     for (int k = 0; k < 2; ++k) for (int m = 0; m < 4; ++m) for (int n = 0; n < 2; ++n) \
;       acc[ai][bj][m][n] = __builtin_amdgcn_mfma_f32_16x16x32_bf16(At_[m][k], Bt_[n][k], acc[ai][bj][m][n], 0, 0, 0); \
;     __builtin_amdgcn_s_setprio(0); } while (0)
; #define WAIT_V(n) asm volatile("s_waitcnt vmcnt(" #n ")" ::: "memory")
; #define WAIT_L(n) asm volatile("s_waitcnt lgkmcnt(" #n ")" ::: "memory")
; #define BAR __builtin_amdgcn_s_barrier()
; #define SCHED __builtin_amdgcn_sched_barrier(0)
; template <int EPI, int lda, int ldb, int N, int K>
; __device__ __forceinline__ void gemm_phase(const u16* __restrict__ A, const u16* __restrict__ Bt, const GemmEpi ep, int wv) {
;     ...
;       STAGE(SB(0, 1), Bt, ldb, bcol + HALF, t + 2);
;       WAIT_V(6); BAR; MMA(1, 1, At, B1); BAR;
;       LDB(B0, 1, 0); SCHED; LDA(At, 1, 0); STAGE(SA(0, 1), Ab, lda, brow + HALF, t + 2);
;       WAIT_L(8); BAR; WAIT_L(0); MMA(0, 0, At, B0); BAR; SCHED;
;       LDB(B1, 1, 1); STAGE(SB(1, 0), Bt, ldb, bcol, t + 3);
;       BAR; WAIT_L(0); MMA(0, 1, At, B1); BAR;
	v_add_u32_e32 v165, s55, v153
	v_lshl_add_u64 v[166:167], v[240:241], 0, s[20:21]
	v_readfirstlane_b32 s45, v165
	s_mov_b32 m0, s45
	v_lshl_add_u64 v[172:173], v[242:243], 0, s[20:21]
	global_load_lds_dwordx4 v[166:167], off
	s_nop 1
	v_add_u32_e32 v166, 0x2000, v165
	s_nop 0
	v_readfirstlane_b32 s45, v166
	s_mov_b32 m0, s45
	s_nop 0
	global_load_lds_dwordx4 v[172:173], off
	s_waitcnt vmcnt(6)
	s_barrier
	v_mfma_f32_16x16x32_bf16 v[28:31], v[216:219], v[188:191], v[28:31]
	v_mfma_f32_16x16x32_bf16 v[24:27], v[224:227], v[188:191], v[24:27]
	v_mfma_f32_16x16x32_bf16 v[20:23], v[216:219], v[196:199], v[20:23]
	v_mfma_f32_16x16x32_bf16 v[16:19], v[224:227], v[196:199], v[16:19]
	v_mfma_f32_16x16x32_bf16 v[12:15], v[216:219], v[204:207], v[12:15]
	v_mfma_f32_16x16x32_bf16 v[8:11], v[224:227], v[204:207], v[8:11]
	v_mfma_f32_16x16x32_bf16 v[4:7], v[216:219], v[212:215], v[4:7]
	v_mfma_f32_16x16x32_bf16 v[0:3], v[224:227], v[212:215], v[0:3]
	v_mfma_f32_16x16x32_bf16 v[28:31], v[220:223], v[192:195], v[28:31]
	v_mfma_f32_16x16x32_bf16 v[24:27], v[228:231], v[192:195], v[24:27]
	v_mfma_f32_16x16x32_bf16 v[20:23], v[220:223], v[200:203], v[20:23]
	v_mfma_f32_16x16x32_bf16 v[16:19], v[228:231], v[200:203], v[16:19]
	v_mfma_f32_16x16x32_bf16 v[12:15], v[220:223], v[208:211], v[12:15]
	v_mfma_f32_16x16x32_bf16 v[8:11], v[228:231], v[208:211], v[8:11]
	v_mfma_f32_16x16x32_bf16 v[4:7], v[220:223], v[232:235], v[4:7]
	v_mfma_f32_16x16x32_bf16 v[0:3], v[228:231], v[232:235], v[0:3]
	s_barrier
	ds_read_b128 v[172:175], v156
	ds_read_b128 v[176:179], v156 offset:1024
	ds_read_b128 v[180:183], v156 offset:2048
	ds_read_b128 v[184:187], v156 offset:3072
	v_add_u32_e32 v167, 0x4000, v148
	v_add_u32_e32 v168, 0x6000, v148
	v_readfirstlane_b32 s45, v167
	v_lshl_add_u64 v[220:221], v[236:237], 0, s[22:23]
	s_mov_b32 m0, s45
	v_readfirstlane_b32 s45, v168
	ds_read_b128 v[188:191], v152 offset:32768
	ds_read_b128 v[192:195], v152 offset:33792
	ds_read_b128 v[196:199], v151 offset:32768
	ds_read_b128 v[200:203], v151 offset:33792
	ds_read_b128 v[204:207], v150 offset:32768
	ds_read_b128 v[208:211], v150 offset:33792
	ds_read_b128 v[212:215], v149 offset:32768
	ds_read_b128 v[216:219], v149 offset:33792
	global_load_lds_dwordx4 v[220:221], off
	s_nop 1
	v_lshl_add_u64 v[220:221], v[238:239], 0, s[22:23]
	s_mov_b32 m0, s45
	s_nop 0
	global_load_lds_dwordx4 v[220:221], off
	s_waitcnt lgkmcnt(8)
	s_barrier
	s_waitcnt lgkmcnt(0)
	s_waitcnt lgkmcnt(0)
	v_mfma_f32_16x16x32_bf16 v[124:127], v[172:175], v[188:191], v[124:127]
	v_mfma_f32_16x16x32_bf16 v[120:123], v[180:183], v[188:191], v[120:123]
	v_mfma_f32_16x16x32_bf16 v[116:119], v[172:175], v[196:199], v[116:119]
	v_mfma_f32_16x16x32_bf16 v[112:115], v[180:183], v[196:199], v[112:115]
	v_mfma_f32_16x16x32_bf16 v[108:111], v[172:175], v[204:207], v[108:111]
	v_mfma_f32_16x16x32_bf16 v[104:107], v[180:183], v[204:207], v[104:107]
	v_mfma_f32_16x16x32_bf16 v[100:103], v[172:175], v[212:215], v[100:103]
	v_mfma_f32_16x16x32_bf16 v[96:99], v[180:183], v[212:215], v[96:99]
	v_mfma_f32_16x16x32_bf16 v[124:127], v[176:179], v[192:195], v[124:127]
	v_mfma_f32_16x16x32_bf16 v[120:123], v[184:187], v[192:195], v[120:123]
	v_mfma_f32_16x16x32_bf16 v[116:119], v[176:179], v[200:203], v[116:119]
	v_mfma_f32_16x16x32_bf16 v[112:115], v[184:187], v[200:203], v[112:115]
	v_mfma_f32_16x16x32_bf16 v[108:111], v[176:179], v[208:211], v[108:111]
	v_mfma_f32_16x16x32_bf16 v[104:107], v[184:187], v[208:211], v[104:107]
	v_mfma_f32_16x16x32_bf16 v[100:103], v[176:179], v[216:219], v[100:103]
	v_mfma_f32_16x16x32_bf16 v[96:99], v[184:187], v[216:219], v[96:99]
	s_barrier
	v_readfirstlane_b32 s45, v155
	v_add_u32_e32 v171, 0x2000, v155
	v_lshl_add_u64 v[244:245], v[240:241], 0, s[24:25]
	s_mov_b32 m0, s45
	v_readfirstlane_b32 s45, v171
	ds_read_b128 v[220:223], v154
	ds_read_b128 v[224:227], v154 offset:1024
	ds_read_b128 v[228:231], v154 offset:2048
	ds_read_b128 v[232:235], v154 offset:3072
	global_load_lds_dwordx4 v[244:245], off
	s_nop 1
	v_lshl_add_u64 v[244:245], v[242:243], 0, s[24:25]
	s_mov_b32 m0, s45
	s_nop 0
	global_load_lds_dwordx4 v[244:245], off
	s_barrier
	s_waitcnt lgkmcnt(0)
	s_waitcnt lgkmcnt(0)
	v_mfma_f32_16x16x32_bf16 v[92:95], v[220:223], v[188:191], v[92:95]
	v_mfma_f32_16x16x32_bf16 v[88:91], v[228:231], v[188:191], v[88:91]
	v_mfma_f32_16x16x32_bf16 v[84:87], v[220:223], v[196:199], v[84:87]
	v_mfma_f32_16x16x32_bf16 v[80:83], v[228:231], v[196:199], v[80:83]
	v_mfma_f32_16x16x32_bf16 v[76:79], v[220:223], v[204:207], v[76:79]
	v_mfma_f32_16x16x32_bf16 v[72:75], v[228:231], v[204:207], v[72:75]
	v_mfma_f32_16x16x32_bf16 v[68:71], v[220:223], v[212:215], v[68:71]
	v_mfma_f32_16x16x32_bf16 v[64:67], v[228:231], v[212:215], v[64:67]
	v_mfma_f32_16x16x32_bf16 v[92:95], v[224:227], v[192:195], v[92:95]
	v_mfma_f32_16x16x32_bf16 v[88:91], v[232:235], v[192:195], v[88:91]
	v_mfma_f32_16x16x32_bf16 v[84:87], v[224:227], v[200:203], v[84:87]
	v_mfma_f32_16x16x32_bf16 v[80:83], v[232:235], v[200:203], v[80:83]
	v_mfma_f32_16x16x32_bf16 v[76:79], v[224:227], v[208:211], v[76:79]
	v_mfma_f32_16x16x32_bf16 v[72:75], v[232:235], v[208:211], v[72:75]
	v_mfma_f32_16x16x32_bf16 v[68:71], v[224:227], v[216:219], v[68:71]
	v_mfma_f32_16x16x32_bf16 v[64:67], v[232:235], v[216:219], v[64:67]
	v_readfirstlane_b32 s45, v157
	v_lshl_add_u64 v[236:237], v[236:237], 0, s[26:27]
	s_mov_b32 m0, s45
	v_readfirstlane_b32 s45, v158
	s_barrier
; #define STAGE(P, BASE, LD, br, kt) do { const char* _g = (const char*)((BASE) + (size_t)(br) * (LD) + (size_t)(kt) * 64); \
;     for (int _i = 0; _i < 2; ++_i) { int _b = tidx * 16 + _i * 8192; int _r, _c; stage_rc(_b, _r, _c); \
;       __builtin_amdgcn_global_load_lds((const unsigned*)(_g + (unsigned)((_r * (LD) + _c) * 2)), (unsigned*)((char*)(P) + _b), 16, 0, 0); } } while (0)
; #define LDA(dst, b, h) for (int m = 0; m < 4; ++m) for (int k = 0; k < 2; ++k) \
;     dst[m][k] = *reinterpret_cast<const bf16x8*>((char*)SA(b, h) + lds_byte(wr * 64 + m * 16 + fr, k * 32 + fq * 8))
; #define LDB(dst, b, h) for (int n = 0; n < 2; ++n) for (int k = 0; k < 2; ++k) \
;     dst[n][k] = *reinterpret_cast<const bf16x8*>((char*)SB(b, h) + lds_byte(wc * 32 + n * 16 + fr, k * 32 + fq * 8))
; #define MMA(ai, bj, At_, Bt_) do { __builtin_amdgcn_s_setprio(1); \
;     for (int k = 0; k < 2; ++k) for (int m = 0; m < 4; ++m) for (int n = 0; n < 2; ++n) \
;       acc[ai][bj][m][n] = __builtin_amdgcn_mfma_f32_16x16x32_bf16(At_[m][k], Bt_[n][k], acc[ai][bj][m][n], 0, 0, 0); \
;     __builtin_amdgcn_s_setprio(0); } while (0)
; #define WAIT_V(n) asm volatile("s_waitcnt vmcnt(" #n ")" ::: "memory")
; #define WAIT_L(n) asm volatile("s_waitcnt lgkmcnt(" #n ")" ::: "memory")
; #define BAR __builtin_amdgcn_s_barrier()
; #define SCHED __builtin_amdgcn_sched_barrier(0)
; template <int EPI, int lda, int ldb, int N, int K>
; __device__ __forceinline__ void gemm_phase(const u16* __restrict__ A, const u16* __restrict__ Bt, const GemmEpi ep, int wv) {
;     ...
;       LDA(At, 1, 1); STAGE(SA(1, 0), Ab, lda, brow, t + 3);
;       BAR; WAIT_L(0); MMA(1, 0, At, B0); BAR; SCHED;
;       STAGE(SB(1, 1), Bt, ldb, bcol + HALF, t + 3);
;       WAIT_V(6); BAR; MMA(1, 1, At, B1); BAR;
;     }
;     { LDB(B0, 0, 0); LDA(At, 0, 0); STAGE(SA(1, 1), Ab, lda, brow + HALF, nt - 1);
;       BAR; WAIT_L(0); MMA(0, 0, At, B0); BAR;
;       LDB(B1, 0, 1); BAR; WAIT_L(0); MMA(0, 1, At, B1); BAR;
	ds_read_b128 v[188:191], v152 offset:49152
	ds_read_b128 v[192:195], v152 offset:50176
	ds_read_b128 v[196:199], v151 offset:49152
	ds_read_b128 v[200:203], v151 offset:50176
	ds_read_b128 v[204:207], v150 offset:49152
	ds_read_b128 v[208:211], v150 offset:50176
	ds_read_b128 v[212:215], v149 offset:49152
	ds_read_b128 v[216:219], v149 offset:50176
	global_load_lds_dwordx4 v[236:237], off
	s_nop 1
	v_lshl_add_u64 v[236:237], v[238:239], 0, s[26:27]
	s_mov_b32 m0, s45
	s_nop 0
	global_load_lds_dwordx4 v[236:237], off
	s_barrier
	s_waitcnt lgkmcnt(0)
	s_waitcnt lgkmcnt(0)
	v_mfma_f32_16x16x32_bf16 v[60:63], v[172:175], v[188:191], v[60:63]
	v_mfma_f32_16x16x32_bf16 v[56:59], v[180:183], v[188:191], v[56:59]
	v_mfma_f32_16x16x32_bf16 v[52:55], v[172:175], v[196:199], v[52:55]
	v_mfma_f32_16x16x32_bf16 v[48:51], v[180:183], v[196:199], v[48:51]
	v_mfma_f32_16x16x32_bf16 v[44:47], v[172:175], v[204:207], v[44:47]
	v_mfma_f32_16x16x32_bf16 v[40:43], v[180:183], v[204:207], v[40:43]
	v_mfma_f32_16x16x32_bf16 v[36:39], v[172:175], v[212:215], v[36:39]
	v_mfma_f32_16x16x32_bf16 v[32:35], v[180:183], v[212:215], v[32:35]
	v_mfma_f32_16x16x32_bf16 v[60:63], v[176:179], v[192:195], v[60:63]
	v_mfma_f32_16x16x32_bf16 v[56:59], v[184:187], v[192:195], v[56:59]
	v_mfma_f32_16x16x32_bf16 v[52:55], v[176:179], v[200:203], v[52:55]
	v_mfma_f32_16x16x32_bf16 v[48:51], v[184:187], v[200:203], v[48:51]
	v_mfma_f32_16x16x32_bf16 v[44:47], v[176:179], v[208:211], v[44:47]
	v_mfma_f32_16x16x32_bf16 v[40:43], v[184:187], v[208:211], v[40:43]
	v_mfma_f32_16x16x32_bf16 v[36:39], v[176:179], v[216:219], v[36:39]
	v_mfma_f32_16x16x32_bf16 v[32:35], v[184:187], v[216:219], v[32:35]
	s_barrier
	v_readfirstlane_b32 s45, v159
	v_add_u32_e32 v171, 0x2000, v159
	v_lshl_add_u64 v[172:173], v[240:241], 0, s[34:35]
	s_mov_b32 m0, s45
	v_readfirstlane_b32 s45, v171
	global_load_lds_dwordx4 v[172:173], off
	s_nop 1
	v_lshl_add_u64 v[172:173], v[242:243], 0, s[34:35]
	s_mov_b32 m0, s45
	s_nop 0
	global_load_lds_dwordx4 v[172:173], off
	s_waitcnt vmcnt(6)
	s_barrier
	v_mfma_f32_16x16x32_bf16 v[28:31], v[220:223], v[188:191], v[28:31]
	v_mfma_f32_16x16x32_bf16 v[24:27], v[228:231], v[188:191], v[24:27]
	v_mfma_f32_16x16x32_bf16 v[20:23], v[220:223], v[196:199], v[20:23]
	v_mfma_f32_16x16x32_bf16 v[16:19], v[228:231], v[196:199], v[16:19]
	v_mfma_f32_16x16x32_bf16 v[12:15], v[220:223], v[204:207], v[12:15]
	v_mfma_f32_16x16x32_bf16 v[8:11], v[228:231], v[204:207], v[8:11]
	v_mfma_f32_16x16x32_bf16 v[4:7], v[220:223], v[212:215], v[4:7]
	v_mfma_f32_16x16x32_bf16 v[0:3], v[228:231], v[212:215], v[0:3]
	v_mfma_f32_16x16x32_bf16 v[28:31], v[224:227], v[192:195], v[28:31]
	v_mfma_f32_16x16x32_bf16 v[24:27], v[232:235], v[192:195], v[24:27]
	v_mfma_f32_16x16x32_bf16 v[20:23], v[224:227], v[200:203], v[20:23]
	v_mfma_f32_16x16x32_bf16 v[16:19], v[232:235], v[200:203], v[16:19]
	v_mfma_f32_16x16x32_bf16 v[12:15], v[224:227], v[208:211], v[12:15]
	v_mfma_f32_16x16x32_bf16 v[8:11], v[232:235], v[208:211], v[8:11]
	v_mfma_f32_16x16x32_bf16 v[4:7], v[224:227], v[216:219], v[4:7]
	v_mfma_f32_16x16x32_bf16 v[0:3], v[232:235], v[216:219], v[0:3]
	s_add_i32 s44, s44, 2
	s_add_u32 s42, s42, 0x100
	s_addc_u32 s43, s43, 0
	s_cmp_gt_u32 s44, 27
	s_barrier
	s_cbranch_scc0 .LBB0_53
	s_add_i32 s42, s38, 0x80
	s_mul_hi_i32 s43, s42, 0x1080
	s_mulk_i32 s42, 0x1080
	s_add_u32 s42, s51, s42
	s_addc_u32 s43, s52, s43
	v_lshl_add_u64 v[158:159], s[42:43], 0, v[128:129]
	v_readfirstlane_b32 s44, v169
	v_lshl_add_u64 v[158:159], v[158:159], 0, s[36:37]
	s_mov_b32 m0, s44
	ds_read_b128 v[134:137], v161
	ds_read_b128 v[138:141], v161 offset:1024
	ds_read_b128 v[172:175], v161 offset:2048
	ds_read_b128 v[176:179], v161 offset:3072
	ds_read_b128 v[180:183], v152
	ds_read_b128 v[184:187], v152 offset:1024
	ds_read_b128 v[188:191], v151
	ds_read_b128 v[192:195], v151 offset:1024
	ds_read_b128 v[196:199], v150
	ds_read_b128 v[200:203], v150 offset:1024
	ds_read_b128 v[204:207], v149
	ds_read_b128 v[208:211], v149 offset:1024
	global_load_lds_dwordx4 v[158:159], off
	v_lshl_add_u64 v[158:159], s[42:43], 0, v[132:133]
	v_readfirstlane_b32 s42, v170
	v_lshl_add_u64 v[158:159], v[158:159], 0, s[36:37]
	s_mov_b32 m0, s42
	s_nop 0
	global_load_lds_dwordx4 v[158:159], off
	s_barrier
	s_waitcnt lgkmcnt(0)
	s_waitcnt lgkmcnt(0)
	v_mfma_f32_16x16x32_bf16 v[124:127], v[134:137], v[180:183], v[124:127]
	v_mfma_f32_16x16x32_bf16 v[120:123], v[172:175], v[180:183], v[120:123]
	v_mfma_f32_16x16x32_bf16 v[116:119], v[134:137], v[188:191], v[116:119]
	v_mfma_f32_16x16x32_bf16 v[112:115], v[172:175], v[188:191], v[112:115]
	v_mfma_f32_16x16x32_bf16 v[108:111], v[134:137], v[196:199], v[108:111]
	v_mfma_f32_16x16x32_bf16 v[104:107], v[172:175], v[196:199], v[104:107]
	v_mfma_f32_16x16x32_bf16 v[100:103], v[134:137], v[204:207], v[100:103]
	v_mfma_f32_16x16x32_bf16 v[96:99], v[172:175], v[204:207], v[96:99]
	v_mfma_f32_16x16x32_bf16 v[124:127], v[138:141], v[184:187], v[124:127]
	v_mfma_f32_16x16x32_bf16 v[120:123], v[176:179], v[184:187], v[120:123]
	v_mfma_f32_16x16x32_bf16 v[116:119], v[138:141], v[192:195], v[116:119]
	v_mfma_f32_16x16x32_bf16 v[112:115], v[176:179], v[192:195], v[112:115]
	v_mfma_f32_16x16x32_bf16 v[108:111], v[138:141], v[200:203], v[108:111]
	v_mfma_f32_16x16x32_bf16 v[104:107], v[176:179], v[200:203], v[104:107]
	v_mfma_f32_16x16x32_bf16 v[100:103], v[138:141], v[208:211], v[100:103]
	v_mfma_f32_16x16x32_bf16 v[96:99], v[176:179], v[208:211], v[96:99]
	s_barrier
	ds_read_b128 v[212:215], v160
	ds_read_b128 v[216:219], v160 offset:1024
	ds_read_b128 v[220:223], v160 offset:2048
	ds_read_b128 v[158:161], v160 offset:3072
	s_barrier
; #define LDA(dst, b, h) for (int m = 0; m < 4; ++m) for (int k = 0; k < 2; ++k) \
;     dst[m][k] = *reinterpret_cast<const bf16x8*>((char*)SA(b, h) + lds_byte(wr * 64 + m * 16 + fr, k * 32 + fq * 8))
; #define LDB(dst, b, h) for (int n = 0; n < 2; ++n) for (int k = 0; k < 2; ++k) \
;     dst[n][k] = *reinterpret_cast<const bf16x8*>((char*)SB(b, h) + lds_byte(wc * 32 + n * 16 + fr, k * 32 + fq * 8))
; #define MMA(ai, bj, At_, Bt_) do { __builtin_amdgcn_s_setprio(1); \
;     for (int k = 0; k < 2; ++k) for (int m = 0; m < 4; ++m) for (int n = 0; n < 2; ++n) \
;       acc[ai][bj][m][n] = __builtin_amdgcn_mfma_f32_16x16x32_bf16(At_[m][k], Bt_[n][k], acc[ai][bj][m][n], 0, 0, 0); \
;     __builtin_amdgcn_s_setprio(0); } while (0)
; #define WAIT_V(n) asm volatile("s_waitcnt vmcnt(" #n ")" ::: "memory")
; #define WAIT_L(n) asm volatile("s_waitcnt lgkmcnt(" #n ")" ::: "memory")
; #define BAR __builtin_amdgcn_s_barrier()
; template <int EPI, int lda, int ldb, int N, int K>
; __device__ __forceinline__ void gemm_phase(const u16* __restrict__ A, const u16* __restrict__ Bt, const GemmEpi ep, int wv) {
;     ...
;       LDB(B1, 0, 1); BAR; WAIT_L(0); MMA(0, 1, At, B1); BAR;
;       LDA(At, 0, 1); WAIT_V(4); BAR; WAIT_L(0); MMA(1, 0, At, B0); MMA(1, 1, At, B1); BAR; }
;     { LDB(B0, 1, 0); LDA(At, 1, 0); WAIT_V(2); BAR; WAIT_L(0); MMA(0, 0, At, B0); BAR;
	s_waitcnt lgkmcnt(0)
	s_waitcnt lgkmcnt(0)
	v_mfma_f32_16x16x32_bf16 v[92:95], v[212:215], v[180:183], v[92:95]
	v_mfma_f32_16x16x32_bf16 v[88:91], v[220:223], v[180:183], v[88:91]
	v_mfma_f32_16x16x32_bf16 v[76:79], v[212:215], v[196:199], v[76:79]
	v_mfma_f32_16x16x32_bf16 v[72:75], v[220:223], v[196:199], v[72:75]
	v_mfma_f32_16x16x32_bf16 v[84:87], v[212:215], v[188:191], v[84:87]
	v_mfma_f32_16x16x32_bf16 v[80:83], v[220:223], v[188:191], v[80:83]
	v_mfma_f32_16x16x32_bf16 v[68:71], v[212:215], v[204:207], v[68:71]
	v_mfma_f32_16x16x32_bf16 v[64:67], v[220:223], v[204:207], v[64:67]
	v_mfma_f32_16x16x32_bf16 v[92:95], v[216:219], v[184:187], v[92:95]
	v_mfma_f32_16x16x32_bf16 v[88:91], v[158:161], v[184:187], v[88:91]
	v_mfma_f32_16x16x32_bf16 v[76:79], v[216:219], v[200:203], v[76:79]
	v_mfma_f32_16x16x32_bf16 v[72:75], v[158:161], v[200:203], v[72:75]
	v_mfma_f32_16x16x32_bf16 v[180:183], v[216:219], v[192:195], v[84:87]
	v_mfma_f32_16x16x32_bf16 v[184:187], v[158:161], v[192:195], v[80:83]
	v_mfma_f32_16x16x32_bf16 v[188:191], v[216:219], v[208:211], v[68:71]
	v_mfma_f32_16x16x32_bf16 v[192:195], v[158:161], v[208:211], v[64:67]
	s_barrier
	s_nop 0
	ds_read_b128 v[64:67], v152 offset:16384
	ds_read_b128 v[68:71], v152 offset:17408
	ds_read_b128 v[80:83], v151 offset:16384
	ds_read_b128 v[84:87], v151 offset:17408
	ds_read_b128 v[196:199], v150 offset:16384
	ds_read_b128 v[200:203], v150 offset:17408
	ds_read_b128 v[204:207], v149 offset:16384
	ds_read_b128 v[208:211], v149 offset:17408
	s_waitcnt vmcnt(4)
	s_barrier
	s_waitcnt lgkmcnt(0)
	s_waitcnt lgkmcnt(0)
	v_mfma_f32_16x16x32_bf16 v[60:63], v[134:137], v[64:67], v[60:63]
	v_mfma_f32_16x16x32_bf16 v[56:59], v[172:175], v[64:67], v[56:59]
	v_mfma_f32_16x16x32_bf16 v[52:55], v[134:137], v[80:83], v[52:55]
	v_mfma_f32_16x16x32_bf16 v[48:51], v[172:175], v[80:83], v[48:51]
	v_mfma_f32_16x16x32_bf16 v[44:47], v[134:137], v[196:199], v[44:47]
	v_mfma_f32_16x16x32_bf16 v[40:43], v[172:175], v[196:199], v[40:43]
	v_mfma_f32_16x16x32_bf16 v[36:39], v[134:137], v[204:207], v[36:39]
	v_mfma_f32_16x16x32_bf16 v[32:35], v[172:175], v[204:207], v[32:35]
	v_mfma_f32_16x16x32_bf16 v[60:63], v[138:141], v[68:71], v[60:63]
	v_mfma_f32_16x16x32_bf16 v[56:59], v[176:179], v[68:71], v[56:59]
	v_mfma_f32_16x16x32_bf16 v[52:55], v[138:141], v[84:87], v[52:55]
	v_mfma_f32_16x16x32_bf16 v[48:51], v[176:179], v[84:87], v[48:51]
	v_mfma_f32_16x16x32_bf16 v[44:47], v[138:141], v[200:203], v[44:47]
	v_mfma_f32_16x16x32_bf16 v[40:43], v[176:179], v[200:203], v[40:43]
	v_mfma_f32_16x16x32_bf16 v[36:39], v[138:141], v[208:211], v[36:39]
	v_mfma_f32_16x16x32_bf16 v[32:35], v[176:179], v[208:211], v[32:35]
	v_mfma_f32_16x16x32_bf16 v[28:31], v[212:215], v[64:67], v[28:31]
	v_mfma_f32_16x16x32_bf16 v[24:27], v[220:223], v[64:67], v[24:27]
	v_mfma_f32_16x16x32_bf16 v[12:15], v[212:215], v[196:199], v[12:15]
	v_mfma_f32_16x16x32_bf16 v[8:11], v[220:223], v[196:199], v[8:11]
	v_mfma_f32_16x16x32_bf16 v[20:23], v[212:215], v[80:83], v[20:23]
	v_mfma_f32_16x16x32_bf16 v[16:19], v[220:223], v[80:83], v[16:19]
	v_mfma_f32_16x16x32_bf16 v[4:7], v[212:215], v[204:207], v[4:7]
	v_mfma_f32_16x16x32_bf16 v[0:3], v[220:223], v[204:207], v[0:3]
	v_mfma_f32_16x16x32_bf16 v[28:31], v[216:219], v[68:71], v[28:31]
	v_mfma_f32_16x16x32_bf16 v[24:27], v[158:161], v[68:71], v[24:27]
	v_mfma_f32_16x16x32_bf16 v[12:15], v[216:219], v[200:203], v[12:15]
	v_mfma_f32_16x16x32_bf16 v[8:11], v[158:161], v[200:203], v[8:11]
	v_mfma_f32_16x16x32_bf16 v[134:137], v[216:219], v[84:87], v[20:23]
	v_mfma_f32_16x16x32_bf16 v[138:141], v[158:161], v[84:87], v[16:19]
	v_mfma_f32_16x16x32_bf16 v[170:173], v[216:219], v[208:211], v[4:7]
	v_mfma_f32_16x16x32_bf16 v[158:161], v[158:161], v[208:211], v[0:3]
	s_barrier
	s_nop 0
	ds_read_b128 v[0:3], v156
	ds_read_b128 v[4:7], v156 offset:1024
	ds_read_b128 v[16:19], v156 offset:2048
	ds_read_b128 v[174:177], v156 offset:3072
	ds_read_b128 v[20:23], v152 offset:32768
	ds_read_b128 v[196:199], v152 offset:33792
	ds_read_b128 v[200:203], v151 offset:32768
	ds_read_b128 v[204:207], v151 offset:33792
	ds_read_b128 v[208:211], v150 offset:32768
	ds_read_b128 v[212:215], v150 offset:33792
	ds_read_b128 v[216:219], v149 offset:32768
	ds_read_b128 v[220:223], v149 offset:33792
	s_waitcnt vmcnt(2)
	s_barrier
; #define LDA(dst, b, h) for (int m = 0; m < 4; ++m) for (int k = 0; k < 2; ++k) \
;     dst[m][k] = *reinterpret_cast<const bf16x8*>((char*)SA(b, h) + lds_byte(wr * 64 + m * 16 + fr, k * 32 + fq * 8))
; #define LDB(dst, b, h) for (int n = 0; n < 2; ++n) for (int k = 0; k < 2; ++k) \
;     dst[n][k] = *reinterpret_cast<const bf16x8*>((char*)SB(b, h) + lds_byte(wc * 32 + n * 16 + fr, k * 32 + fq * 8))
; #define MMA(ai, bj, At_, Bt_) do { __builtin_amdgcn_s_setprio(1); \
;     for (int k = 0; k < 2; ++k) for (int m = 0; m < 4; ++m) for (int n = 0; n < 2; ++n) \
;       acc[ai][bj][m][n] = __builtin_amdgcn_mfma_f32_16x16x32_bf16(At_[m][k], Bt_[n][k], acc[ai][bj][m][n], 0, 0, 0); \
;     __builtin_amdgcn_s_setprio(0); } while (0)
; #define WAIT_V(n) asm volatile("s_waitcnt vmcnt(" #n ")" ::: "memory")
; #define WAIT_L(n) asm volatile("s_waitcnt lgkmcnt(" #n ")" ::: "memory")
; #define BAR __builtin_amdgcn_s_barrier()
; template <int EPI, int lda, int ldb, int N, int K>
; __device__ __forceinline__ void gemm_phase(const u16* __restrict__ A, const u16* __restrict__ Bt, const GemmEpi ep, int wv) {
;     ...
;     { LDB(B0, 1, 0); LDA(At, 1, 0); WAIT_V(2); BAR; WAIT_L(0); MMA(0, 0, At, B0); BAR;
;       LDB(B1, 1, 1); WAIT_V(0); BAR; WAIT_L(0); MMA(0, 1, At, B1); BAR;
;       LDA(At, 1, 1); BAR; WAIT_L(0); MMA(1, 0, At, B0); MMA(1, 1, At, B1); BAR; }
;     if (wr == 0) BAR;
	s_waitcnt lgkmcnt(0)
	s_waitcnt lgkmcnt(0)
	v_mfma_f32_16x16x32_bf16 v[64:67], v[0:3], v[20:23], v[124:127]
	v_mfma_f32_16x16x32_bf16 v[68:71], v[16:19], v[20:23], v[120:123]
	v_mfma_f32_16x16x32_bf16 v[80:83], v[0:3], v[200:203], v[116:119]
	v_mfma_f32_16x16x32_bf16 v[84:87], v[16:19], v[200:203], v[112:115]
	v_mfma_f32_16x16x32_bf16 v[108:111], v[0:3], v[208:211], v[108:111]
	v_mfma_f32_16x16x32_bf16 v[104:107], v[16:19], v[208:211], v[104:107]
	v_mfma_f32_16x16x32_bf16 v[120:123], v[0:3], v[216:219], v[100:103]
	v_mfma_f32_16x16x32_bf16 v[124:127], v[16:19], v[216:219], v[96:99]
	v_mfma_f32_16x16x32_bf16 v[116:119], v[4:7], v[196:199], v[64:67]
	v_mfma_f32_16x16x32_bf16 v[112:115], v[174:177], v[196:199], v[68:71]
	v_mfma_f32_16x16x32_bf16 v[100:103], v[4:7], v[204:207], v[80:83]
	v_mfma_f32_16x16x32_bf16 v[96:99], v[174:177], v[204:207], v[84:87]
	v_mfma_f32_16x16x32_bf16 v[84:87], v[4:7], v[212:215], v[108:111]
	v_mfma_f32_16x16x32_bf16 v[80:83], v[174:177], v[212:215], v[104:107]
	v_mfma_f32_16x16x32_bf16 v[68:71], v[4:7], v[220:223], v[120:123]
	v_mfma_f32_16x16x32_bf16 v[64:67], v[174:177], v[220:223], v[124:127]
	s_barrier
	ds_read_b128 v[224:227], v154
	ds_read_b128 v[228:231], v154 offset:1024
	ds_read_b128 v[232:235], v154 offset:2048
	ds_read_b128 v[154:157], v154 offset:3072
	s_waitcnt vmcnt(0)
	s_barrier
	s_waitcnt lgkmcnt(0)
	s_waitcnt lgkmcnt(0)
	v_mfma_f32_16x16x32_bf16 v[92:95], v[224:227], v[20:23], v[92:95]
	v_mfma_f32_16x16x32_bf16 v[20:23], v[232:235], v[20:23], v[88:91]
	v_mfma_f32_16x16x32_bf16 v[88:91], v[224:227], v[200:203], v[180:183]
	v_mfma_f32_16x16x32_bf16 v[104:107], v[232:235], v[200:203], v[184:187]
	v_mfma_f32_16x16x32_bf16 v[76:79], v[224:227], v[208:211], v[76:79]
	v_mfma_f32_16x16x32_bf16 v[72:75], v[232:235], v[208:211], v[72:75]
	v_mfma_f32_16x16x32_bf16 v[178:181], v[224:227], v[216:219], v[188:191]
	v_mfma_f32_16x16x32_bf16 v[182:185], v[232:235], v[216:219], v[192:195]
	v_mfma_f32_16x16x32_bf16 v[124:127], v[228:231], v[196:199], v[92:95]
	v_mfma_f32_16x16x32_bf16 v[120:123], v[154:157], v[196:199], v[20:23]
	v_mfma_f32_16x16x32_bf16 v[108:111], v[228:231], v[204:207], v[88:91]
	v_mfma_f32_16x16x32_bf16 v[104:107], v[154:157], v[204:207], v[104:107]
	v_mfma_f32_16x16x32_bf16 v[92:95], v[228:231], v[212:215], v[76:79]
	v_mfma_f32_16x16x32_bf16 v[88:91], v[154:157], v[212:215], v[72:75]
	v_mfma_f32_16x16x32_bf16 v[76:79], v[228:231], v[220:223], v[178:181]
	v_mfma_f32_16x16x32_bf16 v[72:75], v[154:157], v[220:223], v[182:185]
	s_barrier
	ds_read_b128 v[178:181], v152 offset:49152
	ds_read_b128 v[182:185], v152 offset:50176
	ds_read_b128 v[186:189], v151 offset:49152
	ds_read_b128 v[190:193], v151 offset:50176
	ds_read_b128 v[194:197], v150 offset:49152
	ds_read_b128 v[150:153], v150 offset:50176
	ds_read_b128 v[198:201], v149 offset:49152
	ds_read_b128 v[202:205], v149 offset:50176
	s_barrier
	s_waitcnt lgkmcnt(0)
	s_waitcnt lgkmcnt(0)
	v_mfma_f32_16x16x32_bf16 v[20:23], v[0:3], v[178:181], v[60:63]
	v_mfma_f32_16x16x32_bf16 v[56:59], v[16:19], v[178:181], v[56:59]
	v_mfma_f32_16x16x32_bf16 v[60:63], v[0:3], v[186:189], v[52:55]
	v_mfma_f32_16x16x32_bf16 v[206:209], v[16:19], v[186:189], v[48:51]
	v_mfma_f32_16x16x32_bf16 v[44:47], v[0:3], v[194:197], v[44:47]
	v_mfma_f32_16x16x32_bf16 v[40:43], v[16:19], v[194:197], v[40:43]
	v_mfma_f32_16x16x32_bf16 v[0:3], v[0:3], v[198:201], v[36:39]
	v_mfma_f32_16x16x32_bf16 v[210:213], v[16:19], v[198:201], v[32:35]
	v_mfma_f32_16x16x32_bf16 v[52:55], v[4:7], v[182:185], v[20:23]
	v_mfma_f32_16x16x32_bf16 v[48:51], v[174:177], v[182:185], v[56:59]
	v_mfma_f32_16x16x32_bf16 v[36:39], v[4:7], v[190:193], v[60:63]
	v_mfma_f32_16x16x32_bf16 v[32:35], v[174:177], v[190:193], v[206:209]
	v_mfma_f32_16x16x32_bf16 v[20:23], v[4:7], v[150:153], v[44:47]
	v_mfma_f32_16x16x32_bf16 v[16:19], v[174:177], v[150:153], v[40:43]
	v_mfma_f32_16x16x32_bf16 v[4:7], v[4:7], v[202:205], v[0:3]
	v_mfma_f32_16x16x32_bf16 v[0:3], v[174:177], v[202:205], v[210:213]
	v_mfma_f32_16x16x32_bf16 v[28:31], v[224:227], v[178:181], v[28:31]
	v_mfma_f32_16x16x32_bf16 v[24:27], v[232:235], v[178:181], v[24:27]
	v_mfma_f32_16x16x32_bf16 v[40:43], v[224:227], v[186:189], v[134:137]
	v_mfma_f32_16x16x32_bf16 v[134:137], v[232:235], v[186:189], v[138:141]
	v_mfma_f32_16x16x32_bf16 v[12:15], v[224:227], v[194:197], v[12:15]
	v_mfma_f32_16x16x32_bf16 v[8:11], v[232:235], v[194:197], v[8:11]
	v_mfma_f32_16x16x32_bf16 v[138:141], v[224:227], v[198:201], v[170:173]
	v_mfma_f32_16x16x32_bf16 v[158:161], v[232:235], v[198:201], v[158:161]
	v_mfma_f32_16x16x32_bf16 v[60:63], v[228:231], v[182:185], v[28:31]
	v_mfma_f32_16x16x32_bf16 v[56:59], v[154:157], v[182:185], v[24:27]
	v_mfma_f32_16x16x32_bf16 v[44:47], v[228:231], v[190:193], v[40:43]
	v_mfma_f32_16x16x32_bf16 v[40:43], v[154:157], v[190:193], v[134:137]
	v_mfma_f32_16x16x32_bf16 v[28:31], v[228:231], v[150:153], v[12:15]
	v_mfma_f32_16x16x32_bf16 v[24:27], v[154:157], v[150:153], v[8:11]
	v_mfma_f32_16x16x32_bf16 v[12:15], v[228:231], v[202:205], v[138:141]
	v_mfma_f32_16x16x32_bf16 v[8:11], v[154:157], v[202:205], v[158:161]
	v_cmp_gt_u32_e32 vcc, s56, v130
	s_barrier
	s_and_saveexec_b64 s[42:43], vcc
	s_cbranch_execz .LBB0_56
	s_barrier

; #define STAGE(P, BASE, LD, br, kt) do { const char* _g = (const char*)((BASE) + (size_t)(br) * (LD) + (size_t)(kt) * 64); \
;     for (int _i = 0; _i < 2; ++_i) { int _b = tidx * 16 + _i * 8192; int _r, _c; stage_rc(_b, _r, _c); \
;       __builtin_amdgcn_global_load_lds((const unsigned*)(_g + (unsigned)((_r * (LD) + _c) * 2)), (unsigned*)((char*)(P) + _b), 16, 0, 0); } } while (0)
; #define LDA(dst, b, h) for (int m = 0; m < 4; ++m) for (int k = 0; k < 2; ++k) \
;     dst[m][k] = *reinterpret_cast<const bf16x8*>((char*)SA(b, h) + lds_byte(wr * 64 + m * 16 + fr, k * 32 + fq * 8))
; #define LDB(dst, b, h) for (int n = 0; n < 2; ++n) for (int k = 0; k < 2; ++k) \
;     dst[n][k] = *reinterpret_cast<const bf16x8*>((char*)SB(b, h) + lds_byte(wc * 32 + n * 16 + fr, k * 32 + fq * 8))
; #define MMA(ai, bj, At_, Bt_) do { __builtin_amdgcn_s_setprio(1); \
;     for (int k = 0; k < 2; ++k) for (int m = 0; m < 4; ++m) for (int n = 0; n < 2; ++n) \
;       acc[ai][bj][m][n] = __builtin_amdgcn_mfma_f32_16x16x32_bf16(At_[m][k], Bt_[n][k], acc[ai][bj][m][n], 0, 0, 0); \
;     __builtin_amdgcn_s_setprio(0); } while (0)
; #define WAIT_L(n) asm volatile("s_waitcnt lgkmcnt(" #n ")" ::: "memory")
; #define BAR __builtin_amdgcn_s_barrier()
; #define SCHED __builtin_amdgcn_sched_barrier(0)
; template <int EPI, int lda, int ldb, int N, int K>
; __device__ __forceinline__ void gemm_phase(const u16* __restrict__ A, const u16* __restrict__ Bt, const GemmEpi ep, int wv) {
;     ...
;     for (int t = 0; t < nt - 2; t += 2) {
;       LDB(B0, 0, 0); SCHED; LDA(At, 0, 0); STAGE(SA(1, 1), Ab, lda, brow + HALF, t + 1);
;       WAIT_L(8); BAR; WAIT_L(0); MMA(0, 0, At, B0); BAR; SCHED;
;       LDB(B1, 0, 1); STAGE(SB(0, 0), Bt, ldb, bcol, t + 2);
;       BAR; WAIT_L(0); MMA(0, 1, At, B1); BAR;
;       LDA(At, 0, 1); STAGE(SA(0, 0), Ab, lda, brow, t + 2);
;       BAR; WAIT_L(0); MMA(1, 0, At, B0); BAR; SCHED;
.LBB0_224:
	ds_read_b128 v[168:171], v164
	ds_read_b128 v[174:177], v164 offset:1024
	ds_read_b128 v[178:181], v164 offset:2048
	ds_read_b128 v[182:185], v164 offset:3072
	v_add_u32_e32 v172, 0xc000, v147
	v_lshl_add_u64 v[238:239], v[136:137], 0, s[44:45]
	v_readfirstlane_b32 s66, v172
	v_add_u32_e32 v173, 0xe000, v147
	v_lshl_add_u64 v[166:167], v[238:239], 0, s[18:19]
	s_mov_b32 m0, s66
	v_lshl_add_u64 v[240:241], v[134:135], 0, s[44:45]
	v_readfirstlane_b32 s66, v173
	ds_read_b128 v[186:189], v155
	ds_read_b128 v[190:193], v155 offset:1024
	ds_read_b128 v[194:197], v154
	ds_read_b128 v[198:201], v154 offset:1024
	ds_read_b128 v[202:205], v153
	ds_read_b128 v[206:209], v153 offset:1024
	ds_read_b128 v[210:213], v152
	ds_read_b128 v[214:217], v152 offset:1024
	global_load_lds_dwordx4 v[166:167], off
	s_nop 1
	v_lshl_add_u64 v[166:167], v[240:241], 0, s[18:19]
	s_mov_b32 m0, s66
	s_nop 0
	global_load_lds_dwordx4 v[166:167], off
	s_waitcnt lgkmcnt(8)
	s_barrier
	s_waitcnt lgkmcnt(0)
	s_waitcnt lgkmcnt(0)
	v_mfma_f32_16x16x32_bf16 v[124:127], v[168:171], v[186:189], v[124:127]
	v_mfma_f32_16x16x32_bf16 v[120:123], v[178:181], v[186:189], v[120:123]
	v_mfma_f32_16x16x32_bf16 v[116:119], v[168:171], v[194:197], v[116:119]
	v_mfma_f32_16x16x32_bf16 v[112:115], v[178:181], v[194:197], v[112:115]
	v_mfma_f32_16x16x32_bf16 v[108:111], v[168:171], v[202:205], v[108:111]
	v_mfma_f32_16x16x32_bf16 v[104:107], v[178:181], v[202:205], v[104:107]
	v_mfma_f32_16x16x32_bf16 v[100:103], v[168:171], v[210:213], v[100:103]
	v_mfma_f32_16x16x32_bf16 v[96:99], v[178:181], v[210:213], v[96:99]
	v_mfma_f32_16x16x32_bf16 v[124:127], v[174:177], v[190:193], v[124:127]
	v_mfma_f32_16x16x32_bf16 v[120:123], v[182:185], v[190:193], v[120:123]
	v_mfma_f32_16x16x32_bf16 v[116:119], v[174:177], v[198:201], v[116:119]
	v_mfma_f32_16x16x32_bf16 v[112:115], v[182:185], v[198:201], v[112:115]
	v_mfma_f32_16x16x32_bf16 v[108:111], v[174:177], v[206:209], v[108:111]
	v_mfma_f32_16x16x32_bf16 v[104:107], v[182:185], v[206:209], v[104:107]
	v_mfma_f32_16x16x32_bf16 v[100:103], v[174:177], v[214:217], v[100:103]
	v_mfma_f32_16x16x32_bf16 v[96:99], v[182:185], v[214:217], v[96:99]
	s_barrier
	v_add_u32_e32 v165, s55, v156
	v_lshl_add_u64 v[242:243], v[144:145], 0, s[44:45]
	v_readfirstlane_b32 s66, v165
	v_lshl_add_u64 v[166:167], v[242:243], 0, s[20:21]
	s_mov_b32 m0, s66
	ds_read_b128 v[218:221], v163
	ds_read_b128 v[222:225], v163 offset:1024
	ds_read_b128 v[226:229], v163 offset:2048
	ds_read_b128 v[230:233], v163 offset:3072
	global_load_lds_dwordx4 v[166:167], off
	s_nop 1
	v_add_u32_e32 v166, 0x2000, v165
	v_lshl_add_u64 v[244:245], v[142:143], 0, s[44:45]
	v_readfirstlane_b32 s66, v166
	v_lshl_add_u64 v[234:235], v[244:245], 0, s[20:21]
	s_mov_b32 m0, s66
	s_nop 0
	global_load_lds_dwordx4 v[234:235], off
	s_barrier
	s_waitcnt lgkmcnt(0)
	s_waitcnt lgkmcnt(0)
	v_mfma_f32_16x16x32_bf16 v[92:95], v[218:221], v[186:189], v[92:95]
	v_mfma_f32_16x16x32_bf16 v[88:91], v[226:229], v[186:189], v[88:91]
	v_mfma_f32_16x16x32_bf16 v[84:87], v[218:221], v[194:197], v[84:87]
	v_mfma_f32_16x16x32_bf16 v[80:83], v[226:229], v[194:197], v[80:83]
	v_mfma_f32_16x16x32_bf16 v[76:79], v[218:221], v[202:205], v[76:79]
	v_mfma_f32_16x16x32_bf16 v[72:75], v[226:229], v[202:205], v[72:75]
	v_mfma_f32_16x16x32_bf16 v[68:71], v[218:221], v[210:213], v[68:71]
	v_mfma_f32_16x16x32_bf16 v[64:67], v[226:229], v[210:213], v[64:67]
	v_mfma_f32_16x16x32_bf16 v[92:95], v[222:225], v[190:193], v[92:95]
	v_mfma_f32_16x16x32_bf16 v[88:91], v[230:233], v[190:193], v[88:91]
	v_mfma_f32_16x16x32_bf16 v[84:87], v[222:225], v[198:201], v[84:87]
	v_mfma_f32_16x16x32_bf16 v[80:83], v[230:233], v[198:201], v[80:83]
	v_mfma_f32_16x16x32_bf16 v[76:79], v[222:225], v[206:209], v[76:79]
	v_mfma_f32_16x16x32_bf16 v[72:75], v[230:233], v[206:209], v[72:75]
	v_mfma_f32_16x16x32_bf16 v[68:71], v[222:225], v[214:217], v[68:71]
	v_mfma_f32_16x16x32_bf16 v[64:67], v[230:233], v[214:217], v[64:67]
	v_readfirstlane_b32 s66, v147
	v_add_u32_e32 v167, 0x2000, v147
	v_lshl_add_u64 v[234:235], v[238:239], 0, s[22:23]
	s_mov_b32 m0, s66
	v_readfirstlane_b32 s66, v167
	s_barrier
	ds_read_b128 v[186:189], v155 offset:16384
	ds_read_b128 v[190:193], v155 offset:17408
	ds_read_b128 v[194:197], v154 offset:16384
	ds_read_b128 v[198:201], v154 offset:17408
	ds_read_b128 v[202:205], v153 offset:16384
	ds_read_b128 v[206:209], v153 offset:17408
	ds_read_b128 v[210:213], v152 offset:16384
	ds_read_b128 v[214:217], v152 offset:17408
	global_load_lds_dwordx4 v[234:235], off
	s_nop 1
	v_lshl_add_u64 v[234:235], v[240:241], 0, s[22:23]
	s_mov_b32 m0, s66
	s_nop 0
	global_load_lds_dwordx4 v[234:235], off
	s_barrier
	s_waitcnt lgkmcnt(0)
	s_waitcnt lgkmcnt(0)
	v_mfma_f32_16x16x32_bf16 v[60:63], v[168:171], v[186:189], v[60:63]
	v_mfma_f32_16x16x32_bf16 v[56:59], v[178:181], v[186:189], v[56:59]
	v_mfma_f32_16x16x32_bf16 v[52:55], v[168:171], v[194:197], v[52:55]
	v_mfma_f32_16x16x32_bf16 v[48:51], v[178:181], v[194:197], v[48:51]
	v_mfma_f32_16x16x32_bf16 v[44:47], v[168:171], v[202:205], v[44:47]
	v_mfma_f32_16x16x32_bf16 v[40:43], v[178:181], v[202:205], v[40:43]
	v_mfma_f32_16x16x32_bf16 v[36:39], v[168:171], v[210:213], v[36:39]
	v_mfma_f32_16x16x32_bf16 v[32:35], v[178:181], v[210:213], v[32:35]
	v_mfma_f32_16x16x32_bf16 v[60:63], v[174:177], v[190:193], v[60:63]
	v_mfma_f32_16x16x32_bf16 v[56:59], v[182:185], v[190:193], v[56:59]
	v_mfma_f32_16x16x32_bf16 v[52:55], v[174:177], v[198:201], v[52:55]
	v_mfma_f32_16x16x32_bf16 v[48:51], v[182:185], v[198:201], v[48:51]
	v_mfma_f32_16x16x32_bf16 v[44:47], v[174:177], v[206:209], v[44:47]
	v_mfma_f32_16x16x32_bf16 v[40:43], v[182:185], v[206:209], v[40:43]
	v_mfma_f32_16x16x32_bf16 v[36:39], v[174:177], v[214:217], v[36:39]
	v_mfma_f32_16x16x32_bf16 v[32:35], v[182:185], v[214:217], v[32:35]
	s_barrier
; #define STAGE(P, BASE, LD, br, kt) do { const char* _g = (const char*)((BASE) + (size_t)(br) * (LD) + (size_t)(kt) * 64); \
;     for (int _i = 0; _i < 2; ++_i) { int _b = tidx * 16 + _i * 8192; int _r, _c; stage_rc(_b, _r, _c); \
;       __builtin_amdgcn_global_load_lds((const unsigned*)(_g + (unsigned)((_r * (LD) + _c) * 2)), (unsigned*)((char*)(P) + _b), 16, 0, 0); } } while (0)
; #define LDA(dst, b, h) for (int m = 0; m < 4; ++m) for (int k = 0; k < 2; ++k) \
;     dst[m][k] = *reinterpret_cast<const bf16x8*>((char*)SA(b, h) + lds_byte(wr * 64 + m * 16 + fr, k * 32 + fq * 8))
; #define LDB(dst, b, h) for (int n = 0; n < 2; ++n) for (int k = 0; k < 2; ++k) \
;     dst[n][k] = *reinterpret_cast<const bf16x8*>((char*)SB(b, h) + lds_byte(wc * 32 + n * 16 + fr, k * 32 + fq * 8))
; #define MMA(ai, bj, At_, Bt_) do { __builtin_amdgcn_s_setprio(1); \
;     for (int k = 0; k < 2; ++k) for (int m = 0; m < 4; ++m) for (int n = 0; n < 2; ++n) \
;       acc[ai][bj][m][n] = __builtin_amdgcn_mfma_f32_16x16x32_bf16(At_[m][k], Bt_[n][k], acc[ai][bj][m][n], 0, 0, 0); \
;     __builtin_amdgcn_s_setprio(0); } while (0)
; #define WAIT_V(n) asm volatile("s_waitcnt vmcnt(" #n ")" ::: "memory")
; #define WAIT_L(n) asm volatile("s_waitcnt lgkmcnt(" #n ")" ::: "memory")
; #define BAR __builtin_amdgcn_s_barrier()
; #define SCHED __builtin_amdgcn_sched_barrier(0)
; template <int EPI, int lda, int ldb, int N, int K>
; __device__ __forceinline__ void gemm_phase(const u16* __restrict__ A, const u16* __restrict__ Bt, const GemmEpi ep, int wv) {
;     ...
;       STAGE(SB(0, 1), Bt, ldb, bcol + HALF, t + 2);
;       WAIT_V(6); BAR; MMA(1, 1, At, B1); BAR;
;       LDB(B0, 1, 0); SCHED; LDA(At, 1, 0); STAGE(SA(0, 1), Ab, lda, brow + HALF, t + 2);
;       WAIT_L(8); BAR; WAIT_L(0); MMA(0, 0, At, B0); BAR; SCHED;
;       LDB(B1, 1, 1); STAGE(SB(1, 0), Bt, ldb, bcol, t + 3);
;       BAR; WAIT_L(0); MMA(0, 1, At, B1); BAR;
;       LDA(At, 1, 1); STAGE(SA(1, 0), Ab, lda, brow, t + 3);
	v_add_u32_e32 v168, s56, v156
	v_lshl_add_u64 v[246:247], v[140:141], 0, s[44:45]
	v_readfirstlane_b32 s66, v168
	v_add_u32_e32 v169, 0x2000, v168
	v_lshl_add_u64 v[170:171], v[246:247], 0, s[24:25]
	s_mov_b32 m0, s66
	v_lshl_add_u64 v[248:249], v[138:139], 0, s[44:45]
	v_readfirstlane_b32 s66, v169
	global_load_lds_dwordx4 v[170:171], off
	s_nop 1
	v_lshl_add_u64 v[170:171], v[248:249], 0, s[24:25]
	s_mov_b32 m0, s66
	s_nop 0
	global_load_lds_dwordx4 v[170:171], off
	s_waitcnt vmcnt(6)
	s_barrier
	v_mfma_f32_16x16x32_bf16 v[28:31], v[218:221], v[186:189], v[28:31]
	v_mfma_f32_16x16x32_bf16 v[24:27], v[226:229], v[186:189], v[24:27]
	v_mfma_f32_16x16x32_bf16 v[20:23], v[218:221], v[194:197], v[20:23]
	v_mfma_f32_16x16x32_bf16 v[16:19], v[226:229], v[194:197], v[16:19]
	v_mfma_f32_16x16x32_bf16 v[12:15], v[218:221], v[202:205], v[12:15]
	v_mfma_f32_16x16x32_bf16 v[8:11], v[226:229], v[202:205], v[8:11]
	v_mfma_f32_16x16x32_bf16 v[4:7], v[218:221], v[210:213], v[4:7]
	v_mfma_f32_16x16x32_bf16 v[0:3], v[226:229], v[210:213], v[0:3]
	v_mfma_f32_16x16x32_bf16 v[28:31], v[222:225], v[190:193], v[28:31]
	v_mfma_f32_16x16x32_bf16 v[24:27], v[230:233], v[190:193], v[24:27]
	v_mfma_f32_16x16x32_bf16 v[20:23], v[222:225], v[198:201], v[20:23]
	v_mfma_f32_16x16x32_bf16 v[16:19], v[230:233], v[198:201], v[16:19]
	v_mfma_f32_16x16x32_bf16 v[12:15], v[222:225], v[206:209], v[12:15]
	v_mfma_f32_16x16x32_bf16 v[8:11], v[230:233], v[206:209], v[8:11]
	v_mfma_f32_16x16x32_bf16 v[4:7], v[222:225], v[214:217], v[4:7]
	v_mfma_f32_16x16x32_bf16 v[0:3], v[230:233], v[214:217], v[0:3]
	s_barrier
	ds_read_b128 v[174:177], v159
	ds_read_b128 v[178:181], v159 offset:1024
	ds_read_b128 v[182:185], v159 offset:2048
	ds_read_b128 v[186:189], v159 offset:3072
	v_add_u32_e32 v170, 0x4000, v147
	v_add_u32_e32 v171, 0x6000, v147
	v_readfirstlane_b32 s66, v170
	v_lshl_add_u64 v[222:223], v[238:239], 0, s[26:27]
	s_mov_b32 m0, s66
	v_readfirstlane_b32 s66, v171
	ds_read_b128 v[190:193], v155 offset:32768
	ds_read_b128 v[194:197], v155 offset:33792
	ds_read_b128 v[198:201], v154 offset:32768
	ds_read_b128 v[202:205], v154 offset:33792
	ds_read_b128 v[206:209], v153 offset:32768
	ds_read_b128 v[210:213], v153 offset:33792
	ds_read_b128 v[214:217], v152 offset:32768
	ds_read_b128 v[218:221], v152 offset:33792
	global_load_lds_dwordx4 v[222:223], off
	s_nop 1
	v_lshl_add_u64 v[222:223], v[240:241], 0, s[26:27]
	s_mov_b32 m0, s66
	s_nop 0
	global_load_lds_dwordx4 v[222:223], off
	s_waitcnt lgkmcnt(8)
	s_barrier
	s_waitcnt lgkmcnt(0)
	s_waitcnt lgkmcnt(0)
	v_mfma_f32_16x16x32_bf16 v[124:127], v[174:177], v[190:193], v[124:127]
	v_mfma_f32_16x16x32_bf16 v[120:123], v[182:185], v[190:193], v[120:123]
	v_mfma_f32_16x16x32_bf16 v[116:119], v[174:177], v[198:201], v[116:119]
	v_mfma_f32_16x16x32_bf16 v[112:115], v[182:185], v[198:201], v[112:115]
	v_mfma_f32_16x16x32_bf16 v[108:111], v[174:177], v[206:209], v[108:111]
	v_mfma_f32_16x16x32_bf16 v[104:107], v[182:185], v[206:209], v[104:107]
	v_mfma_f32_16x16x32_bf16 v[100:103], v[174:177], v[214:217], v[100:103]
	v_mfma_f32_16x16x32_bf16 v[96:99], v[182:185], v[214:217], v[96:99]
	v_mfma_f32_16x16x32_bf16 v[124:127], v[178:181], v[194:197], v[124:127]
	v_mfma_f32_16x16x32_bf16 v[120:123], v[186:189], v[194:197], v[120:123]
	v_mfma_f32_16x16x32_bf16 v[116:119], v[178:181], v[202:205], v[116:119]
	v_mfma_f32_16x16x32_bf16 v[112:115], v[186:189], v[202:205], v[112:115]
	v_mfma_f32_16x16x32_bf16 v[108:111], v[178:181], v[210:213], v[108:111]
	v_mfma_f32_16x16x32_bf16 v[104:107], v[186:189], v[210:213], v[104:107]
	v_mfma_f32_16x16x32_bf16 v[100:103], v[178:181], v[218:221], v[100:103]
	v_mfma_f32_16x16x32_bf16 v[96:99], v[186:189], v[218:221], v[96:99]
	s_barrier
	v_readfirstlane_b32 s66, v158
	v_lshl_add_u64 v[242:243], v[242:243], 0, s[36:37]
	s_mov_b32 m0, s66
	ds_read_b128 v[222:225], v157
	ds_read_b128 v[226:229], v157 offset:1024
	ds_read_b128 v[230:233], v157 offset:2048
	ds_read_b128 v[234:237], v157 offset:3072
	global_load_lds_dwordx4 v[242:243], off
	s_nop 1
	v_lshl_add_u64 v[242:243], v[244:245], 0, s[36:37]
	v_add_u32_e32 v244, 0x2000, v158
	s_nop 0
	v_readfirstlane_b32 s66, v244
	s_mov_b32 m0, s66
	s_nop 0
	global_load_lds_dwordx4 v[242:243], off
	s_barrier
	s_waitcnt lgkmcnt(0)
	s_waitcnt lgkmcnt(0)
	v_mfma_f32_16x16x32_bf16 v[92:95], v[222:225], v[190:193], v[92:95]
	v_mfma_f32_16x16x32_bf16 v[88:91], v[230:233], v[190:193], v[88:91]
	v_mfma_f32_16x16x32_bf16 v[84:87], v[222:225], v[198:201], v[84:87]
	v_mfma_f32_16x16x32_bf16 v[80:83], v[230:233], v[198:201], v[80:83]
	v_mfma_f32_16x16x32_bf16 v[76:79], v[222:225], v[206:209], v[76:79]
	v_mfma_f32_16x16x32_bf16 v[72:75], v[230:233], v[206:209], v[72:75]
	v_mfma_f32_16x16x32_bf16 v[68:71], v[222:225], v[214:217], v[68:71]
	v_mfma_f32_16x16x32_bf16 v[64:67], v[230:233], v[214:217], v[64:67]
	v_mfma_f32_16x16x32_bf16 v[92:95], v[226:229], v[194:197], v[92:95]
	v_mfma_f32_16x16x32_bf16 v[88:91], v[234:237], v[194:197], v[88:91]
	v_mfma_f32_16x16x32_bf16 v[84:87], v[226:229], v[202:205], v[84:87]
	v_mfma_f32_16x16x32_bf16 v[80:83], v[234:237], v[202:205], v[80:83]
	v_mfma_f32_16x16x32_bf16 v[76:79], v[226:229], v[210:213], v[76:79]
	v_mfma_f32_16x16x32_bf16 v[72:75], v[234:237], v[210:213], v[72:75]
	v_mfma_f32_16x16x32_bf16 v[68:71], v[226:229], v[218:221], v[68:71]
	v_mfma_f32_16x16x32_bf16 v[64:67], v[234:237], v[218:221], v[64:67]
	v_readfirstlane_b32 s66, v160
	v_lshl_add_u64 v[238:239], v[238:239], 0, s[38:39]
	s_mov_b32 m0, s66
	v_readfirstlane_b32 s66, v161
	s_barrier
; #define STAGE(P, BASE, LD, br, kt) do { const char* _g = (const char*)((BASE) + (size_t)(br) * (LD) + (size_t)(kt) * 64); \
;     for (int _i = 0; _i < 2; ++_i) { int _b = tidx * 16 + _i * 8192; int _r, _c; stage_rc(_b, _r, _c); \
;       __builtin_amdgcn_global_load_lds((const unsigned*)(_g + (unsigned)((_r * (LD) + _c) * 2)), (unsigned*)((char*)(P) + _b), 16, 0, 0); } } while (0)
; #define LDA(dst, b, h) for (int m = 0; m < 4; ++m) for (int k = 0; k < 2; ++k) \
;     dst[m][k] = *reinterpret_cast<const bf16x8*>((char*)SA(b, h) + lds_byte(wr * 64 + m * 16 + fr, k * 32 + fq * 8))
; #define LDB(dst, b, h) for (int n = 0; n < 2; ++n) for (int k = 0; k < 2; ++k) \
;     dst[n][k] = *reinterpret_cast<const bf16x8*>((char*)SB(b, h) + lds_byte(wc * 32 + n * 16 + fr, k * 32 + fq * 8))
; #define MMA(ai, bj, At_, Bt_) do { __builtin_amdgcn_s_setprio(1); \
;     for (int k = 0; k < 2; ++k) for (int m = 0; m < 4; ++m) for (int n = 0; n < 2; ++n) \
;       acc[ai][bj][m][n] = __builtin_amdgcn_mfma_f32_16x16x32_bf16(At_[m][k], Bt_[n][k], acc[ai][bj][m][n], 0, 0, 0); \
;     __builtin_amdgcn_s_setprio(0); } while (0)
; #define WAIT_V(n) asm volatile("s_waitcnt vmcnt(" #n ")" ::: "memory")
; #define WAIT_L(n) asm volatile("s_waitcnt lgkmcnt(" #n ")" ::: "memory")
; #define BAR __builtin_amdgcn_s_barrier()
; #define SCHED __builtin_amdgcn_sched_barrier(0)
; template <int EPI, int lda, int ldb, int N, int K>
; __device__ __forceinline__ void gemm_phase(const u16* __restrict__ A, const u16* __restrict__ Bt, const GemmEpi ep, int wv) {
;     ...
;       BAR; WAIT_L(0); MMA(1, 0, At, B0); BAR; SCHED;
;       STAGE(SB(1, 1), Bt, ldb, bcol + HALF, t + 3);
;       WAIT_V(6); BAR; MMA(1, 1, At, B1); BAR;
;     }
;     { LDB(B0, 0, 0); LDA(At, 0, 0); STAGE(SA(1, 1), Ab, lda, brow + HALF, nt - 1);
;       BAR; WAIT_L(0); MMA(0, 0, At, B0); BAR;
;       LDB(B1, 0, 1); BAR; WAIT_L(0); MMA(0, 1, At, B1); BAR;
	ds_read_b128 v[190:193], v155 offset:49152
	ds_read_b128 v[194:197], v155 offset:50176
	ds_read_b128 v[198:201], v154 offset:49152
	ds_read_b128 v[202:205], v154 offset:50176
	ds_read_b128 v[206:209], v153 offset:49152
	ds_read_b128 v[210:213], v153 offset:50176
	ds_read_b128 v[214:217], v152 offset:49152
	ds_read_b128 v[218:221], v152 offset:50176
	global_load_lds_dwordx4 v[238:239], off
	s_nop 1
	v_lshl_add_u64 v[238:239], v[240:241], 0, s[38:39]
	s_mov_b32 m0, s66
	s_nop 0
	global_load_lds_dwordx4 v[238:239], off
	s_barrier
	s_waitcnt lgkmcnt(0)
	s_waitcnt lgkmcnt(0)
	v_mfma_f32_16x16x32_bf16 v[60:63], v[174:177], v[190:193], v[60:63]
	v_mfma_f32_16x16x32_bf16 v[56:59], v[182:185], v[190:193], v[56:59]
	v_mfma_f32_16x16x32_bf16 v[52:55], v[174:177], v[198:201], v[52:55]
	v_mfma_f32_16x16x32_bf16 v[48:51], v[182:185], v[198:201], v[48:51]
	v_mfma_f32_16x16x32_bf16 v[44:47], v[174:177], v[206:209], v[44:47]
	v_mfma_f32_16x16x32_bf16 v[40:43], v[182:185], v[206:209], v[40:43]
	v_mfma_f32_16x16x32_bf16 v[36:39], v[174:177], v[214:217], v[36:39]
	v_mfma_f32_16x16x32_bf16 v[32:35], v[182:185], v[214:217], v[32:35]
	v_mfma_f32_16x16x32_bf16 v[60:63], v[178:181], v[194:197], v[60:63]
	v_mfma_f32_16x16x32_bf16 v[56:59], v[186:189], v[194:197], v[56:59]
	v_mfma_f32_16x16x32_bf16 v[52:55], v[178:181], v[202:205], v[52:55]
	v_mfma_f32_16x16x32_bf16 v[48:51], v[186:189], v[202:205], v[48:51]
	v_mfma_f32_16x16x32_bf16 v[44:47], v[178:181], v[210:213], v[44:47]
	v_mfma_f32_16x16x32_bf16 v[40:43], v[186:189], v[210:213], v[40:43]
	v_mfma_f32_16x16x32_bf16 v[36:39], v[178:181], v[218:221], v[36:39]
	v_mfma_f32_16x16x32_bf16 v[32:35], v[186:189], v[218:221], v[32:35]
	s_barrier
	v_readfirstlane_b32 s66, v162
	v_add_u32_e32 v176, 0x2000, v162
	v_lshl_add_u64 v[174:175], v[246:247], 0, s[42:43]
	s_mov_b32 m0, s66
	v_readfirstlane_b32 s66, v176
	global_load_lds_dwordx4 v[174:175], off
	s_nop 1
	v_lshl_add_u64 v[174:175], v[248:249], 0, s[42:43]
	s_mov_b32 m0, s66
	s_nop 0
	global_load_lds_dwordx4 v[174:175], off
	s_waitcnt vmcnt(6)
	s_barrier
	v_mfma_f32_16x16x32_bf16 v[28:31], v[222:225], v[190:193], v[28:31]
	v_mfma_f32_16x16x32_bf16 v[24:27], v[230:233], v[190:193], v[24:27]
	v_mfma_f32_16x16x32_bf16 v[20:23], v[222:225], v[198:201], v[20:23]
	v_mfma_f32_16x16x32_bf16 v[16:19], v[230:233], v[198:201], v[16:19]
	v_mfma_f32_16x16x32_bf16 v[12:15], v[222:225], v[206:209], v[12:15]
	v_mfma_f32_16x16x32_bf16 v[8:11], v[230:233], v[206:209], v[8:11]
	v_mfma_f32_16x16x32_bf16 v[4:7], v[222:225], v[214:217], v[4:7]
	v_mfma_f32_16x16x32_bf16 v[0:3], v[230:233], v[214:217], v[0:3]
	v_mfma_f32_16x16x32_bf16 v[28:31], v[226:229], v[194:197], v[28:31]
	v_mfma_f32_16x16x32_bf16 v[24:27], v[234:237], v[194:197], v[24:27]
	v_mfma_f32_16x16x32_bf16 v[20:23], v[226:229], v[202:205], v[20:23]
	v_mfma_f32_16x16x32_bf16 v[16:19], v[234:237], v[202:205], v[16:19]
	v_mfma_f32_16x16x32_bf16 v[12:15], v[226:229], v[210:213], v[12:15]
	v_mfma_f32_16x16x32_bf16 v[8:11], v[234:237], v[210:213], v[8:11]
	v_mfma_f32_16x16x32_bf16 v[4:7], v[226:229], v[218:221], v[4:7]
	v_mfma_f32_16x16x32_bf16 v[0:3], v[234:237], v[218:221], v[0:3]
	s_add_i32 s65, s65, 2
	s_add_u32 s44, s44, 0x100
	s_addc_u32 s45, s45, 0
	s_cmpk_gt_u32 s65, 0x51
	s_barrier
	s_cbranch_scc0 .LBB0_224
	s_add_i32 s44, s14, 0x80
	s_mul_hi_i32 s45, s44, 0x2b00
	s_mulk_i32 s44, 0x2b00
	s_add_u32 s44, s48, s44
	s_addc_u32 s45, s49, s45
	s_add_u32 s44, s44, 0x2a80
	s_addc_u32 s45, s45, 0
	v_readfirstlane_b32 s65, v172
	v_lshl_add_u64 v[160:161], s[44:45], 0, v[128:129]
	s_mov_b32 m0, s65
	ds_read_b128 v[134:137], v164
	ds_read_b128 v[138:141], v164 offset:1024
	ds_read_b128 v[142:145], v164 offset:2048
	ds_read_b128 v[174:177], v164 offset:3072
	ds_read_b128 v[178:181], v155
	ds_read_b128 v[182:185], v155 offset:1024
	ds_read_b128 v[186:189], v154
	ds_read_b128 v[190:193], v154 offset:1024
	ds_read_b128 v[194:197], v153
	ds_read_b128 v[198:201], v153 offset:1024
	ds_read_b128 v[202:205], v152
	ds_read_b128 v[206:209], v152 offset:1024
	global_load_lds_dwordx4 v[160:161], off
	v_lshl_add_u64 v[160:161], s[44:45], 0, v[132:133]
	v_readfirstlane_b32 s44, v173
	s_mov_b32 m0, s44
	s_nop 0
	global_load_lds_dwordx4 v[160:161], off
	s_barrier
	s_waitcnt lgkmcnt(0)
	s_waitcnt lgkmcnt(0)
	v_mfma_f32_16x16x32_bf16 v[124:127], v[134:137], v[178:181], v[124:127]
	v_mfma_f32_16x16x32_bf16 v[120:123], v[142:145], v[178:181], v[120:123]
	v_mfma_f32_16x16x32_bf16 v[116:119], v[134:137], v[186:189], v[116:119]
	v_mfma_f32_16x16x32_bf16 v[112:115], v[142:145], v[186:189], v[112:115]
	v_mfma_f32_16x16x32_bf16 v[108:111], v[134:137], v[194:197], v[108:111]
	v_mfma_f32_16x16x32_bf16 v[104:107], v[142:145], v[194:197], v[104:107]
	v_mfma_f32_16x16x32_bf16 v[100:103], v[134:137], v[202:205], v[100:103]
	v_mfma_f32_16x16x32_bf16 v[96:99], v[142:145], v[202:205], v[96:99]
	v_mfma_f32_16x16x32_bf16 v[124:127], v[138:141], v[182:185], v[124:127]
	v_mfma_f32_16x16x32_bf16 v[120:123], v[174:177], v[182:185], v[120:123]
	v_mfma_f32_16x16x32_bf16 v[116:119], v[138:141], v[190:193], v[116:119]
	v_mfma_f32_16x16x32_bf16 v[112:115], v[174:177], v[190:193], v[112:115]
	v_mfma_f32_16x16x32_bf16 v[108:111], v[138:141], v[198:201], v[108:111]
	v_mfma_f32_16x16x32_bf16 v[104:107], v[174:177], v[198:201], v[104:107]
	v_mfma_f32_16x16x32_bf16 v[100:103], v[138:141], v[206:209], v[100:103]
	v_mfma_f32_16x16x32_bf16 v[96:99], v[174:177], v[206:209], v[96:99]
	s_barrier
	ds_read_b128 v[210:213], v163
	ds_read_b128 v[214:217], v163 offset:1024
	ds_read_b128 v[218:221], v163 offset:2048
	ds_read_b128 v[160:163], v163 offset:3072
	s_barrier
; #define LDA(dst, b, h) for (int m = 0; m < 4; ++m) for (int k = 0; k < 2; ++k) \
;     dst[m][k] = *reinterpret_cast<const bf16x8*>((char*)SA(b, h) + lds_byte(wr * 64 + m * 16 + fr, k * 32 + fq * 8))
; #define LDB(dst, b, h) for (int n = 0; n < 2; ++n) for (int k = 0; k < 2; ++k) \
;     dst[n][k] = *reinterpret_cast<const bf16x8*>((char*)SB(b, h) + lds_byte(wc * 32 + n * 16 + fr, k * 32 + fq * 8))
; #define MMA(ai, bj, At_, Bt_) do { __builtin_amdgcn_s_setprio(1); \
;     for (int k = 0; k < 2; ++k) for (int m = 0; m < 4; ++m) for (int n = 0; n < 2; ++n) \
;       acc[ai][bj][m][n] = __builtin_amdgcn_mfma_f32_16x16x32_bf16(At_[m][k], Bt_[n][k], acc[ai][bj][m][n], 0, 0, 0); \
;     __builtin_amdgcn_s_setprio(0); } while (0)
; #define WAIT_V(n) asm volatile("s_waitcnt vmcnt(" #n ")" ::: "memory")
; #define WAIT_L(n) asm volatile("s_waitcnt lgkmcnt(" #n ")" ::: "memory")
; #define BAR __builtin_amdgcn_s_barrier()
; template <int EPI, int lda, int ldb, int N, int K>
; __device__ __forceinline__ void gemm_phase(const u16* __restrict__ A, const u16* __restrict__ Bt, const GemmEpi ep, int wv) {
;     ...
;       LDB(B1, 0, 1); BAR; WAIT_L(0); MMA(0, 1, At, B1); BAR;
;       LDA(At, 0, 1); WAIT_V(4); BAR; WAIT_L(0); MMA(1, 0, At, B0); MMA(1, 1, At, B1); BAR; }
;     { LDB(B0, 1, 0); LDA(At, 1, 0); WAIT_V(2); BAR; WAIT_L(0); MMA(0, 0, At, B0); BAR;
	s_waitcnt lgkmcnt(0)
	s_waitcnt lgkmcnt(0)
	v_mfma_f32_16x16x32_bf16 v[92:95], v[210:213], v[178:181], v[92:95]
	v_mfma_f32_16x16x32_bf16 v[88:91], v[218:221], v[178:181], v[88:91]
	v_mfma_f32_16x16x32_bf16 v[76:79], v[210:213], v[194:197], v[76:79]
	v_mfma_f32_16x16x32_bf16 v[72:75], v[218:221], v[194:197], v[72:75]
	v_mfma_f32_16x16x32_bf16 v[84:87], v[210:213], v[186:189], v[84:87]
	v_mfma_f32_16x16x32_bf16 v[80:83], v[218:221], v[186:189], v[80:83]
	v_mfma_f32_16x16x32_bf16 v[68:71], v[210:213], v[202:205], v[68:71]
	v_mfma_f32_16x16x32_bf16 v[64:67], v[218:221], v[202:205], v[64:67]
	v_mfma_f32_16x16x32_bf16 v[92:95], v[214:217], v[182:185], v[92:95]
	v_mfma_f32_16x16x32_bf16 v[88:91], v[160:163], v[182:185], v[88:91]
	v_mfma_f32_16x16x32_bf16 v[76:79], v[214:217], v[198:201], v[76:79]
	v_mfma_f32_16x16x32_bf16 v[72:75], v[160:163], v[198:201], v[72:75]
	v_mfma_f32_16x16x32_bf16 v[178:181], v[214:217], v[190:193], v[84:87]
	v_mfma_f32_16x16x32_bf16 v[182:185], v[160:163], v[190:193], v[80:83]
	v_mfma_f32_16x16x32_bf16 v[186:189], v[214:217], v[206:209], v[68:71]
	v_mfma_f32_16x16x32_bf16 v[190:193], v[160:163], v[206:209], v[64:67]
	s_barrier
	s_nop 0
	ds_read_b128 v[64:67], v155 offset:16384
	ds_read_b128 v[68:71], v155 offset:17408
	ds_read_b128 v[80:83], v154 offset:16384
	ds_read_b128 v[84:87], v154 offset:17408
	ds_read_b128 v[194:197], v153 offset:16384
	ds_read_b128 v[198:201], v153 offset:17408
	ds_read_b128 v[202:205], v152 offset:16384
	ds_read_b128 v[206:209], v152 offset:17408
	s_waitcnt vmcnt(4)
	s_barrier
	s_waitcnt lgkmcnt(0)
	s_waitcnt lgkmcnt(0)
	v_mfma_f32_16x16x32_bf16 v[60:63], v[134:137], v[64:67], v[60:63]
	v_mfma_f32_16x16x32_bf16 v[56:59], v[142:145], v[64:67], v[56:59]
	v_mfma_f32_16x16x32_bf16 v[52:55], v[134:137], v[80:83], v[52:55]
	v_mfma_f32_16x16x32_bf16 v[48:51], v[142:145], v[80:83], v[48:51]
	v_mfma_f32_16x16x32_bf16 v[44:47], v[134:137], v[194:197], v[44:47]
	v_mfma_f32_16x16x32_bf16 v[40:43], v[142:145], v[194:197], v[40:43]
	v_mfma_f32_16x16x32_bf16 v[36:39], v[134:137], v[202:205], v[36:39]
	v_mfma_f32_16x16x32_bf16 v[32:35], v[142:145], v[202:205], v[32:35]
	v_mfma_f32_16x16x32_bf16 v[60:63], v[138:141], v[68:71], v[60:63]
	v_mfma_f32_16x16x32_bf16 v[56:59], v[174:177], v[68:71], v[56:59]
	v_mfma_f32_16x16x32_bf16 v[52:55], v[138:141], v[84:87], v[52:55]
	v_mfma_f32_16x16x32_bf16 v[48:51], v[174:177], v[84:87], v[48:51]
	v_mfma_f32_16x16x32_bf16 v[44:47], v[138:141], v[198:201], v[44:47]
	v_mfma_f32_16x16x32_bf16 v[40:43], v[174:177], v[198:201], v[40:43]
	v_mfma_f32_16x16x32_bf16 v[36:39], v[138:141], v[206:209], v[36:39]
	v_mfma_f32_16x16x32_bf16 v[32:35], v[174:177], v[206:209], v[32:35]
	v_mfma_f32_16x16x32_bf16 v[28:31], v[210:213], v[64:67], v[28:31]
	v_mfma_f32_16x16x32_bf16 v[16:19], v[218:221], v[80:83], v[16:19]
	v_mfma_f32_16x16x32_bf16 v[12:15], v[210:213], v[194:197], v[12:15]
	v_mfma_f32_16x16x32_bf16 v[0:3], v[218:221], v[202:205], v[0:3]
	v_mfma_f32_16x16x32_bf16 v[24:27], v[218:221], v[64:67], v[24:27]
	v_mfma_f32_16x16x32_bf16 v[20:23], v[210:213], v[80:83], v[20:23]
	v_mfma_f32_16x16x32_bf16 v[8:11], v[218:221], v[194:197], v[8:11]
	v_mfma_f32_16x16x32_bf16 v[4:7], v[210:213], v[202:205], v[4:7]
	v_mfma_f32_16x16x32_bf16 v[28:31], v[214:217], v[68:71], v[28:31]
	v_mfma_f32_16x16x32_bf16 v[16:19], v[160:163], v[84:87], v[16:19]
	v_mfma_f32_16x16x32_bf16 v[12:15], v[214:217], v[198:201], v[12:15]
	v_mfma_f32_16x16x32_bf16 v[0:3], v[160:163], v[206:209], v[0:3]
	v_mfma_f32_16x16x32_bf16 v[134:137], v[160:163], v[68:71], v[24:27]
	v_mfma_f32_16x16x32_bf16 v[138:141], v[214:217], v[84:87], v[20:23]
	v_mfma_f32_16x16x32_bf16 v[142:145], v[160:163], v[198:201], v[8:11]
	v_mfma_f32_16x16x32_bf16 v[172:175], v[214:217], v[206:209], v[4:7]
	s_barrier
	s_nop 0
	ds_read_b128 v[4:7], v159
	ds_read_b128 v[8:11], v159 offset:1024
	ds_read_b128 v[20:23], v159 offset:2048
	ds_read_b128 v[158:161], v159 offset:3072
	ds_read_b128 v[24:27], v155 offset:32768
	ds_read_b128 v[194:197], v155 offset:33792
	ds_read_b128 v[198:201], v154 offset:32768
	ds_read_b128 v[202:205], v154 offset:33792
	ds_read_b128 v[206:209], v153 offset:32768
	ds_read_b128 v[210:213], v153 offset:33792
	ds_read_b128 v[214:217], v152 offset:32768
	ds_read_b128 v[218:221], v152 offset:33792
	s_waitcnt vmcnt(2)
	s_barrier
; #define LDA(dst, b, h) for (int m = 0; m < 4; ++m) for (int k = 0; k < 2; ++k) \
;     dst[m][k] = *reinterpret_cast<const bf16x8*>((char*)SA(b, h) + lds_byte(wr * 64 + m * 16 + fr, k * 32 + fq * 8))
; #define LDB(dst, b, h) for (int n = 0; n < 2; ++n) for (int k = 0; k < 2; ++k) \
;     dst[n][k] = *reinterpret_cast<const bf16x8*>((char*)SB(b, h) + lds_byte(wc * 32 + n * 16 + fr, k * 32 + fq * 8))
; #define MMA(ai, bj, At_, Bt_) do { __builtin_amdgcn_s_setprio(1); \
;     for (int k = 0; k < 2; ++k) for (int m = 0; m < 4; ++m) for (int n = 0; n < 2; ++n) \
;       acc[ai][bj][m][n] = __builtin_amdgcn_mfma_f32_16x16x32_bf16(At_[m][k], Bt_[n][k], acc[ai][bj][m][n], 0, 0, 0); \
;     __builtin_amdgcn_s_setprio(0); } while (0)
; #define WAIT_V(n) asm volatile("s_waitcnt vmcnt(" #n ")" ::: "memory")
; #define WAIT_L(n) asm volatile("s_waitcnt lgkmcnt(" #n ")" ::: "memory")
; #define BAR __builtin_amdgcn_s_barrier()
; template <int EPI, int lda, int ldb, int N, int K>
; __device__ __forceinline__ void gemm_phase(const u16* __restrict__ A, const u16* __restrict__ Bt, const GemmEpi ep, int wv) {
;     ...
;     { LDB(B0, 1, 0); LDA(At, 1, 0); WAIT_V(2); BAR; WAIT_L(0); MMA(0, 0, At, B0); BAR;
;       LDB(B1, 1, 1); WAIT_V(0); BAR; WAIT_L(0); MMA(0, 1, At, B1); BAR;
;       LDA(At, 1, 1); BAR; WAIT_L(0); MMA(1, 0, At, B0); MMA(1, 1, At, B1); BAR; }
;     if (wr == 0) BAR;
	s_waitcnt lgkmcnt(0)
	s_waitcnt lgkmcnt(0)
	v_mfma_f32_16x16x32_bf16 v[64:67], v[4:7], v[24:27], v[124:127]
	v_mfma_f32_16x16x32_bf16 v[68:71], v[20:23], v[24:27], v[120:123]
	v_mfma_f32_16x16x32_bf16 v[80:83], v[4:7], v[198:201], v[116:119]
	v_mfma_f32_16x16x32_bf16 v[84:87], v[20:23], v[198:201], v[112:115]
	v_mfma_f32_16x16x32_bf16 v[108:111], v[4:7], v[206:209], v[108:111]
	v_mfma_f32_16x16x32_bf16 v[104:107], v[20:23], v[206:209], v[104:107]
	v_mfma_f32_16x16x32_bf16 v[120:123], v[4:7], v[214:217], v[100:103]
	v_mfma_f32_16x16x32_bf16 v[124:127], v[20:23], v[214:217], v[96:99]
	v_mfma_f32_16x16x32_bf16 v[116:119], v[8:11], v[194:197], v[64:67]
	v_mfma_f32_16x16x32_bf16 v[112:115], v[158:161], v[194:197], v[68:71]
	v_mfma_f32_16x16x32_bf16 v[100:103], v[8:11], v[202:205], v[80:83]
	v_mfma_f32_16x16x32_bf16 v[96:99], v[158:161], v[202:205], v[84:87]
	v_mfma_f32_16x16x32_bf16 v[84:87], v[8:11], v[210:213], v[108:111]
	v_mfma_f32_16x16x32_bf16 v[80:83], v[158:161], v[210:213], v[104:107]
	v_mfma_f32_16x16x32_bf16 v[68:71], v[8:11], v[218:221], v[120:123]
	v_mfma_f32_16x16x32_bf16 v[64:67], v[158:161], v[218:221], v[124:127]
	s_barrier
	ds_read_b128 v[222:225], v157
	ds_read_b128 v[226:229], v157 offset:1024
	ds_read_b128 v[230:233], v157 offset:2048
	ds_read_b128 v[234:237], v157 offset:3072
	s_waitcnt vmcnt(0)
	s_barrier
	s_waitcnt lgkmcnt(0)
	s_waitcnt lgkmcnt(0)
	v_mfma_f32_16x16x32_bf16 v[92:95], v[222:225], v[24:27], v[92:95]
	v_mfma_f32_16x16x32_bf16 v[24:27], v[230:233], v[24:27], v[88:91]
	v_mfma_f32_16x16x32_bf16 v[88:91], v[222:225], v[198:201], v[178:181]
	v_mfma_f32_16x16x32_bf16 v[104:107], v[230:233], v[198:201], v[182:185]
	v_mfma_f32_16x16x32_bf16 v[76:79], v[222:225], v[206:209], v[76:79]
	v_mfma_f32_16x16x32_bf16 v[72:75], v[230:233], v[206:209], v[72:75]
	v_mfma_f32_16x16x32_bf16 v[176:179], v[222:225], v[214:217], v[186:189]
	v_mfma_f32_16x16x32_bf16 v[180:183], v[230:233], v[214:217], v[190:193]
	v_mfma_f32_16x16x32_bf16 v[124:127], v[226:229], v[194:197], v[92:95]
	v_mfma_f32_16x16x32_bf16 v[120:123], v[234:237], v[194:197], v[24:27]
	v_mfma_f32_16x16x32_bf16 v[108:111], v[226:229], v[202:205], v[88:91]
	v_mfma_f32_16x16x32_bf16 v[104:107], v[234:237], v[202:205], v[104:107]
	v_mfma_f32_16x16x32_bf16 v[92:95], v[226:229], v[210:213], v[76:79]
	v_mfma_f32_16x16x32_bf16 v[88:91], v[234:237], v[210:213], v[72:75]
	v_mfma_f32_16x16x32_bf16 v[76:79], v[226:229], v[218:221], v[176:179]
	v_mfma_f32_16x16x32_bf16 v[72:75], v[234:237], v[218:221], v[180:183]
	s_barrier
	ds_read_b128 v[176:179], v155 offset:49152
	ds_read_b128 v[180:183], v155 offset:50176
	ds_read_b128 v[184:187], v154 offset:49152
	ds_read_b128 v[154:157], v154 offset:50176
	ds_read_b128 v[188:191], v153 offset:49152
	ds_read_b128 v[192:195], v153 offset:50176
	ds_read_b128 v[196:199], v152 offset:49152
	ds_read_b128 v[200:203], v152 offset:50176
	s_barrier
	s_waitcnt lgkmcnt(0)
	s_waitcnt lgkmcnt(0)
	v_mfma_f32_16x16x32_bf16 v[24:27], v[4:7], v[176:179], v[60:63]
	v_mfma_f32_16x16x32_bf16 v[60:63], v[20:23], v[176:179], v[56:59]
	v_mfma_f32_16x16x32_bf16 v[204:207], v[4:7], v[184:187], v[52:55]
	v_mfma_f32_16x16x32_bf16 v[48:51], v[20:23], v[184:187], v[48:51]
	v_mfma_f32_16x16x32_bf16 v[44:47], v[4:7], v[188:191], v[44:47]
	v_mfma_f32_16x16x32_bf16 v[208:211], v[20:23], v[188:191], v[40:43]
	v_mfma_f32_16x16x32_bf16 v[4:7], v[4:7], v[196:199], v[36:39]
	v_mfma_f32_16x16x32_bf16 v[32:35], v[20:23], v[196:199], v[32:35]
	v_mfma_f32_16x16x32_bf16 v[56:59], v[8:11], v[180:183], v[24:27]
	v_mfma_f32_16x16x32_bf16 v[52:55], v[158:161], v[180:183], v[60:63]
	v_mfma_f32_16x16x32_bf16 v[40:43], v[8:11], v[154:157], v[204:207]
	v_mfma_f32_16x16x32_bf16 v[36:39], v[158:161], v[154:157], v[48:51]
	v_mfma_f32_16x16x32_bf16 v[24:27], v[8:11], v[192:195], v[44:47]
	v_mfma_f32_16x16x32_bf16 v[20:23], v[158:161], v[192:195], v[208:211]
	v_mfma_f32_16x16x32_bf16 v[8:11], v[8:11], v[200:203], v[4:7]
	v_mfma_f32_16x16x32_bf16 v[4:7], v[158:161], v[200:203], v[32:35]
	v_mfma_f32_16x16x32_bf16 v[28:31], v[222:225], v[176:179], v[28:31]
	v_mfma_f32_16x16x32_bf16 v[32:35], v[230:233], v[176:179], v[134:137]
	v_mfma_f32_16x16x32_bf16 v[44:47], v[222:225], v[184:187], v[138:141]
	v_mfma_f32_16x16x32_bf16 v[16:19], v[230:233], v[184:187], v[16:19]
	v_mfma_f32_16x16x32_bf16 v[12:15], v[222:225], v[188:191], v[12:15]
	v_mfma_f32_16x16x32_bf16 v[134:137], v[230:233], v[188:191], v[142:145]
	v_mfma_f32_16x16x32_bf16 v[138:141], v[222:225], v[196:199], v[172:175]
	v_mfma_f32_16x16x32_bf16 v[0:3], v[230:233], v[196:199], v[0:3]
	v_mfma_f32_16x16x32_bf16 v[60:63], v[226:229], v[180:183], v[28:31]
	v_mfma_f32_16x16x32_bf16 v[48:51], v[234:237], v[180:183], v[32:35]
	v_mfma_f32_16x16x32_bf16 v[44:47], v[226:229], v[154:157], v[44:47]
	v_mfma_f32_16x16x32_bf16 v[32:35], v[234:237], v[154:157], v[16:19]
	v_mfma_f32_16x16x32_bf16 v[28:31], v[226:229], v[192:195], v[12:15]
	v_mfma_f32_16x16x32_bf16 v[16:19], v[234:237], v[192:195], v[134:137]
	v_mfma_f32_16x16x32_bf16 v[12:15], v[226:229], v[200:203], v[138:141]
	v_mfma_f32_16x16x32_bf16 v[0:3], v[234:237], v[200:203], v[0:3]
	v_cmp_gt_u32_e32 vcc, s62, v130
	s_barrier
	s_and_saveexec_b64 s[44:45], vcc
	s_cbranch_execz .LBB0_227
	s_barrier

; #define STAGE(P, BASE, LD, br, kt) do { const char* _g = (const char*)((BASE) + (size_t)(br) * (LD) + (size_t)(kt) * 64); \
;     for (int _i = 0; _i < 2; ++_i) { int _b = tidx * 16 + _i * 8192; int _r, _c; stage_rc(_b, _r, _c); \
;       __builtin_amdgcn_global_load_lds((const unsigned*)(_g + (unsigned)((_r * (LD) + _c) * 2)), (unsigned*)((char*)(P) + _b), 16, 0, 0); } } while (0)
; #define LDA(dst, b, h) for (int m = 0; m < 4; ++m) for (int k = 0; k < 2; ++k) \
;     dst[m][k] = *reinterpret_cast<const bf16x8*>((char*)SA(b, h) + lds_byte(wr * 64 + m * 16 + fr, k * 32 + fq * 8))
; #define LDB(dst, b, h) for (int n = 0; n < 2; ++n) for (int k = 0; k < 2; ++k) \
;     dst[n][k] = *reinterpret_cast<const bf16x8*>((char*)SB(b, h) + lds_byte(wc * 32 + n * 16 + fr, k * 32 + fq * 8))
; #define MMA(ai, bj, At_, Bt_) do { __builtin_amdgcn_s_setprio(1); \
;     for (int k = 0; k < 2; ++k) for (int m = 0; m < 4; ++m) for (int n = 0; n < 2; ++n) \
;       acc[ai][bj][m][n] = __builtin_amdgcn_mfma_f32_16x16x32_bf16(At_[m][k], Bt_[n][k], acc[ai][bj][m][n], 0, 0, 0); \
;     __builtin_amdgcn_s_setprio(0); } while (0)
; #define WAIT_L(n) asm volatile("s_waitcnt lgkmcnt(" #n ")" ::: "memory")
; #define BAR __builtin_amdgcn_s_barrier()
; #define SCHED __builtin_amdgcn_sched_barrier(0)
; template <int EPI, int lda, int ldb, int N, int K>
; __device__ __forceinline__ void gemm_phase(const u16* __restrict__ A, const u16* __restrict__ Bt, const GemmEpi ep, int wv) {
;     ...
;     for (int t = 0; t < nt - 2; t += 2) {
;       LDB(B0, 0, 0); SCHED; LDA(At, 0, 0); STAGE(SA(1, 1), Ab, lda, brow + HALF, t + 1);
;       WAIT_L(8); BAR; WAIT_L(0); MMA(0, 0, At, B0); BAR; SCHED;
;       LDB(B1, 0, 1); STAGE(SB(0, 0), Bt, ldb, bcol, t + 2);
;       BAR; WAIT_L(0); MMA(0, 1, At, B1); BAR;
;       LDA(At, 0, 1); STAGE(SA(0, 0), Ab, lda, brow, t + 2);
;       BAR; WAIT_L(0); MMA(1, 0, At, B0); BAR; SCHED;
.LBB0_340:
	ds_read_b128 v[166:169], v162
	ds_read_b128 v[172:175], v162 offset:1024
	ds_read_b128 v[176:179], v162 offset:2048
	ds_read_b128 v[180:183], v162 offset:3072
	v_add_u32_e32 v170, 0xc000, v149
	v_lshl_add_u64 v[236:237], v[138:139], 0, s[48:49]
	v_readfirstlane_b32 s51, v170
	v_add_u32_e32 v171, 0xe000, v149
	v_lshl_add_u64 v[164:165], v[236:237], 0, s[18:19]
	s_mov_b32 m0, s51
	v_lshl_add_u64 v[238:239], v[140:141], 0, s[48:49]
	v_readfirstlane_b32 s51, v171
	ds_read_b128 v[184:187], v153
	ds_read_b128 v[188:191], v153 offset:1024
	ds_read_b128 v[192:195], v152
	ds_read_b128 v[196:199], v152 offset:1024
	ds_read_b128 v[200:203], v151
	ds_read_b128 v[204:207], v151 offset:1024
	ds_read_b128 v[208:211], v150
	ds_read_b128 v[212:215], v150 offset:1024
	global_load_lds_dwordx4 v[164:165], off
	s_nop 1
	v_lshl_add_u64 v[164:165], v[238:239], 0, s[18:19]
	s_mov_b32 m0, s51
	s_nop 0
	global_load_lds_dwordx4 v[164:165], off
	s_waitcnt lgkmcnt(8)
	s_barrier
	s_waitcnt lgkmcnt(0)
	s_waitcnt lgkmcnt(0)
	v_mfma_f32_16x16x32_bf16 v[124:127], v[184:187], v[166:169], v[124:127]
	v_mfma_f32_16x16x32_bf16 v[120:123], v[184:187], v[176:179], v[120:123]
	v_mfma_f32_16x16x32_bf16 v[116:119], v[192:195], v[166:169], v[116:119]
	v_mfma_f32_16x16x32_bf16 v[112:115], v[192:195], v[176:179], v[112:115]
	v_mfma_f32_16x16x32_bf16 v[108:111], v[200:203], v[166:169], v[108:111]
	v_mfma_f32_16x16x32_bf16 v[104:107], v[200:203], v[176:179], v[104:107]
	v_mfma_f32_16x16x32_bf16 v[100:103], v[208:211], v[166:169], v[100:103]
	v_mfma_f32_16x16x32_bf16 v[96:99], v[208:211], v[176:179], v[96:99]
	v_mfma_f32_16x16x32_bf16 v[124:127], v[188:191], v[172:175], v[124:127]
	v_mfma_f32_16x16x32_bf16 v[120:123], v[188:191], v[180:183], v[120:123]
	v_mfma_f32_16x16x32_bf16 v[116:119], v[196:199], v[172:175], v[116:119]
	v_mfma_f32_16x16x32_bf16 v[112:115], v[196:199], v[180:183], v[112:115]
	v_mfma_f32_16x16x32_bf16 v[108:111], v[204:207], v[172:175], v[108:111]
	v_mfma_f32_16x16x32_bf16 v[104:107], v[204:207], v[180:183], v[104:107]
	v_mfma_f32_16x16x32_bf16 v[100:103], v[212:215], v[172:175], v[100:103]
	v_mfma_f32_16x16x32_bf16 v[96:99], v[212:215], v[180:183], v[96:99]
	s_barrier
	v_add_u32_e32 v163, s62, v155
	v_lshl_add_u64 v[240:241], v[134:135], 0, s[48:49]
	v_readfirstlane_b32 s51, v163
	v_lshl_add_u64 v[164:165], v[240:241], 0, s[20:21]
	s_mov_b32 m0, s51
	ds_read_b128 v[216:219], v161
	ds_read_b128 v[220:223], v161 offset:1024
	ds_read_b128 v[224:227], v161 offset:2048
	ds_read_b128 v[228:231], v161 offset:3072
	global_load_lds_dwordx4 v[164:165], off
	s_nop 1
	v_add_u32_e32 v164, 0x2000, v163
	v_lshl_add_u64 v[242:243], v[136:137], 0, s[48:49]
	v_readfirstlane_b32 s51, v164
	v_lshl_add_u64 v[232:233], v[242:243], 0, s[20:21]
	s_mov_b32 m0, s51
	s_nop 0
	global_load_lds_dwordx4 v[232:233], off
	s_barrier
	s_waitcnt lgkmcnt(0)
	s_waitcnt lgkmcnt(0)
	v_mfma_f32_16x16x32_bf16 v[92:95], v[184:187], v[216:219], v[92:95]
	v_mfma_f32_16x16x32_bf16 v[88:91], v[184:187], v[224:227], v[88:91]
	v_mfma_f32_16x16x32_bf16 v[84:87], v[192:195], v[216:219], v[84:87]
	v_mfma_f32_16x16x32_bf16 v[80:83], v[192:195], v[224:227], v[80:83]
	v_mfma_f32_16x16x32_bf16 v[76:79], v[200:203], v[216:219], v[76:79]
	v_mfma_f32_16x16x32_bf16 v[72:75], v[200:203], v[224:227], v[72:75]
	v_mfma_f32_16x16x32_bf16 v[68:71], v[208:211], v[216:219], v[68:71]
	v_mfma_f32_16x16x32_bf16 v[64:67], v[208:211], v[224:227], v[64:67]
	v_mfma_f32_16x16x32_bf16 v[92:95], v[188:191], v[220:223], v[92:95]
	v_mfma_f32_16x16x32_bf16 v[88:91], v[188:191], v[228:231], v[88:91]
	v_mfma_f32_16x16x32_bf16 v[84:87], v[196:199], v[220:223], v[84:87]
	v_mfma_f32_16x16x32_bf16 v[80:83], v[196:199], v[228:231], v[80:83]
	v_mfma_f32_16x16x32_bf16 v[76:79], v[204:207], v[220:223], v[76:79]
	v_mfma_f32_16x16x32_bf16 v[72:75], v[204:207], v[228:231], v[72:75]
	v_mfma_f32_16x16x32_bf16 v[68:71], v[212:215], v[220:223], v[68:71]
	v_mfma_f32_16x16x32_bf16 v[64:67], v[212:215], v[228:231], v[64:67]
	v_readfirstlane_b32 s51, v149
	v_add_u32_e32 v165, 0x2000, v149
	v_lshl_add_u64 v[232:233], v[236:237], 0, s[22:23]
	s_mov_b32 m0, s51
	v_readfirstlane_b32 s51, v165
	s_barrier
	ds_read_b128 v[184:187], v153 offset:16384
	ds_read_b128 v[188:191], v153 offset:17408
	ds_read_b128 v[192:195], v152 offset:16384
	ds_read_b128 v[196:199], v152 offset:17408
	ds_read_b128 v[200:203], v151 offset:16384
	ds_read_b128 v[204:207], v151 offset:17408
	ds_read_b128 v[208:211], v150 offset:16384
	ds_read_b128 v[212:215], v150 offset:17408
	global_load_lds_dwordx4 v[232:233], off
	s_nop 1
	v_lshl_add_u64 v[232:233], v[238:239], 0, s[22:23]
	s_mov_b32 m0, s51
	s_nop 0
	global_load_lds_dwordx4 v[232:233], off
	s_barrier
	s_waitcnt lgkmcnt(0)
	s_waitcnt lgkmcnt(0)
	v_mfma_f32_16x16x32_bf16 v[60:63], v[184:187], v[166:169], v[60:63]
	v_mfma_f32_16x16x32_bf16 v[56:59], v[184:187], v[176:179], v[56:59]
	v_mfma_f32_16x16x32_bf16 v[52:55], v[192:195], v[166:169], v[52:55]
	v_mfma_f32_16x16x32_bf16 v[48:51], v[192:195], v[176:179], v[48:51]
	v_mfma_f32_16x16x32_bf16 v[44:47], v[200:203], v[166:169], v[44:47]
	v_mfma_f32_16x16x32_bf16 v[40:43], v[200:203], v[176:179], v[40:43]
	v_mfma_f32_16x16x32_bf16 v[36:39], v[208:211], v[166:169], v[36:39]
	v_mfma_f32_16x16x32_bf16 v[32:35], v[208:211], v[176:179], v[32:35]
	v_mfma_f32_16x16x32_bf16 v[60:63], v[188:191], v[172:175], v[60:63]
	v_mfma_f32_16x16x32_bf16 v[56:59], v[188:191], v[180:183], v[56:59]
	v_mfma_f32_16x16x32_bf16 v[52:55], v[196:199], v[172:175], v[52:55]
	v_mfma_f32_16x16x32_bf16 v[48:51], v[196:199], v[180:183], v[48:51]
	v_mfma_f32_16x16x32_bf16 v[44:47], v[204:207], v[172:175], v[44:47]
	v_mfma_f32_16x16x32_bf16 v[40:43], v[204:207], v[180:183], v[40:43]
	v_mfma_f32_16x16x32_bf16 v[36:39], v[212:215], v[172:175], v[36:39]
	v_mfma_f32_16x16x32_bf16 v[32:35], v[212:215], v[180:183], v[32:35]
	s_barrier
; #define STAGE(P, BASE, LD, br, kt) do { const char* _g = (const char*)((BASE) + (size_t)(br) * (LD) + (size_t)(kt) * 64); \
;     for (int _i = 0; _i < 2; ++_i) { int _b = tidx * 16 + _i * 8192; int _r, _c; stage_rc(_b, _r, _c); \
;       __builtin_amdgcn_global_load_lds((const unsigned*)(_g + (unsigned)((_r * (LD) + _c) * 2)), (unsigned*)((char*)(P) + _b), 16, 0, 0); } } while (0)
; #define LDA(dst, b, h) for (int m = 0; m < 4; ++m) for (int k = 0; k < 2; ++k) \
;     dst[m][k] = *reinterpret_cast<const bf16x8*>((char*)SA(b, h) + lds_byte(wr * 64 + m * 16 + fr, k * 32 + fq * 8))
; #define LDB(dst, b, h) for (int n = 0; n < 2; ++n) for (int k = 0; k < 2; ++k) \
;     dst[n][k] = *reinterpret_cast<const bf16x8*>((char*)SB(b, h) + lds_byte(wc * 32 + n * 16 + fr, k * 32 + fq * 8))
; #define MMA(ai, bj, At_, Bt_) do { __builtin_amdgcn_s_setprio(1); \
;     for (int k = 0; k < 2; ++k) for (int m = 0; m < 4; ++m) for (int n = 0; n < 2; ++n) \
;       acc[ai][bj][m][n] = __builtin_amdgcn_mfma_f32_16x16x32_bf16(At_[m][k], Bt_[n][k], acc[ai][bj][m][n], 0, 0, 0); \
;     __builtin_amdgcn_s_setprio(0); } while (0)
; #define WAIT_V(n) asm volatile("s_waitcnt vmcnt(" #n ")" ::: "memory")
; #define WAIT_L(n) asm volatile("s_waitcnt lgkmcnt(" #n ")" ::: "memory")
; #define BAR __builtin_amdgcn_s_barrier()
; #define SCHED __builtin_amdgcn_sched_barrier(0)
; template <int EPI, int lda, int ldb, int N, int K>
; __device__ __forceinline__ void gemm_phase(const u16* __restrict__ A, const u16* __restrict__ Bt, const GemmEpi ep, int wv) {
;     ...
;       STAGE(SB(0, 1), Bt, ldb, bcol + HALF, t + 2);
;       WAIT_V(6); BAR; MMA(1, 1, At, B1); BAR;
;       LDB(B0, 1, 0); SCHED; LDA(At, 1, 0); STAGE(SA(0, 1), Ab, lda, brow + HALF, t + 2);
;       WAIT_L(8); BAR; WAIT_L(0); MMA(0, 0, At, B0); BAR; SCHED;
;       LDB(B1, 1, 1); STAGE(SB(1, 0), Bt, ldb, bcol, t + 3);
;       BAR; WAIT_L(0); MMA(0, 1, At, B1); BAR;
;       LDA(At, 1, 1); STAGE(SA(1, 0), Ab, lda, brow, t + 3);
	v_add_u32_e32 v166, s63, v155
	v_add_u32_e32 v167, 0x2000, v166
	v_readfirstlane_b32 s51, v166
	v_lshl_add_u64 v[168:169], v[240:241], 0, s[24:25]
	s_mov_b32 m0, s51
	v_readfirstlane_b32 s51, v167
	global_load_lds_dwordx4 v[168:169], off
	s_nop 1
	v_lshl_add_u64 v[168:169], v[242:243], 0, s[24:25]
	s_mov_b32 m0, s51
	s_nop 0
	global_load_lds_dwordx4 v[168:169], off
	s_waitcnt vmcnt(6)
	s_barrier
	v_mfma_f32_16x16x32_bf16 v[28:31], v[184:187], v[216:219], v[28:31]
	v_mfma_f32_16x16x32_bf16 v[24:27], v[184:187], v[224:227], v[24:27]
	v_mfma_f32_16x16x32_bf16 v[20:23], v[192:195], v[216:219], v[20:23]
	v_mfma_f32_16x16x32_bf16 v[16:19], v[192:195], v[224:227], v[16:19]
	v_mfma_f32_16x16x32_bf16 v[12:15], v[200:203], v[216:219], v[12:15]
	v_mfma_f32_16x16x32_bf16 v[8:11], v[200:203], v[224:227], v[8:11]
	v_mfma_f32_16x16x32_bf16 v[4:7], v[208:211], v[216:219], v[4:7]
	v_mfma_f32_16x16x32_bf16 v[0:3], v[208:211], v[224:227], v[0:3]
	v_mfma_f32_16x16x32_bf16 v[28:31], v[188:191], v[220:223], v[28:31]
	v_mfma_f32_16x16x32_bf16 v[24:27], v[188:191], v[228:231], v[24:27]
	v_mfma_f32_16x16x32_bf16 v[20:23], v[196:199], v[220:223], v[20:23]
	v_mfma_f32_16x16x32_bf16 v[16:19], v[196:199], v[228:231], v[16:19]
	v_mfma_f32_16x16x32_bf16 v[12:15], v[204:207], v[220:223], v[12:15]
	v_mfma_f32_16x16x32_bf16 v[8:11], v[204:207], v[228:231], v[8:11]
	v_mfma_f32_16x16x32_bf16 v[4:7], v[212:215], v[220:223], v[4:7]
	v_mfma_f32_16x16x32_bf16 v[0:3], v[212:215], v[228:231], v[0:3]
	s_barrier
	ds_read_b128 v[172:175], v156
	ds_read_b128 v[176:179], v156 offset:1024
	ds_read_b128 v[180:183], v156 offset:2048
	ds_read_b128 v[184:187], v156 offset:3072
	v_add_u32_e32 v168, 0x4000, v149
	v_add_u32_e32 v169, 0x6000, v149
	v_readfirstlane_b32 s51, v168
	v_lshl_add_u64 v[220:221], v[236:237], 0, s[26:27]
	s_mov_b32 m0, s51
	v_readfirstlane_b32 s51, v169
	ds_read_b128 v[188:191], v153 offset:32768
	ds_read_b128 v[192:195], v153 offset:33792
	ds_read_b128 v[196:199], v152 offset:32768
	ds_read_b128 v[200:203], v152 offset:33792
	ds_read_b128 v[204:207], v151 offset:32768
	ds_read_b128 v[208:211], v151 offset:33792
	ds_read_b128 v[212:215], v150 offset:32768
	ds_read_b128 v[216:219], v150 offset:33792
	global_load_lds_dwordx4 v[220:221], off
	s_nop 1
	v_lshl_add_u64 v[220:221], v[238:239], 0, s[26:27]
	s_mov_b32 m0, s51
	s_nop 0
	global_load_lds_dwordx4 v[220:221], off
	s_waitcnt lgkmcnt(8)
	s_barrier
	s_waitcnt lgkmcnt(0)
	s_waitcnt lgkmcnt(0)
	v_mfma_f32_16x16x32_bf16 v[124:127], v[188:191], v[172:175], v[124:127]
	v_mfma_f32_16x16x32_bf16 v[120:123], v[188:191], v[180:183], v[120:123]
	v_mfma_f32_16x16x32_bf16 v[116:119], v[196:199], v[172:175], v[116:119]
	v_mfma_f32_16x16x32_bf16 v[112:115], v[196:199], v[180:183], v[112:115]
	v_mfma_f32_16x16x32_bf16 v[108:111], v[204:207], v[172:175], v[108:111]
	v_mfma_f32_16x16x32_bf16 v[104:107], v[204:207], v[180:183], v[104:107]
	v_mfma_f32_16x16x32_bf16 v[100:103], v[212:215], v[172:175], v[100:103]
	v_mfma_f32_16x16x32_bf16 v[96:99], v[212:215], v[180:183], v[96:99]
	v_mfma_f32_16x16x32_bf16 v[124:127], v[192:195], v[176:179], v[124:127]
	v_mfma_f32_16x16x32_bf16 v[120:123], v[192:195], v[184:187], v[120:123]
	v_mfma_f32_16x16x32_bf16 v[116:119], v[200:203], v[176:179], v[116:119]
	v_mfma_f32_16x16x32_bf16 v[112:115], v[200:203], v[184:187], v[112:115]
	v_mfma_f32_16x16x32_bf16 v[108:111], v[208:211], v[176:179], v[108:111]
	v_mfma_f32_16x16x32_bf16 v[104:107], v[208:211], v[184:187], v[104:107]
	v_mfma_f32_16x16x32_bf16 v[100:103], v[216:219], v[176:179], v[100:103]
	v_mfma_f32_16x16x32_bf16 v[96:99], v[216:219], v[184:187], v[96:99]
	s_barrier
	v_readfirstlane_b32 s51, v157
	v_add_u32_e32 v246, 0x2000, v157
	v_lshl_add_u64 v[244:245], v[240:241], 0, s[36:37]
	s_mov_b32 m0, s51
	v_readfirstlane_b32 s51, v246
	ds_read_b128 v[220:223], v154
	ds_read_b128 v[224:227], v154 offset:1024
	ds_read_b128 v[228:231], v154 offset:2048
	ds_read_b128 v[232:235], v154 offset:3072
	global_load_lds_dwordx4 v[244:245], off
	s_nop 1
	v_lshl_add_u64 v[244:245], v[242:243], 0, s[36:37]
	s_mov_b32 m0, s51
	s_nop 0
	global_load_lds_dwordx4 v[244:245], off
	s_barrier
	s_waitcnt lgkmcnt(0)
	s_waitcnt lgkmcnt(0)
	v_mfma_f32_16x16x32_bf16 v[92:95], v[188:191], v[220:223], v[92:95]
	v_mfma_f32_16x16x32_bf16 v[88:91], v[188:191], v[228:231], v[88:91]
	v_mfma_f32_16x16x32_bf16 v[84:87], v[196:199], v[220:223], v[84:87]
	v_mfma_f32_16x16x32_bf16 v[80:83], v[196:199], v[228:231], v[80:83]
	v_mfma_f32_16x16x32_bf16 v[76:79], v[204:207], v[220:223], v[76:79]
	v_mfma_f32_16x16x32_bf16 v[72:75], v[204:207], v[228:231], v[72:75]
	v_mfma_f32_16x16x32_bf16 v[68:71], v[212:215], v[220:223], v[68:71]
	v_mfma_f32_16x16x32_bf16 v[64:67], v[212:215], v[228:231], v[64:67]
	v_mfma_f32_16x16x32_bf16 v[92:95], v[192:195], v[224:227], v[92:95]
	v_mfma_f32_16x16x32_bf16 v[88:91], v[192:195], v[232:235], v[88:91]
	v_mfma_f32_16x16x32_bf16 v[84:87], v[200:203], v[224:227], v[84:87]
	v_mfma_f32_16x16x32_bf16 v[80:83], v[200:203], v[232:235], v[80:83]
	v_mfma_f32_16x16x32_bf16 v[76:79], v[208:211], v[224:227], v[76:79]
	v_mfma_f32_16x16x32_bf16 v[72:75], v[208:211], v[232:235], v[72:75]
	v_mfma_f32_16x16x32_bf16 v[68:71], v[216:219], v[224:227], v[68:71]
	v_mfma_f32_16x16x32_bf16 v[64:67], v[216:219], v[232:235], v[64:67]
	v_readfirstlane_b32 s51, v158
	v_lshl_add_u64 v[236:237], v[236:237], 0, s[38:39]
	s_mov_b32 m0, s51
	v_readfirstlane_b32 s51, v159
	s_barrier
; #define STAGE(P, BASE, LD, br, kt) do { const char* _g = (const char*)((BASE) + (size_t)(br) * (LD) + (size_t)(kt) * 64); \
;     for (int _i = 0; _i < 2; ++_i) { int _b = tidx * 16 + _i * 8192; int _r, _c; stage_rc(_b, _r, _c); \
;       __builtin_amdgcn_global_load_lds((const unsigned*)(_g + (unsigned)((_r * (LD) + _c) * 2)), (unsigned*)((char*)(P) + _b), 16, 0, 0); } } while (0)
; #define LDA(dst, b, h) for (int m = 0; m < 4; ++m) for (int k = 0; k < 2; ++k) \
;     dst[m][k] = *reinterpret_cast<const bf16x8*>((char*)SA(b, h) + lds_byte(wr * 64 + m * 16 + fr, k * 32 + fq * 8))
; #define LDB(dst, b, h) for (int n = 0; n < 2; ++n) for (int k = 0; k < 2; ++k) \
;     dst[n][k] = *reinterpret_cast<const bf16x8*>((char*)SB(b, h) + lds_byte(wc * 32 + n * 16 + fr, k * 32 + fq * 8))
; #define MMA(ai, bj, At_, Bt_) do { __builtin_amdgcn_s_setprio(1); \
;     for (int k = 0; k < 2; ++k) for (int m = 0; m < 4; ++m) for (int n = 0; n < 2; ++n) \
;       acc[ai][bj][m][n] = __builtin_amdgcn_mfma_f32_16x16x32_bf16(At_[m][k], Bt_[n][k], acc[ai][bj][m][n], 0, 0, 0); \
;     __builtin_amdgcn_s_setprio(0); } while (0)
; #define WAIT_V(n) asm volatile("s_waitcnt vmcnt(" #n ")" ::: "memory")
; #define WAIT_L(n) asm volatile("s_waitcnt lgkmcnt(" #n ")" ::: "memory")
; #define BAR __builtin_amdgcn_s_barrier()
; #define SCHED __builtin_amdgcn_sched_barrier(0)
; template <int EPI, int lda, int ldb, int N, int K>
; __device__ __forceinline__ void gemm_phase(const u16* __restrict__ A, const u16* __restrict__ Bt, const GemmEpi ep, int wv) {
;     ...
;       LDA(At, 1, 1); STAGE(SA(1, 0), Ab, lda, brow, t + 3);
;       BAR; WAIT_L(0); MMA(1, 0, At, B0); BAR; SCHED;
;       STAGE(SB(1, 1), Bt, ldb, bcol + HALF, t + 3);
;       WAIT_V(6); BAR; MMA(1, 1, At, B1); BAR;
;     }
;     { LDB(B0, 0, 0); LDA(At, 0, 0); STAGE(SA(1, 1), Ab, lda, brow + HALF, nt - 1);
;       BAR; WAIT_L(0); MMA(0, 0, At, B0); BAR;
;       LDB(B1, 0, 1); BAR; WAIT_L(0); MMA(0, 1, At, B1); BAR;
	ds_read_b128 v[188:191], v153 offset:49152
	ds_read_b128 v[192:195], v153 offset:50176
	ds_read_b128 v[196:199], v152 offset:49152
	ds_read_b128 v[200:203], v152 offset:50176
	ds_read_b128 v[204:207], v151 offset:49152
	ds_read_b128 v[208:211], v151 offset:50176
	ds_read_b128 v[212:215], v150 offset:49152
	ds_read_b128 v[216:219], v150 offset:50176
	global_load_lds_dwordx4 v[236:237], off
	s_nop 1
	v_lshl_add_u64 v[236:237], v[238:239], 0, s[38:39]
	s_mov_b32 m0, s51
	s_nop 0
	global_load_lds_dwordx4 v[236:237], off
	s_barrier
	s_waitcnt lgkmcnt(0)
	s_waitcnt lgkmcnt(0)
	v_mfma_f32_16x16x32_bf16 v[60:63], v[188:191], v[172:175], v[60:63]
	v_mfma_f32_16x16x32_bf16 v[56:59], v[188:191], v[180:183], v[56:59]
	v_mfma_f32_16x16x32_bf16 v[52:55], v[196:199], v[172:175], v[52:55]
	v_mfma_f32_16x16x32_bf16 v[48:51], v[196:199], v[180:183], v[48:51]
	v_mfma_f32_16x16x32_bf16 v[44:47], v[204:207], v[172:175], v[44:47]
	v_mfma_f32_16x16x32_bf16 v[40:43], v[204:207], v[180:183], v[40:43]
	v_mfma_f32_16x16x32_bf16 v[36:39], v[212:215], v[172:175], v[36:39]
	v_mfma_f32_16x16x32_bf16 v[32:35], v[212:215], v[180:183], v[32:35]
	v_mfma_f32_16x16x32_bf16 v[60:63], v[192:195], v[176:179], v[60:63]
	v_mfma_f32_16x16x32_bf16 v[56:59], v[192:195], v[184:187], v[56:59]
	v_mfma_f32_16x16x32_bf16 v[52:55], v[200:203], v[176:179], v[52:55]
	v_mfma_f32_16x16x32_bf16 v[48:51], v[200:203], v[184:187], v[48:51]
	v_mfma_f32_16x16x32_bf16 v[44:47], v[208:211], v[176:179], v[44:47]
	v_mfma_f32_16x16x32_bf16 v[40:43], v[208:211], v[184:187], v[40:43]
	v_mfma_f32_16x16x32_bf16 v[36:39], v[216:219], v[176:179], v[36:39]
	v_mfma_f32_16x16x32_bf16 v[32:35], v[216:219], v[184:187], v[32:35]
	s_barrier
	v_readfirstlane_b32 s51, v160
	v_add_u32_e32 v174, 0x2000, v160
	v_lshl_add_u64 v[172:173], v[240:241], 0, s[42:43]
	s_mov_b32 m0, s51
	v_readfirstlane_b32 s51, v174
	global_load_lds_dwordx4 v[172:173], off
	s_nop 1
	v_lshl_add_u64 v[172:173], v[242:243], 0, s[42:43]
	s_mov_b32 m0, s51
	s_nop 0
	global_load_lds_dwordx4 v[172:173], off
	s_waitcnt vmcnt(6)
	s_barrier
	v_mfma_f32_16x16x32_bf16 v[28:31], v[188:191], v[220:223], v[28:31]
	v_mfma_f32_16x16x32_bf16 v[24:27], v[188:191], v[228:231], v[24:27]
	v_mfma_f32_16x16x32_bf16 v[20:23], v[196:199], v[220:223], v[20:23]
	v_mfma_f32_16x16x32_bf16 v[16:19], v[196:199], v[228:231], v[16:19]
	v_mfma_f32_16x16x32_bf16 v[12:15], v[204:207], v[220:223], v[12:15]
	v_mfma_f32_16x16x32_bf16 v[8:11], v[204:207], v[228:231], v[8:11]
	v_mfma_f32_16x16x32_bf16 v[4:7], v[212:215], v[220:223], v[4:7]
	v_mfma_f32_16x16x32_bf16 v[0:3], v[212:215], v[228:231], v[0:3]
	v_mfma_f32_16x16x32_bf16 v[28:31], v[192:195], v[224:227], v[28:31]
	v_mfma_f32_16x16x32_bf16 v[24:27], v[192:195], v[232:235], v[24:27]
	v_mfma_f32_16x16x32_bf16 v[20:23], v[200:203], v[224:227], v[20:23]
	v_mfma_f32_16x16x32_bf16 v[16:19], v[200:203], v[232:235], v[16:19]
	v_mfma_f32_16x16x32_bf16 v[12:15], v[208:211], v[224:227], v[12:15]
	v_mfma_f32_16x16x32_bf16 v[8:11], v[208:211], v[232:235], v[8:11]
	v_mfma_f32_16x16x32_bf16 v[4:7], v[216:219], v[224:227], v[4:7]
	v_mfma_f32_16x16x32_bf16 v[0:3], v[216:219], v[232:235], v[0:3]
	s_add_i32 s50, s50, 2
	s_add_u32 s48, s48, 0x100
	s_addc_u32 s49, s49, 0
	s_cmp_gt_u32 s50, 27
	s_barrier
	s_cbranch_scc0 .LBB0_340
	s_add_i32 s48, s46, 0x80
	s_mul_hi_i32 s49, s48, 0x1080
	s_mulk_i32 s48, 0x1080
	s_add_u32 s48, s31, s48
	s_addc_u32 s49, s56, s49
	v_lshl_add_u64 v[158:159], s[48:49], 0, v[128:129]
	v_readfirstlane_b32 s50, v170
	v_lshl_add_u64 v[158:159], v[158:159], 0, s[44:45]
	s_mov_b32 m0, s50
	ds_read_b128 v[134:137], v162
	ds_read_b128 v[138:141], v162 offset:1024
	ds_read_b128 v[172:175], v162 offset:2048
	ds_read_b128 v[176:179], v162 offset:3072
	ds_read_b128 v[180:183], v153
	ds_read_b128 v[184:187], v153 offset:1024
	ds_read_b128 v[188:191], v152
	ds_read_b128 v[192:195], v152 offset:1024
	ds_read_b128 v[196:199], v151
	ds_read_b128 v[200:203], v151 offset:1024
	ds_read_b128 v[204:207], v150
	ds_read_b128 v[208:211], v150 offset:1024
	global_load_lds_dwordx4 v[158:159], off
	v_lshl_add_u64 v[158:159], s[48:49], 0, v[132:133]
	v_readfirstlane_b32 s48, v171
	v_lshl_add_u64 v[158:159], v[158:159], 0, s[44:45]
	s_mov_b32 m0, s48
	s_nop 0
	global_load_lds_dwordx4 v[158:159], off
	s_barrier
	s_waitcnt lgkmcnt(0)
	s_waitcnt lgkmcnt(0)
	v_mfma_f32_16x16x32_bf16 v[124:127], v[180:183], v[134:137], v[124:127]
	v_mfma_f32_16x16x32_bf16 v[120:123], v[180:183], v[172:175], v[120:123]
	v_mfma_f32_16x16x32_bf16 v[116:119], v[188:191], v[134:137], v[116:119]
	v_mfma_f32_16x16x32_bf16 v[112:115], v[188:191], v[172:175], v[112:115]
	v_mfma_f32_16x16x32_bf16 v[108:111], v[196:199], v[134:137], v[108:111]
	v_mfma_f32_16x16x32_bf16 v[104:107], v[196:199], v[172:175], v[104:107]
	v_mfma_f32_16x16x32_bf16 v[100:103], v[204:207], v[134:137], v[100:103]
	v_mfma_f32_16x16x32_bf16 v[96:99], v[204:207], v[172:175], v[96:99]
	v_mfma_f32_16x16x32_bf16 v[124:127], v[184:187], v[138:141], v[124:127]
	v_mfma_f32_16x16x32_bf16 v[120:123], v[184:187], v[176:179], v[120:123]
	v_mfma_f32_16x16x32_bf16 v[116:119], v[192:195], v[138:141], v[116:119]
	v_mfma_f32_16x16x32_bf16 v[112:115], v[192:195], v[176:179], v[112:115]
	v_mfma_f32_16x16x32_bf16 v[108:111], v[200:203], v[138:141], v[108:111]
	v_mfma_f32_16x16x32_bf16 v[104:107], v[200:203], v[176:179], v[104:107]
	v_mfma_f32_16x16x32_bf16 v[100:103], v[208:211], v[138:141], v[100:103]
	v_mfma_f32_16x16x32_bf16 v[96:99], v[208:211], v[176:179], v[96:99]
	s_barrier
	ds_read_b128 v[212:215], v161
	ds_read_b128 v[216:219], v161 offset:1024
	ds_read_b128 v[220:223], v161 offset:2048
	ds_read_b128 v[158:161], v161 offset:3072
	s_barrier
; #define LDA(dst, b, h) for (int m = 0; m < 4; ++m) for (int k = 0; k < 2; ++k) \
;     dst[m][k] = *reinterpret_cast<const bf16x8*>((char*)SA(b, h) + lds_byte(wr * 64 + m * 16 + fr, k * 32 + fq * 8))
; #define LDB(dst, b, h) for (int n = 0; n < 2; ++n) for (int k = 0; k < 2; ++k) \
;     dst[n][k] = *reinterpret_cast<const bf16x8*>((char*)SB(b, h) + lds_byte(wc * 32 + n * 16 + fr, k * 32 + fq * 8))
; #define MMA(ai, bj, At_, Bt_) do { __builtin_amdgcn_s_setprio(1); \
;     for (int k = 0; k < 2; ++k) for (int m = 0; m < 4; ++m) for (int n = 0; n < 2; ++n) \
;       acc[ai][bj][m][n] = __builtin_amdgcn_mfma_f32_16x16x32_bf16(At_[m][k], Bt_[n][k], acc[ai][bj][m][n], 0, 0, 0); \
;     __builtin_amdgcn_s_setprio(0); } while (0)
; #define WAIT_V(n) asm volatile("s_waitcnt vmcnt(" #n ")" ::: "memory")
; #define WAIT_L(n) asm volatile("s_waitcnt lgkmcnt(" #n ")" ::: "memory")
; #define BAR __builtin_amdgcn_s_barrier()
; template <int EPI, int lda, int ldb, int N, int K>
; __device__ __forceinline__ void gemm_phase(const u16* __restrict__ A, const u16* __restrict__ Bt, const GemmEpi ep, int wv) {
;     ...
;       LDB(B1, 0, 1); BAR; WAIT_L(0); MMA(0, 1, At, B1); BAR;
;       LDA(At, 0, 1); WAIT_V(4); BAR; WAIT_L(0); MMA(1, 0, At, B0); MMA(1, 1, At, B1); BAR; }
;     { LDB(B0, 1, 0); LDA(At, 1, 0); WAIT_V(2); BAR; WAIT_L(0); MMA(0, 0, At, B0); BAR;
	s_waitcnt lgkmcnt(0)
	s_waitcnt lgkmcnt(0)
	v_mfma_f32_16x16x32_bf16 v[92:95], v[180:183], v[212:215], v[92:95]
	v_mfma_f32_16x16x32_bf16 v[88:91], v[180:183], v[220:223], v[88:91]
	v_mfma_f32_16x16x32_bf16 v[76:79], v[196:199], v[212:215], v[76:79]
	v_mfma_f32_16x16x32_bf16 v[72:75], v[196:199], v[220:223], v[72:75]
	v_mfma_f32_16x16x32_bf16 v[68:71], v[204:207], v[212:215], v[68:71]
	v_mfma_f32_16x16x32_bf16 v[64:67], v[204:207], v[220:223], v[64:67]
	v_mfma_f32_16x16x32_bf16 v[84:87], v[188:191], v[212:215], v[84:87]
	v_mfma_f32_16x16x32_bf16 v[80:83], v[188:191], v[220:223], v[80:83]
	v_mfma_f32_16x16x32_bf16 v[92:95], v[184:187], v[216:219], v[92:95]
	v_mfma_f32_16x16x32_bf16 v[88:91], v[184:187], v[158:161], v[88:91]
	v_mfma_f32_16x16x32_bf16 v[76:79], v[200:203], v[216:219], v[76:79]
	v_mfma_f32_16x16x32_bf16 v[72:75], v[200:203], v[158:161], v[72:75]
	v_mfma_f32_16x16x32_bf16 v[68:71], v[208:211], v[216:219], v[68:71]
	v_mfma_f32_16x16x32_bf16 v[64:67], v[208:211], v[158:161], v[64:67]
	v_mfma_f32_16x16x32_bf16 v[180:183], v[192:195], v[216:219], v[84:87]
	v_mfma_f32_16x16x32_bf16 v[184:187], v[192:195], v[158:161], v[80:83]
	s_barrier
	s_nop 0
	ds_read_b128 v[80:83], v153 offset:16384
	ds_read_b128 v[84:87], v153 offset:17408
	ds_read_b128 v[188:191], v152 offset:16384
	ds_read_b128 v[192:195], v152 offset:17408
	ds_read_b128 v[196:199], v151 offset:16384
	ds_read_b128 v[200:203], v151 offset:17408
	ds_read_b128 v[204:207], v150 offset:16384
	ds_read_b128 v[208:211], v150 offset:17408
	s_waitcnt vmcnt(4)
	s_barrier
	s_waitcnt lgkmcnt(0)
	s_waitcnt lgkmcnt(0)
	v_mfma_f32_16x16x32_bf16 v[60:63], v[80:83], v[134:137], v[60:63]
	v_mfma_f32_16x16x32_bf16 v[44:47], v[196:199], v[134:137], v[44:47]
	v_mfma_f32_16x16x32_bf16 v[40:43], v[196:199], v[172:175], v[40:43]
	v_mfma_f32_16x16x32_bf16 v[36:39], v[204:207], v[134:137], v[36:39]
	v_mfma_f32_16x16x32_bf16 v[32:35], v[204:207], v[172:175], v[32:35]
	v_mfma_f32_16x16x32_bf16 v[56:59], v[80:83], v[172:175], v[56:59]
	v_mfma_f32_16x16x32_bf16 v[52:55], v[188:191], v[134:137], v[52:55]
	v_mfma_f32_16x16x32_bf16 v[48:51], v[188:191], v[172:175], v[48:51]
	v_mfma_f32_16x16x32_bf16 v[60:63], v[84:87], v[138:141], v[60:63]
	v_mfma_f32_16x16x32_bf16 v[44:47], v[200:203], v[138:141], v[44:47]
	v_mfma_f32_16x16x32_bf16 v[40:43], v[200:203], v[176:179], v[40:43]
	v_mfma_f32_16x16x32_bf16 v[36:39], v[208:211], v[138:141], v[36:39]
	v_mfma_f32_16x16x32_bf16 v[32:35], v[208:211], v[176:179], v[32:35]
	v_mfma_f32_16x16x32_bf16 v[134:137], v[84:87], v[176:179], v[56:59]
	v_mfma_f32_16x16x32_bf16 v[170:173], v[192:195], v[138:141], v[52:55]
	v_mfma_f32_16x16x32_bf16 v[224:227], v[192:195], v[176:179], v[48:51]
	v_mfma_f32_16x16x32_bf16 v[28:31], v[80:83], v[212:215], v[28:31]
	v_mfma_f32_16x16x32_bf16 v[20:23], v[188:191], v[212:215], v[20:23]
	v_mfma_f32_16x16x32_bf16 v[12:15], v[196:199], v[212:215], v[12:15]
	v_mfma_f32_16x16x32_bf16 v[4:7], v[204:207], v[212:215], v[4:7]
	v_mfma_f32_16x16x32_bf16 v[24:27], v[80:83], v[220:223], v[24:27]
	v_mfma_f32_16x16x32_bf16 v[16:19], v[188:191], v[220:223], v[16:19]
	v_mfma_f32_16x16x32_bf16 v[8:11], v[196:199], v[220:223], v[8:11]
	v_mfma_f32_16x16x32_bf16 v[0:3], v[204:207], v[220:223], v[0:3]
	v_mfma_f32_16x16x32_bf16 v[28:31], v[84:87], v[216:219], v[28:31]
	v_mfma_f32_16x16x32_bf16 v[20:23], v[192:195], v[216:219], v[20:23]
	v_mfma_f32_16x16x32_bf16 v[12:15], v[200:203], v[216:219], v[12:15]
	v_mfma_f32_16x16x32_bf16 v[4:7], v[208:211], v[216:219], v[4:7]
	v_mfma_f32_16x16x32_bf16 v[138:141], v[84:87], v[158:161], v[24:27]
	v_mfma_f32_16x16x32_bf16 v[174:177], v[192:195], v[158:161], v[16:19]
	v_mfma_f32_16x16x32_bf16 v[188:191], v[200:203], v[158:161], v[8:11]
	v_mfma_f32_16x16x32_bf16 v[158:161], v[208:211], v[158:161], v[0:3]
	s_barrier
	s_nop 0
	ds_read_b128 v[0:3], v156
	ds_read_b128 v[8:11], v156 offset:1024
	ds_read_b128 v[16:19], v156 offset:2048
	ds_read_b128 v[192:195], v156 offset:3072
	ds_read_b128 v[24:27], v153 offset:32768
	ds_read_b128 v[56:59], v153 offset:33792
	ds_read_b128 v[196:199], v152 offset:32768
	ds_read_b128 v[200:203], v152 offset:33792
	ds_read_b128 v[204:207], v151 offset:32768
	ds_read_b128 v[208:211], v151 offset:33792
	ds_read_b128 v[212:215], v150 offset:32768
	ds_read_b128 v[216:219], v150 offset:33792
	s_waitcnt vmcnt(2)
	s_barrier
; #define LDA(dst, b, h) for (int m = 0; m < 4; ++m) for (int k = 0; k < 2; ++k) \
;     dst[m][k] = *reinterpret_cast<const bf16x8*>((char*)SA(b, h) + lds_byte(wr * 64 + m * 16 + fr, k * 32 + fq * 8))
; #define LDB(dst, b, h) for (int n = 0; n < 2; ++n) for (int k = 0; k < 2; ++k) \
;     dst[n][k] = *reinterpret_cast<const bf16x8*>((char*)SB(b, h) + lds_byte(wc * 32 + n * 16 + fr, k * 32 + fq * 8))
; #define MMA(ai, bj, At_, Bt_) do { __builtin_amdgcn_s_setprio(1); \
;     for (int k = 0; k < 2; ++k) for (int m = 0; m < 4; ++m) for (int n = 0; n < 2; ++n) \
;       acc[ai][bj][m][n] = __builtin_amdgcn_mfma_f32_16x16x32_bf16(At_[m][k], Bt_[n][k], acc[ai][bj][m][n], 0, 0, 0); \
;     __builtin_amdgcn_s_setprio(0); } while (0)
; #define WAIT_V(n) asm volatile("s_waitcnt vmcnt(" #n ")" ::: "memory")
; #define WAIT_L(n) asm volatile("s_waitcnt lgkmcnt(" #n ")" ::: "memory")
; #define BAR __builtin_amdgcn_s_barrier()
; template <int EPI, int lda, int ldb, int N, int K>
; __device__ __forceinline__ void gemm_phase(const u16* __restrict__ A, const u16* __restrict__ Bt, const GemmEpi ep, int wv) {
;     ...
;     { LDB(B0, 1, 0); LDA(At, 1, 0); WAIT_V(2); BAR; WAIT_L(0); MMA(0, 0, At, B0); BAR;
;       LDB(B1, 1, 1); WAIT_V(0); BAR; WAIT_L(0); MMA(0, 1, At, B1); BAR;
;       LDA(At, 1, 1); BAR; WAIT_L(0); MMA(1, 0, At, B0); MMA(1, 1, At, B1); BAR; }
;     if (wr == 0) BAR;
	s_waitcnt lgkmcnt(0)
	s_waitcnt lgkmcnt(0)
	v_mfma_f32_16x16x32_bf16 v[48:51], v[24:27], v[0:3], v[124:127]
	v_mfma_f32_16x16x32_bf16 v[52:55], v[24:27], v[16:19], v[120:123]
	v_mfma_f32_16x16x32_bf16 v[80:83], v[196:199], v[0:3], v[116:119]
	v_mfma_f32_16x16x32_bf16 v[84:87], v[196:199], v[16:19], v[112:115]
	v_mfma_f32_16x16x32_bf16 v[108:111], v[204:207], v[0:3], v[108:111]
	v_mfma_f32_16x16x32_bf16 v[104:107], v[204:207], v[16:19], v[104:107]
	v_mfma_f32_16x16x32_bf16 v[112:115], v[212:215], v[0:3], v[100:103]
	v_mfma_f32_16x16x32_bf16 v[120:123], v[212:215], v[16:19], v[96:99]
	v_mfma_f32_16x16x32_bf16 v[124:127], v[56:59], v[8:11], v[48:51]
	v_mfma_f32_16x16x32_bf16 v[116:119], v[56:59], v[192:195], v[52:55]
	v_mfma_f32_16x16x32_bf16 v[100:103], v[200:203], v[8:11], v[80:83]
	v_mfma_f32_16x16x32_bf16 v[96:99], v[200:203], v[192:195], v[84:87]
	v_mfma_f32_16x16x32_bf16 v[84:87], v[208:211], v[8:11], v[108:111]
	v_mfma_f32_16x16x32_bf16 v[80:83], v[208:211], v[192:195], v[104:107]
	v_mfma_f32_16x16x32_bf16 v[52:55], v[216:219], v[8:11], v[112:115]
	v_mfma_f32_16x16x32_bf16 v[48:51], v[216:219], v[192:195], v[120:123]
	s_barrier
	ds_read_b128 v[220:223], v154
	ds_read_b128 v[228:231], v154 offset:1024
	ds_read_b128 v[232:235], v154 offset:2048
	ds_read_b128 v[154:157], v154 offset:3072
	s_waitcnt vmcnt(0)
	s_barrier
	s_waitcnt lgkmcnt(0)
	s_waitcnt lgkmcnt(0)
	v_mfma_f32_16x16x32_bf16 v[92:95], v[24:27], v[220:223], v[92:95]
	v_mfma_f32_16x16x32_bf16 v[24:27], v[24:27], v[232:235], v[88:91]
	v_mfma_f32_16x16x32_bf16 v[88:91], v[196:199], v[220:223], v[180:183]
	v_mfma_f32_16x16x32_bf16 v[104:107], v[196:199], v[232:235], v[184:187]
	v_mfma_f32_16x16x32_bf16 v[76:79], v[204:207], v[220:223], v[76:79]
	v_mfma_f32_16x16x32_bf16 v[72:75], v[204:207], v[232:235], v[72:75]
	v_mfma_f32_16x16x32_bf16 v[68:71], v[212:215], v[220:223], v[68:71]
	v_mfma_f32_16x16x32_bf16 v[64:67], v[212:215], v[232:235], v[64:67]
	v_mfma_f32_16x16x32_bf16 v[120:123], v[56:59], v[228:231], v[92:95]
	v_mfma_f32_16x16x32_bf16 v[112:115], v[56:59], v[154:157], v[24:27]
	v_mfma_f32_16x16x32_bf16 v[108:111], v[200:203], v[228:231], v[88:91]
	v_mfma_f32_16x16x32_bf16 v[104:107], v[200:203], v[154:157], v[104:107]
	v_mfma_f32_16x16x32_bf16 v[92:95], v[208:211], v[228:231], v[76:79]
	v_mfma_f32_16x16x32_bf16 v[88:91], v[208:211], v[154:157], v[72:75]
	v_mfma_f32_16x16x32_bf16 v[68:71], v[216:219], v[228:231], v[68:71]
	v_mfma_f32_16x16x32_bf16 v[56:59], v[216:219], v[154:157], v[64:67]
	s_barrier
	s_nop 0
	ds_read_b128 v[64:67], v153 offset:49152
	ds_read_b128 v[178:181], v153 offset:50176
	ds_read_b128 v[76:79], v152 offset:49152
	ds_read_b128 v[182:185], v152 offset:50176
	ds_read_b128 v[196:199], v151 offset:49152
	ds_read_b128 v[200:203], v151 offset:50176
	ds_read_b128 v[204:207], v150 offset:49152
	ds_read_b128 v[150:153], v150 offset:50176
	s_barrier
	s_waitcnt lgkmcnt(0)
	s_waitcnt lgkmcnt(0)
	v_mfma_f32_16x16x32_bf16 v[24:27], v[64:67], v[0:3], v[60:63]
	v_mfma_f32_16x16x32_bf16 v[60:63], v[64:67], v[16:19], v[134:137]
	v_mfma_f32_16x16x32_bf16 v[134:137], v[76:79], v[0:3], v[170:173]
	v_mfma_f32_16x16x32_bf16 v[170:173], v[76:79], v[16:19], v[224:227]
	v_mfma_f32_16x16x32_bf16 v[44:47], v[196:199], v[0:3], v[44:47]
	v_mfma_f32_16x16x32_bf16 v[208:211], v[196:199], v[16:19], v[40:43]
	v_mfma_f32_16x16x32_bf16 v[0:3], v[204:207], v[0:3], v[36:39]
	v_mfma_f32_16x16x32_bf16 v[36:39], v[204:207], v[16:19], v[32:35]
	v_mfma_f32_16x16x32_bf16 v[72:75], v[178:181], v[8:11], v[24:27]
	v_mfma_f32_16x16x32_bf16 v[60:63], v[178:181], v[192:195], v[60:63]
	v_mfma_f32_16x16x32_bf16 v[40:43], v[182:185], v[8:11], v[134:137]
	v_mfma_f32_16x16x32_bf16 v[32:35], v[182:185], v[192:195], v[170:173]
	v_mfma_f32_16x16x32_bf16 v[24:27], v[200:203], v[8:11], v[44:47]
	v_mfma_f32_16x16x32_bf16 v[16:19], v[200:203], v[192:195], v[208:211]
	v_mfma_f32_16x16x32_bf16 v[8:11], v[150:153], v[8:11], v[0:3]
	v_mfma_f32_16x16x32_bf16 v[0:3], v[150:153], v[192:195], v[36:39]
	v_mfma_f32_16x16x32_bf16 v[28:31], v[64:67], v[220:223], v[28:31]
	v_mfma_f32_16x16x32_bf16 v[36:39], v[64:67], v[232:235], v[138:141]
	v_mfma_f32_16x16x32_bf16 v[20:23], v[76:79], v[220:223], v[20:23]
	v_mfma_f32_16x16x32_bf16 v[134:137], v[76:79], v[232:235], v[174:177]
	v_mfma_f32_16x16x32_bf16 v[12:15], v[196:199], v[220:223], v[12:15]
	v_mfma_f32_16x16x32_bf16 v[138:141], v[196:199], v[232:235], v[188:191]
	v_mfma_f32_16x16x32_bf16 v[4:7], v[204:207], v[220:223], v[4:7]
	v_mfma_f32_16x16x32_bf16 v[158:161], v[204:207], v[232:235], v[158:161]
	v_mfma_f32_16x16x32_bf16 v[76:79], v[178:181], v[228:231], v[28:31]
	v_mfma_f32_16x16x32_bf16 v[64:67], v[178:181], v[154:157], v[36:39]
	v_mfma_f32_16x16x32_bf16 v[44:47], v[182:185], v[228:231], v[20:23]
	v_mfma_f32_16x16x32_bf16 v[36:39], v[182:185], v[154:157], v[134:137]
	v_mfma_f32_16x16x32_bf16 v[28:31], v[200:203], v[228:231], v[12:15]
	v_mfma_f32_16x16x32_bf16 v[20:23], v[200:203], v[154:157], v[138:141]
	v_mfma_f32_16x16x32_bf16 v[12:15], v[150:153], v[228:231], v[4:7]
	v_mfma_f32_16x16x32_bf16 v[4:7], v[150:153], v[154:157], v[158:161]
	v_cmp_gt_u32_e32 vcc, s64, v130
	s_barrier
	s_and_saveexec_b64 s[48:49], vcc
	s_cbranch_execz .LBB0_343
	s_barrier

; #define STAGE(P, BASE, LD, br, kt) do { const char* _g = (const char*)((BASE) + (size_t)(br) * (LD) + (size_t)(kt) * 64); \
;     for (int _i = 0; _i < 2; ++_i) { int _b = tidx * 16 + _i * 8192; int _r, _c; stage_rc(_b, _r, _c); \
;       __builtin_amdgcn_global_load_lds((const unsigned*)(_g + (unsigned)((_r * (LD) + _c) * 2)), (unsigned*)((char*)(P) + _b), 16, 0, 0); } } while (0)
; #define LDA(dst, b, h) for (int m = 0; m < 4; ++m) for (int k = 0; k < 2; ++k) \
;     dst[m][k] = *reinterpret_cast<const bf16x8*>((char*)SA(b, h) + lds_byte(wr * 64 + m * 16 + fr, k * 32 + fq * 8))
; #define LDB(dst, b, h) for (int n = 0; n < 2; ++n) for (int k = 0; k < 2; ++k) \
;     dst[n][k] = *reinterpret_cast<const bf16x8*>((char*)SB(b, h) + lds_byte(wc * 32 + n * 16 + fr, k * 32 + fq * 8))
; #define MMA(ai, bj, At_, Bt_) do { __builtin_amdgcn_s_setprio(1); \
;     for (int k = 0; k < 2; ++k) for (int m = 0; m < 4; ++m) for (int n = 0; n < 2; ++n) \
;       acc[ai][bj][m][n] = __builtin_amdgcn_mfma_f32_16x16x32_bf16(At_[m][k], Bt_[n][k], acc[ai][bj][m][n], 0, 0, 0); \
;     __builtin_amdgcn_s_setprio(0); } while (0)
; #define WAIT_L(n) asm volatile("s_waitcnt lgkmcnt(" #n ")" ::: "memory")
; #define BAR __builtin_amdgcn_s_barrier()
; #define SCHED __builtin_amdgcn_sched_barrier(0)
; template <int EPI, int lda, int ldb, int N, int K>
; __device__ __forceinline__ void gemm_phase(const u16* __restrict__ A, const u16* __restrict__ Bt, const GemmEpi ep, int wv) {
;     ...
;     for (int t = 0; t < nt - 2; t += 2) {
;       LDB(B0, 0, 0); SCHED; LDA(At, 0, 0); STAGE(SA(1, 1), Ab, lda, brow + HALF, t + 1);
;       WAIT_L(8); BAR; WAIT_L(0); MMA(0, 0, At, B0); BAR; SCHED;
;       LDB(B1, 0, 1); STAGE(SB(0, 0), Bt, ldb, bcol, t + 2);
;       BAR; WAIT_L(0); MMA(0, 1, At, B1); BAR;
;       LDA(At, 0, 1); STAGE(SA(0, 0), Ab, lda, brow, t + 2);
;       BAR; WAIT_L(0); MMA(1, 0, At, B0); BAR; SCHED;
.LBB0_654:
	ds_read_b128 v[164:167], v160
	ds_read_b128 v[170:173], v160 offset:1024
	ds_read_b128 v[174:177], v160 offset:2048
	ds_read_b128 v[178:181], v160 offset:3072
	v_add_u32_e32 v168, 0xc000, v143
	v_lshl_add_u64 v[234:235], v[138:139], 0, s[52:53]
	v_readfirstlane_b32 s55, v168
	v_add_u32_e32 v169, 0xe000, v143
	v_lshl_add_u64 v[162:163], v[234:235], 0, s[20:21]
	s_mov_b32 m0, s55
	v_lshl_add_u64 v[236:237], v[140:141], 0, s[52:53]
	v_readfirstlane_b32 s55, v169
	ds_read_b128 v[182:185], v151
	ds_read_b128 v[186:189], v151 offset:1024
	ds_read_b128 v[190:193], v150
	ds_read_b128 v[194:197], v150 offset:1024
	ds_read_b128 v[198:201], v149
	ds_read_b128 v[202:205], v149 offset:1024
	ds_read_b128 v[206:209], v148
	ds_read_b128 v[210:213], v148 offset:1024
	global_load_lds_dwordx4 v[162:163], off
	s_nop 1
	v_lshl_add_u64 v[162:163], v[236:237], 0, s[20:21]
	s_mov_b32 m0, s55
	s_nop 0
	global_load_lds_dwordx4 v[162:163], off
	s_waitcnt lgkmcnt(8)
	s_barrier
	s_waitcnt lgkmcnt(0)
	s_waitcnt lgkmcnt(0)
	v_mfma_f32_16x16x32_bf16 v[124:127], v[164:167], v[182:185], v[124:127]
	v_mfma_f32_16x16x32_bf16 v[120:123], v[174:177], v[182:185], v[120:123]
	v_mfma_f32_16x16x32_bf16 v[116:119], v[164:167], v[190:193], v[116:119]
	v_mfma_f32_16x16x32_bf16 v[112:115], v[174:177], v[190:193], v[112:115]
	v_mfma_f32_16x16x32_bf16 v[108:111], v[164:167], v[198:201], v[108:111]
	v_mfma_f32_16x16x32_bf16 v[104:107], v[174:177], v[198:201], v[104:107]
	v_mfma_f32_16x16x32_bf16 v[100:103], v[164:167], v[206:209], v[100:103]
	v_mfma_f32_16x16x32_bf16 v[96:99], v[174:177], v[206:209], v[96:99]
	v_mfma_f32_16x16x32_bf16 v[124:127], v[170:173], v[186:189], v[124:127]
	v_mfma_f32_16x16x32_bf16 v[120:123], v[178:181], v[186:189], v[120:123]
	v_mfma_f32_16x16x32_bf16 v[116:119], v[170:173], v[194:197], v[116:119]
	v_mfma_f32_16x16x32_bf16 v[112:115], v[178:181], v[194:197], v[112:115]
	v_mfma_f32_16x16x32_bf16 v[108:111], v[170:173], v[202:205], v[108:111]
	v_mfma_f32_16x16x32_bf16 v[104:107], v[178:181], v[202:205], v[104:107]
	v_mfma_f32_16x16x32_bf16 v[100:103], v[170:173], v[210:213], v[100:103]
	v_mfma_f32_16x16x32_bf16 v[96:99], v[178:181], v[210:213], v[96:99]
	s_barrier
	v_add_u32_e32 v161, s65, v153
	v_lshl_add_u64 v[238:239], v[134:135], 0, s[52:53]
	v_readfirstlane_b32 s55, v161
	v_lshl_add_u64 v[162:163], v[238:239], 0, s[22:23]
	s_mov_b32 m0, s55
	ds_read_b128 v[214:217], v159
	ds_read_b128 v[218:221], v159 offset:1024
	ds_read_b128 v[222:225], v159 offset:2048
	ds_read_b128 v[226:229], v159 offset:3072
	global_load_lds_dwordx4 v[162:163], off
	s_nop 1
	v_add_u32_e32 v162, 0x2000, v161
	v_lshl_add_u64 v[240:241], v[136:137], 0, s[52:53]
	v_readfirstlane_b32 s55, v162
	v_lshl_add_u64 v[230:231], v[240:241], 0, s[22:23]
	s_mov_b32 m0, s55
	s_nop 0
	global_load_lds_dwordx4 v[230:231], off
	s_barrier
	s_waitcnt lgkmcnt(0)
	s_waitcnt lgkmcnt(0)
	v_mfma_f32_16x16x32_bf16 v[92:95], v[214:217], v[182:185], v[92:95]
	v_mfma_f32_16x16x32_bf16 v[88:91], v[222:225], v[182:185], v[88:91]
	v_mfma_f32_16x16x32_bf16 v[84:87], v[214:217], v[190:193], v[84:87]
	v_mfma_f32_16x16x32_bf16 v[80:83], v[222:225], v[190:193], v[80:83]
	v_mfma_f32_16x16x32_bf16 v[76:79], v[214:217], v[198:201], v[76:79]
	v_mfma_f32_16x16x32_bf16 v[72:75], v[222:225], v[198:201], v[72:75]
	v_mfma_f32_16x16x32_bf16 v[68:71], v[214:217], v[206:209], v[68:71]
	v_mfma_f32_16x16x32_bf16 v[64:67], v[222:225], v[206:209], v[64:67]
	v_mfma_f32_16x16x32_bf16 v[92:95], v[218:221], v[186:189], v[92:95]
	v_mfma_f32_16x16x32_bf16 v[88:91], v[226:229], v[186:189], v[88:91]
	v_mfma_f32_16x16x32_bf16 v[84:87], v[218:221], v[194:197], v[84:87]
	v_mfma_f32_16x16x32_bf16 v[80:83], v[226:229], v[194:197], v[80:83]
	v_mfma_f32_16x16x32_bf16 v[76:79], v[218:221], v[202:205], v[76:79]
	v_mfma_f32_16x16x32_bf16 v[72:75], v[226:229], v[202:205], v[72:75]
	v_mfma_f32_16x16x32_bf16 v[68:71], v[218:221], v[210:213], v[68:71]
	v_mfma_f32_16x16x32_bf16 v[64:67], v[226:229], v[210:213], v[64:67]
	v_readfirstlane_b32 s55, v143
	v_add_u32_e32 v163, 0x2000, v143
	v_lshl_add_u64 v[230:231], v[234:235], 0, s[24:25]
	s_mov_b32 m0, s55
	v_readfirstlane_b32 s55, v163
	s_barrier
	ds_read_b128 v[182:185], v151 offset:16384
	ds_read_b128 v[186:189], v151 offset:17408
	ds_read_b128 v[190:193], v150 offset:16384
	ds_read_b128 v[194:197], v150 offset:17408
	ds_read_b128 v[198:201], v149 offset:16384
	ds_read_b128 v[202:205], v149 offset:17408
	ds_read_b128 v[206:209], v148 offset:16384
	ds_read_b128 v[210:213], v148 offset:17408
	global_load_lds_dwordx4 v[230:231], off
	s_nop 1
	v_lshl_add_u64 v[230:231], v[236:237], 0, s[24:25]
	s_mov_b32 m0, s55
	s_nop 0
	global_load_lds_dwordx4 v[230:231], off
	s_barrier
	s_waitcnt lgkmcnt(0)
	s_waitcnt lgkmcnt(0)
	v_mfma_f32_16x16x32_bf16 v[60:63], v[164:167], v[182:185], v[60:63]
	v_mfma_f32_16x16x32_bf16 v[56:59], v[174:177], v[182:185], v[56:59]
	v_mfma_f32_16x16x32_bf16 v[52:55], v[164:167], v[190:193], v[52:55]
	v_mfma_f32_16x16x32_bf16 v[48:51], v[174:177], v[190:193], v[48:51]
	v_mfma_f32_16x16x32_bf16 v[44:47], v[164:167], v[198:201], v[44:47]
	v_mfma_f32_16x16x32_bf16 v[40:43], v[174:177], v[198:201], v[40:43]
	v_mfma_f32_16x16x32_bf16 v[36:39], v[164:167], v[206:209], v[36:39]
	v_mfma_f32_16x16x32_bf16 v[32:35], v[174:177], v[206:209], v[32:35]
	v_mfma_f32_16x16x32_bf16 v[60:63], v[170:173], v[186:189], v[60:63]
	v_mfma_f32_16x16x32_bf16 v[56:59], v[178:181], v[186:189], v[56:59]
	v_mfma_f32_16x16x32_bf16 v[52:55], v[170:173], v[194:197], v[52:55]
	v_mfma_f32_16x16x32_bf16 v[48:51], v[178:181], v[194:197], v[48:51]
	v_mfma_f32_16x16x32_bf16 v[44:47], v[170:173], v[202:205], v[44:47]
	v_mfma_f32_16x16x32_bf16 v[40:43], v[178:181], v[202:205], v[40:43]
	v_mfma_f32_16x16x32_bf16 v[36:39], v[170:173], v[210:213], v[36:39]
	v_mfma_f32_16x16x32_bf16 v[32:35], v[178:181], v[210:213], v[32:35]
	s_barrier
; #define STAGE(P, BASE, LD, br, kt) do { const char* _g = (const char*)((BASE) + (size_t)(br) * (LD) + (size_t)(kt) * 64); \
;     for (int _i = 0; _i < 2; ++_i) { int _b = tidx * 16 + _i * 8192; int _r, _c; stage_rc(_b, _r, _c); \
;       __builtin_amdgcn_global_load_lds((const unsigned*)(_g + (unsigned)((_r * (LD) + _c) * 2)), (unsigned*)((char*)(P) + _b), 16, 0, 0); } } while (0)
; #define LDA(dst, b, h) for (int m = 0; m < 4; ++m) for (int k = 0; k < 2; ++k) \
;     dst[m][k] = *reinterpret_cast<const bf16x8*>((char*)SA(b, h) + lds_byte(wr * 64 + m * 16 + fr, k * 32 + fq * 8))
; #define LDB(dst, b, h) for (int n = 0; n < 2; ++n) for (int k = 0; k < 2; ++k) \
;     dst[n][k] = *reinterpret_cast<const bf16x8*>((char*)SB(b, h) + lds_byte(wc * 32 + n * 16 + fr, k * 32 + fq * 8))
; #define MMA(ai, bj, At_, Bt_) do { __builtin_amdgcn_s_setprio(1); \
;     for (int k = 0; k < 2; ++k) for (int m = 0; m < 4; ++m) for (int n = 0; n < 2; ++n) \
;       acc[ai][bj][m][n] = __builtin_amdgcn_mfma_f32_16x16x32_bf16(At_[m][k], Bt_[n][k], acc[ai][bj][m][n], 0, 0, 0); \
;     __builtin_amdgcn_s_setprio(0); } while (0)
; #define WAIT_V(n) asm volatile("s_waitcnt vmcnt(" #n ")" ::: "memory")
; #define WAIT_L(n) asm volatile("s_waitcnt lgkmcnt(" #n ")" ::: "memory")
; #define BAR __builtin_amdgcn_s_barrier()
; #define SCHED __builtin_amdgcn_sched_barrier(0)
; template <int EPI, int lda, int ldb, int N, int K>
; __device__ __forceinline__ void gemm_phase(const u16* __restrict__ A, const u16* __restrict__ Bt, const GemmEpi ep, int wv) {
;     ...
;       STAGE(SB(0, 1), Bt, ldb, bcol + HALF, t + 2);
;       WAIT_V(6); BAR; MMA(1, 1, At, B1); BAR;
;       LDB(B0, 1, 0); SCHED; LDA(At, 1, 0); STAGE(SA(0, 1), Ab, lda, brow + HALF, t + 2);
;       WAIT_L(8); BAR; WAIT_L(0); MMA(0, 0, At, B0); BAR; SCHED;
;       LDB(B1, 1, 1); STAGE(SB(1, 0), Bt, ldb, bcol, t + 3);
;       BAR; WAIT_L(0); MMA(0, 1, At, B1); BAR;
;       LDA(At, 1, 1); STAGE(SA(1, 0), Ab, lda, brow, t + 3);
	v_add_u32_e32 v164, s66, v153
	v_add_u32_e32 v165, 0x2000, v164
	v_readfirstlane_b32 s55, v164
	v_lshl_add_u64 v[166:167], v[238:239], 0, s[26:27]
	s_mov_b32 m0, s55
	v_readfirstlane_b32 s55, v165
	global_load_lds_dwordx4 v[166:167], off
	s_nop 1
	v_lshl_add_u64 v[166:167], v[240:241], 0, s[26:27]
	s_mov_b32 m0, s55
	s_nop 0
	global_load_lds_dwordx4 v[166:167], off
	s_waitcnt vmcnt(6)
	s_barrier
	v_mfma_f32_16x16x32_bf16 v[28:31], v[214:217], v[182:185], v[28:31]
	v_mfma_f32_16x16x32_bf16 v[24:27], v[222:225], v[182:185], v[24:27]
	v_mfma_f32_16x16x32_bf16 v[20:23], v[214:217], v[190:193], v[20:23]
	v_mfma_f32_16x16x32_bf16 v[16:19], v[222:225], v[190:193], v[16:19]
	v_mfma_f32_16x16x32_bf16 v[12:15], v[214:217], v[198:201], v[12:15]
	v_mfma_f32_16x16x32_bf16 v[8:11], v[222:225], v[198:201], v[8:11]
	v_mfma_f32_16x16x32_bf16 v[4:7], v[214:217], v[206:209], v[4:7]
	v_mfma_f32_16x16x32_bf16 v[0:3], v[222:225], v[206:209], v[0:3]
	v_mfma_f32_16x16x32_bf16 v[28:31], v[218:221], v[186:189], v[28:31]
	v_mfma_f32_16x16x32_bf16 v[24:27], v[226:229], v[186:189], v[24:27]
	v_mfma_f32_16x16x32_bf16 v[20:23], v[218:221], v[194:197], v[20:23]
	v_mfma_f32_16x16x32_bf16 v[16:19], v[226:229], v[194:197], v[16:19]
	v_mfma_f32_16x16x32_bf16 v[12:15], v[218:221], v[202:205], v[12:15]
	v_mfma_f32_16x16x32_bf16 v[8:11], v[226:229], v[202:205], v[8:11]
	v_mfma_f32_16x16x32_bf16 v[4:7], v[218:221], v[210:213], v[4:7]
	v_mfma_f32_16x16x32_bf16 v[0:3], v[226:229], v[210:213], v[0:3]
	s_barrier
	ds_read_b128 v[170:173], v154
	ds_read_b128 v[174:177], v154 offset:1024
	ds_read_b128 v[178:181], v154 offset:2048
	ds_read_b128 v[182:185], v154 offset:3072
	v_add_u32_e32 v166, 0x4000, v143
	v_add_u32_e32 v167, 0x6000, v143
	v_readfirstlane_b32 s55, v166
	v_lshl_add_u64 v[218:219], v[234:235], 0, s[42:43]
	s_mov_b32 m0, s55
	v_readfirstlane_b32 s55, v167
	ds_read_b128 v[186:189], v151 offset:32768
	ds_read_b128 v[190:193], v151 offset:33792
	ds_read_b128 v[194:197], v150 offset:32768
	ds_read_b128 v[198:201], v150 offset:33792
	ds_read_b128 v[202:205], v149 offset:32768
	ds_read_b128 v[206:209], v149 offset:33792
	ds_read_b128 v[210:213], v148 offset:32768
	ds_read_b128 v[214:217], v148 offset:33792
	global_load_lds_dwordx4 v[218:219], off
	s_nop 1
	v_lshl_add_u64 v[218:219], v[236:237], 0, s[42:43]
	s_mov_b32 m0, s55
	s_nop 0
	global_load_lds_dwordx4 v[218:219], off
	s_waitcnt lgkmcnt(8)
	s_barrier
	s_waitcnt lgkmcnt(0)
	s_waitcnt lgkmcnt(0)
	v_mfma_f32_16x16x32_bf16 v[124:127], v[170:173], v[186:189], v[124:127]
	v_mfma_f32_16x16x32_bf16 v[120:123], v[178:181], v[186:189], v[120:123]
	v_mfma_f32_16x16x32_bf16 v[116:119], v[170:173], v[194:197], v[116:119]
	v_mfma_f32_16x16x32_bf16 v[112:115], v[178:181], v[194:197], v[112:115]
	v_mfma_f32_16x16x32_bf16 v[108:111], v[170:173], v[202:205], v[108:111]
	v_mfma_f32_16x16x32_bf16 v[104:107], v[178:181], v[202:205], v[104:107]
	v_mfma_f32_16x16x32_bf16 v[100:103], v[170:173], v[210:213], v[100:103]
	v_mfma_f32_16x16x32_bf16 v[96:99], v[178:181], v[210:213], v[96:99]
	v_mfma_f32_16x16x32_bf16 v[124:127], v[174:177], v[190:193], v[124:127]
	v_mfma_f32_16x16x32_bf16 v[120:123], v[182:185], v[190:193], v[120:123]
	v_mfma_f32_16x16x32_bf16 v[116:119], v[174:177], v[198:201], v[116:119]
	v_mfma_f32_16x16x32_bf16 v[112:115], v[182:185], v[198:201], v[112:115]
	v_mfma_f32_16x16x32_bf16 v[108:111], v[174:177], v[206:209], v[108:111]
	v_mfma_f32_16x16x32_bf16 v[104:107], v[182:185], v[206:209], v[104:107]
	v_mfma_f32_16x16x32_bf16 v[100:103], v[174:177], v[214:217], v[100:103]
	v_mfma_f32_16x16x32_bf16 v[96:99], v[182:185], v[214:217], v[96:99]
	s_barrier
	v_readfirstlane_b32 s55, v155
	v_add_u32_e32 v244, 0x2000, v155
	v_lshl_add_u64 v[242:243], v[238:239], 0, s[44:45]
	s_mov_b32 m0, s55
	v_readfirstlane_b32 s55, v244
	ds_read_b128 v[218:221], v152
	ds_read_b128 v[222:225], v152 offset:1024
	ds_read_b128 v[226:229], v152 offset:2048
	ds_read_b128 v[230:233], v152 offset:3072
	global_load_lds_dwordx4 v[242:243], off
	s_nop 1
	v_lshl_add_u64 v[242:243], v[240:241], 0, s[44:45]
	s_mov_b32 m0, s55
	s_nop 0
	global_load_lds_dwordx4 v[242:243], off
	s_barrier
	s_waitcnt lgkmcnt(0)
	s_waitcnt lgkmcnt(0)
	v_mfma_f32_16x16x32_bf16 v[92:95], v[218:221], v[186:189], v[92:95]
	v_mfma_f32_16x16x32_bf16 v[88:91], v[226:229], v[186:189], v[88:91]
	v_mfma_f32_16x16x32_bf16 v[84:87], v[218:221], v[194:197], v[84:87]
	v_mfma_f32_16x16x32_bf16 v[80:83], v[226:229], v[194:197], v[80:83]
	v_mfma_f32_16x16x32_bf16 v[76:79], v[218:221], v[202:205], v[76:79]
	v_mfma_f32_16x16x32_bf16 v[72:75], v[226:229], v[202:205], v[72:75]
	v_mfma_f32_16x16x32_bf16 v[68:71], v[218:221], v[210:213], v[68:71]
	v_mfma_f32_16x16x32_bf16 v[64:67], v[226:229], v[210:213], v[64:67]
	v_mfma_f32_16x16x32_bf16 v[92:95], v[222:225], v[190:193], v[92:95]
	v_mfma_f32_16x16x32_bf16 v[88:91], v[230:233], v[190:193], v[88:91]
	v_mfma_f32_16x16x32_bf16 v[84:87], v[222:225], v[198:201], v[84:87]
	v_mfma_f32_16x16x32_bf16 v[80:83], v[230:233], v[198:201], v[80:83]
	v_mfma_f32_16x16x32_bf16 v[76:79], v[222:225], v[206:209], v[76:79]
	v_mfma_f32_16x16x32_bf16 v[72:75], v[230:233], v[206:209], v[72:75]
	v_mfma_f32_16x16x32_bf16 v[68:71], v[222:225], v[214:217], v[68:71]
	v_mfma_f32_16x16x32_bf16 v[64:67], v[230:233], v[214:217], v[64:67]
	v_readfirstlane_b32 s55, v156
	v_lshl_add_u64 v[234:235], v[234:235], 0, s[46:47]
	s_mov_b32 m0, s55
	v_readfirstlane_b32 s55, v157
	s_barrier
; #define STAGE(P, BASE, LD, br, kt) do { const char* _g = (const char*)((BASE) + (size_t)(br) * (LD) + (size_t)(kt) * 64); \
;     for (int _i = 0; _i < 2; ++_i) { int _b = tidx * 16 + _i * 8192; int _r, _c; stage_rc(_b, _r, _c); \
;       __builtin_amdgcn_global_load_lds((const unsigned*)(_g + (unsigned)((_r * (LD) + _c) * 2)), (unsigned*)((char*)(P) + _b), 16, 0, 0); } } while (0)
; #define LDA(dst, b, h) for (int m = 0; m < 4; ++m) for (int k = 0; k < 2; ++k) \
;     dst[m][k] = *reinterpret_cast<const bf16x8*>((char*)SA(b, h) + lds_byte(wr * 64 + m * 16 + fr, k * 32 + fq * 8))
; #define LDB(dst, b, h) for (int n = 0; n < 2; ++n) for (int k = 0; k < 2; ++k) \
;     dst[n][k] = *reinterpret_cast<const bf16x8*>((char*)SB(b, h) + lds_byte(wc * 32 + n * 16 + fr, k * 32 + fq * 8))
; #define MMA(ai, bj, At_, Bt_) do { __builtin_amdgcn_s_setprio(1); \
;     for (int k = 0; k < 2; ++k) for (int m = 0; m < 4; ++m) for (int n = 0; n < 2; ++n) \
;       acc[ai][bj][m][n] = __builtin_amdgcn_mfma_f32_16x16x32_bf16(At_[m][k], Bt_[n][k], acc[ai][bj][m][n], 0, 0, 0); \
;     __builtin_amdgcn_s_setprio(0); } while (0)
; #define WAIT_V(n) asm volatile("s_waitcnt vmcnt(" #n ")" ::: "memory")
; #define WAIT_L(n) asm volatile("s_waitcnt lgkmcnt(" #n ")" ::: "memory")
; #define BAR __builtin_amdgcn_s_barrier()
; #define SCHED __builtin_amdgcn_sched_barrier(0)
; template <int EPI, int lda, int ldb, int N, int K>
; __device__ __forceinline__ void gemm_phase(const u16* __restrict__ A, const u16* __restrict__ Bt, const GemmEpi ep, int wv) {
;     ...
;       LDA(At, 1, 1); STAGE(SA(1, 0), Ab, lda, brow, t + 3);
;       BAR; WAIT_L(0); MMA(1, 0, At, B0); BAR; SCHED;
;       STAGE(SB(1, 1), Bt, ldb, bcol + HALF, t + 3);
;       WAIT_V(6); BAR; MMA(1, 1, At, B1); BAR;
;     }
;     { LDB(B0, 0, 0); LDA(At, 0, 0); STAGE(SA(1, 1), Ab, lda, brow + HALF, nt - 1);
;       BAR; WAIT_L(0); MMA(0, 0, At, B0); BAR;
;       LDB(B1, 0, 1); BAR; WAIT_L(0); MMA(0, 1, At, B1); BAR;
	ds_read_b128 v[186:189], v151 offset:49152
	ds_read_b128 v[190:193], v151 offset:50176
	ds_read_b128 v[194:197], v150 offset:49152
	ds_read_b128 v[198:201], v150 offset:50176
	ds_read_b128 v[202:205], v149 offset:49152
	ds_read_b128 v[206:209], v149 offset:50176
	ds_read_b128 v[210:213], v148 offset:49152
	ds_read_b128 v[214:217], v148 offset:50176
	global_load_lds_dwordx4 v[234:235], off
	s_nop 1
	v_lshl_add_u64 v[234:235], v[236:237], 0, s[46:47]
	s_mov_b32 m0, s55
	s_nop 0
	global_load_lds_dwordx4 v[234:235], off
	s_barrier
	s_waitcnt lgkmcnt(0)
	s_waitcnt lgkmcnt(0)
	v_mfma_f32_16x16x32_bf16 v[60:63], v[170:173], v[186:189], v[60:63]
	v_mfma_f32_16x16x32_bf16 v[56:59], v[178:181], v[186:189], v[56:59]
	v_mfma_f32_16x16x32_bf16 v[52:55], v[170:173], v[194:197], v[52:55]
	v_mfma_f32_16x16x32_bf16 v[48:51], v[178:181], v[194:197], v[48:51]
	v_mfma_f32_16x16x32_bf16 v[44:47], v[170:173], v[202:205], v[44:47]
	v_mfma_f32_16x16x32_bf16 v[40:43], v[178:181], v[202:205], v[40:43]
	v_mfma_f32_16x16x32_bf16 v[36:39], v[170:173], v[210:213], v[36:39]
	v_mfma_f32_16x16x32_bf16 v[32:35], v[178:181], v[210:213], v[32:35]
	v_mfma_f32_16x16x32_bf16 v[60:63], v[174:177], v[190:193], v[60:63]
	v_mfma_f32_16x16x32_bf16 v[56:59], v[182:185], v[190:193], v[56:59]
	v_mfma_f32_16x16x32_bf16 v[52:55], v[174:177], v[198:201], v[52:55]
	v_mfma_f32_16x16x32_bf16 v[48:51], v[182:185], v[198:201], v[48:51]
	v_mfma_f32_16x16x32_bf16 v[44:47], v[174:177], v[206:209], v[44:47]
	v_mfma_f32_16x16x32_bf16 v[40:43], v[182:185], v[206:209], v[40:43]
	v_mfma_f32_16x16x32_bf16 v[36:39], v[174:177], v[214:217], v[36:39]
	v_mfma_f32_16x16x32_bf16 v[32:35], v[182:185], v[214:217], v[32:35]
	s_barrier
	v_readfirstlane_b32 s55, v158
	v_add_u32_e32 v172, 0x2000, v158
	v_lshl_add_u64 v[170:171], v[238:239], 0, s[48:49]
	s_mov_b32 m0, s55
	v_readfirstlane_b32 s55, v172
	global_load_lds_dwordx4 v[170:171], off
	s_nop 1
	v_lshl_add_u64 v[170:171], v[240:241], 0, s[48:49]
	s_mov_b32 m0, s55
	s_nop 0
	global_load_lds_dwordx4 v[170:171], off
	s_waitcnt vmcnt(6)
	s_barrier
	v_mfma_f32_16x16x32_bf16 v[28:31], v[218:221], v[186:189], v[28:31]
	v_mfma_f32_16x16x32_bf16 v[24:27], v[226:229], v[186:189], v[24:27]
	v_mfma_f32_16x16x32_bf16 v[20:23], v[218:221], v[194:197], v[20:23]
	v_mfma_f32_16x16x32_bf16 v[16:19], v[226:229], v[194:197], v[16:19]
	v_mfma_f32_16x16x32_bf16 v[12:15], v[218:221], v[202:205], v[12:15]
	v_mfma_f32_16x16x32_bf16 v[8:11], v[226:229], v[202:205], v[8:11]
	v_mfma_f32_16x16x32_bf16 v[4:7], v[218:221], v[210:213], v[4:7]
	v_mfma_f32_16x16x32_bf16 v[0:3], v[226:229], v[210:213], v[0:3]
	v_mfma_f32_16x16x32_bf16 v[28:31], v[222:225], v[190:193], v[28:31]
	v_mfma_f32_16x16x32_bf16 v[24:27], v[230:233], v[190:193], v[24:27]
	v_mfma_f32_16x16x32_bf16 v[20:23], v[222:225], v[198:201], v[20:23]
	v_mfma_f32_16x16x32_bf16 v[16:19], v[230:233], v[198:201], v[16:19]
	v_mfma_f32_16x16x32_bf16 v[12:15], v[222:225], v[206:209], v[12:15]
	v_mfma_f32_16x16x32_bf16 v[8:11], v[230:233], v[206:209], v[8:11]
	v_mfma_f32_16x16x32_bf16 v[4:7], v[222:225], v[214:217], v[4:7]
	v_mfma_f32_16x16x32_bf16 v[0:3], v[230:233], v[214:217], v[0:3]
	s_add_i32 s54, s54, 2
	s_add_u32 s52, s52, 0x100
	s_addc_u32 s53, s53, 0
	s_cmp_gt_u32 s54, 27
	s_barrier
	s_cbranch_scc0 .LBB0_654
	s_lshl_b64 s[52:53], s[16:17], 12
	s_add_u32 s52, s14, s52
	s_addc_u32 s53, s15, s53
	s_add_u32 s52, s52, 0x80000
	s_addc_u32 s53, s53, 0
	v_lshl_add_u64 v[156:157], s[52:53], 0, v[128:129]
	v_readfirstlane_b32 s54, v168
	v_lshl_add_u64 v[156:157], v[156:157], 0, s[50:51]
	s_mov_b32 m0, s54
	ds_read_b128 v[134:137], v160
	ds_read_b128 v[138:141], v160 offset:1024
	ds_read_b128 v[170:173], v160 offset:2048
	ds_read_b128 v[174:177], v160 offset:3072
	ds_read_b128 v[178:181], v151
	ds_read_b128 v[182:185], v151 offset:1024
	ds_read_b128 v[186:189], v150
	ds_read_b128 v[190:193], v150 offset:1024
	ds_read_b128 v[194:197], v149
	ds_read_b128 v[198:201], v149 offset:1024
	ds_read_b128 v[202:205], v148
	ds_read_b128 v[206:209], v148 offset:1024
	global_load_lds_dwordx4 v[156:157], off
	v_lshl_add_u64 v[156:157], s[52:53], 0, v[132:133]
	v_readfirstlane_b32 s52, v169
	v_lshl_add_u64 v[156:157], v[156:157], 0, s[50:51]
	s_mov_b32 m0, s52
	s_nop 0
	global_load_lds_dwordx4 v[156:157], off
	s_barrier
	s_waitcnt lgkmcnt(0)
	s_waitcnt lgkmcnt(0)
	v_mfma_f32_16x16x32_bf16 v[124:127], v[134:137], v[178:181], v[124:127]
	v_mfma_f32_16x16x32_bf16 v[120:123], v[170:173], v[178:181], v[120:123]
	v_mfma_f32_16x16x32_bf16 v[116:119], v[134:137], v[186:189], v[116:119]
	v_mfma_f32_16x16x32_bf16 v[112:115], v[170:173], v[186:189], v[112:115]
	v_mfma_f32_16x16x32_bf16 v[108:111], v[134:137], v[194:197], v[108:111]
	v_mfma_f32_16x16x32_bf16 v[104:107], v[170:173], v[194:197], v[104:107]
	v_mfma_f32_16x16x32_bf16 v[100:103], v[134:137], v[202:205], v[100:103]
	v_mfma_f32_16x16x32_bf16 v[96:99], v[170:173], v[202:205], v[96:99]
	v_mfma_f32_16x16x32_bf16 v[124:127], v[138:141], v[182:185], v[124:127]
	v_mfma_f32_16x16x32_bf16 v[120:123], v[174:177], v[182:185], v[120:123]
	v_mfma_f32_16x16x32_bf16 v[116:119], v[138:141], v[190:193], v[116:119]
	v_mfma_f32_16x16x32_bf16 v[112:115], v[174:177], v[190:193], v[112:115]
	v_mfma_f32_16x16x32_bf16 v[108:111], v[138:141], v[198:201], v[108:111]
	v_mfma_f32_16x16x32_bf16 v[104:107], v[174:177], v[198:201], v[104:107]
	v_mfma_f32_16x16x32_bf16 v[100:103], v[138:141], v[206:209], v[100:103]
	v_mfma_f32_16x16x32_bf16 v[96:99], v[174:177], v[206:209], v[96:99]
	s_barrier
	ds_read_b128 v[210:213], v159
	ds_read_b128 v[214:217], v159 offset:1024
	ds_read_b128 v[218:221], v159 offset:2048
	ds_read_b128 v[156:159], v159 offset:3072
	s_barrier
; #define LDA(dst, b, h) for (int m = 0; m < 4; ++m) for (int k = 0; k < 2; ++k) \
;     dst[m][k] = *reinterpret_cast<const bf16x8*>((char*)SA(b, h) + lds_byte(wr * 64 + m * 16 + fr, k * 32 + fq * 8))
; #define LDB(dst, b, h) for (int n = 0; n < 2; ++n) for (int k = 0; k < 2; ++k) \
;     dst[n][k] = *reinterpret_cast<const bf16x8*>((char*)SB(b, h) + lds_byte(wc * 32 + n * 16 + fr, k * 32 + fq * 8))
; #define MMA(ai, bj, At_, Bt_) do { __builtin_amdgcn_s_setprio(1); \
;     for (int k = 0; k < 2; ++k) for (int m = 0; m < 4; ++m) for (int n = 0; n < 2; ++n) \
;       acc[ai][bj][m][n] = __builtin_amdgcn_mfma_f32_16x16x32_bf16(At_[m][k], Bt_[n][k], acc[ai][bj][m][n], 0, 0, 0); \
;     __builtin_amdgcn_s_setprio(0); } while (0)
; #define WAIT_V(n) asm volatile("s_waitcnt vmcnt(" #n ")" ::: "memory")
; #define WAIT_L(n) asm volatile("s_waitcnt lgkmcnt(" #n ")" ::: "memory")
; #define BAR __builtin_amdgcn_s_barrier()
; template <int EPI, int lda, int ldb, int N, int K>
; __device__ __forceinline__ void gemm_phase(const u16* __restrict__ A, const u16* __restrict__ Bt, const GemmEpi ep, int wv) {
;     ...
;       LDB(B1, 0, 1); BAR; WAIT_L(0); MMA(0, 1, At, B1); BAR;
;       LDA(At, 0, 1); WAIT_V(4); BAR; WAIT_L(0); MMA(1, 0, At, B0); MMA(1, 1, At, B1); BAR; }
;     { LDB(B0, 1, 0); LDA(At, 1, 0); WAIT_V(2); BAR; WAIT_L(0); MMA(0, 0, At, B0); BAR;
	s_waitcnt lgkmcnt(0)
	s_waitcnt lgkmcnt(0)
	v_mfma_f32_16x16x32_bf16 v[92:95], v[210:213], v[178:181], v[92:95]
	v_mfma_f32_16x16x32_bf16 v[88:91], v[218:221], v[178:181], v[88:91]
	v_mfma_f32_16x16x32_bf16 v[76:79], v[210:213], v[194:197], v[76:79]
	v_mfma_f32_16x16x32_bf16 v[72:75], v[218:221], v[194:197], v[72:75]
	v_mfma_f32_16x16x32_bf16 v[84:87], v[210:213], v[186:189], v[84:87]
	v_mfma_f32_16x16x32_bf16 v[80:83], v[218:221], v[186:189], v[80:83]
	v_mfma_f32_16x16x32_bf16 v[68:71], v[210:213], v[202:205], v[68:71]
	v_mfma_f32_16x16x32_bf16 v[64:67], v[218:221], v[202:205], v[64:67]
	v_mfma_f32_16x16x32_bf16 v[92:95], v[214:217], v[182:185], v[92:95]
	v_mfma_f32_16x16x32_bf16 v[88:91], v[156:159], v[182:185], v[88:91]
	v_mfma_f32_16x16x32_bf16 v[76:79], v[214:217], v[198:201], v[76:79]
	v_mfma_f32_16x16x32_bf16 v[72:75], v[156:159], v[198:201], v[72:75]
	v_mfma_f32_16x16x32_bf16 v[178:181], v[214:217], v[190:193], v[84:87]
	v_mfma_f32_16x16x32_bf16 v[182:185], v[156:159], v[190:193], v[80:83]
	v_mfma_f32_16x16x32_bf16 v[186:189], v[214:217], v[206:209], v[68:71]
	v_mfma_f32_16x16x32_bf16 v[190:193], v[156:159], v[206:209], v[64:67]
	s_barrier
	s_nop 0
	ds_read_b128 v[64:67], v151 offset:16384
	ds_read_b128 v[68:71], v151 offset:17408
	ds_read_b128 v[80:83], v150 offset:16384
	ds_read_b128 v[84:87], v150 offset:17408
	ds_read_b128 v[194:197], v149 offset:16384
	ds_read_b128 v[198:201], v149 offset:17408
	ds_read_b128 v[202:205], v148 offset:16384
	ds_read_b128 v[206:209], v148 offset:17408
	s_waitcnt vmcnt(4)
	s_barrier
	s_waitcnt lgkmcnt(0)
	s_waitcnt lgkmcnt(0)
	v_mfma_f32_16x16x32_bf16 v[60:63], v[134:137], v[64:67], v[60:63]
	v_mfma_f32_16x16x32_bf16 v[56:59], v[170:173], v[64:67], v[56:59]
	v_mfma_f32_16x16x32_bf16 v[52:55], v[134:137], v[80:83], v[52:55]
	v_mfma_f32_16x16x32_bf16 v[48:51], v[170:173], v[80:83], v[48:51]
	v_mfma_f32_16x16x32_bf16 v[44:47], v[134:137], v[194:197], v[44:47]
	v_mfma_f32_16x16x32_bf16 v[40:43], v[170:173], v[194:197], v[40:43]
	v_mfma_f32_16x16x32_bf16 v[36:39], v[134:137], v[202:205], v[36:39]
	v_mfma_f32_16x16x32_bf16 v[32:35], v[170:173], v[202:205], v[32:35]
	v_mfma_f32_16x16x32_bf16 v[60:63], v[138:141], v[68:71], v[60:63]
	v_mfma_f32_16x16x32_bf16 v[56:59], v[174:177], v[68:71], v[56:59]
	v_mfma_f32_16x16x32_bf16 v[52:55], v[138:141], v[84:87], v[52:55]
	v_mfma_f32_16x16x32_bf16 v[48:51], v[174:177], v[84:87], v[48:51]
	v_mfma_f32_16x16x32_bf16 v[44:47], v[138:141], v[198:201], v[44:47]
	v_mfma_f32_16x16x32_bf16 v[40:43], v[174:177], v[198:201], v[40:43]
	v_mfma_f32_16x16x32_bf16 v[36:39], v[138:141], v[206:209], v[36:39]
	v_mfma_f32_16x16x32_bf16 v[32:35], v[174:177], v[206:209], v[32:35]
	v_mfma_f32_16x16x32_bf16 v[28:31], v[210:213], v[64:67], v[28:31]
	v_mfma_f32_16x16x32_bf16 v[20:23], v[210:213], v[80:83], v[20:23]
	v_mfma_f32_16x16x32_bf16 v[12:15], v[210:213], v[194:197], v[12:15]
	v_mfma_f32_16x16x32_bf16 v[4:7], v[210:213], v[202:205], v[4:7]
	v_mfma_f32_16x16x32_bf16 v[24:27], v[218:221], v[64:67], v[24:27]
	v_mfma_f32_16x16x32_bf16 v[16:19], v[218:221], v[80:83], v[16:19]
	v_mfma_f32_16x16x32_bf16 v[8:11], v[218:221], v[194:197], v[8:11]
	v_mfma_f32_16x16x32_bf16 v[0:3], v[218:221], v[202:205], v[0:3]
	v_mfma_f32_16x16x32_bf16 v[28:31], v[214:217], v[68:71], v[28:31]
	v_mfma_f32_16x16x32_bf16 v[20:23], v[214:217], v[84:87], v[20:23]
	v_mfma_f32_16x16x32_bf16 v[12:15], v[214:217], v[198:201], v[12:15]
	v_mfma_f32_16x16x32_bf16 v[4:7], v[214:217], v[206:209], v[4:7]
	v_mfma_f32_16x16x32_bf16 v[134:137], v[156:159], v[68:71], v[24:27]
	v_mfma_f32_16x16x32_bf16 v[138:141], v[156:159], v[84:87], v[16:19]
	v_mfma_f32_16x16x32_bf16 v[168:171], v[156:159], v[198:201], v[8:11]
	v_mfma_f32_16x16x32_bf16 v[156:159], v[156:159], v[206:209], v[0:3]
	s_barrier
	s_nop 0
	ds_read_b128 v[0:3], v154
	ds_read_b128 v[8:11], v154 offset:1024
	ds_read_b128 v[16:19], v154 offset:2048
	ds_read_b128 v[172:175], v154 offset:3072
	ds_read_b128 v[24:27], v151 offset:32768
	ds_read_b128 v[194:197], v151 offset:33792
	ds_read_b128 v[198:201], v150 offset:32768
	ds_read_b128 v[202:205], v150 offset:33792
	ds_read_b128 v[206:209], v149 offset:32768
	ds_read_b128 v[210:213], v149 offset:33792
	ds_read_b128 v[214:217], v148 offset:32768
	ds_read_b128 v[218:221], v148 offset:33792
	s_waitcnt vmcnt(2)
	s_barrier
; #define LDA(dst, b, h) for (int m = 0; m < 4; ++m) for (int k = 0; k < 2; ++k) \
;     dst[m][k] = *reinterpret_cast<const bf16x8*>((char*)SA(b, h) + lds_byte(wr * 64 + m * 16 + fr, k * 32 + fq * 8))
; #define LDB(dst, b, h) for (int n = 0; n < 2; ++n) for (int k = 0; k < 2; ++k) \
;     dst[n][k] = *reinterpret_cast<const bf16x8*>((char*)SB(b, h) + lds_byte(wc * 32 + n * 16 + fr, k * 32 + fq * 8))
; #define MMA(ai, bj, At_, Bt_) do { __builtin_amdgcn_s_setprio(1); \
;     for (int k = 0; k < 2; ++k) for (int m = 0; m < 4; ++m) for (int n = 0; n < 2; ++n) \
;       acc[ai][bj][m][n] = __builtin_amdgcn_mfma_f32_16x16x32_bf16(At_[m][k], Bt_[n][k], acc[ai][bj][m][n], 0, 0, 0); \
;     __builtin_amdgcn_s_setprio(0); } while (0)
; #define WAIT_V(n) asm volatile("s_waitcnt vmcnt(" #n ")" ::: "memory")
; #define WAIT_L(n) asm volatile("s_waitcnt lgkmcnt(" #n ")" ::: "memory")
; #define BAR __builtin_amdgcn_s_barrier()
; template <int EPI, int lda, int ldb, int N, int K>
; __device__ __forceinline__ void gemm_phase(const u16* __restrict__ A, const u16* __restrict__ Bt, const GemmEpi ep, int wv) {
;     ...
;     { LDB(B0, 1, 0); LDA(At, 1, 0); WAIT_V(2); BAR; WAIT_L(0); MMA(0, 0, At, B0); BAR;
;       LDB(B1, 1, 1); WAIT_V(0); BAR; WAIT_L(0); MMA(0, 1, At, B1); BAR;
;       LDA(At, 1, 1); BAR; WAIT_L(0); MMA(1, 0, At, B0); MMA(1, 1, At, B1); BAR; }
;     if (wr == 0) BAR;
	s_waitcnt lgkmcnt(0)
	s_waitcnt lgkmcnt(0)
	v_mfma_f32_16x16x32_bf16 v[64:67], v[0:3], v[24:27], v[124:127]
	v_mfma_f32_16x16x32_bf16 v[68:71], v[16:19], v[24:27], v[120:123]
	v_mfma_f32_16x16x32_bf16 v[80:83], v[0:3], v[198:201], v[116:119]
	v_mfma_f32_16x16x32_bf16 v[84:87], v[16:19], v[198:201], v[112:115]
	v_mfma_f32_16x16x32_bf16 v[108:111], v[0:3], v[206:209], v[108:111]
	v_mfma_f32_16x16x32_bf16 v[104:107], v[16:19], v[206:209], v[104:107]
	v_mfma_f32_16x16x32_bf16 v[120:123], v[0:3], v[214:217], v[100:103]
	v_mfma_f32_16x16x32_bf16 v[124:127], v[16:19], v[214:217], v[96:99]
	v_mfma_f32_16x16x32_bf16 v[116:119], v[8:11], v[194:197], v[64:67]
	v_mfma_f32_16x16x32_bf16 v[112:115], v[172:175], v[194:197], v[68:71]
	v_mfma_f32_16x16x32_bf16 v[100:103], v[8:11], v[202:205], v[80:83]
	v_mfma_f32_16x16x32_bf16 v[96:99], v[172:175], v[202:205], v[84:87]
	v_mfma_f32_16x16x32_bf16 v[84:87], v[8:11], v[210:213], v[108:111]
	v_mfma_f32_16x16x32_bf16 v[80:83], v[172:175], v[210:213], v[104:107]
	v_mfma_f32_16x16x32_bf16 v[68:71], v[8:11], v[218:221], v[120:123]
	v_mfma_f32_16x16x32_bf16 v[64:67], v[172:175], v[218:221], v[124:127]
	s_barrier
	ds_read_b128 v[222:225], v152
	ds_read_b128 v[226:229], v152 offset:1024
	ds_read_b128 v[230:233], v152 offset:2048
	ds_read_b128 v[152:155], v152 offset:3072
	s_waitcnt vmcnt(0)
	s_barrier
	s_waitcnt lgkmcnt(0)
	s_waitcnt lgkmcnt(0)
	v_mfma_f32_16x16x32_bf16 v[92:95], v[222:225], v[24:27], v[92:95]
	v_mfma_f32_16x16x32_bf16 v[24:27], v[230:233], v[24:27], v[88:91]
	v_mfma_f32_16x16x32_bf16 v[88:91], v[222:225], v[198:201], v[178:181]
	v_mfma_f32_16x16x32_bf16 v[104:107], v[230:233], v[198:201], v[182:185]
	v_mfma_f32_16x16x32_bf16 v[76:79], v[222:225], v[206:209], v[76:79]
	v_mfma_f32_16x16x32_bf16 v[72:75], v[230:233], v[206:209], v[72:75]
	v_mfma_f32_16x16x32_bf16 v[176:179], v[222:225], v[214:217], v[186:189]
	v_mfma_f32_16x16x32_bf16 v[180:183], v[230:233], v[214:217], v[190:193]
	v_mfma_f32_16x16x32_bf16 v[124:127], v[226:229], v[194:197], v[92:95]
	v_mfma_f32_16x16x32_bf16 v[120:123], v[152:155], v[194:197], v[24:27]
	v_mfma_f32_16x16x32_bf16 v[108:111], v[226:229], v[202:205], v[88:91]
	v_mfma_f32_16x16x32_bf16 v[104:107], v[152:155], v[202:205], v[104:107]
	v_mfma_f32_16x16x32_bf16 v[92:95], v[226:229], v[210:213], v[76:79]
	v_mfma_f32_16x16x32_bf16 v[88:91], v[152:155], v[210:213], v[72:75]
	v_mfma_f32_16x16x32_bf16 v[76:79], v[226:229], v[218:221], v[176:179]
	v_mfma_f32_16x16x32_bf16 v[72:75], v[152:155], v[218:221], v[180:183]
	s_barrier
	ds_read_b128 v[176:179], v151 offset:49152
	ds_read_b128 v[180:183], v151 offset:50176
	ds_read_b128 v[184:187], v150 offset:49152
	ds_read_b128 v[188:191], v150 offset:50176
	ds_read_b128 v[192:195], v149 offset:49152
	ds_read_b128 v[196:199], v149 offset:50176
	ds_read_b128 v[200:203], v148 offset:49152
	ds_read_b128 v[148:151], v148 offset:50176
	s_barrier
	s_waitcnt lgkmcnt(0)
	s_waitcnt lgkmcnt(0)
	v_mfma_f32_16x16x32_bf16 v[24:27], v[0:3], v[176:179], v[60:63]
	v_mfma_f32_16x16x32_bf16 v[60:63], v[16:19], v[176:179], v[56:59]
	v_mfma_f32_16x16x32_bf16 v[52:55], v[0:3], v[184:187], v[52:55]
	v_mfma_f32_16x16x32_bf16 v[204:207], v[16:19], v[184:187], v[48:51]
	v_mfma_f32_16x16x32_bf16 v[44:47], v[0:3], v[192:195], v[44:47]
	v_mfma_f32_16x16x32_bf16 v[208:211], v[16:19], v[192:195], v[40:43]
	v_mfma_f32_16x16x32_bf16 v[0:3], v[0:3], v[200:203], v[36:39]
	v_mfma_f32_16x16x32_bf16 v[36:39], v[16:19], v[200:203], v[32:35]
	v_mfma_f32_16x16x32_bf16 v[56:59], v[8:11], v[180:183], v[24:27]
	v_mfma_f32_16x16x32_bf16 v[48:51], v[172:175], v[180:183], v[60:63]
	v_mfma_f32_16x16x32_bf16 v[40:43], v[8:11], v[188:191], v[52:55]
	v_mfma_f32_16x16x32_bf16 v[32:35], v[172:175], v[188:191], v[204:207]
	v_mfma_f32_16x16x32_bf16 v[24:27], v[8:11], v[196:199], v[44:47]
	v_mfma_f32_16x16x32_bf16 v[16:19], v[172:175], v[196:199], v[208:211]
	v_mfma_f32_16x16x32_bf16 v[8:11], v[8:11], v[148:151], v[0:3]
	v_mfma_f32_16x16x32_bf16 v[0:3], v[172:175], v[148:151], v[36:39]
	v_mfma_f32_16x16x32_bf16 v[28:31], v[222:225], v[176:179], v[28:31]
	v_mfma_f32_16x16x32_bf16 v[36:39], v[230:233], v[176:179], v[134:137]
	v_mfma_f32_16x16x32_bf16 v[20:23], v[222:225], v[184:187], v[20:23]
	v_mfma_f32_16x16x32_bf16 v[134:137], v[230:233], v[184:187], v[138:141]
	v_mfma_f32_16x16x32_bf16 v[12:15], v[222:225], v[192:195], v[12:15]
	v_mfma_f32_16x16x32_bf16 v[138:141], v[230:233], v[192:195], v[168:171]
	v_mfma_f32_16x16x32_bf16 v[4:7], v[222:225], v[200:203], v[4:7]
	v_mfma_f32_16x16x32_bf16 v[156:159], v[230:233], v[200:203], v[156:159]
	v_mfma_f32_16x16x32_bf16 v[60:63], v[226:229], v[180:183], v[28:31]
	v_mfma_f32_16x16x32_bf16 v[52:55], v[152:155], v[180:183], v[36:39]
	v_mfma_f32_16x16x32_bf16 v[44:47], v[226:229], v[188:191], v[20:23]
	v_mfma_f32_16x16x32_bf16 v[36:39], v[152:155], v[188:191], v[134:137]
	v_mfma_f32_16x16x32_bf16 v[28:31], v[226:229], v[196:199], v[12:15]
	v_mfma_f32_16x16x32_bf16 v[20:23], v[152:155], v[196:199], v[138:141]
	v_mfma_f32_16x16x32_bf16 v[12:15], v[226:229], v[148:151], v[4:7]
	v_mfma_f32_16x16x32_bf16 v[4:7], v[152:155], v[148:151], v[156:159]
	v_cmp_gt_u32_e32 vcc, s70, v130
	s_barrier
	s_and_saveexec_b64 s[52:53], vcc
	s_cbranch_execz .LBB0_657
	s_barrier

; #define STAGE(P, BASE, LD, br, kt) do { const char* _g = (const char*)((BASE) + (size_t)(br) * (LD) + (size_t)(kt) * 64); \
;     for (int _i = 0; _i < 2; ++_i) { int _b = tidx * 16 + _i * 8192; int _r, _c; stage_rc(_b, _r, _c); \
;       __builtin_amdgcn_global_load_lds((const unsigned*)(_g + (unsigned)((_r * (LD) + _c) * 2)), (unsigned*)((char*)(P) + _b), 16, 0, 0); } } while (0)
; #define LDA(dst, b, h) for (int m = 0; m < 4; ++m) for (int k = 0; k < 2; ++k) \
;     dst[m][k] = *reinterpret_cast<const bf16x8*>((char*)SA(b, h) + lds_byte(wr * 64 + m * 16 + fr, k * 32 + fq * 8))
; #define LDB(dst, b, h) for (int n = 0; n < 2; ++n) for (int k = 0; k < 2; ++k) \
;     dst[n][k] = *reinterpret_cast<const bf16x8*>((char*)SB(b, h) + lds_byte(wc * 32 + n * 16 + fr, k * 32 + fq * 8))
; #define MMA(ai, bj, At_, Bt_) do { __builtin_amdgcn_s_setprio(1); \
;     for (int k = 0; k < 2; ++k) for (int m = 0; m < 4; ++m) for (int n = 0; n < 2; ++n) \
;       acc[ai][bj][m][n] = __builtin_amdgcn_mfma_f32_16x16x32_bf16(At_[m][k], Bt_[n][k], acc[ai][bj][m][n], 0, 0, 0); \
;     __builtin_amdgcn_s_setprio(0); } while (0)
; #define WAIT_L(n) asm volatile("s_waitcnt lgkmcnt(" #n ")" ::: "memory")
; #define BAR __builtin_amdgcn_s_barrier()
; #define SCHED __builtin_amdgcn_sched_barrier(0)
; template <int EPI, int lda, int ldb, int N, int K>
; __device__ __forceinline__ void gemm_phase(const u16* __restrict__ A, const u16* __restrict__ Bt, const GemmEpi ep, int wv) {
;     ...
;     for (int t = 0; t < nt - 2; t += 2) {
;       LDB(B0, 0, 0); SCHED; LDA(At, 0, 0); STAGE(SA(1, 1), Ab, lda, brow + HALF, t + 1);
;       WAIT_L(8); BAR; WAIT_L(0); MMA(0, 0, At, B0); BAR; SCHED;
;       LDB(B1, 0, 1); STAGE(SB(0, 0), Bt, ldb, bcol, t + 2);
;       BAR; WAIT_L(0); MMA(0, 1, At, B1); BAR;
;       LDA(At, 0, 1); STAGE(SA(0, 0), Ab, lda, brow, t + 2);
;       BAR; WAIT_L(0); MMA(1, 0, At, B0); BAR; SCHED;
.LBB0_770:
	ds_read_b128 v[172:175], v161
	ds_read_b128 v[176:179], v161 offset:1024
	ds_read_b128 v[180:183], v161 offset:2048
	ds_read_b128 v[184:187], v161 offset:3072
	v_add_u32_e32 v169, 0xc000, v148
	v_lshl_add_u64 v[236:237], v[136:137], 0, s[50:51]
	v_readfirstlane_b32 s53, v169
	v_add_u32_e32 v170, 0xe000, v148
	v_lshl_add_u64 v[162:163], v[236:237], 0, s[18:19]
	s_mov_b32 m0, s53
	v_lshl_add_u64 v[238:239], v[134:135], 0, s[50:51]
	v_readfirstlane_b32 s53, v170
	ds_read_b128 v[164:167], v152
	ds_read_b128 v[188:191], v152 offset:1024
	ds_read_b128 v[192:195], v151
	ds_read_b128 v[196:199], v151 offset:1024
	ds_read_b128 v[200:203], v150
	ds_read_b128 v[204:207], v150 offset:1024
	ds_read_b128 v[208:211], v149
	ds_read_b128 v[212:215], v149 offset:1024
	global_load_lds_dwordx4 v[162:163], off
	s_nop 1
	v_lshl_add_u64 v[162:163], v[238:239], 0, s[18:19]
	s_mov_b32 m0, s53
	s_nop 0
	global_load_lds_dwordx4 v[162:163], off
	s_waitcnt lgkmcnt(8)
	s_barrier
	s_waitcnt lgkmcnt(0)
	s_waitcnt lgkmcnt(0)
	v_mfma_f32_16x16x32_bf16 v[124:127], v[172:175], v[164:167], v[124:127]
	v_mfma_f32_16x16x32_bf16 v[120:123], v[180:183], v[164:167], v[120:123]
	v_mfma_f32_16x16x32_bf16 v[116:119], v[172:175], v[192:195], v[116:119]
	v_mfma_f32_16x16x32_bf16 v[112:115], v[180:183], v[192:195], v[112:115]
	v_mfma_f32_16x16x32_bf16 v[108:111], v[172:175], v[200:203], v[108:111]
	v_mfma_f32_16x16x32_bf16 v[104:107], v[180:183], v[200:203], v[104:107]
	v_mfma_f32_16x16x32_bf16 v[100:103], v[172:175], v[208:211], v[100:103]
	v_mfma_f32_16x16x32_bf16 v[96:99], v[180:183], v[208:211], v[96:99]
	v_mfma_f32_16x16x32_bf16 v[124:127], v[176:179], v[188:191], v[124:127]
	v_mfma_f32_16x16x32_bf16 v[120:123], v[184:187], v[188:191], v[120:123]
	v_mfma_f32_16x16x32_bf16 v[116:119], v[176:179], v[196:199], v[116:119]
	v_mfma_f32_16x16x32_bf16 v[112:115], v[184:187], v[196:199], v[112:115]
	v_mfma_f32_16x16x32_bf16 v[108:111], v[176:179], v[204:207], v[108:111]
	v_mfma_f32_16x16x32_bf16 v[104:107], v[184:187], v[204:207], v[104:107]
	v_mfma_f32_16x16x32_bf16 v[100:103], v[176:179], v[212:215], v[100:103]
	v_mfma_f32_16x16x32_bf16 v[96:99], v[184:187], v[212:215], v[96:99]
	s_barrier
	v_add_u32_e32 v162, s64, v153
	v_lshl_add_u64 v[240:241], v[140:141], 0, s[50:51]
	v_readfirstlane_b32 s53, v162
	v_add_u32_e32 v163, 0x2000, v162
	v_lshl_add_u64 v[232:233], v[240:241], 0, s[20:21]
	s_mov_b32 m0, s53
	v_lshl_add_u64 v[242:243], v[138:139], 0, s[50:51]
	v_readfirstlane_b32 s53, v163
	ds_read_b128 v[216:219], v160
	ds_read_b128 v[220:223], v160 offset:1024
	ds_read_b128 v[224:227], v160 offset:2048
	ds_read_b128 v[228:231], v160 offset:3072
	global_load_lds_dwordx4 v[232:233], off
	s_nop 1
	v_lshl_add_u64 v[232:233], v[242:243], 0, s[20:21]
	s_mov_b32 m0, s53
	s_nop 0
	global_load_lds_dwordx4 v[232:233], off
	s_barrier
	s_waitcnt lgkmcnt(0)
	s_waitcnt lgkmcnt(0)
	v_mfma_f32_16x16x32_bf16 v[92:95], v[216:219], v[164:167], v[92:95]
	v_mfma_f32_16x16x32_bf16 v[88:91], v[224:227], v[164:167], v[88:91]
	v_mfma_f32_16x16x32_bf16 v[84:87], v[216:219], v[192:195], v[84:87]
	v_mfma_f32_16x16x32_bf16 v[80:83], v[224:227], v[192:195], v[80:83]
	v_mfma_f32_16x16x32_bf16 v[76:79], v[216:219], v[200:203], v[76:79]
	v_mfma_f32_16x16x32_bf16 v[72:75], v[224:227], v[200:203], v[72:75]
	v_mfma_f32_16x16x32_bf16 v[68:71], v[216:219], v[208:211], v[68:71]
	v_mfma_f32_16x16x32_bf16 v[64:67], v[224:227], v[208:211], v[64:67]
	v_mfma_f32_16x16x32_bf16 v[92:95], v[220:223], v[188:191], v[92:95]
	v_mfma_f32_16x16x32_bf16 v[88:91], v[228:231], v[188:191], v[88:91]
	v_mfma_f32_16x16x32_bf16 v[84:87], v[220:223], v[196:199], v[84:87]
	v_mfma_f32_16x16x32_bf16 v[80:83], v[228:231], v[196:199], v[80:83]
	v_mfma_f32_16x16x32_bf16 v[76:79], v[220:223], v[204:207], v[76:79]
	v_mfma_f32_16x16x32_bf16 v[72:75], v[228:231], v[204:207], v[72:75]
	v_mfma_f32_16x16x32_bf16 v[68:71], v[220:223], v[212:215], v[68:71]
	v_mfma_f32_16x16x32_bf16 v[64:67], v[228:231], v[212:215], v[64:67]
	v_readfirstlane_b32 s53, v148
	v_lshl_add_u64 v[164:165], v[236:237], 0, s[22:23]
	s_mov_b32 m0, s53
	s_barrier
	ds_read_b128 v[188:191], v152 offset:16384
	ds_read_b128 v[192:195], v152 offset:17408
	ds_read_b128 v[196:199], v151 offset:16384
	ds_read_b128 v[200:203], v151 offset:17408
	ds_read_b128 v[204:207], v150 offset:16384
	ds_read_b128 v[208:211], v150 offset:17408
	ds_read_b128 v[212:215], v149 offset:16384
	ds_read_b128 v[232:235], v149 offset:17408
	global_load_lds_dwordx4 v[164:165], off
	s_nop 1
	v_add_u32_e32 v164, 0x2000, v148
	v_lshl_add_u64 v[166:167], v[238:239], 0, s[22:23]
	v_readfirstlane_b32 s53, v164
	s_mov_b32 m0, s53
	s_nop 0
	global_load_lds_dwordx4 v[166:167], off
	s_barrier
	s_waitcnt lgkmcnt(0)
	s_waitcnt lgkmcnt(0)
	v_mfma_f32_16x16x32_bf16 v[60:63], v[172:175], v[188:191], v[60:63]
	v_mfma_f32_16x16x32_bf16 v[56:59], v[180:183], v[188:191], v[56:59]
	v_mfma_f32_16x16x32_bf16 v[52:55], v[172:175], v[196:199], v[52:55]
	v_mfma_f32_16x16x32_bf16 v[48:51], v[180:183], v[196:199], v[48:51]
	v_mfma_f32_16x16x32_bf16 v[44:47], v[172:175], v[204:207], v[44:47]
	v_mfma_f32_16x16x32_bf16 v[40:43], v[180:183], v[204:207], v[40:43]
	v_mfma_f32_16x16x32_bf16 v[36:39], v[172:175], v[212:215], v[36:39]
	v_mfma_f32_16x16x32_bf16 v[32:35], v[180:183], v[212:215], v[32:35]
	v_mfma_f32_16x16x32_bf16 v[60:63], v[176:179], v[192:195], v[60:63]
	v_mfma_f32_16x16x32_bf16 v[56:59], v[184:187], v[192:195], v[56:59]
	v_mfma_f32_16x16x32_bf16 v[52:55], v[176:179], v[200:203], v[52:55]
	v_mfma_f32_16x16x32_bf16 v[48:51], v[184:187], v[200:203], v[48:51]
	v_mfma_f32_16x16x32_bf16 v[44:47], v[176:179], v[208:211], v[44:47]
	v_mfma_f32_16x16x32_bf16 v[40:43], v[184:187], v[208:211], v[40:43]
	v_mfma_f32_16x16x32_bf16 v[36:39], v[176:179], v[232:235], v[36:39]
	v_mfma_f32_16x16x32_bf16 v[32:35], v[184:187], v[232:235], v[32:35]
	s_barrier
; #define STAGE(P, BASE, LD, br, kt) do { const char* _g = (const char*)((BASE) + (size_t)(br) * (LD) + (size_t)(kt) * 64); \
;     for (int _i = 0; _i < 2; ++_i) { int _b = tidx * 16 + _i * 8192; int _r, _c; stage_rc(_b, _r, _c); \
;       __builtin_amdgcn_global_load_lds((const unsigned*)(_g + (unsigned)((_r * (LD) + _c) * 2)), (unsigned*)((char*)(P) + _b), 16, 0, 0); } } while (0)
; #define LDA(dst, b, h) for (int m = 0; m < 4; ++m) for (int k = 0; k < 2; ++k) \
;     dst[m][k] = *reinterpret_cast<const bf16x8*>((char*)SA(b, h) + lds_byte(wr * 64 + m * 16 + fr, k * 32 + fq * 8))
; #define LDB(dst, b, h) for (int n = 0; n < 2; ++n) for (int k = 0; k < 2; ++k) \
;     dst[n][k] = *reinterpret_cast<const bf16x8*>((char*)SB(b, h) + lds_byte(wc * 32 + n * 16 + fr, k * 32 + fq * 8))
; #define MMA(ai, bj, At_, Bt_) do { __builtin_amdgcn_s_setprio(1); \
;     for (int k = 0; k < 2; ++k) for (int m = 0; m < 4; ++m) for (int n = 0; n < 2; ++n) \
;       acc[ai][bj][m][n] = __builtin_amdgcn_mfma_f32_16x16x32_bf16(At_[m][k], Bt_[n][k], acc[ai][bj][m][n], 0, 0, 0); \
;     __builtin_amdgcn_s_setprio(0); } while (0)
; #define WAIT_V(n) asm volatile("s_waitcnt vmcnt(" #n ")" ::: "memory")
; #define WAIT_L(n) asm volatile("s_waitcnt lgkmcnt(" #n ")" ::: "memory")
; #define BAR __builtin_amdgcn_s_barrier()
; #define SCHED __builtin_amdgcn_sched_barrier(0)
; template <int EPI, int lda, int ldb, int N, int K>
; __device__ __forceinline__ void gemm_phase(const u16* __restrict__ A, const u16* __restrict__ Bt, const GemmEpi ep, int wv) {
;     ...
;       STAGE(SB(0, 1), Bt, ldb, bcol + HALF, t + 2);
;       WAIT_V(6); BAR; MMA(1, 1, At, B1); BAR;
;       LDB(B0, 1, 0); SCHED; LDA(At, 1, 0); STAGE(SA(0, 1), Ab, lda, brow + HALF, t + 2);
;       WAIT_L(8); BAR; WAIT_L(0); MMA(0, 0, At, B0); BAR; SCHED;
;       LDB(B1, 1, 1); STAGE(SB(1, 0), Bt, ldb, bcol, t + 3);
;       BAR; WAIT_L(0); MMA(0, 1, At, B1); BAR;
;       LDA(At, 1, 1); STAGE(SA(1, 0), Ab, lda, brow, t + 3);
	v_add_u32_e32 v165, s65, v153
	v_lshl_add_u64 v[166:167], v[240:241], 0, s[24:25]
	v_readfirstlane_b32 s53, v165
	s_mov_b32 m0, s53
	v_lshl_add_u64 v[172:173], v[242:243], 0, s[24:25]
	global_load_lds_dwordx4 v[166:167], off
	s_nop 1
	v_add_u32_e32 v166, 0x2000, v165
	s_nop 0
	v_readfirstlane_b32 s53, v166
	s_mov_b32 m0, s53
	s_nop 0
	global_load_lds_dwordx4 v[172:173], off
	s_waitcnt vmcnt(6)
	s_barrier
	v_mfma_f32_16x16x32_bf16 v[28:31], v[216:219], v[188:191], v[28:31]
	v_mfma_f32_16x16x32_bf16 v[24:27], v[224:227], v[188:191], v[24:27]
	v_mfma_f32_16x16x32_bf16 v[20:23], v[216:219], v[196:199], v[20:23]
	v_mfma_f32_16x16x32_bf16 v[16:19], v[224:227], v[196:199], v[16:19]
	v_mfma_f32_16x16x32_bf16 v[12:15], v[216:219], v[204:207], v[12:15]
	v_mfma_f32_16x16x32_bf16 v[8:11], v[224:227], v[204:207], v[8:11]
	v_mfma_f32_16x16x32_bf16 v[4:7], v[216:219], v[212:215], v[4:7]
	v_mfma_f32_16x16x32_bf16 v[0:3], v[224:227], v[212:215], v[0:3]
	v_mfma_f32_16x16x32_bf16 v[28:31], v[220:223], v[192:195], v[28:31]
	v_mfma_f32_16x16x32_bf16 v[24:27], v[228:231], v[192:195], v[24:27]
	v_mfma_f32_16x16x32_bf16 v[20:23], v[220:223], v[200:203], v[20:23]
	v_mfma_f32_16x16x32_bf16 v[16:19], v[228:231], v[200:203], v[16:19]
	v_mfma_f32_16x16x32_bf16 v[12:15], v[220:223], v[208:211], v[12:15]
	v_mfma_f32_16x16x32_bf16 v[8:11], v[228:231], v[208:211], v[8:11]
	v_mfma_f32_16x16x32_bf16 v[4:7], v[220:223], v[232:235], v[4:7]
	v_mfma_f32_16x16x32_bf16 v[0:3], v[228:231], v[232:235], v[0:3]
	s_barrier
	ds_read_b128 v[172:175], v156
	ds_read_b128 v[176:179], v156 offset:1024
	ds_read_b128 v[180:183], v156 offset:2048
	ds_read_b128 v[184:187], v156 offset:3072
	v_add_u32_e32 v167, 0x4000, v148
	v_add_u32_e32 v168, 0x6000, v148
	v_readfirstlane_b32 s53, v167
	v_lshl_add_u64 v[220:221], v[236:237], 0, s[26:27]
	s_mov_b32 m0, s53
	v_readfirstlane_b32 s53, v168
	ds_read_b128 v[188:191], v152 offset:32768
	ds_read_b128 v[192:195], v152 offset:33792
	ds_read_b128 v[196:199], v151 offset:32768
	ds_read_b128 v[200:203], v151 offset:33792
	ds_read_b128 v[204:207], v150 offset:32768
	ds_read_b128 v[208:211], v150 offset:33792
	ds_read_b128 v[212:215], v149 offset:32768
	ds_read_b128 v[216:219], v149 offset:33792
	global_load_lds_dwordx4 v[220:221], off
	s_nop 1
	v_lshl_add_u64 v[220:221], v[238:239], 0, s[26:27]
	s_mov_b32 m0, s53
	s_nop 0
	global_load_lds_dwordx4 v[220:221], off
	s_waitcnt lgkmcnt(8)
	s_barrier
	s_waitcnt lgkmcnt(0)
	s_waitcnt lgkmcnt(0)
	v_mfma_f32_16x16x32_bf16 v[124:127], v[172:175], v[188:191], v[124:127]
	v_mfma_f32_16x16x32_bf16 v[120:123], v[180:183], v[188:191], v[120:123]
	v_mfma_f32_16x16x32_bf16 v[116:119], v[172:175], v[196:199], v[116:119]
	v_mfma_f32_16x16x32_bf16 v[112:115], v[180:183], v[196:199], v[112:115]
	v_mfma_f32_16x16x32_bf16 v[108:111], v[172:175], v[204:207], v[108:111]
	v_mfma_f32_16x16x32_bf16 v[104:107], v[180:183], v[204:207], v[104:107]
	v_mfma_f32_16x16x32_bf16 v[100:103], v[172:175], v[212:215], v[100:103]
	v_mfma_f32_16x16x32_bf16 v[96:99], v[180:183], v[212:215], v[96:99]
	v_mfma_f32_16x16x32_bf16 v[124:127], v[176:179], v[192:195], v[124:127]
	v_mfma_f32_16x16x32_bf16 v[120:123], v[184:187], v[192:195], v[120:123]
	v_mfma_f32_16x16x32_bf16 v[116:119], v[176:179], v[200:203], v[116:119]
	v_mfma_f32_16x16x32_bf16 v[112:115], v[184:187], v[200:203], v[112:115]
	v_mfma_f32_16x16x32_bf16 v[108:111], v[176:179], v[208:211], v[108:111]
	v_mfma_f32_16x16x32_bf16 v[104:107], v[184:187], v[208:211], v[104:107]
	v_mfma_f32_16x16x32_bf16 v[100:103], v[176:179], v[216:219], v[100:103]
	v_mfma_f32_16x16x32_bf16 v[96:99], v[184:187], v[216:219], v[96:99]
	s_barrier
	v_readfirstlane_b32 s53, v155
	v_add_u32_e32 v171, 0x2000, v155
	v_lshl_add_u64 v[244:245], v[240:241], 0, s[40:41]
	s_mov_b32 m0, s53
	v_readfirstlane_b32 s53, v171
	ds_read_b128 v[220:223], v154
	ds_read_b128 v[224:227], v154 offset:1024
	ds_read_b128 v[228:231], v154 offset:2048
	ds_read_b128 v[232:235], v154 offset:3072
	global_load_lds_dwordx4 v[244:245], off
	s_nop 1
	v_lshl_add_u64 v[244:245], v[242:243], 0, s[40:41]
	s_mov_b32 m0, s53
	s_nop 0
	global_load_lds_dwordx4 v[244:245], off
	s_barrier
	s_waitcnt lgkmcnt(0)
	s_waitcnt lgkmcnt(0)
	v_mfma_f32_16x16x32_bf16 v[92:95], v[220:223], v[188:191], v[92:95]
	v_mfma_f32_16x16x32_bf16 v[88:91], v[228:231], v[188:191], v[88:91]
	v_mfma_f32_16x16x32_bf16 v[84:87], v[220:223], v[196:199], v[84:87]
	v_mfma_f32_16x16x32_bf16 v[80:83], v[228:231], v[196:199], v[80:83]
	v_mfma_f32_16x16x32_bf16 v[76:79], v[220:223], v[204:207], v[76:79]
	v_mfma_f32_16x16x32_bf16 v[72:75], v[228:231], v[204:207], v[72:75]
	v_mfma_f32_16x16x32_bf16 v[68:71], v[220:223], v[212:215], v[68:71]
	v_mfma_f32_16x16x32_bf16 v[64:67], v[228:231], v[212:215], v[64:67]
	v_mfma_f32_16x16x32_bf16 v[92:95], v[224:227], v[192:195], v[92:95]
	v_mfma_f32_16x16x32_bf16 v[88:91], v[232:235], v[192:195], v[88:91]
	v_mfma_f32_16x16x32_bf16 v[84:87], v[224:227], v[200:203], v[84:87]
	v_mfma_f32_16x16x32_bf16 v[80:83], v[232:235], v[200:203], v[80:83]
	v_mfma_f32_16x16x32_bf16 v[76:79], v[224:227], v[208:211], v[76:79]
	v_mfma_f32_16x16x32_bf16 v[72:75], v[232:235], v[208:211], v[72:75]
	v_mfma_f32_16x16x32_bf16 v[68:71], v[224:227], v[216:219], v[68:71]
	v_mfma_f32_16x16x32_bf16 v[64:67], v[232:235], v[216:219], v[64:67]
	v_readfirstlane_b32 s53, v157
	v_lshl_add_u64 v[236:237], v[236:237], 0, s[42:43]
	s_mov_b32 m0, s53
	v_readfirstlane_b32 s53, v158
	s_barrier
; #define STAGE(P, BASE, LD, br, kt) do { const char* _g = (const char*)((BASE) + (size_t)(br) * (LD) + (size_t)(kt) * 64); \
;     for (int _i = 0; _i < 2; ++_i) { int _b = tidx * 16 + _i * 8192; int _r, _c; stage_rc(_b, _r, _c); \
;       __builtin_amdgcn_global_load_lds((const unsigned*)(_g + (unsigned)((_r * (LD) + _c) * 2)), (unsigned*)((char*)(P) + _b), 16, 0, 0); } } while (0)
; #define LDA(dst, b, h) for (int m = 0; m < 4; ++m) for (int k = 0; k < 2; ++k) \
;     dst[m][k] = *reinterpret_cast<const bf16x8*>((char*)SA(b, h) + lds_byte(wr * 64 + m * 16 + fr, k * 32 + fq * 8))
; #define LDB(dst, b, h) for (int n = 0; n < 2; ++n) for (int k = 0; k < 2; ++k) \
;     dst[n][k] = *reinterpret_cast<const bf16x8*>((char*)SB(b, h) + lds_byte(wc * 32 + n * 16 + fr, k * 32 + fq * 8))
; #define MMA(ai, bj, At_, Bt_) do { __builtin_amdgcn_s_setprio(1); \
;     for (int k = 0; k < 2; ++k) for (int m = 0; m < 4; ++m) for (int n = 0; n < 2; ++n) \
;       acc[ai][bj][m][n] = __builtin_amdgcn_mfma_f32_16x16x32_bf16(At_[m][k], Bt_[n][k], acc[ai][bj][m][n], 0, 0, 0); \
;     __builtin_amdgcn_s_setprio(0); } while (0)
; #define WAIT_V(n) asm volatile("s_waitcnt vmcnt(" #n ")" ::: "memory")
; #define WAIT_L(n) asm volatile("s_waitcnt lgkmcnt(" #n ")" ::: "memory")
; #define BAR __builtin_amdgcn_s_barrier()
; #define SCHED __builtin_amdgcn_sched_barrier(0)
; template <int EPI, int lda, int ldb, int N, int K>
; __device__ __forceinline__ void gemm_phase(const u16* __restrict__ A, const u16* __restrict__ Bt, const GemmEpi ep, int wv) {
;     ...
;       LDA(At, 1, 1); STAGE(SA(1, 0), Ab, lda, brow, t + 3);
;       BAR; WAIT_L(0); MMA(1, 0, At, B0); BAR; SCHED;
;       STAGE(SB(1, 1), Bt, ldb, bcol + HALF, t + 3);
;       WAIT_V(6); BAR; MMA(1, 1, At, B1); BAR;
;     }
;     { LDB(B0, 0, 0); LDA(At, 0, 0); STAGE(SA(1, 1), Ab, lda, brow + HALF, nt - 1);
;       BAR; WAIT_L(0); MMA(0, 0, At, B0); BAR;
;       LDB(B1, 0, 1); BAR; WAIT_L(0); MMA(0, 1, At, B1); BAR;
	ds_read_b128 v[188:191], v152 offset:49152
	ds_read_b128 v[192:195], v152 offset:50176
	ds_read_b128 v[196:199], v151 offset:49152
	ds_read_b128 v[200:203], v151 offset:50176
	ds_read_b128 v[204:207], v150 offset:49152
	ds_read_b128 v[208:211], v150 offset:50176
	ds_read_b128 v[212:215], v149 offset:49152
	ds_read_b128 v[216:219], v149 offset:50176
	global_load_lds_dwordx4 v[236:237], off
	s_nop 1
	v_lshl_add_u64 v[236:237], v[238:239], 0, s[42:43]
	s_mov_b32 m0, s53
	s_nop 0
	global_load_lds_dwordx4 v[236:237], off
	s_barrier
	s_waitcnt lgkmcnt(0)
	s_waitcnt lgkmcnt(0)
	v_mfma_f32_16x16x32_bf16 v[60:63], v[172:175], v[188:191], v[60:63]
	v_mfma_f32_16x16x32_bf16 v[56:59], v[180:183], v[188:191], v[56:59]
	v_mfma_f32_16x16x32_bf16 v[52:55], v[172:175], v[196:199], v[52:55]
	v_mfma_f32_16x16x32_bf16 v[48:51], v[180:183], v[196:199], v[48:51]
	v_mfma_f32_16x16x32_bf16 v[44:47], v[172:175], v[204:207], v[44:47]
	v_mfma_f32_16x16x32_bf16 v[40:43], v[180:183], v[204:207], v[40:43]
	v_mfma_f32_16x16x32_bf16 v[36:39], v[172:175], v[212:215], v[36:39]
	v_mfma_f32_16x16x32_bf16 v[32:35], v[180:183], v[212:215], v[32:35]
	v_mfma_f32_16x16x32_bf16 v[60:63], v[176:179], v[192:195], v[60:63]
	v_mfma_f32_16x16x32_bf16 v[56:59], v[184:187], v[192:195], v[56:59]
	v_mfma_f32_16x16x32_bf16 v[52:55], v[176:179], v[200:203], v[52:55]
	v_mfma_f32_16x16x32_bf16 v[48:51], v[184:187], v[200:203], v[48:51]
	v_mfma_f32_16x16x32_bf16 v[44:47], v[176:179], v[208:211], v[44:47]
	v_mfma_f32_16x16x32_bf16 v[40:43], v[184:187], v[208:211], v[40:43]
	v_mfma_f32_16x16x32_bf16 v[36:39], v[176:179], v[216:219], v[36:39]
	v_mfma_f32_16x16x32_bf16 v[32:35], v[184:187], v[216:219], v[32:35]
	s_barrier
	v_readfirstlane_b32 s53, v159
	v_add_u32_e32 v171, 0x2000, v159
	v_lshl_add_u64 v[172:173], v[240:241], 0, s[44:45]
	s_mov_b32 m0, s53
	v_readfirstlane_b32 s53, v171
	global_load_lds_dwordx4 v[172:173], off
	s_nop 1
	v_lshl_add_u64 v[172:173], v[242:243], 0, s[44:45]
	s_mov_b32 m0, s53
	s_nop 0
	global_load_lds_dwordx4 v[172:173], off
	s_waitcnt vmcnt(6)
	s_barrier
	v_mfma_f32_16x16x32_bf16 v[28:31], v[220:223], v[188:191], v[28:31]
	v_mfma_f32_16x16x32_bf16 v[24:27], v[228:231], v[188:191], v[24:27]
	v_mfma_f32_16x16x32_bf16 v[20:23], v[220:223], v[196:199], v[20:23]
	v_mfma_f32_16x16x32_bf16 v[16:19], v[228:231], v[196:199], v[16:19]
	v_mfma_f32_16x16x32_bf16 v[12:15], v[220:223], v[204:207], v[12:15]
	v_mfma_f32_16x16x32_bf16 v[8:11], v[228:231], v[204:207], v[8:11]
	v_mfma_f32_16x16x32_bf16 v[4:7], v[220:223], v[212:215], v[4:7]
	v_mfma_f32_16x16x32_bf16 v[0:3], v[228:231], v[212:215], v[0:3]
	v_mfma_f32_16x16x32_bf16 v[28:31], v[224:227], v[192:195], v[28:31]
	v_mfma_f32_16x16x32_bf16 v[24:27], v[232:235], v[192:195], v[24:27]
	v_mfma_f32_16x16x32_bf16 v[20:23], v[224:227], v[200:203], v[20:23]
	v_mfma_f32_16x16x32_bf16 v[16:19], v[232:235], v[200:203], v[16:19]
	v_mfma_f32_16x16x32_bf16 v[12:15], v[224:227], v[208:211], v[12:15]
	v_mfma_f32_16x16x32_bf16 v[8:11], v[232:235], v[208:211], v[8:11]
	v_mfma_f32_16x16x32_bf16 v[4:7], v[224:227], v[216:219], v[4:7]
	v_mfma_f32_16x16x32_bf16 v[0:3], v[232:235], v[216:219], v[0:3]
	s_add_i32 s52, s52, 2
	s_add_u32 s50, s50, 0x100
	s_addc_u32 s51, s51, 0
	s_cmp_gt_u32 s52, 27
	s_barrier
	s_cbranch_scc0 .LBB0_770
	s_add_i32 s50, s48, 0x80
	s_mul_hi_i32 s51, s50, 0x1080
	s_mulk_i32 s50, 0x1080
	s_add_u32 s50, s61, s50
	s_addc_u32 s51, s62, s51
	v_lshl_add_u64 v[158:159], s[50:51], 0, v[128:129]
	v_readfirstlane_b32 s52, v169
	v_lshl_add_u64 v[158:159], v[158:159], 0, s[46:47]
	s_mov_b32 m0, s52
	ds_read_b128 v[134:137], v161
	ds_read_b128 v[138:141], v161 offset:1024
	ds_read_b128 v[172:175], v161 offset:2048
	ds_read_b128 v[176:179], v161 offset:3072
	ds_read_b128 v[180:183], v152
	ds_read_b128 v[184:187], v152 offset:1024
	ds_read_b128 v[188:191], v151
	ds_read_b128 v[192:195], v151 offset:1024
	ds_read_b128 v[196:199], v150
	ds_read_b128 v[200:203], v150 offset:1024
	ds_read_b128 v[204:207], v149
	ds_read_b128 v[208:211], v149 offset:1024
	global_load_lds_dwordx4 v[158:159], off
	v_lshl_add_u64 v[158:159], s[50:51], 0, v[132:133]
	v_readfirstlane_b32 s50, v170
	v_lshl_add_u64 v[158:159], v[158:159], 0, s[46:47]
	s_mov_b32 m0, s50
	s_nop 0
	global_load_lds_dwordx4 v[158:159], off
	s_barrier
	s_waitcnt lgkmcnt(0)
	s_waitcnt lgkmcnt(0)
	v_mfma_f32_16x16x32_bf16 v[124:127], v[134:137], v[180:183], v[124:127]
	v_mfma_f32_16x16x32_bf16 v[120:123], v[172:175], v[180:183], v[120:123]
	v_mfma_f32_16x16x32_bf16 v[116:119], v[134:137], v[188:191], v[116:119]
	v_mfma_f32_16x16x32_bf16 v[112:115], v[172:175], v[188:191], v[112:115]
	v_mfma_f32_16x16x32_bf16 v[108:111], v[134:137], v[196:199], v[108:111]
	v_mfma_f32_16x16x32_bf16 v[104:107], v[172:175], v[196:199], v[104:107]
	v_mfma_f32_16x16x32_bf16 v[100:103], v[134:137], v[204:207], v[100:103]
	v_mfma_f32_16x16x32_bf16 v[96:99], v[172:175], v[204:207], v[96:99]
	v_mfma_f32_16x16x32_bf16 v[124:127], v[138:141], v[184:187], v[124:127]
	v_mfma_f32_16x16x32_bf16 v[120:123], v[176:179], v[184:187], v[120:123]
	v_mfma_f32_16x16x32_bf16 v[116:119], v[138:141], v[192:195], v[116:119]
	v_mfma_f32_16x16x32_bf16 v[112:115], v[176:179], v[192:195], v[112:115]
	v_mfma_f32_16x16x32_bf16 v[108:111], v[138:141], v[200:203], v[108:111]
	v_mfma_f32_16x16x32_bf16 v[104:107], v[176:179], v[200:203], v[104:107]
	v_mfma_f32_16x16x32_bf16 v[100:103], v[138:141], v[208:211], v[100:103]
	v_mfma_f32_16x16x32_bf16 v[96:99], v[176:179], v[208:211], v[96:99]
	s_barrier
	ds_read_b128 v[212:215], v160
	ds_read_b128 v[216:219], v160 offset:1024
	ds_read_b128 v[220:223], v160 offset:2048
	ds_read_b128 v[158:161], v160 offset:3072
	s_barrier
; #define LDA(dst, b, h) for (int m = 0; m < 4; ++m) for (int k = 0; k < 2; ++k) \
;     dst[m][k] = *reinterpret_cast<const bf16x8*>((char*)SA(b, h) + lds_byte(wr * 64 + m * 16 + fr, k * 32 + fq * 8))
; #define LDB(dst, b, h) for (int n = 0; n < 2; ++n) for (int k = 0; k < 2; ++k) \
;     dst[n][k] = *reinterpret_cast<const bf16x8*>((char*)SB(b, h) + lds_byte(wc * 32 + n * 16 + fr, k * 32 + fq * 8))
; #define MMA(ai, bj, At_, Bt_) do { __builtin_amdgcn_s_setprio(1); \
;     for (int k = 0; k < 2; ++k) for (int m = 0; m < 4; ++m) for (int n = 0; n < 2; ++n) \
;       acc[ai][bj][m][n] = __builtin_amdgcn_mfma_f32_16x16x32_bf16(At_[m][k], Bt_[n][k], acc[ai][bj][m][n], 0, 0, 0); \
;     __builtin_amdgcn_s_setprio(0); } while (0)
; #define WAIT_V(n) asm volatile("s_waitcnt vmcnt(" #n ")" ::: "memory")
; #define WAIT_L(n) asm volatile("s_waitcnt lgkmcnt(" #n ")" ::: "memory")
; #define BAR __builtin_amdgcn_s_barrier()
; template <int EPI, int lda, int ldb, int N, int K>
; __device__ __forceinline__ void gemm_phase(const u16* __restrict__ A, const u16* __restrict__ Bt, const GemmEpi ep, int wv) {
;     ...
;       LDB(B1, 0, 1); BAR; WAIT_L(0); MMA(0, 1, At, B1); BAR;
;       LDA(At, 0, 1); WAIT_V(4); BAR; WAIT_L(0); MMA(1, 0, At, B0); MMA(1, 1, At, B1); BAR; }
;     { LDB(B0, 1, 0); LDA(At, 1, 0); WAIT_V(2); BAR; WAIT_L(0); MMA(0, 0, At, B0); BAR;
	s_waitcnt lgkmcnt(0)
	s_waitcnt lgkmcnt(0)
	v_mfma_f32_16x16x32_bf16 v[92:95], v[212:215], v[180:183], v[92:95]
	v_mfma_f32_16x16x32_bf16 v[88:91], v[220:223], v[180:183], v[88:91]
	v_mfma_f32_16x16x32_bf16 v[76:79], v[212:215], v[196:199], v[76:79]
	v_mfma_f32_16x16x32_bf16 v[72:75], v[220:223], v[196:199], v[72:75]
	v_mfma_f32_16x16x32_bf16 v[84:87], v[212:215], v[188:191], v[84:87]
	v_mfma_f32_16x16x32_bf16 v[80:83], v[220:223], v[188:191], v[80:83]
	v_mfma_f32_16x16x32_bf16 v[68:71], v[212:215], v[204:207], v[68:71]
	v_mfma_f32_16x16x32_bf16 v[64:67], v[220:223], v[204:207], v[64:67]
	v_mfma_f32_16x16x32_bf16 v[92:95], v[216:219], v[184:187], v[92:95]
	v_mfma_f32_16x16x32_bf16 v[88:91], v[158:161], v[184:187], v[88:91]
	v_mfma_f32_16x16x32_bf16 v[76:79], v[216:219], v[200:203], v[76:79]
	v_mfma_f32_16x16x32_bf16 v[72:75], v[158:161], v[200:203], v[72:75]
	v_mfma_f32_16x16x32_bf16 v[180:183], v[216:219], v[192:195], v[84:87]
	v_mfma_f32_16x16x32_bf16 v[184:187], v[158:161], v[192:195], v[80:83]
	v_mfma_f32_16x16x32_bf16 v[188:191], v[216:219], v[208:211], v[68:71]
	v_mfma_f32_16x16x32_bf16 v[192:195], v[158:161], v[208:211], v[64:67]
	s_barrier
	s_nop 0
	ds_read_b128 v[64:67], v152 offset:16384
	ds_read_b128 v[68:71], v152 offset:17408
	ds_read_b128 v[80:83], v151 offset:16384
	ds_read_b128 v[84:87], v151 offset:17408
	ds_read_b128 v[196:199], v150 offset:16384
	ds_read_b128 v[200:203], v150 offset:17408
	ds_read_b128 v[204:207], v149 offset:16384
	ds_read_b128 v[208:211], v149 offset:17408
	s_waitcnt vmcnt(4)
	s_barrier
	s_waitcnt lgkmcnt(0)
	s_waitcnt lgkmcnt(0)
	v_mfma_f32_16x16x32_bf16 v[60:63], v[134:137], v[64:67], v[60:63]
	v_mfma_f32_16x16x32_bf16 v[56:59], v[172:175], v[64:67], v[56:59]
	v_mfma_f32_16x16x32_bf16 v[52:55], v[134:137], v[80:83], v[52:55]
	v_mfma_f32_16x16x32_bf16 v[48:51], v[172:175], v[80:83], v[48:51]
	v_mfma_f32_16x16x32_bf16 v[44:47], v[134:137], v[196:199], v[44:47]
	v_mfma_f32_16x16x32_bf16 v[40:43], v[172:175], v[196:199], v[40:43]
	v_mfma_f32_16x16x32_bf16 v[36:39], v[134:137], v[204:207], v[36:39]
	v_mfma_f32_16x16x32_bf16 v[32:35], v[172:175], v[204:207], v[32:35]
	v_mfma_f32_16x16x32_bf16 v[60:63], v[138:141], v[68:71], v[60:63]
	v_mfma_f32_16x16x32_bf16 v[56:59], v[176:179], v[68:71], v[56:59]
	v_mfma_f32_16x16x32_bf16 v[52:55], v[138:141], v[84:87], v[52:55]
	v_mfma_f32_16x16x32_bf16 v[48:51], v[176:179], v[84:87], v[48:51]
	v_mfma_f32_16x16x32_bf16 v[44:47], v[138:141], v[200:203], v[44:47]
	v_mfma_f32_16x16x32_bf16 v[40:43], v[176:179], v[200:203], v[40:43]
	v_mfma_f32_16x16x32_bf16 v[36:39], v[138:141], v[208:211], v[36:39]
	v_mfma_f32_16x16x32_bf16 v[32:35], v[176:179], v[208:211], v[32:35]
	v_mfma_f32_16x16x32_bf16 v[28:31], v[212:215], v[64:67], v[28:31]
	v_mfma_f32_16x16x32_bf16 v[24:27], v[220:223], v[64:67], v[24:27]
	v_mfma_f32_16x16x32_bf16 v[12:15], v[212:215], v[196:199], v[12:15]
	v_mfma_f32_16x16x32_bf16 v[8:11], v[220:223], v[196:199], v[8:11]
	v_mfma_f32_16x16x32_bf16 v[20:23], v[212:215], v[80:83], v[20:23]
	v_mfma_f32_16x16x32_bf16 v[16:19], v[220:223], v[80:83], v[16:19]
	v_mfma_f32_16x16x32_bf16 v[4:7], v[212:215], v[204:207], v[4:7]
	v_mfma_f32_16x16x32_bf16 v[0:3], v[220:223], v[204:207], v[0:3]
	v_mfma_f32_16x16x32_bf16 v[28:31], v[216:219], v[68:71], v[28:31]
	v_mfma_f32_16x16x32_bf16 v[24:27], v[158:161], v[68:71], v[24:27]
	v_mfma_f32_16x16x32_bf16 v[12:15], v[216:219], v[200:203], v[12:15]
	v_mfma_f32_16x16x32_bf16 v[8:11], v[158:161], v[200:203], v[8:11]
	v_mfma_f32_16x16x32_bf16 v[134:137], v[216:219], v[84:87], v[20:23]
	v_mfma_f32_16x16x32_bf16 v[138:141], v[158:161], v[84:87], v[16:19]
	v_mfma_f32_16x16x32_bf16 v[170:173], v[216:219], v[208:211], v[4:7]
	v_mfma_f32_16x16x32_bf16 v[158:161], v[158:161], v[208:211], v[0:3]
	s_barrier
	s_nop 0
	ds_read_b128 v[0:3], v156
	ds_read_b128 v[4:7], v156 offset:1024
	ds_read_b128 v[16:19], v156 offset:2048
	ds_read_b128 v[174:177], v156 offset:3072
	ds_read_b128 v[20:23], v152 offset:32768
	ds_read_b128 v[196:199], v152 offset:33792
	ds_read_b128 v[200:203], v151 offset:32768
	ds_read_b128 v[204:207], v151 offset:33792
	ds_read_b128 v[208:211], v150 offset:32768
	ds_read_b128 v[212:215], v150 offset:33792
	ds_read_b128 v[216:219], v149 offset:32768
	ds_read_b128 v[220:223], v149 offset:33792
	s_waitcnt vmcnt(2)
	s_barrier
; #define LDA(dst, b, h) for (int m = 0; m < 4; ++m) for (int k = 0; k < 2; ++k) \
;     dst[m][k] = *reinterpret_cast<const bf16x8*>((char*)SA(b, h) + lds_byte(wr * 64 + m * 16 + fr, k * 32 + fq * 8))
; #define LDB(dst, b, h) for (int n = 0; n < 2; ++n) for (int k = 0; k < 2; ++k) \
;     dst[n][k] = *reinterpret_cast<const bf16x8*>((char*)SB(b, h) + lds_byte(wc * 32 + n * 16 + fr, k * 32 + fq * 8))
; #define MMA(ai, bj, At_, Bt_) do { __builtin_amdgcn_s_setprio(1); \
;     for (int k = 0; k < 2; ++k) for (int m = 0; m < 4; ++m) for (int n = 0; n < 2; ++n) \
;       acc[ai][bj][m][n] = __builtin_amdgcn_mfma_f32_16x16x32_bf16(At_[m][k], Bt_[n][k], acc[ai][bj][m][n], 0, 0, 0); \
;     __builtin_amdgcn_s_setprio(0); } while (0)
; #define WAIT_V(n) asm volatile("s_waitcnt vmcnt(" #n ")" ::: "memory")
; #define WAIT_L(n) asm volatile("s_waitcnt lgkmcnt(" #n ")" ::: "memory")
; #define BAR __builtin_amdgcn_s_barrier()
; template <int EPI, int lda, int ldb, int N, int K>
; __device__ __forceinline__ void gemm_phase(const u16* __restrict__ A, const u16* __restrict__ Bt, const GemmEpi ep, int wv) {
;     ...
;     { LDB(B0, 1, 0); LDA(At, 1, 0); WAIT_V(2); BAR; WAIT_L(0); MMA(0, 0, At, B0); BAR;
;       LDB(B1, 1, 1); WAIT_V(0); BAR; WAIT_L(0); MMA(0, 1, At, B1); BAR;
;       LDA(At, 1, 1); BAR; WAIT_L(0); MMA(1, 0, At, B0); MMA(1, 1, At, B1); BAR; }
;     if (wr == 0) BAR;
	s_waitcnt lgkmcnt(0)
	s_waitcnt lgkmcnt(0)
	v_mfma_f32_16x16x32_bf16 v[64:67], v[0:3], v[20:23], v[124:127]
	v_mfma_f32_16x16x32_bf16 v[68:71], v[16:19], v[20:23], v[120:123]
	v_mfma_f32_16x16x32_bf16 v[80:83], v[0:3], v[200:203], v[116:119]
	v_mfma_f32_16x16x32_bf16 v[84:87], v[16:19], v[200:203], v[112:115]
	v_mfma_f32_16x16x32_bf16 v[108:111], v[0:3], v[208:211], v[108:111]
	v_mfma_f32_16x16x32_bf16 v[104:107], v[16:19], v[208:211], v[104:107]
	v_mfma_f32_16x16x32_bf16 v[120:123], v[0:3], v[216:219], v[100:103]
	v_mfma_f32_16x16x32_bf16 v[124:127], v[16:19], v[216:219], v[96:99]
	v_mfma_f32_16x16x32_bf16 v[116:119], v[4:7], v[196:199], v[64:67]
	v_mfma_f32_16x16x32_bf16 v[112:115], v[174:177], v[196:199], v[68:71]
	v_mfma_f32_16x16x32_bf16 v[100:103], v[4:7], v[204:207], v[80:83]
	v_mfma_f32_16x16x32_bf16 v[96:99], v[174:177], v[204:207], v[84:87]
	v_mfma_f32_16x16x32_bf16 v[84:87], v[4:7], v[212:215], v[108:111]
	v_mfma_f32_16x16x32_bf16 v[80:83], v[174:177], v[212:215], v[104:107]
	v_mfma_f32_16x16x32_bf16 v[68:71], v[4:7], v[220:223], v[120:123]
	v_mfma_f32_16x16x32_bf16 v[64:67], v[174:177], v[220:223], v[124:127]
	s_barrier
	ds_read_b128 v[224:227], v154
	ds_read_b128 v[228:231], v154 offset:1024
	ds_read_b128 v[232:235], v154 offset:2048
	ds_read_b128 v[154:157], v154 offset:3072
	s_waitcnt vmcnt(0)
	s_barrier
	s_waitcnt lgkmcnt(0)
	s_waitcnt lgkmcnt(0)
	v_mfma_f32_16x16x32_bf16 v[92:95], v[224:227], v[20:23], v[92:95]
	v_mfma_f32_16x16x32_bf16 v[20:23], v[232:235], v[20:23], v[88:91]
	v_mfma_f32_16x16x32_bf16 v[88:91], v[224:227], v[200:203], v[180:183]
	v_mfma_f32_16x16x32_bf16 v[104:107], v[232:235], v[200:203], v[184:187]
	v_mfma_f32_16x16x32_bf16 v[76:79], v[224:227], v[208:211], v[76:79]
	v_mfma_f32_16x16x32_bf16 v[72:75], v[232:235], v[208:211], v[72:75]
	v_mfma_f32_16x16x32_bf16 v[178:181], v[224:227], v[216:219], v[188:191]
	v_mfma_f32_16x16x32_bf16 v[182:185], v[232:235], v[216:219], v[192:195]
	v_mfma_f32_16x16x32_bf16 v[124:127], v[228:231], v[196:199], v[92:95]
	v_mfma_f32_16x16x32_bf16 v[120:123], v[154:157], v[196:199], v[20:23]
	v_mfma_f32_16x16x32_bf16 v[108:111], v[228:231], v[204:207], v[88:91]
	v_mfma_f32_16x16x32_bf16 v[104:107], v[154:157], v[204:207], v[104:107]
	v_mfma_f32_16x16x32_bf16 v[92:95], v[228:231], v[212:215], v[76:79]
	v_mfma_f32_16x16x32_bf16 v[88:91], v[154:157], v[212:215], v[72:75]
	v_mfma_f32_16x16x32_bf16 v[76:79], v[228:231], v[220:223], v[178:181]
	v_mfma_f32_16x16x32_bf16 v[72:75], v[154:157], v[220:223], v[182:185]
	s_barrier
	ds_read_b128 v[178:181], v152 offset:49152
	ds_read_b128 v[182:185], v152 offset:50176
	ds_read_b128 v[186:189], v151 offset:49152
	ds_read_b128 v[190:193], v151 offset:50176
	ds_read_b128 v[194:197], v150 offset:49152
	ds_read_b128 v[150:153], v150 offset:50176
	ds_read_b128 v[198:201], v149 offset:49152
	ds_read_b128 v[202:205], v149 offset:50176
	s_barrier
	s_waitcnt lgkmcnt(0)
	s_waitcnt lgkmcnt(0)
	v_mfma_f32_16x16x32_bf16 v[20:23], v[0:3], v[178:181], v[60:63]
	v_mfma_f32_16x16x32_bf16 v[56:59], v[16:19], v[178:181], v[56:59]
	v_mfma_f32_16x16x32_bf16 v[60:63], v[0:3], v[186:189], v[52:55]
	v_mfma_f32_16x16x32_bf16 v[206:209], v[16:19], v[186:189], v[48:51]
	v_mfma_f32_16x16x32_bf16 v[44:47], v[0:3], v[194:197], v[44:47]
	v_mfma_f32_16x16x32_bf16 v[40:43], v[16:19], v[194:197], v[40:43]
	v_mfma_f32_16x16x32_bf16 v[0:3], v[0:3], v[198:201], v[36:39]
	v_mfma_f32_16x16x32_bf16 v[210:213], v[16:19], v[198:201], v[32:35]
	v_mfma_f32_16x16x32_bf16 v[52:55], v[4:7], v[182:185], v[20:23]
	v_mfma_f32_16x16x32_bf16 v[48:51], v[174:177], v[182:185], v[56:59]
	v_mfma_f32_16x16x32_bf16 v[36:39], v[4:7], v[190:193], v[60:63]
	v_mfma_f32_16x16x32_bf16 v[32:35], v[174:177], v[190:193], v[206:209]
	v_mfma_f32_16x16x32_bf16 v[20:23], v[4:7], v[150:153], v[44:47]
	v_mfma_f32_16x16x32_bf16 v[16:19], v[174:177], v[150:153], v[40:43]
	v_mfma_f32_16x16x32_bf16 v[4:7], v[4:7], v[202:205], v[0:3]
	v_mfma_f32_16x16x32_bf16 v[0:3], v[174:177], v[202:205], v[210:213]
	v_mfma_f32_16x16x32_bf16 v[28:31], v[224:227], v[178:181], v[28:31]
	v_mfma_f32_16x16x32_bf16 v[24:27], v[232:235], v[178:181], v[24:27]
	v_mfma_f32_16x16x32_bf16 v[40:43], v[224:227], v[186:189], v[134:137]
	v_mfma_f32_16x16x32_bf16 v[134:137], v[232:235], v[186:189], v[138:141]
	v_mfma_f32_16x16x32_bf16 v[12:15], v[224:227], v[194:197], v[12:15]
	v_mfma_f32_16x16x32_bf16 v[8:11], v[232:235], v[194:197], v[8:11]
	v_mfma_f32_16x16x32_bf16 v[138:141], v[224:227], v[198:201], v[170:173]
	v_mfma_f32_16x16x32_bf16 v[158:161], v[232:235], v[198:201], v[158:161]
	v_mfma_f32_16x16x32_bf16 v[60:63], v[228:231], v[182:185], v[28:31]
	v_mfma_f32_16x16x32_bf16 v[56:59], v[154:157], v[182:185], v[24:27]
	v_mfma_f32_16x16x32_bf16 v[44:47], v[228:231], v[190:193], v[40:43]
	v_mfma_f32_16x16x32_bf16 v[40:43], v[154:157], v[190:193], v[134:137]
	v_mfma_f32_16x16x32_bf16 v[28:31], v[228:231], v[150:153], v[12:15]
	v_mfma_f32_16x16x32_bf16 v[24:27], v[154:157], v[150:153], v[8:11]
	v_mfma_f32_16x16x32_bf16 v[12:15], v[228:231], v[202:205], v[138:141]
	v_mfma_f32_16x16x32_bf16 v[8:11], v[154:157], v[202:205], v[158:161]
	v_cmp_gt_u32_e32 vcc, s66, v130
	s_barrier
	s_and_saveexec_b64 s[50:51], vcc
	s_cbranch_execz .LBB0_773
	s_barrier

; #define STAGE(P, BASE, LD, br, kt) do { const char* _g = (const char*)((BASE) + (size_t)(br) * (LD) + (size_t)(kt) * 64); \
;     for (int _i = 0; _i < 2; ++_i) { int _b = tidx * 16 + _i * 8192; int _r, _c; stage_rc(_b, _r, _c); \
;       __builtin_amdgcn_global_load_lds((const unsigned*)(_g + (unsigned)((_r * (LD) + _c) * 2)), (unsigned*)((char*)(P) + _b), 16, 0, 0); } } while (0)
; #define LDA(dst, b, h) for (int m = 0; m < 4; ++m) for (int k = 0; k < 2; ++k) \
;     dst[m][k] = *reinterpret_cast<const bf16x8*>((char*)SA(b, h) + lds_byte(wr * 64 + m * 16 + fr, k * 32 + fq * 8))
; #define LDB(dst, b, h) for (int n = 0; n < 2; ++n) for (int k = 0; k < 2; ++k) \
;     dst[n][k] = *reinterpret_cast<const bf16x8*>((char*)SB(b, h) + lds_byte(wc * 32 + n * 16 + fr, k * 32 + fq * 8))
; #define MMA(ai, bj, At_, Bt_) do { __builtin_amdgcn_s_setprio(1); \
;     for (int k = 0; k < 2; ++k) for (int m = 0; m < 4; ++m) for (int n = 0; n < 2; ++n) \
;       acc[ai][bj][m][n] = __builtin_amdgcn_mfma_f32_16x16x32_bf16(At_[m][k], Bt_[n][k], acc[ai][bj][m][n], 0, 0, 0); \
;     __builtin_amdgcn_s_setprio(0); } while (0)
; #define WAIT_L(n) asm volatile("s_waitcnt lgkmcnt(" #n ")" ::: "memory")
; #define BAR __builtin_amdgcn_s_barrier()
; #define SCHED __builtin_amdgcn_sched_barrier(0)
; template <int EPI, int lda, int ldb, int N, int K>
; __device__ __forceinline__ void gemm_phase(const u16* __restrict__ A, const u16* __restrict__ Bt, const GemmEpi ep, int wv) {
;     ...
;     for (int t = 0; t < nt - 2; t += 2) {
;       LDB(B0, 0, 0); SCHED; LDA(At, 0, 0); STAGE(SA(1, 1), Ab, lda, brow + HALF, t + 1);
;       WAIT_L(8); BAR; WAIT_L(0); MMA(0, 0, At, B0); BAR; SCHED;
;       LDB(B1, 0, 1); STAGE(SB(0, 0), Bt, ldb, bcol, t + 2);
;       BAR; WAIT_L(0); MMA(0, 1, At, B1); BAR;
;       LDA(At, 0, 1); STAGE(SA(0, 0), Ab, lda, brow, t + 2);
;       BAR; WAIT_L(0); MMA(1, 0, At, B0); BAR; SCHED;
.LBB0_838:
	ds_read_b128 v[168:171], v164
	ds_read_b128 v[174:177], v164 offset:1024
	ds_read_b128 v[178:181], v164 offset:2048
	ds_read_b128 v[182:185], v164 offset:3072
	v_add_u32_e32 v172, 0xc000, v147
	v_lshl_add_u64 v[238:239], v[136:137], 0, s[50:51]
	v_readfirstlane_b32 s73, v172
	v_add_u32_e32 v173, 0xe000, v147
	v_lshl_add_u64 v[166:167], v[238:239], 0, s[22:23]
	s_mov_b32 m0, s73
	v_lshl_add_u64 v[240:241], v[134:135], 0, s[50:51]
	v_readfirstlane_b32 s73, v173
	ds_read_b128 v[186:189], v155
	ds_read_b128 v[190:193], v155 offset:1024
	ds_read_b128 v[194:197], v154
	ds_read_b128 v[198:201], v154 offset:1024
	ds_read_b128 v[202:205], v153
	ds_read_b128 v[206:209], v153 offset:1024
	ds_read_b128 v[210:213], v152
	ds_read_b128 v[214:217], v152 offset:1024
	global_load_lds_dwordx4 v[166:167], off
	s_nop 1
	v_lshl_add_u64 v[166:167], v[240:241], 0, s[22:23]
	s_mov_b32 m0, s73
	s_nop 0
	global_load_lds_dwordx4 v[166:167], off
	s_waitcnt lgkmcnt(8)
	s_barrier
	s_waitcnt lgkmcnt(0)
	s_waitcnt lgkmcnt(0)
	v_mfma_f32_16x16x32_bf16 v[124:127], v[168:171], v[186:189], v[124:127]
	v_mfma_f32_16x16x32_bf16 v[120:123], v[178:181], v[186:189], v[120:123]
	v_mfma_f32_16x16x32_bf16 v[116:119], v[168:171], v[194:197], v[116:119]
	v_mfma_f32_16x16x32_bf16 v[112:115], v[178:181], v[194:197], v[112:115]
	v_mfma_f32_16x16x32_bf16 v[108:111], v[168:171], v[202:205], v[108:111]
	v_mfma_f32_16x16x32_bf16 v[104:107], v[178:181], v[202:205], v[104:107]
	v_mfma_f32_16x16x32_bf16 v[100:103], v[168:171], v[210:213], v[100:103]
	v_mfma_f32_16x16x32_bf16 v[96:99], v[178:181], v[210:213], v[96:99]
	v_mfma_f32_16x16x32_bf16 v[124:127], v[174:177], v[190:193], v[124:127]
	v_mfma_f32_16x16x32_bf16 v[120:123], v[182:185], v[190:193], v[120:123]
	v_mfma_f32_16x16x32_bf16 v[116:119], v[174:177], v[198:201], v[116:119]
	v_mfma_f32_16x16x32_bf16 v[112:115], v[182:185], v[198:201], v[112:115]
	v_mfma_f32_16x16x32_bf16 v[108:111], v[174:177], v[206:209], v[108:111]
	v_mfma_f32_16x16x32_bf16 v[104:107], v[182:185], v[206:209], v[104:107]
	v_mfma_f32_16x16x32_bf16 v[100:103], v[174:177], v[214:217], v[100:103]
	v_mfma_f32_16x16x32_bf16 v[96:99], v[182:185], v[214:217], v[96:99]
	s_barrier
	v_add_u32_e32 v165, s63, v156
	v_lshl_add_u64 v[242:243], v[144:145], 0, s[50:51]
	v_readfirstlane_b32 s73, v165
	v_lshl_add_u64 v[166:167], v[242:243], 0, s[24:25]
	s_mov_b32 m0, s73
	ds_read_b128 v[218:221], v163
	ds_read_b128 v[222:225], v163 offset:1024
	ds_read_b128 v[226:229], v163 offset:2048
	ds_read_b128 v[230:233], v163 offset:3072
	global_load_lds_dwordx4 v[166:167], off
	s_nop 1
	v_add_u32_e32 v166, 0x2000, v165
	v_lshl_add_u64 v[244:245], v[142:143], 0, s[50:51]
	v_readfirstlane_b32 s73, v166
	v_lshl_add_u64 v[234:235], v[244:245], 0, s[24:25]
	s_mov_b32 m0, s73
	s_nop 0
	global_load_lds_dwordx4 v[234:235], off
	s_barrier
	s_waitcnt lgkmcnt(0)
	s_waitcnt lgkmcnt(0)
	v_mfma_f32_16x16x32_bf16 v[92:95], v[218:221], v[186:189], v[92:95]
	v_mfma_f32_16x16x32_bf16 v[88:91], v[226:229], v[186:189], v[88:91]
	v_mfma_f32_16x16x32_bf16 v[84:87], v[218:221], v[194:197], v[84:87]
	v_mfma_f32_16x16x32_bf16 v[80:83], v[226:229], v[194:197], v[80:83]
	v_mfma_f32_16x16x32_bf16 v[76:79], v[218:221], v[202:205], v[76:79]
	v_mfma_f32_16x16x32_bf16 v[72:75], v[226:229], v[202:205], v[72:75]
	v_mfma_f32_16x16x32_bf16 v[68:71], v[218:221], v[210:213], v[68:71]
	v_mfma_f32_16x16x32_bf16 v[64:67], v[226:229], v[210:213], v[64:67]
	v_mfma_f32_16x16x32_bf16 v[92:95], v[222:225], v[190:193], v[92:95]
	v_mfma_f32_16x16x32_bf16 v[88:91], v[230:233], v[190:193], v[88:91]
	v_mfma_f32_16x16x32_bf16 v[84:87], v[222:225], v[198:201], v[84:87]
	v_mfma_f32_16x16x32_bf16 v[80:83], v[230:233], v[198:201], v[80:83]
	v_mfma_f32_16x16x32_bf16 v[76:79], v[222:225], v[206:209], v[76:79]
	v_mfma_f32_16x16x32_bf16 v[72:75], v[230:233], v[206:209], v[72:75]
	v_mfma_f32_16x16x32_bf16 v[68:71], v[222:225], v[214:217], v[68:71]
	v_mfma_f32_16x16x32_bf16 v[64:67], v[230:233], v[214:217], v[64:67]
	v_readfirstlane_b32 s73, v147
	v_add_u32_e32 v167, 0x2000, v147
	v_lshl_add_u64 v[234:235], v[238:239], 0, s[26:27]
	s_mov_b32 m0, s73
	v_readfirstlane_b32 s73, v167
	s_barrier
	ds_read_b128 v[186:189], v155 offset:16384
	ds_read_b128 v[190:193], v155 offset:17408
	ds_read_b128 v[194:197], v154 offset:16384
	ds_read_b128 v[198:201], v154 offset:17408
	ds_read_b128 v[202:205], v153 offset:16384
	ds_read_b128 v[206:209], v153 offset:17408
	ds_read_b128 v[210:213], v152 offset:16384
	ds_read_b128 v[214:217], v152 offset:17408
	global_load_lds_dwordx4 v[234:235], off
	s_nop 1
	v_lshl_add_u64 v[234:235], v[240:241], 0, s[26:27]
	s_mov_b32 m0, s73
	s_nop 0
	global_load_lds_dwordx4 v[234:235], off
	s_barrier
	s_waitcnt lgkmcnt(0)
	s_waitcnt lgkmcnt(0)
	v_mfma_f32_16x16x32_bf16 v[60:63], v[168:171], v[186:189], v[60:63]
	v_mfma_f32_16x16x32_bf16 v[56:59], v[178:181], v[186:189], v[56:59]
	v_mfma_f32_16x16x32_bf16 v[52:55], v[168:171], v[194:197], v[52:55]
	v_mfma_f32_16x16x32_bf16 v[48:51], v[178:181], v[194:197], v[48:51]
	v_mfma_f32_16x16x32_bf16 v[44:47], v[168:171], v[202:205], v[44:47]
	v_mfma_f32_16x16x32_bf16 v[40:43], v[178:181], v[202:205], v[40:43]
	v_mfma_f32_16x16x32_bf16 v[36:39], v[168:171], v[210:213], v[36:39]
	v_mfma_f32_16x16x32_bf16 v[32:35], v[178:181], v[210:213], v[32:35]
	v_mfma_f32_16x16x32_bf16 v[60:63], v[174:177], v[190:193], v[60:63]
	v_mfma_f32_16x16x32_bf16 v[56:59], v[182:185], v[190:193], v[56:59]
	v_mfma_f32_16x16x32_bf16 v[52:55], v[174:177], v[198:201], v[52:55]
	v_mfma_f32_16x16x32_bf16 v[48:51], v[182:185], v[198:201], v[48:51]
	v_mfma_f32_16x16x32_bf16 v[44:47], v[174:177], v[206:209], v[44:47]
	v_mfma_f32_16x16x32_bf16 v[40:43], v[182:185], v[206:209], v[40:43]
	v_mfma_f32_16x16x32_bf16 v[36:39], v[174:177], v[214:217], v[36:39]
	v_mfma_f32_16x16x32_bf16 v[32:35], v[182:185], v[214:217], v[32:35]
	s_barrier
; #define STAGE(P, BASE, LD, br, kt) do { const char* _g = (const char*)((BASE) + (size_t)(br) * (LD) + (size_t)(kt) * 64); \
;     for (int _i = 0; _i < 2; ++_i) { int _b = tidx * 16 + _i * 8192; int _r, _c; stage_rc(_b, _r, _c); \
;       __builtin_amdgcn_global_load_lds((const unsigned*)(_g + (unsigned)((_r * (LD) + _c) * 2)), (unsigned*)((char*)(P) + _b), 16, 0, 0); } } while (0)
; #define LDA(dst, b, h) for (int m = 0; m < 4; ++m) for (int k = 0; k < 2; ++k) \
;     dst[m][k] = *reinterpret_cast<const bf16x8*>((char*)SA(b, h) + lds_byte(wr * 64 + m * 16 + fr, k * 32 + fq * 8))
; #define LDB(dst, b, h) for (int n = 0; n < 2; ++n) for (int k = 0; k < 2; ++k) \
;     dst[n][k] = *reinterpret_cast<const bf16x8*>((char*)SB(b, h) + lds_byte(wc * 32 + n * 16 + fr, k * 32 + fq * 8))
; #define MMA(ai, bj, At_, Bt_) do { __builtin_amdgcn_s_setprio(1); \
;     for (int k = 0; k < 2; ++k) for (int m = 0; m < 4; ++m) for (int n = 0; n < 2; ++n) \
;       acc[ai][bj][m][n] = __builtin_amdgcn_mfma_f32_16x16x32_bf16(At_[m][k], Bt_[n][k], acc[ai][bj][m][n], 0, 0, 0); \
;     __builtin_amdgcn_s_setprio(0); } while (0)
; #define WAIT_V(n) asm volatile("s_waitcnt vmcnt(" #n ")" ::: "memory")
; #define WAIT_L(n) asm volatile("s_waitcnt lgkmcnt(" #n ")" ::: "memory")
; #define BAR __builtin_amdgcn_s_barrier()
; #define SCHED __builtin_amdgcn_sched_barrier(0)
; template <int EPI, int lda, int ldb, int N, int K>
; __device__ __forceinline__ void gemm_phase(const u16* __restrict__ A, const u16* __restrict__ Bt, const GemmEpi ep, int wv) {
;     ...
;       STAGE(SB(0, 1), Bt, ldb, bcol + HALF, t + 2);
;       WAIT_V(6); BAR; MMA(1, 1, At, B1); BAR;
;       LDB(B0, 1, 0); SCHED; LDA(At, 1, 0); STAGE(SA(0, 1), Ab, lda, brow + HALF, t + 2);
;       WAIT_L(8); BAR; WAIT_L(0); MMA(0, 0, At, B0); BAR; SCHED;
;       LDB(B1, 1, 1); STAGE(SB(1, 0), Bt, ldb, bcol, t + 3);
;       BAR; WAIT_L(0); MMA(0, 1, At, B1); BAR;
;       LDA(At, 1, 1); STAGE(SA(1, 0), Ab, lda, brow, t + 3);
	v_add_u32_e32 v168, s64, v156
	v_lshl_add_u64 v[246:247], v[140:141], 0, s[50:51]
	v_readfirstlane_b32 s73, v168
	v_add_u32_e32 v169, 0x2000, v168
	v_lshl_add_u64 v[170:171], v[246:247], 0, s[40:41]
	s_mov_b32 m0, s73
	v_lshl_add_u64 v[248:249], v[138:139], 0, s[50:51]
	v_readfirstlane_b32 s73, v169
	global_load_lds_dwordx4 v[170:171], off
	s_nop 1
	v_lshl_add_u64 v[170:171], v[248:249], 0, s[40:41]
	s_mov_b32 m0, s73
	s_nop 0
	global_load_lds_dwordx4 v[170:171], off
	s_waitcnt vmcnt(6)
	s_barrier
	v_mfma_f32_16x16x32_bf16 v[28:31], v[218:221], v[186:189], v[28:31]
	v_mfma_f32_16x16x32_bf16 v[24:27], v[226:229], v[186:189], v[24:27]
	v_mfma_f32_16x16x32_bf16 v[20:23], v[218:221], v[194:197], v[20:23]
	v_mfma_f32_16x16x32_bf16 v[16:19], v[226:229], v[194:197], v[16:19]
	v_mfma_f32_16x16x32_bf16 v[12:15], v[218:221], v[202:205], v[12:15]
	v_mfma_f32_16x16x32_bf16 v[8:11], v[226:229], v[202:205], v[8:11]
	v_mfma_f32_16x16x32_bf16 v[4:7], v[218:221], v[210:213], v[4:7]
	v_mfma_f32_16x16x32_bf16 v[0:3], v[226:229], v[210:213], v[0:3]
	v_mfma_f32_16x16x32_bf16 v[28:31], v[222:225], v[190:193], v[28:31]
	v_mfma_f32_16x16x32_bf16 v[24:27], v[230:233], v[190:193], v[24:27]
	v_mfma_f32_16x16x32_bf16 v[20:23], v[222:225], v[198:201], v[20:23]
	v_mfma_f32_16x16x32_bf16 v[16:19], v[230:233], v[198:201], v[16:19]
	v_mfma_f32_16x16x32_bf16 v[12:15], v[222:225], v[206:209], v[12:15]
	v_mfma_f32_16x16x32_bf16 v[8:11], v[230:233], v[206:209], v[8:11]
	v_mfma_f32_16x16x32_bf16 v[4:7], v[222:225], v[214:217], v[4:7]
	v_mfma_f32_16x16x32_bf16 v[0:3], v[230:233], v[214:217], v[0:3]
	s_barrier
	ds_read_b128 v[174:177], v159
	ds_read_b128 v[178:181], v159 offset:1024
	ds_read_b128 v[182:185], v159 offset:2048
	ds_read_b128 v[186:189], v159 offset:3072
	v_add_u32_e32 v170, 0x4000, v147
	v_add_u32_e32 v171, 0x6000, v147
	v_readfirstlane_b32 s73, v170
	v_lshl_add_u64 v[222:223], v[238:239], 0, s[42:43]
	s_mov_b32 m0, s73
	v_readfirstlane_b32 s73, v171
	ds_read_b128 v[190:193], v155 offset:32768
	ds_read_b128 v[194:197], v155 offset:33792
	ds_read_b128 v[198:201], v154 offset:32768
	ds_read_b128 v[202:205], v154 offset:33792
	ds_read_b128 v[206:209], v153 offset:32768
	ds_read_b128 v[210:213], v153 offset:33792
	ds_read_b128 v[214:217], v152 offset:32768
	ds_read_b128 v[218:221], v152 offset:33792
	global_load_lds_dwordx4 v[222:223], off
	s_nop 1
	v_lshl_add_u64 v[222:223], v[240:241], 0, s[42:43]
	s_mov_b32 m0, s73
	s_nop 0
	global_load_lds_dwordx4 v[222:223], off
	s_waitcnt lgkmcnt(8)
	s_barrier
	s_waitcnt lgkmcnt(0)
	s_waitcnt lgkmcnt(0)
	v_mfma_f32_16x16x32_bf16 v[124:127], v[174:177], v[190:193], v[124:127]
	v_mfma_f32_16x16x32_bf16 v[120:123], v[182:185], v[190:193], v[120:123]
	v_mfma_f32_16x16x32_bf16 v[116:119], v[174:177], v[198:201], v[116:119]
	v_mfma_f32_16x16x32_bf16 v[112:115], v[182:185], v[198:201], v[112:115]
	v_mfma_f32_16x16x32_bf16 v[108:111], v[174:177], v[206:209], v[108:111]
	v_mfma_f32_16x16x32_bf16 v[104:107], v[182:185], v[206:209], v[104:107]
	v_mfma_f32_16x16x32_bf16 v[100:103], v[174:177], v[214:217], v[100:103]
	v_mfma_f32_16x16x32_bf16 v[96:99], v[182:185], v[214:217], v[96:99]
	v_mfma_f32_16x16x32_bf16 v[124:127], v[178:181], v[194:197], v[124:127]
	v_mfma_f32_16x16x32_bf16 v[120:123], v[186:189], v[194:197], v[120:123]
	v_mfma_f32_16x16x32_bf16 v[116:119], v[178:181], v[202:205], v[116:119]
	v_mfma_f32_16x16x32_bf16 v[112:115], v[186:189], v[202:205], v[112:115]
	v_mfma_f32_16x16x32_bf16 v[108:111], v[178:181], v[210:213], v[108:111]
	v_mfma_f32_16x16x32_bf16 v[104:107], v[186:189], v[210:213], v[104:107]
	v_mfma_f32_16x16x32_bf16 v[100:103], v[178:181], v[218:221], v[100:103]
	v_mfma_f32_16x16x32_bf16 v[96:99], v[186:189], v[218:221], v[96:99]
	s_barrier
	v_readfirstlane_b32 s73, v158
	v_lshl_add_u64 v[242:243], v[242:243], 0, s[44:45]
	s_mov_b32 m0, s73
	ds_read_b128 v[222:225], v157
	ds_read_b128 v[226:229], v157 offset:1024
	ds_read_b128 v[230:233], v157 offset:2048
	ds_read_b128 v[234:237], v157 offset:3072
	global_load_lds_dwordx4 v[242:243], off
	s_nop 1
	v_lshl_add_u64 v[242:243], v[244:245], 0, s[44:45]
	v_add_u32_e32 v244, 0x2000, v158
	s_nop 0
	v_readfirstlane_b32 s73, v244
	s_mov_b32 m0, s73
	s_nop 0
	global_load_lds_dwordx4 v[242:243], off
	s_barrier
	s_waitcnt lgkmcnt(0)
	s_waitcnt lgkmcnt(0)
	v_mfma_f32_16x16x32_bf16 v[92:95], v[222:225], v[190:193], v[92:95]
	v_mfma_f32_16x16x32_bf16 v[88:91], v[230:233], v[190:193], v[88:91]
	v_mfma_f32_16x16x32_bf16 v[84:87], v[222:225], v[198:201], v[84:87]
	v_mfma_f32_16x16x32_bf16 v[80:83], v[230:233], v[198:201], v[80:83]
	v_mfma_f32_16x16x32_bf16 v[76:79], v[222:225], v[206:209], v[76:79]
	v_mfma_f32_16x16x32_bf16 v[72:75], v[230:233], v[206:209], v[72:75]
	v_mfma_f32_16x16x32_bf16 v[68:71], v[222:225], v[214:217], v[68:71]
	v_mfma_f32_16x16x32_bf16 v[64:67], v[230:233], v[214:217], v[64:67]
	v_mfma_f32_16x16x32_bf16 v[92:95], v[226:229], v[194:197], v[92:95]
	v_mfma_f32_16x16x32_bf16 v[88:91], v[234:237], v[194:197], v[88:91]
	v_mfma_f32_16x16x32_bf16 v[84:87], v[226:229], v[202:205], v[84:87]
	v_mfma_f32_16x16x32_bf16 v[80:83], v[234:237], v[202:205], v[80:83]
	v_mfma_f32_16x16x32_bf16 v[76:79], v[226:229], v[210:213], v[76:79]
	v_mfma_f32_16x16x32_bf16 v[72:75], v[234:237], v[210:213], v[72:75]
	v_mfma_f32_16x16x32_bf16 v[68:71], v[226:229], v[218:221], v[68:71]
	v_mfma_f32_16x16x32_bf16 v[64:67], v[234:237], v[218:221], v[64:67]
	v_readfirstlane_b32 s73, v160
	v_lshl_add_u64 v[238:239], v[238:239], 0, s[46:47]
	s_mov_b32 m0, s73
	v_readfirstlane_b32 s73, v161
	s_barrier
; #define STAGE(P, BASE, LD, br, kt) do { const char* _g = (const char*)((BASE) + (size_t)(br) * (LD) + (size_t)(kt) * 64); \
;     for (int _i = 0; _i < 2; ++_i) { int _b = tidx * 16 + _i * 8192; int _r, _c; stage_rc(_b, _r, _c); \
;       __builtin_amdgcn_global_load_lds((const unsigned*)(_g + (unsigned)((_r * (LD) + _c) * 2)), (unsigned*)((char*)(P) + _b), 16, 0, 0); } } while (0)
; #define LDA(dst, b, h) for (int m = 0; m < 4; ++m) for (int k = 0; k < 2; ++k) \
;     dst[m][k] = *reinterpret_cast<const bf16x8*>((char*)SA(b, h) + lds_byte(wr * 64 + m * 16 + fr, k * 32 + fq * 8))
; #define LDB(dst, b, h) for (int n = 0; n < 2; ++n) for (int k = 0; k < 2; ++k) \
;     dst[n][k] = *reinterpret_cast<const bf16x8*>((char*)SB(b, h) + lds_byte(wc * 32 + n * 16 + fr, k * 32 + fq * 8))
; #define MMA(ai, bj, At_, Bt_) do { __builtin_amdgcn_s_setprio(1); \
;     for (int k = 0; k < 2; ++k) for (int m = 0; m < 4; ++m) for (int n = 0; n < 2; ++n) \
;       acc[ai][bj][m][n] = __builtin_amdgcn_mfma_f32_16x16x32_bf16(At_[m][k], Bt_[n][k], acc[ai][bj][m][n], 0, 0, 0); \
;     __builtin_amdgcn_s_setprio(0); } while (0)
; #define WAIT_V(n) asm volatile("s_waitcnt vmcnt(" #n ")" ::: "memory")
; #define WAIT_L(n) asm volatile("s_waitcnt lgkmcnt(" #n ")" ::: "memory")
; #define BAR __builtin_amdgcn_s_barrier()
; #define SCHED __builtin_amdgcn_sched_barrier(0)
; template <int EPI, int lda, int ldb, int N, int K>
; __device__ __forceinline__ void gemm_phase(const u16* __restrict__ A, const u16* __restrict__ Bt, const GemmEpi ep, int wv) {
;     ...
;       LDA(At, 1, 1); STAGE(SA(1, 0), Ab, lda, brow, t + 3);
;       BAR; WAIT_L(0); MMA(1, 0, At, B0); BAR; SCHED;
;       STAGE(SB(1, 1), Bt, ldb, bcol + HALF, t + 3);
;       WAIT_V(6); BAR; MMA(1, 1, At, B1); BAR;
;     }
;     { LDB(B0, 0, 0); LDA(At, 0, 0); STAGE(SA(1, 1), Ab, lda, brow + HALF, nt - 1);
;       BAR; WAIT_L(0); MMA(0, 0, At, B0); BAR;
;       LDB(B1, 0, 1); BAR; WAIT_L(0); MMA(0, 1, At, B1); BAR;
	ds_read_b128 v[190:193], v155 offset:49152
	ds_read_b128 v[194:197], v155 offset:50176
	ds_read_b128 v[198:201], v154 offset:49152
	ds_read_b128 v[202:205], v154 offset:50176
	ds_read_b128 v[206:209], v153 offset:49152
	ds_read_b128 v[210:213], v153 offset:50176
	ds_read_b128 v[214:217], v152 offset:49152
	ds_read_b128 v[218:221], v152 offset:50176
	global_load_lds_dwordx4 v[238:239], off
	s_nop 1
	v_lshl_add_u64 v[238:239], v[240:241], 0, s[46:47]
	s_mov_b32 m0, s73
	s_nop 0
	global_load_lds_dwordx4 v[238:239], off
	s_barrier
	s_waitcnt lgkmcnt(0)
	s_waitcnt lgkmcnt(0)
	v_mfma_f32_16x16x32_bf16 v[60:63], v[174:177], v[190:193], v[60:63]
	v_mfma_f32_16x16x32_bf16 v[56:59], v[182:185], v[190:193], v[56:59]
	v_mfma_f32_16x16x32_bf16 v[52:55], v[174:177], v[198:201], v[52:55]
	v_mfma_f32_16x16x32_bf16 v[48:51], v[182:185], v[198:201], v[48:51]
	v_mfma_f32_16x16x32_bf16 v[44:47], v[174:177], v[206:209], v[44:47]
	v_mfma_f32_16x16x32_bf16 v[40:43], v[182:185], v[206:209], v[40:43]
	v_mfma_f32_16x16x32_bf16 v[36:39], v[174:177], v[214:217], v[36:39]
	v_mfma_f32_16x16x32_bf16 v[32:35], v[182:185], v[214:217], v[32:35]
	v_mfma_f32_16x16x32_bf16 v[60:63], v[178:181], v[194:197], v[60:63]
	v_mfma_f32_16x16x32_bf16 v[56:59], v[186:189], v[194:197], v[56:59]
	v_mfma_f32_16x16x32_bf16 v[52:55], v[178:181], v[202:205], v[52:55]
	v_mfma_f32_16x16x32_bf16 v[48:51], v[186:189], v[202:205], v[48:51]
	v_mfma_f32_16x16x32_bf16 v[44:47], v[178:181], v[210:213], v[44:47]
	v_mfma_f32_16x16x32_bf16 v[40:43], v[186:189], v[210:213], v[40:43]
	v_mfma_f32_16x16x32_bf16 v[36:39], v[178:181], v[218:221], v[36:39]
	v_mfma_f32_16x16x32_bf16 v[32:35], v[186:189], v[218:221], v[32:35]
	s_barrier
	v_readfirstlane_b32 s73, v162
	v_add_u32_e32 v176, 0x2000, v162
	v_lshl_add_u64 v[174:175], v[246:247], 0, s[48:49]
	s_mov_b32 m0, s73
	v_readfirstlane_b32 s73, v176
	global_load_lds_dwordx4 v[174:175], off
	s_nop 1
	v_lshl_add_u64 v[174:175], v[248:249], 0, s[48:49]
	s_mov_b32 m0, s73
	s_nop 0
	global_load_lds_dwordx4 v[174:175], off
	s_waitcnt vmcnt(6)
	s_barrier
	v_mfma_f32_16x16x32_bf16 v[28:31], v[222:225], v[190:193], v[28:31]
	v_mfma_f32_16x16x32_bf16 v[24:27], v[230:233], v[190:193], v[24:27]
	v_mfma_f32_16x16x32_bf16 v[20:23], v[222:225], v[198:201], v[20:23]
	v_mfma_f32_16x16x32_bf16 v[16:19], v[230:233], v[198:201], v[16:19]
	v_mfma_f32_16x16x32_bf16 v[12:15], v[222:225], v[206:209], v[12:15]
	v_mfma_f32_16x16x32_bf16 v[8:11], v[230:233], v[206:209], v[8:11]
	v_mfma_f32_16x16x32_bf16 v[4:7], v[222:225], v[214:217], v[4:7]
	v_mfma_f32_16x16x32_bf16 v[0:3], v[230:233], v[214:217], v[0:3]
	v_mfma_f32_16x16x32_bf16 v[28:31], v[226:229], v[194:197], v[28:31]
	v_mfma_f32_16x16x32_bf16 v[24:27], v[234:237], v[194:197], v[24:27]
	v_mfma_f32_16x16x32_bf16 v[20:23], v[226:229], v[202:205], v[20:23]
	v_mfma_f32_16x16x32_bf16 v[16:19], v[234:237], v[202:205], v[16:19]
	v_mfma_f32_16x16x32_bf16 v[12:15], v[226:229], v[210:213], v[12:15]
	v_mfma_f32_16x16x32_bf16 v[8:11], v[234:237], v[210:213], v[8:11]
	v_mfma_f32_16x16x32_bf16 v[4:7], v[226:229], v[218:221], v[4:7]
	v_mfma_f32_16x16x32_bf16 v[0:3], v[234:237], v[218:221], v[0:3]
	s_add_i32 s72, s72, 2
	s_add_u32 s50, s50, 0x100
	s_addc_u32 s51, s51, 0
	s_cmpk_gt_u32 s72, 0x51
	s_barrier
	s_cbranch_scc0 .LBB0_838
	s_add_i32 s50, s18, 0x80
	s_mul_hi_i32 s51, s50, 0x2b00
	s_mulk_i32 s50, 0x2b00
	s_add_u32 s50, s56, s50
	s_addc_u32 s51, s57, s51
	s_add_u32 s50, s50, 0x2a80
	s_addc_u32 s51, s51, 0
	v_readfirstlane_b32 s72, v172
	v_lshl_add_u64 v[160:161], s[50:51], 0, v[128:129]
	s_mov_b32 m0, s72
	ds_read_b128 v[134:137], v164
	ds_read_b128 v[138:141], v164 offset:1024
	ds_read_b128 v[142:145], v164 offset:2048
	ds_read_b128 v[174:177], v164 offset:3072
	ds_read_b128 v[178:181], v155
	ds_read_b128 v[182:185], v155 offset:1024
	ds_read_b128 v[186:189], v154
	ds_read_b128 v[190:193], v154 offset:1024
	ds_read_b128 v[194:197], v153
	ds_read_b128 v[198:201], v153 offset:1024
	ds_read_b128 v[202:205], v152
	ds_read_b128 v[206:209], v152 offset:1024
	global_load_lds_dwordx4 v[160:161], off
	v_lshl_add_u64 v[160:161], s[50:51], 0, v[132:133]
	v_readfirstlane_b32 s50, v173
	s_mov_b32 m0, s50
	s_nop 0
	global_load_lds_dwordx4 v[160:161], off
	s_barrier
	s_waitcnt lgkmcnt(0)
	s_waitcnt lgkmcnt(0)
	v_mfma_f32_16x16x32_bf16 v[124:127], v[134:137], v[178:181], v[124:127]
	v_mfma_f32_16x16x32_bf16 v[120:123], v[142:145], v[178:181], v[120:123]
	v_mfma_f32_16x16x32_bf16 v[116:119], v[134:137], v[186:189], v[116:119]
	v_mfma_f32_16x16x32_bf16 v[112:115], v[142:145], v[186:189], v[112:115]
	v_mfma_f32_16x16x32_bf16 v[108:111], v[134:137], v[194:197], v[108:111]
	v_mfma_f32_16x16x32_bf16 v[104:107], v[142:145], v[194:197], v[104:107]
	v_mfma_f32_16x16x32_bf16 v[100:103], v[134:137], v[202:205], v[100:103]
	v_mfma_f32_16x16x32_bf16 v[96:99], v[142:145], v[202:205], v[96:99]
	v_mfma_f32_16x16x32_bf16 v[124:127], v[138:141], v[182:185], v[124:127]
	v_mfma_f32_16x16x32_bf16 v[120:123], v[174:177], v[182:185], v[120:123]
	v_mfma_f32_16x16x32_bf16 v[116:119], v[138:141], v[190:193], v[116:119]
	v_mfma_f32_16x16x32_bf16 v[112:115], v[174:177], v[190:193], v[112:115]
	v_mfma_f32_16x16x32_bf16 v[108:111], v[138:141], v[198:201], v[108:111]
	v_mfma_f32_16x16x32_bf16 v[104:107], v[174:177], v[198:201], v[104:107]
	v_mfma_f32_16x16x32_bf16 v[100:103], v[138:141], v[206:209], v[100:103]
	v_mfma_f32_16x16x32_bf16 v[96:99], v[174:177], v[206:209], v[96:99]
	s_barrier
	ds_read_b128 v[210:213], v163
	ds_read_b128 v[214:217], v163 offset:1024
	ds_read_b128 v[218:221], v163 offset:2048
	ds_read_b128 v[160:163], v163 offset:3072
	s_barrier
; #define LDA(dst, b, h) for (int m = 0; m < 4; ++m) for (int k = 0; k < 2; ++k) \
;     dst[m][k] = *reinterpret_cast<const bf16x8*>((char*)SA(b, h) + lds_byte(wr * 64 + m * 16 + fr, k * 32 + fq * 8))
; #define LDB(dst, b, h) for (int n = 0; n < 2; ++n) for (int k = 0; k < 2; ++k) \
;     dst[n][k] = *reinterpret_cast<const bf16x8*>((char*)SB(b, h) + lds_byte(wc * 32 + n * 16 + fr, k * 32 + fq * 8))
; #define MMA(ai, bj, At_, Bt_) do { __builtin_amdgcn_s_setprio(1); \
;     for (int k = 0; k < 2; ++k) for (int m = 0; m < 4; ++m) for (int n = 0; n < 2; ++n) \
;       acc[ai][bj][m][n] = __builtin_amdgcn_mfma_f32_16x16x32_bf16(At_[m][k], Bt_[n][k], acc[ai][bj][m][n], 0, 0, 0); \
;     __builtin_amdgcn_s_setprio(0); } while (0)
; #define WAIT_V(n) asm volatile("s_waitcnt vmcnt(" #n ")" ::: "memory")
; #define WAIT_L(n) asm volatile("s_waitcnt lgkmcnt(" #n ")" ::: "memory")
; #define BAR __builtin_amdgcn_s_barrier()
; template <int EPI, int lda, int ldb, int N, int K>
; __device__ __forceinline__ void gemm_phase(const u16* __restrict__ A, const u16* __restrict__ Bt, const GemmEpi ep, int wv) {
;     ...
;       LDB(B1, 0, 1); BAR; WAIT_L(0); MMA(0, 1, At, B1); BAR;
;       LDA(At, 0, 1); WAIT_V(4); BAR; WAIT_L(0); MMA(1, 0, At, B0); MMA(1, 1, At, B1); BAR; }
;     { LDB(B0, 1, 0); LDA(At, 1, 0); WAIT_V(2); BAR; WAIT_L(0); MMA(0, 0, At, B0); BAR;
	s_waitcnt lgkmcnt(0)
	s_waitcnt lgkmcnt(0)
	v_mfma_f32_16x16x32_bf16 v[92:95], v[210:213], v[178:181], v[92:95]
	v_mfma_f32_16x16x32_bf16 v[88:91], v[218:221], v[178:181], v[88:91]
	v_mfma_f32_16x16x32_bf16 v[76:79], v[210:213], v[194:197], v[76:79]
	v_mfma_f32_16x16x32_bf16 v[72:75], v[218:221], v[194:197], v[72:75]
	v_mfma_f32_16x16x32_bf16 v[84:87], v[210:213], v[186:189], v[84:87]
	v_mfma_f32_16x16x32_bf16 v[80:83], v[218:221], v[186:189], v[80:83]
	v_mfma_f32_16x16x32_bf16 v[68:71], v[210:213], v[202:205], v[68:71]
	v_mfma_f32_16x16x32_bf16 v[64:67], v[218:221], v[202:205], v[64:67]
	v_mfma_f32_16x16x32_bf16 v[92:95], v[214:217], v[182:185], v[92:95]
	v_mfma_f32_16x16x32_bf16 v[88:91], v[160:163], v[182:185], v[88:91]
	v_mfma_f32_16x16x32_bf16 v[76:79], v[214:217], v[198:201], v[76:79]
	v_mfma_f32_16x16x32_bf16 v[72:75], v[160:163], v[198:201], v[72:75]
	v_mfma_f32_16x16x32_bf16 v[178:181], v[214:217], v[190:193], v[84:87]
	v_mfma_f32_16x16x32_bf16 v[182:185], v[160:163], v[190:193], v[80:83]
	v_mfma_f32_16x16x32_bf16 v[186:189], v[214:217], v[206:209], v[68:71]
	v_mfma_f32_16x16x32_bf16 v[190:193], v[160:163], v[206:209], v[64:67]
	s_barrier
	s_nop 0
	ds_read_b128 v[64:67], v155 offset:16384
	ds_read_b128 v[68:71], v155 offset:17408
	ds_read_b128 v[80:83], v154 offset:16384
	ds_read_b128 v[84:87], v154 offset:17408
	ds_read_b128 v[194:197], v153 offset:16384
	ds_read_b128 v[198:201], v153 offset:17408
	ds_read_b128 v[202:205], v152 offset:16384
	ds_read_b128 v[206:209], v152 offset:17408
	s_waitcnt vmcnt(4)
	s_barrier
	s_waitcnt lgkmcnt(0)
	s_waitcnt lgkmcnt(0)
	v_mfma_f32_16x16x32_bf16 v[60:63], v[134:137], v[64:67], v[60:63]
	v_mfma_f32_16x16x32_bf16 v[56:59], v[142:145], v[64:67], v[56:59]
	v_mfma_f32_16x16x32_bf16 v[52:55], v[134:137], v[80:83], v[52:55]
	v_mfma_f32_16x16x32_bf16 v[48:51], v[142:145], v[80:83], v[48:51]
	v_mfma_f32_16x16x32_bf16 v[44:47], v[134:137], v[194:197], v[44:47]
	v_mfma_f32_16x16x32_bf16 v[40:43], v[142:145], v[194:197], v[40:43]
	v_mfma_f32_16x16x32_bf16 v[36:39], v[134:137], v[202:205], v[36:39]
	v_mfma_f32_16x16x32_bf16 v[32:35], v[142:145], v[202:205], v[32:35]
	v_mfma_f32_16x16x32_bf16 v[60:63], v[138:141], v[68:71], v[60:63]
	v_mfma_f32_16x16x32_bf16 v[56:59], v[174:177], v[68:71], v[56:59]
	v_mfma_f32_16x16x32_bf16 v[52:55], v[138:141], v[84:87], v[52:55]
	v_mfma_f32_16x16x32_bf16 v[48:51], v[174:177], v[84:87], v[48:51]
	v_mfma_f32_16x16x32_bf16 v[44:47], v[138:141], v[198:201], v[44:47]
	v_mfma_f32_16x16x32_bf16 v[40:43], v[174:177], v[198:201], v[40:43]
	v_mfma_f32_16x16x32_bf16 v[36:39], v[138:141], v[206:209], v[36:39]
	v_mfma_f32_16x16x32_bf16 v[32:35], v[174:177], v[206:209], v[32:35]
	v_mfma_f32_16x16x32_bf16 v[28:31], v[210:213], v[64:67], v[28:31]
	v_mfma_f32_16x16x32_bf16 v[16:19], v[218:221], v[80:83], v[16:19]
	v_mfma_f32_16x16x32_bf16 v[12:15], v[210:213], v[194:197], v[12:15]
	v_mfma_f32_16x16x32_bf16 v[0:3], v[218:221], v[202:205], v[0:3]
	v_mfma_f32_16x16x32_bf16 v[24:27], v[218:221], v[64:67], v[24:27]
	v_mfma_f32_16x16x32_bf16 v[20:23], v[210:213], v[80:83], v[20:23]
	v_mfma_f32_16x16x32_bf16 v[8:11], v[218:221], v[194:197], v[8:11]
	v_mfma_f32_16x16x32_bf16 v[4:7], v[210:213], v[202:205], v[4:7]
	v_mfma_f32_16x16x32_bf16 v[28:31], v[214:217], v[68:71], v[28:31]
	v_mfma_f32_16x16x32_bf16 v[16:19], v[160:163], v[84:87], v[16:19]
	v_mfma_f32_16x16x32_bf16 v[12:15], v[214:217], v[198:201], v[12:15]
	v_mfma_f32_16x16x32_bf16 v[0:3], v[160:163], v[206:209], v[0:3]
	v_mfma_f32_16x16x32_bf16 v[134:137], v[160:163], v[68:71], v[24:27]
	v_mfma_f32_16x16x32_bf16 v[138:141], v[214:217], v[84:87], v[20:23]
	v_mfma_f32_16x16x32_bf16 v[142:145], v[160:163], v[198:201], v[8:11]
	v_mfma_f32_16x16x32_bf16 v[172:175], v[214:217], v[206:209], v[4:7]
	s_barrier
	s_nop 0
	ds_read_b128 v[4:7], v159
	ds_read_b128 v[8:11], v159 offset:1024
	ds_read_b128 v[20:23], v159 offset:2048
	ds_read_b128 v[158:161], v159 offset:3072
	ds_read_b128 v[24:27], v155 offset:32768
	ds_read_b128 v[194:197], v155 offset:33792
	ds_read_b128 v[198:201], v154 offset:32768
	ds_read_b128 v[202:205], v154 offset:33792
	ds_read_b128 v[206:209], v153 offset:32768
	ds_read_b128 v[210:213], v153 offset:33792
	ds_read_b128 v[214:217], v152 offset:32768
	ds_read_b128 v[218:221], v152 offset:33792
	s_waitcnt vmcnt(2)
	s_barrier
; #define LDA(dst, b, h) for (int m = 0; m < 4; ++m) for (int k = 0; k < 2; ++k) \
;     dst[m][k] = *reinterpret_cast<const bf16x8*>((char*)SA(b, h) + lds_byte(wr * 64 + m * 16 + fr, k * 32 + fq * 8))
; #define LDB(dst, b, h) for (int n = 0; n < 2; ++n) for (int k = 0; k < 2; ++k) \
;     dst[n][k] = *reinterpret_cast<const bf16x8*>((char*)SB(b, h) + lds_byte(wc * 32 + n * 16 + fr, k * 32 + fq * 8))
; #define MMA(ai, bj, At_, Bt_) do { __builtin_amdgcn_s_setprio(1); \
;     for (int k = 0; k < 2; ++k) for (int m = 0; m < 4; ++m) for (int n = 0; n < 2; ++n) \
;       acc[ai][bj][m][n] = __builtin_amdgcn_mfma_f32_16x16x32_bf16(At_[m][k], Bt_[n][k], acc[ai][bj][m][n], 0, 0, 0); \
;     __builtin_amdgcn_s_setprio(0); } while (0)
; #define WAIT_V(n) asm volatile("s_waitcnt vmcnt(" #n ")" ::: "memory")
; #define WAIT_L(n) asm volatile("s_waitcnt lgkmcnt(" #n ")" ::: "memory")
; #define BAR __builtin_amdgcn_s_barrier()
; template <int EPI, int lda, int ldb, int N, int K>
; __device__ __forceinline__ void gemm_phase(const u16* __restrict__ A, const u16* __restrict__ Bt, const GemmEpi ep, int wv) {
;     ...
;     { LDB(B0, 1, 0); LDA(At, 1, 0); WAIT_V(2); BAR; WAIT_L(0); MMA(0, 0, At, B0); BAR;
;       LDB(B1, 1, 1); WAIT_V(0); BAR; WAIT_L(0); MMA(0, 1, At, B1); BAR;
;       LDA(At, 1, 1); BAR; WAIT_L(0); MMA(1, 0, At, B0); MMA(1, 1, At, B1); BAR; }
;     if (wr == 0) BAR;
	s_waitcnt lgkmcnt(0)
	s_waitcnt lgkmcnt(0)
	v_mfma_f32_16x16x32_bf16 v[64:67], v[4:7], v[24:27], v[124:127]
	v_mfma_f32_16x16x32_bf16 v[68:71], v[20:23], v[24:27], v[120:123]
	v_mfma_f32_16x16x32_bf16 v[80:83], v[4:7], v[198:201], v[116:119]
	v_mfma_f32_16x16x32_bf16 v[84:87], v[20:23], v[198:201], v[112:115]
	v_mfma_f32_16x16x32_bf16 v[108:111], v[4:7], v[206:209], v[108:111]
	v_mfma_f32_16x16x32_bf16 v[104:107], v[20:23], v[206:209], v[104:107]
	v_mfma_f32_16x16x32_bf16 v[120:123], v[4:7], v[214:217], v[100:103]
	v_mfma_f32_16x16x32_bf16 v[124:127], v[20:23], v[214:217], v[96:99]
	v_mfma_f32_16x16x32_bf16 v[116:119], v[8:11], v[194:197], v[64:67]
	v_mfma_f32_16x16x32_bf16 v[112:115], v[158:161], v[194:197], v[68:71]
	v_mfma_f32_16x16x32_bf16 v[100:103], v[8:11], v[202:205], v[80:83]
	v_mfma_f32_16x16x32_bf16 v[96:99], v[158:161], v[202:205], v[84:87]
	v_mfma_f32_16x16x32_bf16 v[84:87], v[8:11], v[210:213], v[108:111]
	v_mfma_f32_16x16x32_bf16 v[80:83], v[158:161], v[210:213], v[104:107]
	v_mfma_f32_16x16x32_bf16 v[68:71], v[8:11], v[218:221], v[120:123]
	v_mfma_f32_16x16x32_bf16 v[64:67], v[158:161], v[218:221], v[124:127]
	s_barrier
	ds_read_b128 v[222:225], v157
	ds_read_b128 v[226:229], v157 offset:1024
	ds_read_b128 v[230:233], v157 offset:2048
	ds_read_b128 v[234:237], v157 offset:3072
	s_waitcnt vmcnt(0)
	s_barrier
	s_waitcnt lgkmcnt(0)
	s_waitcnt lgkmcnt(0)
	v_mfma_f32_16x16x32_bf16 v[92:95], v[222:225], v[24:27], v[92:95]
	v_mfma_f32_16x16x32_bf16 v[24:27], v[230:233], v[24:27], v[88:91]
	v_mfma_f32_16x16x32_bf16 v[88:91], v[222:225], v[198:201], v[178:181]
	v_mfma_f32_16x16x32_bf16 v[104:107], v[230:233], v[198:201], v[182:185]
	v_mfma_f32_16x16x32_bf16 v[76:79], v[222:225], v[206:209], v[76:79]
	v_mfma_f32_16x16x32_bf16 v[72:75], v[230:233], v[206:209], v[72:75]
	v_mfma_f32_16x16x32_bf16 v[176:179], v[222:225], v[214:217], v[186:189]
	v_mfma_f32_16x16x32_bf16 v[180:183], v[230:233], v[214:217], v[190:193]
	v_mfma_f32_16x16x32_bf16 v[124:127], v[226:229], v[194:197], v[92:95]
	v_mfma_f32_16x16x32_bf16 v[120:123], v[234:237], v[194:197], v[24:27]
	v_mfma_f32_16x16x32_bf16 v[108:111], v[226:229], v[202:205], v[88:91]
	v_mfma_f32_16x16x32_bf16 v[104:107], v[234:237], v[202:205], v[104:107]
	v_mfma_f32_16x16x32_bf16 v[92:95], v[226:229], v[210:213], v[76:79]
	v_mfma_f32_16x16x32_bf16 v[88:91], v[234:237], v[210:213], v[72:75]
	v_mfma_f32_16x16x32_bf16 v[76:79], v[226:229], v[218:221], v[176:179]
	v_mfma_f32_16x16x32_bf16 v[72:75], v[234:237], v[218:221], v[180:183]
	s_barrier
	ds_read_b128 v[176:179], v155 offset:49152
	ds_read_b128 v[180:183], v155 offset:50176
	ds_read_b128 v[184:187], v154 offset:49152
	ds_read_b128 v[154:157], v154 offset:50176
	ds_read_b128 v[188:191], v153 offset:49152
	ds_read_b128 v[192:195], v153 offset:50176
	ds_read_b128 v[196:199], v152 offset:49152
	ds_read_b128 v[200:203], v152 offset:50176
	s_barrier
	s_waitcnt lgkmcnt(0)
	s_waitcnt lgkmcnt(0)
	v_mfma_f32_16x16x32_bf16 v[24:27], v[4:7], v[176:179], v[60:63]
	v_mfma_f32_16x16x32_bf16 v[60:63], v[20:23], v[176:179], v[56:59]
	v_mfma_f32_16x16x32_bf16 v[204:207], v[4:7], v[184:187], v[52:55]
	v_mfma_f32_16x16x32_bf16 v[48:51], v[20:23], v[184:187], v[48:51]
	v_mfma_f32_16x16x32_bf16 v[44:47], v[4:7], v[188:191], v[44:47]
	v_mfma_f32_16x16x32_bf16 v[208:211], v[20:23], v[188:191], v[40:43]
	v_mfma_f32_16x16x32_bf16 v[4:7], v[4:7], v[196:199], v[36:39]
	v_mfma_f32_16x16x32_bf16 v[32:35], v[20:23], v[196:199], v[32:35]
	v_mfma_f32_16x16x32_bf16 v[56:59], v[8:11], v[180:183], v[24:27]
	v_mfma_f32_16x16x32_bf16 v[52:55], v[158:161], v[180:183], v[60:63]
	v_mfma_f32_16x16x32_bf16 v[40:43], v[8:11], v[154:157], v[204:207]
	v_mfma_f32_16x16x32_bf16 v[36:39], v[158:161], v[154:157], v[48:51]
	v_mfma_f32_16x16x32_bf16 v[24:27], v[8:11], v[192:195], v[44:47]
	v_mfma_f32_16x16x32_bf16 v[20:23], v[158:161], v[192:195], v[208:211]
	v_mfma_f32_16x16x32_bf16 v[8:11], v[8:11], v[200:203], v[4:7]
	v_mfma_f32_16x16x32_bf16 v[4:7], v[158:161], v[200:203], v[32:35]
	v_mfma_f32_16x16x32_bf16 v[28:31], v[222:225], v[176:179], v[28:31]
	v_mfma_f32_16x16x32_bf16 v[32:35], v[230:233], v[176:179], v[134:137]
	v_mfma_f32_16x16x32_bf16 v[44:47], v[222:225], v[184:187], v[138:141]
	v_mfma_f32_16x16x32_bf16 v[16:19], v[230:233], v[184:187], v[16:19]
	v_mfma_f32_16x16x32_bf16 v[12:15], v[222:225], v[188:191], v[12:15]
	v_mfma_f32_16x16x32_bf16 v[134:137], v[230:233], v[188:191], v[142:145]
	v_mfma_f32_16x16x32_bf16 v[138:141], v[222:225], v[196:199], v[172:175]
	v_mfma_f32_16x16x32_bf16 v[0:3], v[230:233], v[196:199], v[0:3]
	v_mfma_f32_16x16x32_bf16 v[60:63], v[226:229], v[180:183], v[28:31]
	v_mfma_f32_16x16x32_bf16 v[48:51], v[234:237], v[180:183], v[32:35]
	v_mfma_f32_16x16x32_bf16 v[44:47], v[226:229], v[154:157], v[44:47]
	v_mfma_f32_16x16x32_bf16 v[32:35], v[234:237], v[154:157], v[16:19]
	v_mfma_f32_16x16x32_bf16 v[28:31], v[226:229], v[192:195], v[12:15]
	v_mfma_f32_16x16x32_bf16 v[16:19], v[234:237], v[192:195], v[134:137]
	v_mfma_f32_16x16x32_bf16 v[12:15], v[226:229], v[200:203], v[138:141]
	v_mfma_f32_16x16x32_bf16 v[0:3], v[234:237], v[200:203], v[0:3]
	v_cmp_gt_u32_e32 vcc, s69, v130
	s_barrier
	s_and_saveexec_b64 s[50:51], vcc
	s_cbranch_execz .LBB0_841
	s_barrier

; #define STAGE(P, BASE, LD, br, kt) do { const char* _g = (const char*)((BASE) + (size_t)(br) * (LD) + (size_t)(kt) * 64); \
;     for (int _i = 0; _i < 2; ++_i) { int _b = tidx * 16 + _i * 8192; int _r, _c; stage_rc(_b, _r, _c); \
;       __builtin_amdgcn_global_load_lds((const unsigned*)(_g + (unsigned)((_r * (LD) + _c) * 2)), (unsigned*)((char*)(P) + _b), 16, 0, 0); } } while (0)
; #define LDA(dst, b, h) for (int m = 0; m < 4; ++m) for (int k = 0; k < 2; ++k) \
;     dst[m][k] = *reinterpret_cast<const bf16x8*>((char*)SA(b, h) + lds_byte(wr * 64 + m * 16 + fr, k * 32 + fq * 8))
; #define LDB(dst, b, h) for (int n = 0; n < 2; ++n) for (int k = 0; k < 2; ++k) \
;     dst[n][k] = *reinterpret_cast<const bf16x8*>((char*)SB(b, h) + lds_byte(wc * 32 + n * 16 + fr, k * 32 + fq * 8))
; #define MMA(ai, bj, At_, Bt_) do { __builtin_amdgcn_s_setprio(1); \
;     for (int k = 0; k < 2; ++k) for (int m = 0; m < 4; ++m) for (int n = 0; n < 2; ++n) \
;       acc[ai][bj][m][n] = __builtin_amdgcn_mfma_f32_16x16x32_bf16(At_[m][k], Bt_[n][k], acc[ai][bj][m][n], 0, 0, 0); \
;     __builtin_amdgcn_s_setprio(0); } while (0)
; #define WAIT_L(n) asm volatile("s_waitcnt lgkmcnt(" #n ")" ::: "memory")
; #define BAR __builtin_amdgcn_s_barrier()
; #define SCHED __builtin_amdgcn_sched_barrier(0)
; template <int EPI, int lda, int ldb, int N, int K>
; __device__ __forceinline__ void gemm_phase(const u16* __restrict__ A, const u16* __restrict__ Bt, const GemmEpi ep, int wv) {
;     ...
;     for (int t = 0; t < nt - 2; t += 2) {
;       LDB(B0, 0, 0); SCHED; LDA(At, 0, 0); STAGE(SA(1, 1), Ab, lda, brow + HALF, t + 1);
;       WAIT_L(8); BAR; WAIT_L(0); MMA(0, 0, At, B0); BAR; SCHED;
;       LDB(B1, 0, 1); STAGE(SB(0, 0), Bt, ldb, bcol, t + 2);
;       BAR; WAIT_L(0); MMA(0, 1, At, B1); BAR;
;       LDA(At, 0, 1); STAGE(SA(0, 0), Ab, lda, brow, t + 2);
;       BAR; WAIT_L(0); MMA(1, 0, At, B0); BAR; SCHED;
.LBB0_1147:
	ds_read_b128 v[172:175], v161
	ds_read_b128 v[176:179], v161 offset:1024
	ds_read_b128 v[180:183], v161 offset:2048
	ds_read_b128 v[184:187], v161 offset:3072
	v_add_u32_e32 v169, 0xc000, v148
	v_lshl_add_u64 v[236:237], v[138:139], 0, s[60:61]
	v_readfirstlane_b32 s63, v169
	v_add_u32_e32 v170, 0xe000, v148
	v_lshl_add_u64 v[162:163], v[236:237], 0, s[22:23]
	s_mov_b32 m0, s63
	v_lshl_add_u64 v[238:239], v[140:141], 0, s[60:61]
	v_readfirstlane_b32 s63, v170
	ds_read_b128 v[164:167], v152
	ds_read_b128 v[188:191], v152 offset:1024
	ds_read_b128 v[192:195], v151
	ds_read_b128 v[196:199], v151 offset:1024
	ds_read_b128 v[200:203], v150
	ds_read_b128 v[204:207], v150 offset:1024
	ds_read_b128 v[208:211], v149
	ds_read_b128 v[212:215], v149 offset:1024
	global_load_lds_dwordx4 v[162:163], off
	s_nop 1
	v_lshl_add_u64 v[162:163], v[238:239], 0, s[22:23]
	s_mov_b32 m0, s63
	s_nop 0
	global_load_lds_dwordx4 v[162:163], off
	s_waitcnt lgkmcnt(8)
	s_barrier
	s_waitcnt lgkmcnt(0)
	s_waitcnt lgkmcnt(0)
	v_mfma_f32_16x16x32_bf16 v[124:127], v[164:167], v[172:175], v[124:127]
	v_mfma_f32_16x16x32_bf16 v[120:123], v[164:167], v[180:183], v[120:123]
	v_mfma_f32_16x16x32_bf16 v[116:119], v[192:195], v[172:175], v[116:119]
	v_mfma_f32_16x16x32_bf16 v[112:115], v[192:195], v[180:183], v[112:115]
	v_mfma_f32_16x16x32_bf16 v[108:111], v[200:203], v[172:175], v[108:111]
	v_mfma_f32_16x16x32_bf16 v[104:107], v[200:203], v[180:183], v[104:107]
	v_mfma_f32_16x16x32_bf16 v[100:103], v[208:211], v[172:175], v[100:103]
	v_mfma_f32_16x16x32_bf16 v[96:99], v[208:211], v[180:183], v[96:99]
	v_mfma_f32_16x16x32_bf16 v[124:127], v[188:191], v[176:179], v[124:127]
	v_mfma_f32_16x16x32_bf16 v[120:123], v[188:191], v[184:187], v[120:123]
	v_mfma_f32_16x16x32_bf16 v[116:119], v[196:199], v[176:179], v[116:119]
	v_mfma_f32_16x16x32_bf16 v[112:115], v[196:199], v[184:187], v[112:115]
	v_mfma_f32_16x16x32_bf16 v[108:111], v[204:207], v[176:179], v[108:111]
	v_mfma_f32_16x16x32_bf16 v[104:107], v[204:207], v[184:187], v[104:107]
	v_mfma_f32_16x16x32_bf16 v[100:103], v[212:215], v[176:179], v[100:103]
	v_mfma_f32_16x16x32_bf16 v[96:99], v[212:215], v[184:187], v[96:99]
	s_barrier
	v_add_u32_e32 v162, s75, v154
	v_lshl_add_u64 v[240:241], v[134:135], 0, s[60:61]
	v_readfirstlane_b32 s63, v162
	v_add_u32_e32 v163, 0x2000, v162
	v_lshl_add_u64 v[232:233], v[240:241], 0, s[24:25]
	s_mov_b32 m0, s63
	v_lshl_add_u64 v[242:243], v[136:137], 0, s[60:61]
	v_readfirstlane_b32 s63, v163
	ds_read_b128 v[216:219], v160
	ds_read_b128 v[220:223], v160 offset:1024
	ds_read_b128 v[224:227], v160 offset:2048
	ds_read_b128 v[228:231], v160 offset:3072
	global_load_lds_dwordx4 v[232:233], off
	s_nop 1
	v_lshl_add_u64 v[232:233], v[242:243], 0, s[24:25]
	s_mov_b32 m0, s63
	s_nop 0
	global_load_lds_dwordx4 v[232:233], off
	s_barrier
	s_waitcnt lgkmcnt(0)
	s_waitcnt lgkmcnt(0)
	v_mfma_f32_16x16x32_bf16 v[92:95], v[164:167], v[216:219], v[92:95]
	v_mfma_f32_16x16x32_bf16 v[88:91], v[164:167], v[224:227], v[88:91]
	v_mfma_f32_16x16x32_bf16 v[84:87], v[192:195], v[216:219], v[84:87]
	v_mfma_f32_16x16x32_bf16 v[80:83], v[192:195], v[224:227], v[80:83]
	v_mfma_f32_16x16x32_bf16 v[76:79], v[200:203], v[216:219], v[76:79]
	v_mfma_f32_16x16x32_bf16 v[72:75], v[200:203], v[224:227], v[72:75]
	v_mfma_f32_16x16x32_bf16 v[68:71], v[208:211], v[216:219], v[68:71]
	v_mfma_f32_16x16x32_bf16 v[64:67], v[208:211], v[224:227], v[64:67]
	v_mfma_f32_16x16x32_bf16 v[92:95], v[188:191], v[220:223], v[92:95]
	v_mfma_f32_16x16x32_bf16 v[88:91], v[188:191], v[228:231], v[88:91]
	v_mfma_f32_16x16x32_bf16 v[84:87], v[196:199], v[220:223], v[84:87]
	v_mfma_f32_16x16x32_bf16 v[80:83], v[196:199], v[228:231], v[80:83]
	v_mfma_f32_16x16x32_bf16 v[76:79], v[204:207], v[220:223], v[76:79]
	v_mfma_f32_16x16x32_bf16 v[72:75], v[204:207], v[228:231], v[72:75]
	v_mfma_f32_16x16x32_bf16 v[68:71], v[212:215], v[220:223], v[68:71]
	v_mfma_f32_16x16x32_bf16 v[64:67], v[212:215], v[228:231], v[64:67]
	v_readfirstlane_b32 s63, v148
	v_lshl_add_u64 v[164:165], v[236:237], 0, s[26:27]
	s_mov_b32 m0, s63
	s_barrier
	ds_read_b128 v[188:191], v152 offset:16384
	ds_read_b128 v[192:195], v152 offset:17408
	ds_read_b128 v[196:199], v151 offset:16384
	ds_read_b128 v[200:203], v151 offset:17408
	ds_read_b128 v[204:207], v150 offset:16384
	ds_read_b128 v[208:211], v150 offset:17408
	ds_read_b128 v[212:215], v149 offset:16384
	ds_read_b128 v[232:235], v149 offset:17408
	global_load_lds_dwordx4 v[164:165], off
	s_nop 1
	v_add_u32_e32 v164, 0x2000, v148
	v_lshl_add_u64 v[166:167], v[238:239], 0, s[26:27]
	v_readfirstlane_b32 s63, v164
	s_mov_b32 m0, s63
	s_nop 0
	global_load_lds_dwordx4 v[166:167], off
	s_barrier
	s_waitcnt lgkmcnt(0)
	s_waitcnt lgkmcnt(0)
	v_mfma_f32_16x16x32_bf16 v[60:63], v[188:191], v[172:175], v[60:63]
	v_mfma_f32_16x16x32_bf16 v[56:59], v[188:191], v[180:183], v[56:59]
	v_mfma_f32_16x16x32_bf16 v[52:55], v[196:199], v[172:175], v[52:55]
	v_mfma_f32_16x16x32_bf16 v[48:51], v[196:199], v[180:183], v[48:51]
	v_mfma_f32_16x16x32_bf16 v[44:47], v[204:207], v[172:175], v[44:47]
	v_mfma_f32_16x16x32_bf16 v[40:43], v[204:207], v[180:183], v[40:43]
	v_mfma_f32_16x16x32_bf16 v[36:39], v[212:215], v[172:175], v[36:39]
	v_mfma_f32_16x16x32_bf16 v[32:35], v[212:215], v[180:183], v[32:35]
	v_mfma_f32_16x16x32_bf16 v[60:63], v[192:195], v[176:179], v[60:63]
	v_mfma_f32_16x16x32_bf16 v[56:59], v[192:195], v[184:187], v[56:59]
	v_mfma_f32_16x16x32_bf16 v[52:55], v[200:203], v[176:179], v[52:55]
	v_mfma_f32_16x16x32_bf16 v[48:51], v[200:203], v[184:187], v[48:51]
	v_mfma_f32_16x16x32_bf16 v[44:47], v[208:211], v[176:179], v[44:47]
	v_mfma_f32_16x16x32_bf16 v[40:43], v[208:211], v[184:187], v[40:43]
	v_mfma_f32_16x16x32_bf16 v[36:39], v[232:235], v[176:179], v[36:39]
	v_mfma_f32_16x16x32_bf16 v[32:35], v[232:235], v[184:187], v[32:35]
	s_barrier
; #define STAGE(P, BASE, LD, br, kt) do { const char* _g = (const char*)((BASE) + (size_t)(br) * (LD) + (size_t)(kt) * 64); \
;     for (int _i = 0; _i < 2; ++_i) { int _b = tidx * 16 + _i * 8192; int _r, _c; stage_rc(_b, _r, _c); \
;       __builtin_amdgcn_global_load_lds((const unsigned*)(_g + (unsigned)((_r * (LD) + _c) * 2)), (unsigned*)((char*)(P) + _b), 16, 0, 0); } } while (0)
; #define LDA(dst, b, h) for (int m = 0; m < 4; ++m) for (int k = 0; k < 2; ++k) \
;     dst[m][k] = *reinterpret_cast<const bf16x8*>((char*)SA(b, h) + lds_byte(wr * 64 + m * 16 + fr, k * 32 + fq * 8))
; #define LDB(dst, b, h) for (int n = 0; n < 2; ++n) for (int k = 0; k < 2; ++k) \
;     dst[n][k] = *reinterpret_cast<const bf16x8*>((char*)SB(b, h) + lds_byte(wc * 32 + n * 16 + fr, k * 32 + fq * 8))
; #define MMA(ai, bj, At_, Bt_) do { __builtin_amdgcn_s_setprio(1); \
;     for (int k = 0; k < 2; ++k) for (int m = 0; m < 4; ++m) for (int n = 0; n < 2; ++n) \
;       acc[ai][bj][m][n] = __builtin_amdgcn_mfma_f32_16x16x32_bf16(At_[m][k], Bt_[n][k], acc[ai][bj][m][n], 0, 0, 0); \
;     __builtin_amdgcn_s_setprio(0); } while (0)
; #define WAIT_V(n) asm volatile("s_waitcnt vmcnt(" #n ")" ::: "memory")
; #define WAIT_L(n) asm volatile("s_waitcnt lgkmcnt(" #n ")" ::: "memory")
; #define BAR __builtin_amdgcn_s_barrier()
; #define SCHED __builtin_amdgcn_sched_barrier(0)
; template <int EPI, int lda, int ldb, int N, int K>
; __device__ __forceinline__ void gemm_phase(const u16* __restrict__ A, const u16* __restrict__ Bt, const GemmEpi ep, int wv) {
;     ...
;       STAGE(SB(0, 1), Bt, ldb, bcol + HALF, t + 2);
;       WAIT_V(6); BAR; MMA(1, 1, At, B1); BAR;
;       LDB(B0, 1, 0); SCHED; LDA(At, 1, 0); STAGE(SA(0, 1), Ab, lda, brow + HALF, t + 2);
;       WAIT_L(8); BAR; WAIT_L(0); MMA(0, 0, At, B0); BAR; SCHED;
;       LDB(B1, 1, 1); STAGE(SB(1, 0), Bt, ldb, bcol, t + 3);
;       BAR; WAIT_L(0); MMA(0, 1, At, B1); BAR;
;       LDA(At, 1, 1); STAGE(SA(1, 0), Ab, lda, brow, t + 3);
	v_add_u32_e32 v165, s76, v154
	v_lshl_add_u64 v[166:167], v[240:241], 0, s[40:41]
	v_readfirstlane_b32 s63, v165
	s_mov_b32 m0, s63
	v_lshl_add_u64 v[172:173], v[242:243], 0, s[40:41]
	global_load_lds_dwordx4 v[166:167], off
	s_nop 1
	v_add_u32_e32 v166, 0x2000, v165
	s_nop 0
	v_readfirstlane_b32 s63, v166
	s_mov_b32 m0, s63
	s_nop 0
	global_load_lds_dwordx4 v[172:173], off
	s_waitcnt vmcnt(6)
	s_barrier
	v_mfma_f32_16x16x32_bf16 v[28:31], v[188:191], v[216:219], v[28:31]
	v_mfma_f32_16x16x32_bf16 v[24:27], v[188:191], v[224:227], v[24:27]
	v_mfma_f32_16x16x32_bf16 v[20:23], v[196:199], v[216:219], v[20:23]
	v_mfma_f32_16x16x32_bf16 v[16:19], v[196:199], v[224:227], v[16:19]
	v_mfma_f32_16x16x32_bf16 v[12:15], v[204:207], v[216:219], v[12:15]
	v_mfma_f32_16x16x32_bf16 v[8:11], v[204:207], v[224:227], v[8:11]
	v_mfma_f32_16x16x32_bf16 v[4:7], v[212:215], v[216:219], v[4:7]
	v_mfma_f32_16x16x32_bf16 v[0:3], v[212:215], v[224:227], v[0:3]
	v_mfma_f32_16x16x32_bf16 v[28:31], v[192:195], v[220:223], v[28:31]
	v_mfma_f32_16x16x32_bf16 v[24:27], v[192:195], v[228:231], v[24:27]
	v_mfma_f32_16x16x32_bf16 v[20:23], v[200:203], v[220:223], v[20:23]
	v_mfma_f32_16x16x32_bf16 v[16:19], v[200:203], v[228:231], v[16:19]
	v_mfma_f32_16x16x32_bf16 v[12:15], v[208:211], v[220:223], v[12:15]
	v_mfma_f32_16x16x32_bf16 v[8:11], v[208:211], v[228:231], v[8:11]
	v_mfma_f32_16x16x32_bf16 v[4:7], v[232:235], v[220:223], v[4:7]
	v_mfma_f32_16x16x32_bf16 v[0:3], v[232:235], v[228:231], v[0:3]
	s_barrier
	ds_read_b128 v[172:175], v155
	ds_read_b128 v[176:179], v155 offset:1024
	ds_read_b128 v[180:183], v155 offset:2048
	ds_read_b128 v[184:187], v155 offset:3072
	v_add_u32_e32 v167, 0x4000, v148
	v_add_u32_e32 v168, 0x6000, v148
	v_readfirstlane_b32 s63, v167
	v_lshl_add_u64 v[220:221], v[236:237], 0, s[42:43]
	s_mov_b32 m0, s63
	v_readfirstlane_b32 s63, v168
	ds_read_b128 v[188:191], v152 offset:32768
	ds_read_b128 v[192:195], v152 offset:33792
	ds_read_b128 v[196:199], v151 offset:32768
	ds_read_b128 v[200:203], v151 offset:33792
	ds_read_b128 v[204:207], v150 offset:32768
	ds_read_b128 v[208:211], v150 offset:33792
	ds_read_b128 v[212:215], v149 offset:32768
	ds_read_b128 v[216:219], v149 offset:33792
	global_load_lds_dwordx4 v[220:221], off
	s_nop 1
	v_lshl_add_u64 v[220:221], v[238:239], 0, s[42:43]
	s_mov_b32 m0, s63
	s_nop 0
	global_load_lds_dwordx4 v[220:221], off
	s_waitcnt lgkmcnt(8)
	s_barrier
	s_waitcnt lgkmcnt(0)
	s_waitcnt lgkmcnt(0)
	v_mfma_f32_16x16x32_bf16 v[124:127], v[188:191], v[172:175], v[124:127]
	v_mfma_f32_16x16x32_bf16 v[120:123], v[188:191], v[180:183], v[120:123]
	v_mfma_f32_16x16x32_bf16 v[116:119], v[196:199], v[172:175], v[116:119]
	v_mfma_f32_16x16x32_bf16 v[112:115], v[196:199], v[180:183], v[112:115]
	v_mfma_f32_16x16x32_bf16 v[108:111], v[204:207], v[172:175], v[108:111]
	v_mfma_f32_16x16x32_bf16 v[104:107], v[204:207], v[180:183], v[104:107]
	v_mfma_f32_16x16x32_bf16 v[100:103], v[212:215], v[172:175], v[100:103]
	v_mfma_f32_16x16x32_bf16 v[96:99], v[212:215], v[180:183], v[96:99]
	v_mfma_f32_16x16x32_bf16 v[124:127], v[192:195], v[176:179], v[124:127]
	v_mfma_f32_16x16x32_bf16 v[120:123], v[192:195], v[184:187], v[120:123]
	v_mfma_f32_16x16x32_bf16 v[116:119], v[200:203], v[176:179], v[116:119]
	v_mfma_f32_16x16x32_bf16 v[112:115], v[200:203], v[184:187], v[112:115]
	v_mfma_f32_16x16x32_bf16 v[108:111], v[208:211], v[176:179], v[108:111]
	v_mfma_f32_16x16x32_bf16 v[104:107], v[208:211], v[184:187], v[104:107]
	v_mfma_f32_16x16x32_bf16 v[100:103], v[216:219], v[176:179], v[100:103]
	v_mfma_f32_16x16x32_bf16 v[96:99], v[216:219], v[184:187], v[96:99]
	s_barrier
	v_readfirstlane_b32 s63, v156
	v_add_u32_e32 v171, 0x2000, v156
	v_lshl_add_u64 v[244:245], v[240:241], 0, s[44:45]
	s_mov_b32 m0, s63
	v_readfirstlane_b32 s63, v171
	ds_read_b128 v[220:223], v153
	ds_read_b128 v[224:227], v153 offset:1024
	ds_read_b128 v[228:231], v153 offset:2048
	ds_read_b128 v[232:235], v153 offset:3072
	global_load_lds_dwordx4 v[244:245], off
	s_nop 1
	v_lshl_add_u64 v[244:245], v[242:243], 0, s[44:45]
	s_mov_b32 m0, s63
	s_nop 0
	global_load_lds_dwordx4 v[244:245], off
	s_barrier
	s_waitcnt lgkmcnt(0)
	s_waitcnt lgkmcnt(0)
	v_mfma_f32_16x16x32_bf16 v[92:95], v[188:191], v[220:223], v[92:95]
	v_mfma_f32_16x16x32_bf16 v[88:91], v[188:191], v[228:231], v[88:91]
	v_mfma_f32_16x16x32_bf16 v[84:87], v[196:199], v[220:223], v[84:87]
	v_mfma_f32_16x16x32_bf16 v[80:83], v[196:199], v[228:231], v[80:83]
	v_mfma_f32_16x16x32_bf16 v[76:79], v[204:207], v[220:223], v[76:79]
	v_mfma_f32_16x16x32_bf16 v[72:75], v[204:207], v[228:231], v[72:75]
	v_mfma_f32_16x16x32_bf16 v[68:71], v[212:215], v[220:223], v[68:71]
	v_mfma_f32_16x16x32_bf16 v[64:67], v[212:215], v[228:231], v[64:67]
	v_mfma_f32_16x16x32_bf16 v[92:95], v[192:195], v[224:227], v[92:95]
	v_mfma_f32_16x16x32_bf16 v[88:91], v[192:195], v[232:235], v[88:91]
	v_mfma_f32_16x16x32_bf16 v[84:87], v[200:203], v[224:227], v[84:87]
	v_mfma_f32_16x16x32_bf16 v[80:83], v[200:203], v[232:235], v[80:83]
	v_mfma_f32_16x16x32_bf16 v[76:79], v[208:211], v[224:227], v[76:79]
	v_mfma_f32_16x16x32_bf16 v[72:75], v[208:211], v[232:235], v[72:75]
	v_mfma_f32_16x16x32_bf16 v[68:71], v[216:219], v[224:227], v[68:71]
	v_mfma_f32_16x16x32_bf16 v[64:67], v[216:219], v[232:235], v[64:67]
	v_readfirstlane_b32 s63, v157
	v_lshl_add_u64 v[236:237], v[236:237], 0, s[46:47]
	s_mov_b32 m0, s63
	v_readfirstlane_b32 s63, v158
	s_barrier
; #define STAGE(P, BASE, LD, br, kt) do { const char* _g = (const char*)((BASE) + (size_t)(br) * (LD) + (size_t)(kt) * 64); \
;     for (int _i = 0; _i < 2; ++_i) { int _b = tidx * 16 + _i * 8192; int _r, _c; stage_rc(_b, _r, _c); \
;       __builtin_amdgcn_global_load_lds((const unsigned*)(_g + (unsigned)((_r * (LD) + _c) * 2)), (unsigned*)((char*)(P) + _b), 16, 0, 0); } } while (0)
; #define LDA(dst, b, h) for (int m = 0; m < 4; ++m) for (int k = 0; k < 2; ++k) \
;     dst[m][k] = *reinterpret_cast<const bf16x8*>((char*)SA(b, h) + lds_byte(wr * 64 + m * 16 + fr, k * 32 + fq * 8))
; #define LDB(dst, b, h) for (int n = 0; n < 2; ++n) for (int k = 0; k < 2; ++k) \
;     dst[n][k] = *reinterpret_cast<const bf16x8*>((char*)SB(b, h) + lds_byte(wc * 32 + n * 16 + fr, k * 32 + fq * 8))
; #define MMA(ai, bj, At_, Bt_) do { __builtin_amdgcn_s_setprio(1); \
;     for (int k = 0; k < 2; ++k) for (int m = 0; m < 4; ++m) for (int n = 0; n < 2; ++n) \
;       acc[ai][bj][m][n] = __builtin_amdgcn_mfma_f32_16x16x32_bf16(At_[m][k], Bt_[n][k], acc[ai][bj][m][n], 0, 0, 0); \
;     __builtin_amdgcn_s_setprio(0); } while (0)
; #define WAIT_V(n) asm volatile("s_waitcnt vmcnt(" #n ")" ::: "memory")
; #define WAIT_L(n) asm volatile("s_waitcnt lgkmcnt(" #n ")" ::: "memory")
; #define BAR __builtin_amdgcn_s_barrier()
; #define SCHED __builtin_amdgcn_sched_barrier(0)
; template <int EPI, int lda, int ldb, int N, int K>
; __device__ __forceinline__ void gemm_phase(const u16* __restrict__ A, const u16* __restrict__ Bt, const GemmEpi ep, int wv) {
;     ...
;       LDA(At, 1, 1); STAGE(SA(1, 0), Ab, lda, brow, t + 3);
;       BAR; WAIT_L(0); MMA(1, 0, At, B0); BAR; SCHED;
;       STAGE(SB(1, 1), Bt, ldb, bcol + HALF, t + 3);
;       WAIT_V(6); BAR; MMA(1, 1, At, B1); BAR;
;     }
;     { LDB(B0, 0, 0); LDA(At, 0, 0); STAGE(SA(1, 1), Ab, lda, brow + HALF, nt - 1);
;       BAR; WAIT_L(0); MMA(0, 0, At, B0); BAR;
;       LDB(B1, 0, 1); BAR; WAIT_L(0); MMA(0, 1, At, B1); BAR;
	ds_read_b128 v[188:191], v152 offset:49152
	ds_read_b128 v[192:195], v152 offset:50176
	ds_read_b128 v[196:199], v151 offset:49152
	ds_read_b128 v[200:203], v151 offset:50176
	ds_read_b128 v[204:207], v150 offset:49152
	ds_read_b128 v[208:211], v150 offset:50176
	ds_read_b128 v[212:215], v149 offset:49152
	ds_read_b128 v[216:219], v149 offset:50176
	global_load_lds_dwordx4 v[236:237], off
	s_nop 1
	v_lshl_add_u64 v[236:237], v[238:239], 0, s[46:47]
	s_mov_b32 m0, s63
	s_nop 0
	global_load_lds_dwordx4 v[236:237], off
	s_barrier
	s_waitcnt lgkmcnt(0)
	s_waitcnt lgkmcnt(0)
	v_mfma_f32_16x16x32_bf16 v[60:63], v[188:191], v[172:175], v[60:63]
	v_mfma_f32_16x16x32_bf16 v[56:59], v[188:191], v[180:183], v[56:59]
	v_mfma_f32_16x16x32_bf16 v[52:55], v[196:199], v[172:175], v[52:55]
	v_mfma_f32_16x16x32_bf16 v[48:51], v[196:199], v[180:183], v[48:51]
	v_mfma_f32_16x16x32_bf16 v[44:47], v[204:207], v[172:175], v[44:47]
	v_mfma_f32_16x16x32_bf16 v[40:43], v[204:207], v[180:183], v[40:43]
	v_mfma_f32_16x16x32_bf16 v[36:39], v[212:215], v[172:175], v[36:39]
	v_mfma_f32_16x16x32_bf16 v[32:35], v[212:215], v[180:183], v[32:35]
	v_mfma_f32_16x16x32_bf16 v[60:63], v[192:195], v[176:179], v[60:63]
	v_mfma_f32_16x16x32_bf16 v[56:59], v[192:195], v[184:187], v[56:59]
	v_mfma_f32_16x16x32_bf16 v[52:55], v[200:203], v[176:179], v[52:55]
	v_mfma_f32_16x16x32_bf16 v[48:51], v[200:203], v[184:187], v[48:51]
	v_mfma_f32_16x16x32_bf16 v[44:47], v[208:211], v[176:179], v[44:47]
	v_mfma_f32_16x16x32_bf16 v[40:43], v[208:211], v[184:187], v[40:43]
	v_mfma_f32_16x16x32_bf16 v[36:39], v[216:219], v[176:179], v[36:39]
	v_mfma_f32_16x16x32_bf16 v[32:35], v[216:219], v[184:187], v[32:35]
	s_barrier
	v_readfirstlane_b32 s63, v159
	v_add_u32_e32 v171, 0x2000, v159
	v_lshl_add_u64 v[172:173], v[240:241], 0, s[48:49]
	s_mov_b32 m0, s63
	v_readfirstlane_b32 s63, v171
	global_load_lds_dwordx4 v[172:173], off
	s_nop 1
	v_lshl_add_u64 v[172:173], v[242:243], 0, s[48:49]
	s_mov_b32 m0, s63
	s_nop 0
	global_load_lds_dwordx4 v[172:173], off
	s_waitcnt vmcnt(6)
	s_barrier
	v_mfma_f32_16x16x32_bf16 v[28:31], v[188:191], v[220:223], v[28:31]
	v_mfma_f32_16x16x32_bf16 v[24:27], v[188:191], v[228:231], v[24:27]
	v_mfma_f32_16x16x32_bf16 v[20:23], v[196:199], v[220:223], v[20:23]
	v_mfma_f32_16x16x32_bf16 v[16:19], v[196:199], v[228:231], v[16:19]
	v_mfma_f32_16x16x32_bf16 v[12:15], v[204:207], v[220:223], v[12:15]
	v_mfma_f32_16x16x32_bf16 v[8:11], v[204:207], v[228:231], v[8:11]
	v_mfma_f32_16x16x32_bf16 v[4:7], v[212:215], v[220:223], v[4:7]
	v_mfma_f32_16x16x32_bf16 v[0:3], v[212:215], v[228:231], v[0:3]
	v_mfma_f32_16x16x32_bf16 v[28:31], v[192:195], v[224:227], v[28:31]
	v_mfma_f32_16x16x32_bf16 v[24:27], v[192:195], v[232:235], v[24:27]
	v_mfma_f32_16x16x32_bf16 v[20:23], v[200:203], v[224:227], v[20:23]
	v_mfma_f32_16x16x32_bf16 v[16:19], v[200:203], v[232:235], v[16:19]
	v_mfma_f32_16x16x32_bf16 v[12:15], v[208:211], v[224:227], v[12:15]
	v_mfma_f32_16x16x32_bf16 v[8:11], v[208:211], v[232:235], v[8:11]
	v_mfma_f32_16x16x32_bf16 v[4:7], v[216:219], v[224:227], v[4:7]
	v_mfma_f32_16x16x32_bf16 v[0:3], v[216:219], v[232:235], v[0:3]
	s_add_i32 s62, s62, 2
	s_add_u32 s60, s60, 0x100
	s_addc_u32 s61, s61, 0
	s_cmp_gt_u32 s62, 27
	s_barrier
	s_cbranch_scc0 .LBB0_1147
	s_add_i32 s60, s58, 0x80
	s_mul_hi_i32 s61, s60, 0x1080
	s_mulk_i32 s60, 0x1080
	s_add_u32 s60, s69, s60
	s_addc_u32 s61, s70, s61
	v_lshl_add_u64 v[208:209], s[60:61], 0, v[128:129]
	v_readfirstlane_b32 s62, v169
	v_lshl_add_u64 v[208:209], v[208:209], 0, s[50:51]
	s_mov_b32 m0, s62
	ds_read_b128 v[134:137], v161
	ds_read_b128 v[138:141], v161 offset:1024
	ds_read_b128 v[156:159], v161 offset:2048
	ds_read_b128 v[172:175], v161 offset:3072
	ds_read_b128 v[176:179], v152
	ds_read_b128 v[180:183], v152 offset:1024
	ds_read_b128 v[184:187], v151
	ds_read_b128 v[188:191], v151 offset:1024
	ds_read_b128 v[192:195], v150
	ds_read_b128 v[196:199], v150 offset:1024
	ds_read_b128 v[200:203], v149
	ds_read_b128 v[204:207], v149 offset:1024
	global_load_lds_dwordx4 v[208:209], off
	v_lshl_add_u64 v[208:209], s[60:61], 0, v[132:133]
	v_readfirstlane_b32 s60, v170
	v_lshl_add_u64 v[208:209], v[208:209], 0, s[50:51]
	s_mov_b32 m0, s60
	s_nop 0
	global_load_lds_dwordx4 v[208:209], off
	s_barrier
	s_waitcnt lgkmcnt(0)
	s_waitcnt lgkmcnt(0)
	v_mfma_f32_16x16x32_bf16 v[124:127], v[176:179], v[134:137], v[124:127]
	v_mfma_f32_16x16x32_bf16 v[120:123], v[176:179], v[156:159], v[120:123]
	v_mfma_f32_16x16x32_bf16 v[116:119], v[184:187], v[134:137], v[116:119]
	v_mfma_f32_16x16x32_bf16 v[112:115], v[184:187], v[156:159], v[112:115]
	v_mfma_f32_16x16x32_bf16 v[108:111], v[192:195], v[134:137], v[108:111]
	v_mfma_f32_16x16x32_bf16 v[104:107], v[192:195], v[156:159], v[104:107]
	v_mfma_f32_16x16x32_bf16 v[100:103], v[200:203], v[134:137], v[100:103]
	v_mfma_f32_16x16x32_bf16 v[96:99], v[200:203], v[156:159], v[96:99]
	v_mfma_f32_16x16x32_bf16 v[124:127], v[180:183], v[138:141], v[124:127]
	v_mfma_f32_16x16x32_bf16 v[120:123], v[180:183], v[172:175], v[120:123]
	v_mfma_f32_16x16x32_bf16 v[116:119], v[188:191], v[138:141], v[116:119]
	v_mfma_f32_16x16x32_bf16 v[112:115], v[188:191], v[172:175], v[112:115]
	v_mfma_f32_16x16x32_bf16 v[108:111], v[196:199], v[138:141], v[108:111]
	v_mfma_f32_16x16x32_bf16 v[104:107], v[196:199], v[172:175], v[104:107]
	v_mfma_f32_16x16x32_bf16 v[100:103], v[204:207], v[138:141], v[100:103]
	v_mfma_f32_16x16x32_bf16 v[96:99], v[204:207], v[172:175], v[96:99]
	s_barrier
	ds_read_b128 v[208:211], v160
	ds_read_b128 v[212:215], v160 offset:1024
	ds_read_b128 v[216:219], v160 offset:2048
	ds_read_b128 v[220:223], v160 offset:3072
	s_barrier
; #define LDA(dst, b, h) for (int m = 0; m < 4; ++m) for (int k = 0; k < 2; ++k) \
;     dst[m][k] = *reinterpret_cast<const bf16x8*>((char*)SA(b, h) + lds_byte(wr * 64 + m * 16 + fr, k * 32 + fq * 8))
; #define LDB(dst, b, h) for (int n = 0; n < 2; ++n) for (int k = 0; k < 2; ++k) \
;     dst[n][k] = *reinterpret_cast<const bf16x8*>((char*)SB(b, h) + lds_byte(wc * 32 + n * 16 + fr, k * 32 + fq * 8))
; #define MMA(ai, bj, At_, Bt_) do { __builtin_amdgcn_s_setprio(1); \
;     for (int k = 0; k < 2; ++k) for (int m = 0; m < 4; ++m) for (int n = 0; n < 2; ++n) \
;       acc[ai][bj][m][n] = __builtin_amdgcn_mfma_f32_16x16x32_bf16(At_[m][k], Bt_[n][k], acc[ai][bj][m][n], 0, 0, 0); \
;     __builtin_amdgcn_s_setprio(0); } while (0)
; #define WAIT_V(n) asm volatile("s_waitcnt vmcnt(" #n ")" ::: "memory")
; #define WAIT_L(n) asm volatile("s_waitcnt lgkmcnt(" #n ")" ::: "memory")
; #define BAR __builtin_amdgcn_s_barrier()
; template <int EPI, int lda, int ldb, int N, int K>
; __device__ __forceinline__ void gemm_phase(const u16* __restrict__ A, const u16* __restrict__ Bt, const GemmEpi ep, int wv) {
;     ...
;       LDB(B1, 0, 1); BAR; WAIT_L(0); MMA(0, 1, At, B1); BAR;
;       LDA(At, 0, 1); WAIT_V(4); BAR; WAIT_L(0); MMA(1, 0, At, B0); MMA(1, 1, At, B1); BAR; }
;     { LDB(B0, 1, 0); LDA(At, 1, 0); WAIT_V(2); BAR; WAIT_L(0); MMA(0, 0, At, B0); BAR;
	s_waitcnt lgkmcnt(0)
	s_waitcnt lgkmcnt(0)
	v_mfma_f32_16x16x32_bf16 v[92:95], v[176:179], v[208:211], v[92:95]
	v_mfma_f32_16x16x32_bf16 v[88:91], v[176:179], v[216:219], v[88:91]
	v_mfma_f32_16x16x32_bf16 v[76:79], v[192:195], v[208:211], v[76:79]
	v_mfma_f32_16x16x32_bf16 v[72:75], v[192:195], v[216:219], v[72:75]
	v_mfma_f32_16x16x32_bf16 v[84:87], v[184:187], v[208:211], v[84:87]
	v_mfma_f32_16x16x32_bf16 v[80:83], v[184:187], v[216:219], v[80:83]
	v_mfma_f32_16x16x32_bf16 v[68:71], v[200:203], v[208:211], v[68:71]
	v_mfma_f32_16x16x32_bf16 v[64:67], v[200:203], v[216:219], v[64:67]
	v_mfma_f32_16x16x32_bf16 v[92:95], v[180:183], v[212:215], v[92:95]
	v_mfma_f32_16x16x32_bf16 v[88:91], v[180:183], v[220:223], v[88:91]
	v_mfma_f32_16x16x32_bf16 v[76:79], v[196:199], v[212:215], v[76:79]
	v_mfma_f32_16x16x32_bf16 v[72:75], v[196:199], v[220:223], v[72:75]
	v_mfma_f32_16x16x32_bf16 v[176:179], v[188:191], v[212:215], v[84:87]
	v_mfma_f32_16x16x32_bf16 v[180:183], v[188:191], v[220:223], v[80:83]
	v_mfma_f32_16x16x32_bf16 v[184:187], v[204:207], v[212:215], v[68:71]
	v_mfma_f32_16x16x32_bf16 v[188:191], v[204:207], v[220:223], v[64:67]
	s_barrier
	s_nop 0
	ds_read_b128 v[64:67], v152 offset:16384
	ds_read_b128 v[68:71], v152 offset:17408
	ds_read_b128 v[80:83], v151 offset:16384
	ds_read_b128 v[84:87], v151 offset:17408
	ds_read_b128 v[192:195], v150 offset:16384
	ds_read_b128 v[196:199], v150 offset:17408
	ds_read_b128 v[200:203], v149 offset:16384
	ds_read_b128 v[204:207], v149 offset:17408
	s_waitcnt vmcnt(4)
	s_barrier
	s_waitcnt lgkmcnt(0)
	s_waitcnt lgkmcnt(0)
	v_mfma_f32_16x16x32_bf16 v[60:63], v[64:67], v[134:137], v[60:63]
	v_mfma_f32_16x16x32_bf16 v[56:59], v[64:67], v[156:159], v[56:59]
	v_mfma_f32_16x16x32_bf16 v[52:55], v[80:83], v[134:137], v[52:55]
	v_mfma_f32_16x16x32_bf16 v[48:51], v[80:83], v[156:159], v[48:51]
	v_mfma_f32_16x16x32_bf16 v[44:47], v[192:195], v[134:137], v[44:47]
	v_mfma_f32_16x16x32_bf16 v[40:43], v[192:195], v[156:159], v[40:43]
	v_mfma_f32_16x16x32_bf16 v[36:39], v[200:203], v[134:137], v[36:39]
	v_mfma_f32_16x16x32_bf16 v[32:35], v[200:203], v[156:159], v[32:35]
	v_mfma_f32_16x16x32_bf16 v[60:63], v[68:71], v[138:141], v[60:63]
	v_mfma_f32_16x16x32_bf16 v[56:59], v[68:71], v[172:175], v[56:59]
	v_mfma_f32_16x16x32_bf16 v[52:55], v[84:87], v[138:141], v[52:55]
	v_mfma_f32_16x16x32_bf16 v[48:51], v[84:87], v[172:175], v[48:51]
	v_mfma_f32_16x16x32_bf16 v[44:47], v[196:199], v[138:141], v[44:47]
	v_mfma_f32_16x16x32_bf16 v[40:43], v[196:199], v[172:175], v[40:43]
	v_mfma_f32_16x16x32_bf16 v[36:39], v[204:207], v[138:141], v[36:39]
	v_mfma_f32_16x16x32_bf16 v[32:35], v[204:207], v[172:175], v[32:35]
	v_mfma_f32_16x16x32_bf16 v[28:31], v[64:67], v[208:211], v[28:31]
	v_mfma_f32_16x16x32_bf16 v[24:27], v[64:67], v[216:219], v[24:27]
	v_mfma_f32_16x16x32_bf16 v[12:15], v[192:195], v[208:211], v[12:15]
	v_mfma_f32_16x16x32_bf16 v[8:11], v[192:195], v[216:219], v[8:11]
	v_mfma_f32_16x16x32_bf16 v[20:23], v[80:83], v[208:211], v[20:23]
	v_mfma_f32_16x16x32_bf16 v[16:19], v[80:83], v[216:219], v[16:19]
	v_mfma_f32_16x16x32_bf16 v[4:7], v[200:203], v[208:211], v[4:7]
	v_mfma_f32_16x16x32_bf16 v[0:3], v[200:203], v[216:219], v[0:3]
	v_mfma_f32_16x16x32_bf16 v[28:31], v[68:71], v[212:215], v[28:31]
	v_mfma_f32_16x16x32_bf16 v[24:27], v[68:71], v[220:223], v[24:27]
	v_mfma_f32_16x16x32_bf16 v[12:15], v[196:199], v[212:215], v[12:15]
	v_mfma_f32_16x16x32_bf16 v[8:11], v[196:199], v[220:223], v[8:11]
	v_mfma_f32_16x16x32_bf16 v[134:137], v[84:87], v[212:215], v[20:23]
	v_mfma_f32_16x16x32_bf16 v[138:141], v[84:87], v[220:223], v[16:19]
	v_mfma_f32_16x16x32_bf16 v[156:159], v[204:207], v[212:215], v[4:7]
	v_mfma_f32_16x16x32_bf16 v[170:173], v[204:207], v[220:223], v[0:3]
	s_barrier
	s_nop 0
	ds_read_b128 v[0:3], v155
	ds_read_b128 v[4:7], v155 offset:1024
	ds_read_b128 v[16:19], v155 offset:2048
	ds_read_b128 v[192:195], v155 offset:3072
	ds_read_b128 v[20:23], v152 offset:32768
	ds_read_b128 v[196:199], v152 offset:33792
	ds_read_b128 v[200:203], v151 offset:32768
	ds_read_b128 v[204:207], v151 offset:33792
	ds_read_b128 v[208:211], v150 offset:32768
	ds_read_b128 v[212:215], v150 offset:33792
	ds_read_b128 v[216:219], v149 offset:32768
	ds_read_b128 v[220:223], v149 offset:33792
	s_waitcnt vmcnt(2)
	s_barrier
; #define LDA(dst, b, h) for (int m = 0; m < 4; ++m) for (int k = 0; k < 2; ++k) \
;     dst[m][k] = *reinterpret_cast<const bf16x8*>((char*)SA(b, h) + lds_byte(wr * 64 + m * 16 + fr, k * 32 + fq * 8))
; #define LDB(dst, b, h) for (int n = 0; n < 2; ++n) for (int k = 0; k < 2; ++k) \
;     dst[n][k] = *reinterpret_cast<const bf16x8*>((char*)SB(b, h) + lds_byte(wc * 32 + n * 16 + fr, k * 32 + fq * 8))
; #define MMA(ai, bj, At_, Bt_) do { __builtin_amdgcn_s_setprio(1); \
;     for (int k = 0; k < 2; ++k) for (int m = 0; m < 4; ++m) for (int n = 0; n < 2; ++n) \
;       acc[ai][bj][m][n] = __builtin_amdgcn_mfma_f32_16x16x32_bf16(At_[m][k], Bt_[n][k], acc[ai][bj][m][n], 0, 0, 0); \
;     __builtin_amdgcn_s_setprio(0); } while (0)
; #define WAIT_V(n) asm volatile("s_waitcnt vmcnt(" #n ")" ::: "memory")
; #define WAIT_L(n) asm volatile("s_waitcnt lgkmcnt(" #n ")" ::: "memory")
; #define BAR __builtin_amdgcn_s_barrier()
; template <int EPI, int lda, int ldb, int N, int K>
; __device__ __forceinline__ void gemm_phase(const u16* __restrict__ A, const u16* __restrict__ Bt, const GemmEpi ep, int wv) {
;     ...
;     { LDB(B0, 1, 0); LDA(At, 1, 0); WAIT_V(2); BAR; WAIT_L(0); MMA(0, 0, At, B0); BAR;
;       LDB(B1, 1, 1); WAIT_V(0); BAR; WAIT_L(0); MMA(0, 1, At, B1); BAR;
;       LDA(At, 1, 1); BAR; WAIT_L(0); MMA(1, 0, At, B0); MMA(1, 1, At, B1); BAR; }
;     if (wr == 0) BAR;
	s_waitcnt lgkmcnt(0)
	s_waitcnt lgkmcnt(0)
	v_mfma_f32_16x16x32_bf16 v[64:67], v[20:23], v[0:3], v[124:127]
	v_mfma_f32_16x16x32_bf16 v[68:71], v[20:23], v[16:19], v[120:123]
	v_mfma_f32_16x16x32_bf16 v[80:83], v[200:203], v[0:3], v[116:119]
	v_mfma_f32_16x16x32_bf16 v[84:87], v[200:203], v[16:19], v[112:115]
	v_mfma_f32_16x16x32_bf16 v[108:111], v[208:211], v[0:3], v[108:111]
	v_mfma_f32_16x16x32_bf16 v[104:107], v[208:211], v[16:19], v[104:107]
	v_mfma_f32_16x16x32_bf16 v[120:123], v[216:219], v[0:3], v[100:103]
	v_mfma_f32_16x16x32_bf16 v[124:127], v[216:219], v[16:19], v[96:99]
	v_mfma_f32_16x16x32_bf16 v[116:119], v[196:199], v[4:7], v[64:67]
	v_mfma_f32_16x16x32_bf16 v[112:115], v[196:199], v[192:195], v[68:71]
	v_mfma_f32_16x16x32_bf16 v[100:103], v[204:207], v[4:7], v[80:83]
	v_mfma_f32_16x16x32_bf16 v[96:99], v[204:207], v[192:195], v[84:87]
	v_mfma_f32_16x16x32_bf16 v[84:87], v[212:215], v[4:7], v[108:111]
	v_mfma_f32_16x16x32_bf16 v[80:83], v[212:215], v[192:195], v[104:107]
	v_mfma_f32_16x16x32_bf16 v[68:71], v[220:223], v[4:7], v[120:123]
	v_mfma_f32_16x16x32_bf16 v[64:67], v[220:223], v[192:195], v[124:127]
	s_barrier
	ds_read_b128 v[224:227], v153
	ds_read_b128 v[228:231], v153 offset:1024
	ds_read_b128 v[232:235], v153 offset:2048
	ds_read_b128 v[236:239], v153 offset:3072
	s_waitcnt vmcnt(0)
	s_barrier
	s_waitcnt lgkmcnt(0)
	s_waitcnt lgkmcnt(0)
	v_mfma_f32_16x16x32_bf16 v[92:95], v[20:23], v[224:227], v[92:95]
	v_mfma_f32_16x16x32_bf16 v[20:23], v[20:23], v[232:235], v[88:91]
	v_mfma_f32_16x16x32_bf16 v[88:91], v[200:203], v[224:227], v[176:179]
	v_mfma_f32_16x16x32_bf16 v[104:107], v[200:203], v[232:235], v[180:183]
	v_mfma_f32_16x16x32_bf16 v[76:79], v[208:211], v[224:227], v[76:79]
	v_mfma_f32_16x16x32_bf16 v[72:75], v[208:211], v[232:235], v[72:75]
	v_mfma_f32_16x16x32_bf16 v[174:177], v[216:219], v[224:227], v[184:187]
	v_mfma_f32_16x16x32_bf16 v[178:181], v[216:219], v[232:235], v[188:191]
	v_mfma_f32_16x16x32_bf16 v[124:127], v[196:199], v[228:231], v[92:95]
	v_mfma_f32_16x16x32_bf16 v[120:123], v[196:199], v[236:239], v[20:23]
	v_mfma_f32_16x16x32_bf16 v[108:111], v[204:207], v[228:231], v[88:91]
	v_mfma_f32_16x16x32_bf16 v[104:107], v[204:207], v[236:239], v[104:107]
	v_mfma_f32_16x16x32_bf16 v[92:95], v[212:215], v[228:231], v[76:79]
	v_mfma_f32_16x16x32_bf16 v[88:91], v[212:215], v[236:239], v[72:75]
	v_mfma_f32_16x16x32_bf16 v[76:79], v[220:223], v[228:231], v[174:177]
	v_mfma_f32_16x16x32_bf16 v[72:75], v[220:223], v[236:239], v[178:181]
	s_barrier
	ds_read_b128 v[174:177], v152 offset:49152
	ds_read_b128 v[152:155], v152 offset:50176
	ds_read_b128 v[178:181], v151 offset:49152
	ds_read_b128 v[182:185], v151 offset:50176
	ds_read_b128 v[186:189], v150 offset:49152
	ds_read_b128 v[196:199], v150 offset:50176
	ds_read_b128 v[200:203], v149 offset:49152
	ds_read_b128 v[204:207], v149 offset:50176
	s_barrier
	s_waitcnt lgkmcnt(0)
	s_waitcnt lgkmcnt(0)
	v_mfma_f32_16x16x32_bf16 v[20:23], v[174:177], v[0:3], v[60:63]
	v_mfma_f32_16x16x32_bf16 v[56:59], v[174:177], v[16:19], v[56:59]
	v_mfma_f32_16x16x32_bf16 v[60:63], v[178:181], v[0:3], v[52:55]
	v_mfma_f32_16x16x32_bf16 v[208:211], v[178:181], v[16:19], v[48:51]
	v_mfma_f32_16x16x32_bf16 v[44:47], v[186:189], v[0:3], v[44:47]
	v_mfma_f32_16x16x32_bf16 v[40:43], v[186:189], v[16:19], v[40:43]
	v_mfma_f32_16x16x32_bf16 v[0:3], v[200:203], v[0:3], v[36:39]
	v_mfma_f32_16x16x32_bf16 v[212:215], v[200:203], v[16:19], v[32:35]
	v_mfma_f32_16x16x32_bf16 v[52:55], v[152:155], v[4:7], v[20:23]
	v_mfma_f32_16x16x32_bf16 v[48:51], v[152:155], v[192:195], v[56:59]
	v_mfma_f32_16x16x32_bf16 v[36:39], v[182:185], v[4:7], v[60:63]
	v_mfma_f32_16x16x32_bf16 v[32:35], v[182:185], v[192:195], v[208:211]
	v_mfma_f32_16x16x32_bf16 v[20:23], v[196:199], v[4:7], v[44:47]
	v_mfma_f32_16x16x32_bf16 v[16:19], v[196:199], v[192:195], v[40:43]
	v_mfma_f32_16x16x32_bf16 v[4:7], v[204:207], v[4:7], v[0:3]
	v_mfma_f32_16x16x32_bf16 v[0:3], v[204:207], v[192:195], v[212:215]
	v_mfma_f32_16x16x32_bf16 v[28:31], v[174:177], v[224:227], v[28:31]
	v_mfma_f32_16x16x32_bf16 v[24:27], v[174:177], v[232:235], v[24:27]
	v_mfma_f32_16x16x32_bf16 v[40:43], v[178:181], v[224:227], v[134:137]
	v_mfma_f32_16x16x32_bf16 v[134:137], v[178:181], v[232:235], v[138:141]
	v_mfma_f32_16x16x32_bf16 v[12:15], v[186:189], v[224:227], v[12:15]
	v_mfma_f32_16x16x32_bf16 v[8:11], v[186:189], v[232:235], v[8:11]
	v_mfma_f32_16x16x32_bf16 v[138:141], v[200:203], v[224:227], v[156:159]
	v_mfma_f32_16x16x32_bf16 v[156:159], v[200:203], v[232:235], v[170:173]
	v_mfma_f32_16x16x32_bf16 v[60:63], v[152:155], v[228:231], v[28:31]
	v_mfma_f32_16x16x32_bf16 v[56:59], v[152:155], v[236:239], v[24:27]
	v_mfma_f32_16x16x32_bf16 v[44:47], v[182:185], v[228:231], v[40:43]
	v_mfma_f32_16x16x32_bf16 v[40:43], v[182:185], v[236:239], v[134:137]
	v_mfma_f32_16x16x32_bf16 v[28:31], v[196:199], v[228:231], v[12:15]
	v_mfma_f32_16x16x32_bf16 v[24:27], v[196:199], v[236:239], v[8:11]
	v_mfma_f32_16x16x32_bf16 v[12:15], v[204:207], v[228:231], v[138:141]
	v_mfma_f32_16x16x32_bf16 v[8:11], v[204:207], v[236:239], v[156:159]
	v_cmp_gt_u32_e32 vcc, s80, v130
	s_barrier
	s_and_saveexec_b64 s[60:61], vcc
	s_cbranch_execz .LBB0_1150
	s_barrier

; #define STAGE(P, BASE, LD, br, kt) do { const char* _g = (const char*)((BASE) + (size_t)(br) * (LD) + (size_t)(kt) * 64); \
;     for (int _i = 0; _i < 2; ++_i) { int _b = tidx * 16 + _i * 8192; int _r, _c; stage_rc(_b, _r, _c); \
;       __builtin_amdgcn_global_load_lds((const unsigned*)(_g + (unsigned)((_r * (LD) + _c) * 2)), (unsigned*)((char*)(P) + _b), 16, 0, 0); } } while (0)
; #define LDA(dst, b, h) for (int m = 0; m < 4; ++m) for (int k = 0; k < 2; ++k) \
;     dst[m][k] = *reinterpret_cast<const bf16x8*>((char*)SA(b, h) + lds_byte(wr * 64 + m * 16 + fr, k * 32 + fq * 8))
; #define LDB(dst, b, h) for (int n = 0; n < 2; ++n) for (int k = 0; k < 2; ++k) \
;     dst[n][k] = *reinterpret_cast<const bf16x8*>((char*)SB(b, h) + lds_byte(wc * 32 + n * 16 + fr, k * 32 + fq * 8))
; #define MMA(ai, bj, At_, Bt_) do { __builtin_amdgcn_s_setprio(1); \
;     for (int k = 0; k < 2; ++k) for (int m = 0; m < 4; ++m) for (int n = 0; n < 2; ++n) \
;       acc[ai][bj][m][n] = __builtin_amdgcn_mfma_f32_16x16x32_bf16(At_[m][k], Bt_[n][k], acc[ai][bj][m][n], 0, 0, 0); \
;     __builtin_amdgcn_s_setprio(0); } while (0)
; #define WAIT_V(n) asm volatile("s_waitcnt vmcnt(" #n ")" ::: "memory")
; #define WAIT_L(n) asm volatile("s_waitcnt lgkmcnt(" #n ")" ::: "memory")
; #define BAR __builtin_amdgcn_s_barrier()
; #define SCHED __builtin_amdgcn_sched_barrier(0)
; template <int EPI, int lda, int ldb, int N, int K>
; __device__ __forceinline__ void gemm_phase(const u16* __restrict__ A, const u16* __restrict__ Bt, const GemmEpi ep, int wv) {
;     ...
;     if (wr == 1) BAR;
;     WAIT_V(4); BAR;
;     STAGE(SB(1, 0), Bt, ldb, bcol, 1); STAGE(SA(1, 0), Ab, lda, brow, 1); STAGE(SB(1, 1), Bt, ldb, bcol + HALF, 1);
;     WAIT_V(6); BAR;
;     for (int t = 0; t < nt - 2; t += 2) {
;       LDB(B0, 0, 0); SCHED; LDA(At, 0, 0); STAGE(SA(1, 1), Ab, lda, brow + HALF, t + 1);
;       WAIT_L(8); BAR; WAIT_L(0); MMA(0, 0, At, B0); BAR; SCHED;
;       LDB(B1, 0, 1); STAGE(SB(0, 0), Bt, ldb, bcol, t + 2);
;       BAR; WAIT_L(0); MMA(0, 1, At, B1); BAR;
.LBB0_1248:
	s_or_b64 exec, exec, s[54:55]
	v_mov_b32_e32 v1, v129
	v_add_u32_e32 v7, s60, v6
	v_lshl_add_u64 v[12:13], s[46:47], 0, v[128:129]
	v_lshl_add_u64 v[14:15], s[46:47], 0, v[0:1]
	v_lshl_add_u64 v[2:3], s[52:53], 0, v[128:129]
	v_lshl_add_u64 v[0:1], s[52:53], 0, v[0:1]
	v_readfirstlane_b32 s53, v7
	v_add_u32_e32 v7, 0x2000, v7
	v_mov_b32_e32 v5, v129
	v_mov_b32_e32 v17, v129
	v_lshl_add_u64 v[26:27], v[12:13], 0, s[40:41]
	s_mov_b32 m0, s53
	v_readfirstlane_b32 s52, v7
	v_add_u32_e32 v7, 0x8000, v23
	v_lshl_add_u64 v[8:9], s[50:51], 0, v[4:5]
	v_lshl_add_u64 v[10:11], s[50:51], 0, v[16:17]
	s_waitcnt vmcnt(4)
	s_barrier
	global_load_lds_dwordx4 v[26:27], off
	v_lshl_add_u64 v[26:27], v[14:15], 0, s[40:41]
	s_mov_b32 m0, s52
	v_readfirstlane_b32 s51, v7
	v_add_u32_e32 v7, 0xa000, v23
	global_load_lds_dwordx4 v[26:27], off
	v_lshl_add_u64 v[26:27], v[8:9], 0, s[40:41]
	s_mov_b32 m0, s51
	v_readfirstlane_b32 s50, v7
	v_add_u32_e32 v25, s61, v6
	global_load_lds_dwordx4 v[26:27], off
	v_lshl_add_u64 v[26:27], v[10:11], 0, s[40:41]
	s_mov_b32 m0, s50
	v_readfirstlane_b32 s13, v25
	v_add_u32_e32 v25, 0x2000, v25
	global_load_lds_dwordx4 v[26:27], off
	v_lshl_add_u64 v[26:27], v[2:3], 0, s[40:41]
	s_mov_b32 m0, s13
	v_readfirstlane_b32 s11, v25
	global_load_lds_dwordx4 v[26:27], off
	v_lshl_add_u64 v[6:7], v[0:1], 0, s[40:41]
	s_mov_b32 m0, s11
	v_and_b32_e32 v132, 15, v20
	global_load_lds_dwordx4 v[6:7], off
	v_bfe_u32 v128, v20, 4, 2
	v_lshlrev_b32_e32 v7, 2, v20
	v_bfe_u32 v131, v130, 6, 2
	v_lshlrev_b32_e32 v25, 4, v128
	v_lshlrev_b32_e32 v6, 6, v132
	v_and_b32_e32 v50, 32, v7
	v_lshlrev_b32_e32 v126, 12, v131
	v_bitop3_b32 v127, v25, v50, v6 bitop3:0x36
	v_add3_u32 v133, s58, v127, v126
	s_waitcnt vmcnt(6)
	s_barrier
	ds_read_b128 v[26:29], v133
	ds_read_b128 v[30:33], v133 offset:1024
	ds_read_b128 v[34:37], v133 offset:2048
	ds_read_b128 v[38:41], v133 offset:3072
	v_lshl_add_u64 v[6:7], s[48:49], 0, v[4:5]
	v_lshl_add_u64 v[4:5], s[48:49], 0, v[16:17]
	v_lshlrev_b32_e32 v17, 6, v20
	v_and_b32_e32 v17, 0x3c0, v17
	v_add_u32_e32 v20, 0xc000, v23
	v_lshlrev_b32_e32 v16, 13, v143
	v_bitop3_b32 v17, v17, v50, v25 bitop3:0x36
	v_readfirstlane_b32 s47, v20
	v_add_u32_e32 v20, 0xe000, v23
	v_add3_u32 v228, 0, v127, v16
	v_add3_u32 v229, 0, v17, v16
	v_lshl_add_u64 v[16:17], v[6:7], 0, s[40:41]
	s_mov_b32 m0, s47
	v_readfirstlane_b32 s46, v20
	ds_read_b128 v[42:45], v228
	ds_read_b128 v[46:49], v228 offset:1024
	ds_read_b128 v[50:53], v229 offset:2048
	ds_read_b128 v[54:57], v229 offset:3072
	ds_read_b128 v[58:61], v229 offset:4096
	ds_read_b128 v[62:65], v229 offset:5120
	ds_read_b128 v[66:69], v229 offset:6144
	ds_read_b128 v[70:73], v229 offset:7168
	global_load_lds_dwordx4 v[16:17], off
	v_lshl_add_u64 v[16:17], v[4:5], 0, s[40:41]
	s_mov_b32 m0, s46
	s_nop 0
	global_load_lds_dwordx4 v[16:17], off
	s_waitcnt lgkmcnt(8)
	s_barrier
	s_waitcnt lgkmcnt(0)
	s_waitcnt lgkmcnt(0)
	v_mfma_f32_16x16x32_bf16 v[74:77], v[42:45], v[26:29], 0
	v_mfma_f32_16x16x32_bf16 v[78:81], v[42:45], v[34:37], 0
	v_mfma_f32_16x16x32_bf16 v[82:85], v[50:53], v[26:29], 0
	v_mfma_f32_16x16x32_bf16 v[86:89], v[50:53], v[34:37], 0
	v_mfma_f32_16x16x32_bf16 v[90:93], v[58:61], v[26:29], 0
	v_mfma_f32_16x16x32_bf16 v[94:97], v[58:61], v[34:37], 0
	v_mfma_f32_16x16x32_bf16 v[98:101], v[66:69], v[26:29], 0
	v_mfma_f32_16x16x32_bf16 v[102:105], v[66:69], v[34:37], 0
	v_mfma_f32_16x16x32_bf16 v[74:77], v[46:49], v[30:33], v[74:77]
	v_mfma_f32_16x16x32_bf16 v[78:81], v[46:49], v[38:41], v[78:81]
	v_mfma_f32_16x16x32_bf16 v[82:85], v[54:57], v[30:33], v[82:85]
	v_mfma_f32_16x16x32_bf16 v[86:89], v[54:57], v[38:41], v[86:89]
	v_mfma_f32_16x16x32_bf16 v[90:93], v[62:65], v[30:33], v[90:93]
	v_mfma_f32_16x16x32_bf16 v[94:97], v[62:65], v[38:41], v[94:97]
	v_mfma_f32_16x16x32_bf16 v[98:101], v[70:73], v[30:33], v[98:101]
	v_mfma_f32_16x16x32_bf16 v[102:105], v[70:73], v[38:41], v[102:105]
	s_barrier
	v_readfirstlane_b32 s48, v21
	v_add_u32_e32 v20, 0x2000, v21
	v_add3_u32 v224, s59, v127, v126
	v_lshl_add_u64 v[16:17], v[12:13], 0, s[42:43]
	s_mov_b32 m0, s48
	v_readfirstlane_b32 s48, v20
	ds_read_b128 v[106:109], v224
	ds_read_b128 v[110:113], v224 offset:1024
	ds_read_b128 v[114:117], v224 offset:2048
	ds_read_b128 v[118:121], v224 offset:3072
	global_load_lds_dwordx4 v[16:17], off
	s_nop 1
	v_lshl_add_u64 v[16:17], v[14:15], 0, s[42:43]
	s_mov_b32 m0, s48
	s_nop 0
	global_load_lds_dwordx4 v[16:17], off
	s_barrier
	s_waitcnt lgkmcnt(0)
	s_waitcnt lgkmcnt(0)
	v_mfma_f32_16x16x32_bf16 v[122:125], v[42:45], v[106:109], 0
	v_mfma_f32_16x16x32_bf16 v[42:45], v[42:45], v[114:117], 0
	v_mfma_f32_16x16x32_bf16 v[134:137], v[50:53], v[106:109], 0
	v_mfma_f32_16x16x32_bf16 v[50:53], v[50:53], v[114:117], 0
	v_mfma_f32_16x16x32_bf16 v[144:147], v[58:61], v[106:109], 0
	v_mfma_f32_16x16x32_bf16 v[58:61], v[58:61], v[114:117], 0
	v_mfma_f32_16x16x32_bf16 v[148:151], v[66:69], v[106:109], 0
	v_mfma_f32_16x16x32_bf16 v[66:69], v[66:69], v[114:117], 0
	v_mfma_f32_16x16x32_bf16 v[122:125], v[46:49], v[110:113], v[122:125]
	v_mfma_f32_16x16x32_bf16 v[42:45], v[46:49], v[118:121], v[42:45]
	v_mfma_f32_16x16x32_bf16 v[46:49], v[54:57], v[110:113], v[134:137]
	v_mfma_f32_16x16x32_bf16 v[50:53], v[54:57], v[118:121], v[50:53]
	v_mfma_f32_16x16x32_bf16 v[54:57], v[62:65], v[110:113], v[144:147]
	v_mfma_f32_16x16x32_bf16 v[58:61], v[62:65], v[118:121], v[58:61]
	v_mfma_f32_16x16x32_bf16 v[62:65], v[70:73], v[110:113], v[148:151]
	v_mfma_f32_16x16x32_bf16 v[66:69], v[70:73], v[118:121], v[66:69]
	v_readfirstlane_b32 s48, v23
	v_lshl_add_u64 v[16:17], v[8:9], 0, s[42:43]
	s_mov_b32 m0, s48
	v_readfirstlane_b32 s48, v24
	s_barrier
; #define STAGE(P, BASE, LD, br, kt) do { const char* _g = (const char*)((BASE) + (size_t)(br) * (LD) + (size_t)(kt) * 64); \
;     for (int _i = 0; _i < 2; ++_i) { int _b = tidx * 16 + _i * 8192; int _r, _c; stage_rc(_b, _r, _c); \
;       __builtin_amdgcn_global_load_lds((const unsigned*)(_g + (unsigned)((_r * (LD) + _c) * 2)), (unsigned*)((char*)(P) + _b), 16, 0, 0); } } while (0)
; #define LDA(dst, b, h) for (int m = 0; m < 4; ++m) for (int k = 0; k < 2; ++k) \
;     dst[m][k] = *reinterpret_cast<const bf16x8*>((char*)SA(b, h) + lds_byte(wr * 64 + m * 16 + fr, k * 32 + fq * 8))
; #define LDB(dst, b, h) for (int n = 0; n < 2; ++n) for (int k = 0; k < 2; ++k) \
;     dst[n][k] = *reinterpret_cast<const bf16x8*>((char*)SB(b, h) + lds_byte(wc * 32 + n * 16 + fr, k * 32 + fq * 8))
; #define MMA(ai, bj, At_, Bt_) do { __builtin_amdgcn_s_setprio(1); \
;     for (int k = 0; k < 2; ++k) for (int m = 0; m < 4; ++m) for (int n = 0; n < 2; ++n) \
;       acc[ai][bj][m][n] = __builtin_amdgcn_mfma_f32_16x16x32_bf16(At_[m][k], Bt_[n][k], acc[ai][bj][m][n], 0, 0, 0); \
;     __builtin_amdgcn_s_setprio(0); } while (0)
; #define WAIT_V(n) asm volatile("s_waitcnt vmcnt(" #n ")" ::: "memory")
; #define WAIT_L(n) asm volatile("s_waitcnt lgkmcnt(" #n ")" ::: "memory")
; #define BAR __builtin_amdgcn_s_barrier()
; #define SCHED __builtin_amdgcn_sched_barrier(0)
; template <int EPI, int lda, int ldb, int N, int K>
; __device__ __forceinline__ void gemm_phase(const u16* __restrict__ A, const u16* __restrict__ Bt, const GemmEpi ep, int wv) {
;     ...
;       LDA(At, 0, 1); STAGE(SA(0, 0), Ab, lda, brow, t + 2);
;       BAR; WAIT_L(0); MMA(1, 0, At, B0); BAR; SCHED;
;       STAGE(SB(0, 1), Bt, ldb, bcol + HALF, t + 2);
;       WAIT_V(6); BAR; MMA(1, 1, At, B1); BAR;
;       LDB(B0, 1, 0); SCHED; LDA(At, 1, 0); STAGE(SA(0, 1), Ab, lda, brow + HALF, t + 2);
;       WAIT_L(8); BAR; WAIT_L(0); MMA(0, 0, At, B0); BAR; SCHED;
;       LDB(B1, 1, 1); STAGE(SB(1, 0), Bt, ldb, bcol, t + 3);
	ds_read_b128 v[70:73], v228 offset:16384
	ds_read_b128 v[134:137], v228 offset:17408
	ds_read_b128 v[144:147], v229 offset:18432
	ds_read_b128 v[148:151], v229 offset:19456
	ds_read_b128 v[152:155], v229 offset:20480
	ds_read_b128 v[156:159], v229 offset:21504
	ds_read_b128 v[160:163], v229 offset:22528
	ds_read_b128 v[164:167], v229 offset:23552
	global_load_lds_dwordx4 v[16:17], off
	s_nop 1
	v_lshl_add_u64 v[16:17], v[10:11], 0, s[42:43]
	s_mov_b32 m0, s48
	s_nop 0
	global_load_lds_dwordx4 v[16:17], off
	s_barrier
	s_waitcnt lgkmcnt(0)
	s_waitcnt lgkmcnt(0)
	v_mfma_f32_16x16x32_bf16 v[168:171], v[70:73], v[26:29], 0
	v_mfma_f32_16x16x32_bf16 v[172:175], v[70:73], v[34:37], 0
	v_mfma_f32_16x16x32_bf16 v[176:179], v[144:147], v[26:29], 0
	v_mfma_f32_16x16x32_bf16 v[180:183], v[144:147], v[34:37], 0
	v_mfma_f32_16x16x32_bf16 v[184:187], v[152:155], v[26:29], 0
	v_mfma_f32_16x16x32_bf16 v[188:191], v[152:155], v[34:37], 0
	v_mfma_f32_16x16x32_bf16 v[24:27], v[160:163], v[26:29], 0
	v_mfma_f32_16x16x32_bf16 v[34:37], v[160:163], v[34:37], 0
	v_mfma_f32_16x16x32_bf16 v[168:171], v[134:137], v[30:33], v[168:171]
	v_mfma_f32_16x16x32_bf16 v[176:179], v[148:151], v[30:33], v[176:179]
	v_mfma_f32_16x16x32_bf16 v[184:187], v[156:159], v[30:33], v[184:187]
	v_mfma_f32_16x16x32_bf16 v[24:27], v[164:167], v[30:33], v[24:27]
	v_mfma_f32_16x16x32_bf16 v[28:31], v[164:167], v[38:41], v[34:37]
	v_mfma_f32_16x16x32_bf16 v[172:175], v[134:137], v[38:41], v[172:175]
	v_mfma_f32_16x16x32_bf16 v[180:183], v[148:151], v[38:41], v[180:183]
	v_mfma_f32_16x16x32_bf16 v[188:191], v[156:159], v[38:41], v[188:191]
	s_barrier
	v_readfirstlane_b32 s48, v22
	v_add_u32_e32 v20, 0x2000, v22
	v_lshl_add_u64 v[16:17], v[2:3], 0, s[42:43]
	s_mov_b32 m0, s48
	v_readfirstlane_b32 s48, v20
	global_load_lds_dwordx4 v[16:17], off
	s_nop 1
	v_lshl_add_u64 v[16:17], v[0:1], 0, s[42:43]
	s_mov_b32 m0, s48
	s_nop 0
	global_load_lds_dwordx4 v[16:17], off
	s_waitcnt vmcnt(6)
	s_barrier
	v_mfma_f32_16x16x32_bf16 v[20:23], v[70:73], v[106:109], 0
	v_mfma_f32_16x16x32_bf16 v[32:35], v[70:73], v[114:117], 0
	v_mfma_f32_16x16x32_bf16 v[36:39], v[144:147], v[106:109], 0
	v_mfma_f32_16x16x32_bf16 v[70:73], v[144:147], v[114:117], 0
	v_mfma_f32_16x16x32_bf16 v[144:147], v[152:155], v[106:109], 0
	v_mfma_f32_16x16x32_bf16 v[152:155], v[152:155], v[114:117], 0
	v_mfma_f32_16x16x32_bf16 v[106:109], v[160:163], v[106:109], 0
	v_mfma_f32_16x16x32_bf16 v[114:117], v[160:163], v[114:117], 0
	v_mfma_f32_16x16x32_bf16 v[20:23], v[134:137], v[110:113], v[20:23]
	v_mfma_f32_16x16x32_bf16 v[32:35], v[134:137], v[118:121], v[32:35]
	v_mfma_f32_16x16x32_bf16 v[36:39], v[148:151], v[110:113], v[36:39]
	v_mfma_f32_16x16x32_bf16 v[70:73], v[148:151], v[118:121], v[70:73]
	v_mfma_f32_16x16x32_bf16 v[134:137], v[156:159], v[110:113], v[144:147]
	v_mfma_f32_16x16x32_bf16 v[106:109], v[164:167], v[110:113], v[106:109]
	v_mfma_f32_16x16x32_bf16 v[110:113], v[164:167], v[118:121], v[114:117]
	v_mfma_f32_16x16x32_bf16 v[144:147], v[156:159], v[118:121], v[152:155]
	v_add3_u32 v225, s60, v127, v126
	s_barrier
	ds_read_b128 v[114:117], v225
	ds_read_b128 v[118:121], v225 offset:1024
	ds_read_b128 v[148:151], v225 offset:2048
	ds_read_b128 v[152:155], v225 offset:3072
	v_readfirstlane_b32 s48, v18
	v_lshl_add_u64 v[16:17], v[6:7], 0, s[42:43]
	s_mov_b32 m0, s48
	v_readfirstlane_b32 s48, v19
	ds_read_b128 v[156:159], v228 offset:32768
	ds_read_b128 v[160:163], v228 offset:33792
	ds_read_b128 v[164:167], v229 offset:34816
	ds_read_b128 v[192:195], v229 offset:35840
	ds_read_b128 v[196:199], v229 offset:36864
	ds_read_b128 v[200:203], v229 offset:37888
	ds_read_b128 v[204:207], v229 offset:38912
	ds_read_b128 v[208:211], v229 offset:39936
	global_load_lds_dwordx4 v[16:17], off
	s_nop 1
	v_lshl_add_u64 v[16:17], v[4:5], 0, s[42:43]
	s_mov_b32 m0, s48
	s_nop 0
	global_load_lds_dwordx4 v[16:17], off
	s_waitcnt lgkmcnt(8)
	s_barrier
	s_waitcnt lgkmcnt(0)
	s_waitcnt lgkmcnt(0)
	v_mfma_f32_16x16x32_bf16 v[16:19], v[156:159], v[114:117], v[74:77]
	v_mfma_f32_16x16x32_bf16 v[74:77], v[156:159], v[148:151], v[78:81]
	v_mfma_f32_16x16x32_bf16 v[78:81], v[164:167], v[114:117], v[82:85]
	v_mfma_f32_16x16x32_bf16 v[82:85], v[164:167], v[148:151], v[86:89]
	v_mfma_f32_16x16x32_bf16 v[86:89], v[196:199], v[114:117], v[90:93]
	v_mfma_f32_16x16x32_bf16 v[90:93], v[196:199], v[148:151], v[94:97]
	v_mfma_f32_16x16x32_bf16 v[94:97], v[204:207], v[114:117], v[98:101]
	v_mfma_f32_16x16x32_bf16 v[98:101], v[204:207], v[148:151], v[102:105]
	v_mfma_f32_16x16x32_bf16 v[16:19], v[160:163], v[118:121], v[16:19]
	v_mfma_f32_16x16x32_bf16 v[74:77], v[160:163], v[152:155], v[74:77]
	v_mfma_f32_16x16x32_bf16 v[78:81], v[192:195], v[118:121], v[78:81]
	v_mfma_f32_16x16x32_bf16 v[82:85], v[192:195], v[152:155], v[82:85]
	v_mfma_f32_16x16x32_bf16 v[86:89], v[200:203], v[118:121], v[86:89]
	v_mfma_f32_16x16x32_bf16 v[90:93], v[200:203], v[152:155], v[90:93]
	v_mfma_f32_16x16x32_bf16 v[94:97], v[208:211], v[118:121], v[94:97]
	v_mfma_f32_16x16x32_bf16 v[98:101], v[208:211], v[152:155], v[98:101]
	s_barrier
	s_mov_b32 m0, s53
	v_add3_u32 v226, s61, v127, v126
	v_lshl_add_u64 v[12:13], v[12:13], 0, s[44:45]
	ds_read_b128 v[102:105], v226
	ds_read_b128 v[212:215], v226 offset:1024
	ds_read_b128 v[216:219], v226 offset:2048
	ds_read_b128 v[220:223], v226 offset:3072
	global_load_lds_dwordx4 v[12:13], off
	s_nop 1
	v_lshl_add_u64 v[12:13], v[14:15], 0, s[44:45]
	s_mov_b32 m0, s52
	s_nop 0
	global_load_lds_dwordx4 v[12:13], off
	s_barrier
; #define STAGE(P, BASE, LD, br, kt) do { const char* _g = (const char*)((BASE) + (size_t)(br) * (LD) + (size_t)(kt) * 64); \
;     for (int _i = 0; _i < 2; ++_i) { int _b = tidx * 16 + _i * 8192; int _r, _c; stage_rc(_b, _r, _c); \
;       __builtin_amdgcn_global_load_lds((const unsigned*)(_g + (unsigned)((_r * (LD) + _c) * 2)), (unsigned*)((char*)(P) + _b), 16, 0, 0); } } while (0)
; #define LDA(dst, b, h) for (int m = 0; m < 4; ++m) for (int k = 0; k < 2; ++k) \
;     dst[m][k] = *reinterpret_cast<const bf16x8*>((char*)SA(b, h) + lds_byte(wr * 64 + m * 16 + fr, k * 32 + fq * 8))
; #define LDB(dst, b, h) for (int n = 0; n < 2; ++n) for (int k = 0; k < 2; ++k) \
;     dst[n][k] = *reinterpret_cast<const bf16x8*>((char*)SB(b, h) + lds_byte(wc * 32 + n * 16 + fr, k * 32 + fq * 8))
; #define MMA(ai, bj, At_, Bt_) do { __builtin_amdgcn_s_setprio(1); \
;     for (int k = 0; k < 2; ++k) for (int m = 0; m < 4; ++m) for (int n = 0; n < 2; ++n) \
;       acc[ai][bj][m][n] = __builtin_amdgcn_mfma_f32_16x16x32_bf16(At_[m][k], Bt_[n][k], acc[ai][bj][m][n], 0, 0, 0); \
;     __builtin_amdgcn_s_setprio(0); } while (0)
; #define WAIT_V(n) asm volatile("s_waitcnt vmcnt(" #n ")" ::: "memory")
; #define WAIT_L(n) asm volatile("s_waitcnt lgkmcnt(" #n ")" ::: "memory")
; #define BAR __builtin_amdgcn_s_barrier()
; #define SCHED __builtin_amdgcn_sched_barrier(0)
; template <int EPI, int lda, int ldb, int N, int K>
; __device__ __forceinline__ void gemm_phase(const u16* __restrict__ A, const u16* __restrict__ Bt, const GemmEpi ep, int wv) {
;     ...
;       BAR; WAIT_L(0); MMA(0, 1, At, B1); BAR;
;       LDA(At, 1, 1); STAGE(SA(1, 0), Ab, lda, brow, t + 3);
;       BAR; WAIT_L(0); MMA(1, 0, At, B0); BAR; SCHED;
;       STAGE(SB(1, 1), Bt, ldb, bcol + HALF, t + 3);
;       WAIT_V(6); BAR; MMA(1, 1, At, B1); BAR;
;     }
;     { LDB(B0, 0, 0); LDA(At, 0, 0); STAGE(SA(1, 1), Ab, lda, brow + HALF, nt - 1);
;       BAR; WAIT_L(0); MMA(0, 0, At, B0); BAR;
	s_waitcnt lgkmcnt(0)
	s_waitcnt lgkmcnt(0)
	v_mfma_f32_16x16x32_bf16 v[12:15], v[156:159], v[102:105], v[122:125]
	v_mfma_f32_16x16x32_bf16 v[40:43], v[156:159], v[216:219], v[42:45]
	v_mfma_f32_16x16x32_bf16 v[44:47], v[164:167], v[102:105], v[46:49]
	v_mfma_f32_16x16x32_bf16 v[48:51], v[164:167], v[216:219], v[50:53]
	v_mfma_f32_16x16x32_bf16 v[52:55], v[196:199], v[102:105], v[54:57]
	v_mfma_f32_16x16x32_bf16 v[56:59], v[196:199], v[216:219], v[58:61]
	v_mfma_f32_16x16x32_bf16 v[60:63], v[204:207], v[102:105], v[62:65]
	v_mfma_f32_16x16x32_bf16 v[64:67], v[204:207], v[216:219], v[66:69]
	v_mfma_f32_16x16x32_bf16 v[12:15], v[160:163], v[212:215], v[12:15]
	v_mfma_f32_16x16x32_bf16 v[40:43], v[160:163], v[220:223], v[40:43]
	v_mfma_f32_16x16x32_bf16 v[44:47], v[192:195], v[212:215], v[44:47]
	v_mfma_f32_16x16x32_bf16 v[48:51], v[192:195], v[220:223], v[48:51]
	v_mfma_f32_16x16x32_bf16 v[52:55], v[200:203], v[212:215], v[52:55]
	v_mfma_f32_16x16x32_bf16 v[56:59], v[200:203], v[220:223], v[56:59]
	v_mfma_f32_16x16x32_bf16 v[60:63], v[208:211], v[212:215], v[60:63]
	v_mfma_f32_16x16x32_bf16 v[64:67], v[208:211], v[220:223], v[64:67]
	s_mov_b32 m0, s51
	v_lshl_add_u64 v[8:9], v[8:9], 0, s[44:45]
	s_barrier
	ds_read_b128 v[122:125], v228 offset:49152
	ds_read_b128 v[156:159], v228 offset:50176
	ds_read_b128 v[160:163], v229 offset:51200
	ds_read_b128 v[164:167], v229 offset:52224
	ds_read_b128 v[192:195], v229 offset:53248
	ds_read_b128 v[196:199], v229 offset:54272
	ds_read_b128 v[200:203], v229 offset:55296
	ds_read_b128 v[204:207], v229 offset:56320
	global_load_lds_dwordx4 v[8:9], off
	s_nop 1
	v_lshl_add_u64 v[8:9], v[10:11], 0, s[44:45]
	s_mov_b32 m0, s50
	s_nop 0
	global_load_lds_dwordx4 v[8:9], off
	s_barrier
	s_waitcnt lgkmcnt(0)
	s_waitcnt lgkmcnt(0)
	v_mfma_f32_16x16x32_bf16 v[8:11], v[122:125], v[114:117], v[168:171]
	v_mfma_f32_16x16x32_bf16 v[168:171], v[122:125], v[148:151], v[172:175]
	v_mfma_f32_16x16x32_bf16 v[24:27], v[200:203], v[114:117], v[24:27]
	v_mfma_f32_16x16x32_bf16 v[28:31], v[200:203], v[148:151], v[28:31]
	v_mfma_f32_16x16x32_bf16 v[172:175], v[160:163], v[114:117], v[176:179]
	v_mfma_f32_16x16x32_bf16 v[176:179], v[160:163], v[148:151], v[180:183]
	v_mfma_f32_16x16x32_bf16 v[180:183], v[192:195], v[114:117], v[184:187]
	v_mfma_f32_16x16x32_bf16 v[184:187], v[192:195], v[148:151], v[188:191]
	v_mfma_f32_16x16x32_bf16 v[8:11], v[156:159], v[118:121], v[8:11]
	v_mfma_f32_16x16x32_bf16 v[114:117], v[156:159], v[152:155], v[168:171]
	v_mfma_f32_16x16x32_bf16 v[24:27], v[204:207], v[118:121], v[24:27]
	v_mfma_f32_16x16x32_bf16 v[28:31], v[204:207], v[152:155], v[28:31]
	v_mfma_f32_16x16x32_bf16 v[148:151], v[164:167], v[118:121], v[172:175]
	v_mfma_f32_16x16x32_bf16 v[168:171], v[164:167], v[152:155], v[176:179]
	v_mfma_f32_16x16x32_bf16 v[172:175], v[196:199], v[118:121], v[180:183]
	v_mfma_f32_16x16x32_bf16 v[176:179], v[196:199], v[152:155], v[184:187]
	s_barrier
	s_mov_b32 m0, s13
	v_lshl_add_u64 v[2:3], v[2:3], 0, s[44:45]
	global_load_lds_dwordx4 v[2:3], off
	s_nop 1
	v_lshl_add_u64 v[0:1], v[0:1], 0, s[44:45]
	s_mov_b32 m0, s11
	s_nop 0
	global_load_lds_dwordx4 v[0:1], off
	s_waitcnt vmcnt(6)
	s_barrier
	v_mfma_f32_16x16x32_bf16 v[0:3], v[122:125], v[102:105], v[20:23]
	v_mfma_f32_16x16x32_bf16 v[20:23], v[122:125], v[216:219], v[32:35]
	v_mfma_f32_16x16x32_bf16 v[32:35], v[160:163], v[102:105], v[36:39]
	v_mfma_f32_16x16x32_bf16 v[36:39], v[160:163], v[216:219], v[70:73]
	v_mfma_f32_16x16x32_bf16 v[68:71], v[192:195], v[102:105], v[134:137]
	v_mfma_f32_16x16x32_bf16 v[118:121], v[192:195], v[216:219], v[144:147]
	v_mfma_f32_16x16x32_bf16 v[102:105], v[200:203], v[102:105], v[106:109]
	v_mfma_f32_16x16x32_bf16 v[106:109], v[200:203], v[216:219], v[110:113]
	v_mfma_f32_16x16x32_bf16 v[0:3], v[156:159], v[212:215], v[0:3]
	v_mfma_f32_16x16x32_bf16 v[20:23], v[156:159], v[220:223], v[20:23]
	v_mfma_f32_16x16x32_bf16 v[32:35], v[164:167], v[212:215], v[32:35]
	v_mfma_f32_16x16x32_bf16 v[36:39], v[164:167], v[220:223], v[36:39]
	v_mfma_f32_16x16x32_bf16 v[68:71], v[196:199], v[212:215], v[68:71]
	v_mfma_f32_16x16x32_bf16 v[110:113], v[196:199], v[220:223], v[118:121]
	v_mfma_f32_16x16x32_bf16 v[102:105], v[204:207], v[212:215], v[102:105]
	v_mfma_f32_16x16x32_bf16 v[106:109], v[204:207], v[220:223], v[106:109]
	s_mov_b32 m0, s47
	v_lshl_add_u64 v[6:7], v[6:7], 0, s[44:45]
	s_barrier
	ds_read_b128 v[118:121], v133
	ds_read_b128 v[122:125], v133 offset:1024
	ds_read_b128 v[134:137], v133 offset:2048
	ds_read_b128 v[144:147], v133 offset:3072
	ds_read_b128 v[152:155], v228
	ds_read_b128 v[156:159], v228 offset:1024
	ds_read_b128 v[160:163], v229 offset:2048
	ds_read_b128 v[164:167], v229 offset:3072
	ds_read_b128 v[180:183], v229 offset:4096
	ds_read_b128 v[184:187], v229 offset:5120
	ds_read_b128 v[188:191], v229 offset:6144
	ds_read_b128 v[192:195], v229 offset:7168
	global_load_lds_dwordx4 v[6:7], off
	v_lshl_add_u64 v[4:5], v[4:5], 0, s[44:45]
	s_mov_b32 m0, s46
	s_nop 0
	global_load_lds_dwordx4 v[4:5], off
	s_barrier
	s_waitcnt lgkmcnt(0)
	s_waitcnt lgkmcnt(0)
	v_mfma_f32_16x16x32_bf16 v[4:7], v[152:155], v[118:121], v[16:19]
	v_mfma_f32_16x16x32_bf16 v[16:19], v[152:155], v[134:137], v[74:77]
	v_mfma_f32_16x16x32_bf16 v[72:75], v[160:163], v[118:121], v[78:81]
	v_mfma_f32_16x16x32_bf16 v[76:79], v[160:163], v[134:137], v[82:85]
	v_mfma_f32_16x16x32_bf16 v[80:83], v[180:183], v[118:121], v[86:89]
	v_mfma_f32_16x16x32_bf16 v[84:87], v[180:183], v[134:137], v[90:93]
	v_mfma_f32_16x16x32_bf16 v[88:91], v[188:191], v[118:121], v[94:97]
	v_mfma_f32_16x16x32_bf16 v[92:95], v[188:191], v[134:137], v[98:101]
	v_mfma_f32_16x16x32_bf16 v[4:7], v[156:159], v[122:125], v[4:7]
	v_mfma_f32_16x16x32_bf16 v[16:19], v[156:159], v[144:147], v[16:19]
	v_mfma_f32_16x16x32_bf16 v[72:75], v[164:167], v[122:125], v[72:75]
	v_mfma_f32_16x16x32_bf16 v[76:79], v[164:167], v[144:147], v[76:79]
	v_mfma_f32_16x16x32_bf16 v[80:83], v[184:187], v[122:125], v[80:83]
	v_mfma_f32_16x16x32_bf16 v[84:87], v[184:187], v[144:147], v[84:87]
	v_mfma_f32_16x16x32_bf16 v[88:91], v[192:195], v[122:125], v[88:91]
	v_mfma_f32_16x16x32_bf16 v[92:95], v[192:195], v[144:147], v[92:95]
	s_barrier
; #define LDA(dst, b, h) for (int m = 0; m < 4; ++m) for (int k = 0; k < 2; ++k) \
;     dst[m][k] = *reinterpret_cast<const bf16x8*>((char*)SA(b, h) + lds_byte(wr * 64 + m * 16 + fr, k * 32 + fq * 8))
; #define LDB(dst, b, h) for (int n = 0; n < 2; ++n) for (int k = 0; k < 2; ++k) \
;     dst[n][k] = *reinterpret_cast<const bf16x8*>((char*)SB(b, h) + lds_byte(wc * 32 + n * 16 + fr, k * 32 + fq * 8))
; #define MMA(ai, bj, At_, Bt_) do { __builtin_amdgcn_s_setprio(1); \
;     for (int k = 0; k < 2; ++k) for (int m = 0; m < 4; ++m) for (int n = 0; n < 2; ++n) \
;       acc[ai][bj][m][n] = __builtin_amdgcn_mfma_f32_16x16x32_bf16(At_[m][k], Bt_[n][k], acc[ai][bj][m][n], 0, 0, 0); \
;     __builtin_amdgcn_s_setprio(0); } while (0)
; #define WAIT_V(n) asm volatile("s_waitcnt vmcnt(" #n ")" ::: "memory")
; #define WAIT_L(n) asm volatile("s_waitcnt lgkmcnt(" #n ")" ::: "memory")
; #define BAR __builtin_amdgcn_s_barrier()
; template <int EPI, int lda, int ldb, int N, int K>
; __device__ __forceinline__ void gemm_phase(const u16* __restrict__ A, const u16* __restrict__ Bt, const GemmEpi ep, int wv) {
;     ...
;       LDB(B1, 0, 1); BAR; WAIT_L(0); MMA(0, 1, At, B1); BAR;
;       LDA(At, 0, 1); WAIT_V(4); BAR; WAIT_L(0); MMA(1, 0, At, B0); MMA(1, 1, At, B1); BAR; }
;     { LDB(B0, 1, 0); LDA(At, 1, 0); WAIT_V(2); BAR; WAIT_L(0); MMA(0, 0, At, B0); BAR;
	ds_read_b128 v[96:99], v224
	ds_read_b128 v[196:199], v224 offset:1024
	ds_read_b128 v[200:203], v224 offset:2048
	ds_read_b128 v[204:207], v224 offset:3072
	s_barrier
	s_waitcnt lgkmcnt(0)
	s_waitcnt lgkmcnt(0)
	v_mfma_f32_16x16x32_bf16 v[12:15], v[152:155], v[96:99], v[12:15]
	v_mfma_f32_16x16x32_bf16 v[40:43], v[152:155], v[200:203], v[40:43]
	v_mfma_f32_16x16x32_bf16 v[52:55], v[180:183], v[96:99], v[52:55]
	v_mfma_f32_16x16x32_bf16 v[56:59], v[180:183], v[200:203], v[56:59]
	v_mfma_f32_16x16x32_bf16 v[64:67], v[188:191], v[200:203], v[64:67]
	v_mfma_f32_16x16x32_bf16 v[44:47], v[160:163], v[96:99], v[44:47]
	v_mfma_f32_16x16x32_bf16 v[48:51], v[160:163], v[200:203], v[48:51]
	v_mfma_f32_16x16x32_bf16 v[60:63], v[188:191], v[96:99], v[60:63]
	v_mfma_f32_16x16x32_bf16 v[12:15], v[156:159], v[196:199], v[12:15]
	v_mfma_f32_16x16x32_bf16 v[40:43], v[156:159], v[204:207], v[40:43]
	v_mfma_f32_16x16x32_bf16 v[52:55], v[184:187], v[196:199], v[52:55]
	v_mfma_f32_16x16x32_bf16 v[56:59], v[184:187], v[204:207], v[56:59]
	v_mfma_f32_16x16x32_bf16 v[64:67], v[192:195], v[204:207], v[64:67]
	v_mfma_f32_16x16x32_bf16 v[152:155], v[164:167], v[196:199], v[44:47]
	v_mfma_f32_16x16x32_bf16 v[156:159], v[164:167], v[204:207], v[48:51]
	v_mfma_f32_16x16x32_bf16 v[160:163], v[192:195], v[196:199], v[60:63]
	s_barrier
	ds_read_b128 v[44:47], v228 offset:16384
	ds_read_b128 v[48:51], v228 offset:17408
	ds_read_b128 v[60:63], v229 offset:18432
	ds_read_b128 v[164:167], v229 offset:19456
	ds_read_b128 v[180:183], v229 offset:20480
	ds_read_b128 v[184:187], v229 offset:21504
	ds_read_b128 v[188:191], v229 offset:22528
	ds_read_b128 v[192:195], v229 offset:23552
	s_waitcnt vmcnt(4)
	s_barrier
	s_waitcnt lgkmcnt(0)
	s_waitcnt lgkmcnt(0)
	v_mfma_f32_16x16x32_bf16 v[8:11], v[44:47], v[118:121], v[8:11]
	v_mfma_f32_16x16x32_bf16 v[24:27], v[188:191], v[118:121], v[24:27]
	v_mfma_f32_16x16x32_bf16 v[28:31], v[188:191], v[134:137], v[28:31]
	v_mfma_f32_16x16x32_bf16 v[114:117], v[44:47], v[134:137], v[114:117]
	v_mfma_f32_16x16x32_bf16 v[148:151], v[60:63], v[118:121], v[148:151]
	v_mfma_f32_16x16x32_bf16 v[168:171], v[60:63], v[134:137], v[168:171]
	v_mfma_f32_16x16x32_bf16 v[172:175], v[180:183], v[118:121], v[172:175]
	v_mfma_f32_16x16x32_bf16 v[176:179], v[180:183], v[134:137], v[176:179]
	v_mfma_f32_16x16x32_bf16 v[8:11], v[48:51], v[122:125], v[8:11]
	v_mfma_f32_16x16x32_bf16 v[24:27], v[192:195], v[122:125], v[24:27]
	v_mfma_f32_16x16x32_bf16 v[28:31], v[192:195], v[144:147], v[28:31]
	v_mfma_f32_16x16x32_bf16 v[134:137], v[48:51], v[144:147], v[114:117]
	v_mfma_f32_16x16x32_bf16 v[148:151], v[164:167], v[122:125], v[148:151]
	v_mfma_f32_16x16x32_bf16 v[168:171], v[164:167], v[144:147], v[168:171]
	v_mfma_f32_16x16x32_bf16 v[172:175], v[184:187], v[122:125], v[172:175]
	v_mfma_f32_16x16x32_bf16 v[176:179], v[184:187], v[144:147], v[176:179]
	v_mfma_f32_16x16x32_bf16 v[0:3], v[44:47], v[96:99], v[0:3]
	v_mfma_f32_16x16x32_bf16 v[20:23], v[44:47], v[200:203], v[20:23]
	v_mfma_f32_16x16x32_bf16 v[44:47], v[180:183], v[96:99], v[68:71]
	v_mfma_f32_16x16x32_bf16 v[68:71], v[188:191], v[96:99], v[102:105]
	v_mfma_f32_16x16x32_bf16 v[32:35], v[60:63], v[96:99], v[32:35]
	v_mfma_f32_16x16x32_bf16 v[36:39], v[60:63], v[200:203], v[36:39]
	v_mfma_f32_16x16x32_bf16 v[60:63], v[180:183], v[200:203], v[110:113]
	v_mfma_f32_16x16x32_bf16 v[96:99], v[188:191], v[200:203], v[106:109]
	v_mfma_f32_16x16x32_bf16 v[20:23], v[48:51], v[204:207], v[20:23]
	v_mfma_f32_16x16x32_bf16 v[68:71], v[192:195], v[196:199], v[68:71]
	v_mfma_f32_16x16x32_bf16 v[144:147], v[48:51], v[196:199], v[0:3]
	v_mfma_f32_16x16x32_bf16 v[180:183], v[164:167], v[196:199], v[32:35]
	v_mfma_f32_16x16x32_bf16 v[164:167], v[164:167], v[204:207], v[36:39]
	v_mfma_f32_16x16x32_bf16 v[188:191], v[184:187], v[196:199], v[44:47]
	v_mfma_f32_16x16x32_bf16 v[184:187], v[184:187], v[204:207], v[60:63]
	v_mfma_f32_16x16x32_bf16 v[192:195], v[192:195], v[204:207], v[96:99]
	s_barrier
	ds_read_b128 v[0:3], v225
	ds_read_b128 v[196:199], v225 offset:1024
	ds_read_b128 v[200:203], v225 offset:2048
	ds_read_b128 v[204:207], v225 offset:3072
	ds_read_b128 v[36:39], v228 offset:32768
	ds_read_b128 v[100:103], v228 offset:33792
	ds_read_b128 v[108:111], v229 offset:34816
	ds_read_b128 v[208:211], v229 offset:35840
	ds_read_b128 v[116:119], v229 offset:36864
	ds_read_b128 v[212:215], v229 offset:37888
	ds_read_b128 v[124:127], v229 offset:38912
	ds_read_b128 v[216:219], v229 offset:39936
	s_waitcnt vmcnt(2)
	s_barrier
; #define LDA(dst, b, h) for (int m = 0; m < 4; ++m) for (int k = 0; k < 2; ++k) \
;     dst[m][k] = *reinterpret_cast<const bf16x8*>((char*)SA(b, h) + lds_byte(wr * 64 + m * 16 + fr, k * 32 + fq * 8))
; #define LDB(dst, b, h) for (int n = 0; n < 2; ++n) for (int k = 0; k < 2; ++k) \
;     dst[n][k] = *reinterpret_cast<const bf16x8*>((char*)SB(b, h) + lds_byte(wc * 32 + n * 16 + fr, k * 32 + fq * 8))
; #define MMA(ai, bj, At_, Bt_) do { __builtin_amdgcn_s_setprio(1); \
;     for (int k = 0; k < 2; ++k) for (int m = 0; m < 4; ++m) for (int n = 0; n < 2; ++n) \
;       acc[ai][bj][m][n] = __builtin_amdgcn_mfma_f32_16x16x32_bf16(At_[m][k], Bt_[n][k], acc[ai][bj][m][n], 0, 0, 0); \
;     __builtin_amdgcn_s_setprio(0); } while (0)
; #define WAIT_V(n) asm volatile("s_waitcnt vmcnt(" #n ")" ::: "memory")
; #define WAIT_L(n) asm volatile("s_waitcnt lgkmcnt(" #n ")" ::: "memory")
; #define BAR __builtin_amdgcn_s_barrier()
; template <int EPI, int lda, int ldb, int N, int K>
; __device__ __forceinline__ void gemm_phase(const u16* __restrict__ A, const u16* __restrict__ Bt, const GemmEpi ep, int wv) {
;     ...
;     { LDB(B0, 1, 0); LDA(At, 1, 0); WAIT_V(2); BAR; WAIT_L(0); MMA(0, 0, At, B0); BAR;
;       LDB(B1, 1, 1); WAIT_V(0); BAR; WAIT_L(0); MMA(0, 1, At, B1); BAR;
;       LDA(At, 1, 1); BAR; WAIT_L(0); MMA(1, 0, At, B0); MMA(1, 1, At, B1); BAR; }
;     if (wr == 0) BAR;
	s_waitcnt lgkmcnt(0)
	s_waitcnt lgkmcnt(0)
	v_mfma_f32_16x16x32_bf16 v[4:7], v[36:39], v[0:3], v[4:7]
	v_mfma_f32_16x16x32_bf16 v[16:19], v[36:39], v[200:203], v[16:19]
	v_mfma_f32_16x16x32_bf16 v[32:35], v[108:111], v[0:3], v[72:75]
	v_mfma_f32_16x16x32_bf16 v[44:47], v[108:111], v[200:203], v[76:79]
	v_mfma_f32_16x16x32_bf16 v[72:75], v[116:119], v[0:3], v[80:83]
	v_mfma_f32_16x16x32_bf16 v[76:79], v[116:119], v[200:203], v[84:87]
	v_mfma_f32_16x16x32_bf16 v[80:83], v[124:127], v[0:3], v[88:91]
	v_mfma_f32_16x16x32_bf16 v[84:87], v[124:127], v[200:203], v[92:95]
	v_mfma_f32_16x16x32_bf16 v[120:123], v[100:103], v[196:199], v[4:7]
	v_mfma_f32_16x16x32_bf16 v[60:63], v[100:103], v[204:207], v[16:19]
	v_mfma_f32_16x16x32_bf16 v[112:115], v[208:211], v[196:199], v[32:35]
	v_mfma_f32_16x16x32_bf16 v[48:51], v[208:211], v[204:207], v[44:47]
	v_mfma_f32_16x16x32_bf16 v[104:107], v[212:215], v[196:199], v[72:75]
	v_mfma_f32_16x16x32_bf16 v[44:47], v[212:215], v[204:207], v[76:79]
	v_mfma_f32_16x16x32_bf16 v[96:99], v[216:219], v[196:199], v[80:83]
	v_mfma_f32_16x16x32_bf16 v[32:35], v[216:219], v[204:207], v[84:87]
	s_barrier
	ds_read_b128 v[4:7], v226
	ds_read_b128 v[220:223], v226 offset:1024
	ds_read_b128 v[76:79], v226 offset:2048
	ds_read_b128 v[224:227], v226 offset:3072
	s_waitcnt vmcnt(0)
	s_barrier
	s_waitcnt lgkmcnt(0)
	s_waitcnt lgkmcnt(0)
	v_mfma_f32_16x16x32_bf16 v[12:15], v[36:39], v[4:7], v[12:15]
	v_mfma_f32_16x16x32_bf16 v[16:19], v[36:39], v[76:79], v[40:43]
	v_mfma_f32_16x16x32_bf16 v[36:39], v[108:111], v[4:7], v[152:155]
	v_mfma_f32_16x16x32_bf16 v[40:43], v[108:111], v[76:79], v[156:159]
	v_mfma_f32_16x16x32_bf16 v[72:75], v[116:119], v[4:7], v[52:55]
	v_mfma_f32_16x16x32_bf16 v[80:83], v[116:119], v[76:79], v[56:59]
	v_mfma_f32_16x16x32_bf16 v[84:87], v[124:127], v[4:7], v[160:163]
	v_mfma_f32_16x16x32_bf16 v[64:67], v[124:127], v[76:79], v[64:67]
	v_mfma_f32_16x16x32_bf16 v[124:127], v[100:103], v[220:223], v[12:15]
	v_mfma_f32_16x16x32_bf16 v[56:59], v[100:103], v[224:227], v[16:19]
	v_mfma_f32_16x16x32_bf16 v[116:119], v[208:211], v[220:223], v[36:39]
	v_mfma_f32_16x16x32_bf16 v[52:55], v[208:211], v[224:227], v[40:43]
	v_mfma_f32_16x16x32_bf16 v[108:111], v[212:215], v[220:223], v[72:75]
	v_mfma_f32_16x16x32_bf16 v[40:43], v[212:215], v[224:227], v[80:83]
	v_mfma_f32_16x16x32_bf16 v[100:103], v[216:219], v[220:223], v[84:87]
	v_mfma_f32_16x16x32_bf16 v[36:39], v[216:219], v[224:227], v[64:67]
	s_barrier
	ds_read_b128 v[84:87], v228 offset:49152
	ds_read_b128 v[152:155], v228 offset:50176
	ds_read_b128 v[92:95], v229 offset:51200
	ds_read_b128 v[156:159], v229 offset:52224
	ds_read_b128 v[160:163], v229 offset:53248
	ds_read_b128 v[208:211], v229 offset:54272
	ds_read_b128 v[212:215], v229 offset:55296
	ds_read_b128 v[216:219], v229 offset:56320
	s_barrier
	s_waitcnt lgkmcnt(0)
	s_waitcnt lgkmcnt(0)
	v_mfma_f32_16x16x32_bf16 v[8:11], v[84:87], v[0:3], v[8:11]
	v_mfma_f32_16x16x32_bf16 v[12:15], v[84:87], v[200:203], v[134:137]
	v_mfma_f32_16x16x32_bf16 v[16:19], v[92:95], v[0:3], v[148:151]
	v_mfma_f32_16x16x32_bf16 v[64:67], v[92:95], v[200:203], v[168:171]
	v_mfma_f32_16x16x32_bf16 v[72:75], v[160:163], v[0:3], v[172:175]
	v_mfma_f32_16x16x32_bf16 v[134:137], v[160:163], v[200:203], v[176:179]
	v_mfma_f32_16x16x32_bf16 v[0:3], v[212:215], v[0:3], v[24:27]
	v_mfma_f32_16x16x32_bf16 v[24:27], v[212:215], v[200:203], v[28:31]
	v_mfma_f32_16x16x32_bf16 v[88:91], v[152:155], v[196:199], v[8:11]
	v_mfma_f32_16x16x32_bf16 v[28:31], v[152:155], v[204:207], v[12:15]
	v_mfma_f32_16x16x32_bf16 v[80:83], v[156:159], v[196:199], v[16:19]
	v_mfma_f32_16x16x32_bf16 v[16:19], v[156:159], v[204:207], v[64:67]
	v_mfma_f32_16x16x32_bf16 v[72:75], v[208:211], v[196:199], v[72:75]
	v_mfma_f32_16x16x32_bf16 v[12:15], v[208:211], v[204:207], v[134:137]
	v_mfma_f32_16x16x32_bf16 v[64:67], v[216:219], v[196:199], v[0:3]
	v_mfma_f32_16x16x32_bf16 v[0:3], v[216:219], v[204:207], v[24:27]
	v_mfma_f32_16x16x32_bf16 v[8:11], v[84:87], v[4:7], v[144:147]
	v_mfma_f32_16x16x32_bf16 v[20:23], v[84:87], v[76:79], v[20:23]
	v_mfma_f32_16x16x32_bf16 v[84:87], v[92:95], v[4:7], v[180:183]
	v_mfma_f32_16x16x32_bf16 v[134:137], v[92:95], v[76:79], v[164:167]
	v_mfma_f32_16x16x32_bf16 v[144:147], v[160:163], v[4:7], v[188:191]
	v_mfma_f32_16x16x32_bf16 v[148:151], v[160:163], v[76:79], v[184:187]
	v_mfma_f32_16x16x32_bf16 v[4:7], v[212:215], v[4:7], v[68:71]
	v_mfma_f32_16x16x32_bf16 v[160:163], v[212:215], v[76:79], v[192:195]
	v_mfma_f32_16x16x32_bf16 v[92:95], v[152:155], v[220:223], v[8:11]
	v_mfma_f32_16x16x32_bf16 v[24:27], v[152:155], v[224:227], v[20:23]
	v_mfma_f32_16x16x32_bf16 v[84:87], v[156:159], v[220:223], v[84:87]
	v_mfma_f32_16x16x32_bf16 v[20:23], v[156:159], v[224:227], v[134:137]
	v_mfma_f32_16x16x32_bf16 v[76:79], v[208:211], v[220:223], v[144:147]
	v_mfma_f32_16x16x32_bf16 v[8:11], v[208:211], v[224:227], v[148:151]
	v_mfma_f32_16x16x32_bf16 v[68:71], v[216:219], v[220:223], v[4:7]
	v_mfma_f32_16x16x32_bf16 v[4:7], v[216:219], v[224:227], v[160:163]
	v_cmp_gt_u32_e32 vcc, s62, v130
	s_barrier
	s_and_saveexec_b64 s[46:47], vcc
	s_cbranch_execz .LBB0_1245
	s_barrier
	s_branch .LBB0_1245

; #define STAGE(P, BASE, LD, br, kt) do { const char* _g = (const char*)((BASE) + (size_t)(br) * (LD) + (size_t)(kt) * 64); \
;     for (int _i = 0; _i < 2; ++_i) { int _b = tidx * 16 + _i * 8192; int _r, _c; stage_rc(_b, _r, _c); \
;       __builtin_amdgcn_global_load_lds((const unsigned*)(_g + (unsigned)((_r * (LD) + _c) * 2)), (unsigned*)((char*)(P) + _b), 16, 0, 0); } } while (0)
; #define LDA(dst, b, h) for (int m = 0; m < 4; ++m) for (int k = 0; k < 2; ++k) \
;     dst[m][k] = *reinterpret_cast<const bf16x8*>((char*)SA(b, h) + lds_byte(wr * 64 + m * 16 + fr, k * 32 + fq * 8))
; #define LDB(dst, b, h) for (int n = 0; n < 2; ++n) for (int k = 0; k < 2; ++k) \
;     dst[n][k] = *reinterpret_cast<const bf16x8*>((char*)SB(b, h) + lds_byte(wc * 32 + n * 16 + fr, k * 32 + fq * 8))
; #define MMA(ai, bj, At_, Bt_) do { __builtin_amdgcn_s_setprio(1); \
;     for (int k = 0; k < 2; ++k) for (int m = 0; m < 4; ++m) for (int n = 0; n < 2; ++n) \
;       acc[ai][bj][m][n] = __builtin_amdgcn_mfma_f32_16x16x32_bf16(At_[m][k], Bt_[n][k], acc[ai][bj][m][n], 0, 0, 0); \
;     __builtin_amdgcn_s_setprio(0); } while (0)
; #define WAIT_V(n) asm volatile("s_waitcnt vmcnt(" #n ")" ::: "memory")
; #define WAIT_L(n) asm volatile("s_waitcnt lgkmcnt(" #n ")" ::: "memory")
; #define BAR __builtin_amdgcn_s_barrier()
; #define SCHED __builtin_amdgcn_sched_barrier(0)
; template <int EPI, int lda, int ldb, int N, int K>
; __device__ __forceinline__ void gemm_phase(const u16* __restrict__ A, const u16* __restrict__ Bt, const GemmEpi ep, int wv) {
;     ...
;     if (wr == 1) BAR;
;     WAIT_V(4); BAR;
;     STAGE(SB(1, 0), Bt, ldb, bcol, 1); STAGE(SA(1, 0), Ab, lda, brow, 1); STAGE(SB(1, 1), Bt, ldb, bcol + HALF, 1);
;     WAIT_V(6); BAR;
;     for (int t = 0; t < nt - 2; t += 2) {
;       LDB(B0, 0, 0); SCHED; LDA(At, 0, 0); STAGE(SA(1, 1), Ab, lda, brow + HALF, t + 1);
;       WAIT_L(8); BAR; WAIT_L(0); MMA(0, 0, At, B0); BAR; SCHED;
;       LDB(B1, 0, 1); STAGE(SB(0, 0), Bt, ldb, bcol, t + 2);
;       BAR; WAIT_L(0); MMA(0, 1, At, B1); BAR;
.LBB0_1349:
	s_or_b64 exec, exec, s[54:55]
	v_mov_b32_e32 v1, v129
	v_add_u32_e32 v7, s58, v6
	v_lshl_add_u64 v[12:13], s[46:47], 0, v[128:129]
	v_lshl_add_u64 v[14:15], s[46:47], 0, v[0:1]
	v_lshl_add_u64 v[2:3], s[52:53], 0, v[128:129]
	v_lshl_add_u64 v[0:1], s[52:53], 0, v[0:1]
	v_readfirstlane_b32 s53, v7
	v_add_u32_e32 v7, 0x2000, v7
	v_mov_b32_e32 v5, v129
	v_mov_b32_e32 v17, v129
	v_lshl_add_u64 v[26:27], v[12:13], 0, s[36:37]
	s_mov_b32 m0, s53
	v_readfirstlane_b32 s52, v7
	v_add_u32_e32 v7, 0x8000, v23
	v_lshl_add_u64 v[8:9], s[50:51], 0, v[4:5]
	v_lshl_add_u64 v[10:11], s[50:51], 0, v[16:17]
	s_waitcnt vmcnt(4)
	s_barrier
	global_load_lds_dwordx4 v[26:27], off
	v_lshl_add_u64 v[26:27], v[14:15], 0, s[36:37]
	s_mov_b32 m0, s52
	v_readfirstlane_b32 s51, v7
	v_add_u32_e32 v7, 0xa000, v23
	global_load_lds_dwordx4 v[26:27], off
	v_lshl_add_u64 v[26:27], v[8:9], 0, s[36:37]
	s_mov_b32 m0, s51
	v_readfirstlane_b32 s50, v7
	v_add_u32_e32 v25, s59, v6
	global_load_lds_dwordx4 v[26:27], off
	v_lshl_add_u64 v[26:27], v[10:11], 0, s[36:37]
	s_mov_b32 m0, s50
	v_readfirstlane_b32 s11, v25
	v_add_u32_e32 v25, 0x2000, v25
	global_load_lds_dwordx4 v[26:27], off
	v_lshl_add_u64 v[26:27], v[2:3], 0, s[36:37]
	s_mov_b32 m0, s11
	v_readfirstlane_b32 s5, v25
	global_load_lds_dwordx4 v[26:27], off
	v_lshl_add_u64 v[6:7], v[0:1], 0, s[36:37]
	s_mov_b32 m0, s5
	v_and_b32_e32 v132, 15, v20
	global_load_lds_dwordx4 v[6:7], off
	v_bfe_u32 v128, v20, 4, 2
	v_lshlrev_b32_e32 v7, 2, v20
	v_bfe_u32 v131, v130, 6, 2
	v_lshlrev_b32_e32 v25, 4, v128
	v_lshlrev_b32_e32 v6, 6, v132
	v_and_b32_e32 v50, 32, v7
	v_lshlrev_b32_e32 v126, 12, v131
	v_bitop3_b32 v127, v25, v50, v6 bitop3:0x36
	v_add3_u32 v133, s56, v127, v126
	s_waitcnt vmcnt(6)
	s_barrier
	ds_read_b128 v[26:29], v133
	ds_read_b128 v[30:33], v133 offset:1024
	ds_read_b128 v[34:37], v133 offset:2048
	ds_read_b128 v[38:41], v133 offset:3072
	v_lshl_add_u64 v[6:7], s[48:49], 0, v[4:5]
	v_lshl_add_u64 v[4:5], s[48:49], 0, v[16:17]
	v_lshlrev_b32_e32 v17, 6, v20
	v_and_b32_e32 v17, 0x3c0, v17
	v_add_u32_e32 v20, 0xc000, v23
	v_lshlrev_b32_e32 v16, 13, v139
	v_bitop3_b32 v17, v17, v50, v25 bitop3:0x36
	v_readfirstlane_b32 s47, v20
	v_add_u32_e32 v20, 0xe000, v23
	v_add3_u32 v228, 0, v127, v16
	v_add3_u32 v229, 0, v17, v16
	v_lshl_add_u64 v[16:17], v[6:7], 0, s[36:37]
	s_mov_b32 m0, s47
	v_readfirstlane_b32 s46, v20
	ds_read_b128 v[42:45], v228
	ds_read_b128 v[46:49], v228 offset:1024
	ds_read_b128 v[50:53], v229 offset:2048
	ds_read_b128 v[54:57], v229 offset:3072
	ds_read_b128 v[58:61], v229 offset:4096
	ds_read_b128 v[62:65], v229 offset:5120
	ds_read_b128 v[66:69], v229 offset:6144
	ds_read_b128 v[70:73], v229 offset:7168
	global_load_lds_dwordx4 v[16:17], off
	v_lshl_add_u64 v[16:17], v[4:5], 0, s[36:37]
	s_mov_b32 m0, s46
	s_nop 0
	global_load_lds_dwordx4 v[16:17], off
	s_waitcnt lgkmcnt(8)
	s_barrier
	s_waitcnt lgkmcnt(0)
	s_waitcnt lgkmcnt(0)
	v_mfma_f32_16x16x32_bf16 v[74:77], v[42:45], v[26:29], 0
	v_mfma_f32_16x16x32_bf16 v[78:81], v[42:45], v[34:37], 0
	v_mfma_f32_16x16x32_bf16 v[82:85], v[50:53], v[26:29], 0
	v_mfma_f32_16x16x32_bf16 v[86:89], v[50:53], v[34:37], 0
	v_mfma_f32_16x16x32_bf16 v[90:93], v[58:61], v[26:29], 0
	v_mfma_f32_16x16x32_bf16 v[94:97], v[58:61], v[34:37], 0
	v_mfma_f32_16x16x32_bf16 v[98:101], v[66:69], v[26:29], 0
	v_mfma_f32_16x16x32_bf16 v[102:105], v[66:69], v[34:37], 0
	v_mfma_f32_16x16x32_bf16 v[74:77], v[46:49], v[30:33], v[74:77]
	v_mfma_f32_16x16x32_bf16 v[78:81], v[46:49], v[38:41], v[78:81]
	v_mfma_f32_16x16x32_bf16 v[82:85], v[54:57], v[30:33], v[82:85]
	v_mfma_f32_16x16x32_bf16 v[86:89], v[54:57], v[38:41], v[86:89]
	v_mfma_f32_16x16x32_bf16 v[90:93], v[62:65], v[30:33], v[90:93]
	v_mfma_f32_16x16x32_bf16 v[94:97], v[62:65], v[38:41], v[94:97]
	v_mfma_f32_16x16x32_bf16 v[98:101], v[70:73], v[30:33], v[98:101]
	v_mfma_f32_16x16x32_bf16 v[102:105], v[70:73], v[38:41], v[102:105]
	s_barrier
	v_readfirstlane_b32 s48, v21
	v_add_u32_e32 v20, 0x2000, v21
	v_add3_u32 v224, s57, v127, v126
	v_lshl_add_u64 v[16:17], v[12:13], 0, s[38:39]
	s_mov_b32 m0, s48
	v_readfirstlane_b32 s48, v20
	ds_read_b128 v[106:109], v224
	ds_read_b128 v[110:113], v224 offset:1024
	ds_read_b128 v[114:117], v224 offset:2048
	ds_read_b128 v[118:121], v224 offset:3072
	global_load_lds_dwordx4 v[16:17], off
	s_nop 1
	v_lshl_add_u64 v[16:17], v[14:15], 0, s[38:39]
	s_mov_b32 m0, s48
	s_nop 0
	global_load_lds_dwordx4 v[16:17], off
	s_barrier
	s_waitcnt lgkmcnt(0)
	s_waitcnt lgkmcnt(0)
	v_mfma_f32_16x16x32_bf16 v[122:125], v[42:45], v[106:109], 0
	v_mfma_f32_16x16x32_bf16 v[42:45], v[42:45], v[114:117], 0
	v_mfma_f32_16x16x32_bf16 v[140:143], v[50:53], v[106:109], 0
	v_mfma_f32_16x16x32_bf16 v[50:53], v[50:53], v[114:117], 0
	v_mfma_f32_16x16x32_bf16 v[144:147], v[58:61], v[106:109], 0
	v_mfma_f32_16x16x32_bf16 v[58:61], v[58:61], v[114:117], 0
	v_mfma_f32_16x16x32_bf16 v[148:151], v[66:69], v[106:109], 0
	v_mfma_f32_16x16x32_bf16 v[66:69], v[66:69], v[114:117], 0
	v_mfma_f32_16x16x32_bf16 v[122:125], v[46:49], v[110:113], v[122:125]
	v_mfma_f32_16x16x32_bf16 v[42:45], v[46:49], v[118:121], v[42:45]
	v_mfma_f32_16x16x32_bf16 v[46:49], v[54:57], v[110:113], v[140:143]
	v_mfma_f32_16x16x32_bf16 v[50:53], v[54:57], v[118:121], v[50:53]
	v_mfma_f32_16x16x32_bf16 v[54:57], v[62:65], v[110:113], v[144:147]
	v_mfma_f32_16x16x32_bf16 v[58:61], v[62:65], v[118:121], v[58:61]
	v_mfma_f32_16x16x32_bf16 v[62:65], v[70:73], v[110:113], v[148:151]
	v_mfma_f32_16x16x32_bf16 v[66:69], v[70:73], v[118:121], v[66:69]
	v_readfirstlane_b32 s48, v23
	v_lshl_add_u64 v[16:17], v[8:9], 0, s[38:39]
	s_mov_b32 m0, s48
	v_readfirstlane_b32 s48, v24
	s_barrier
; #define STAGE(P, BASE, LD, br, kt) do { const char* _g = (const char*)((BASE) + (size_t)(br) * (LD) + (size_t)(kt) * 64); \
;     for (int _i = 0; _i < 2; ++_i) { int _b = tidx * 16 + _i * 8192; int _r, _c; stage_rc(_b, _r, _c); \
;       __builtin_amdgcn_global_load_lds((const unsigned*)(_g + (unsigned)((_r * (LD) + _c) * 2)), (unsigned*)((char*)(P) + _b), 16, 0, 0); } } while (0)
; #define LDA(dst, b, h) for (int m = 0; m < 4; ++m) for (int k = 0; k < 2; ++k) \
;     dst[m][k] = *reinterpret_cast<const bf16x8*>((char*)SA(b, h) + lds_byte(wr * 64 + m * 16 + fr, k * 32 + fq * 8))
; #define LDB(dst, b, h) for (int n = 0; n < 2; ++n) for (int k = 0; k < 2; ++k) \
;     dst[n][k] = *reinterpret_cast<const bf16x8*>((char*)SB(b, h) + lds_byte(wc * 32 + n * 16 + fr, k * 32 + fq * 8))
; #define MMA(ai, bj, At_, Bt_) do { __builtin_amdgcn_s_setprio(1); \
;     for (int k = 0; k < 2; ++k) for (int m = 0; m < 4; ++m) for (int n = 0; n < 2; ++n) \
;       acc[ai][bj][m][n] = __builtin_amdgcn_mfma_f32_16x16x32_bf16(At_[m][k], Bt_[n][k], acc[ai][bj][m][n], 0, 0, 0); \
;     __builtin_amdgcn_s_setprio(0); } while (0)
; #define WAIT_V(n) asm volatile("s_waitcnt vmcnt(" #n ")" ::: "memory")
; #define WAIT_L(n) asm volatile("s_waitcnt lgkmcnt(" #n ")" ::: "memory")
; #define BAR __builtin_amdgcn_s_barrier()
; #define SCHED __builtin_amdgcn_sched_barrier(0)
; template <int EPI, int lda, int ldb, int N, int K>
; __device__ __forceinline__ void gemm_phase(const u16* __restrict__ A, const u16* __restrict__ Bt, const GemmEpi ep, int wv) {
;     ...
;       LDA(At, 0, 1); STAGE(SA(0, 0), Ab, lda, brow, t + 2);
;       BAR; WAIT_L(0); MMA(1, 0, At, B0); BAR; SCHED;
;       STAGE(SB(0, 1), Bt, ldb, bcol + HALF, t + 2);
;       WAIT_V(6); BAR; MMA(1, 1, At, B1); BAR;
;       LDB(B0, 1, 0); SCHED; LDA(At, 1, 0); STAGE(SA(0, 1), Ab, lda, brow + HALF, t + 2);
;       WAIT_L(8); BAR; WAIT_L(0); MMA(0, 0, At, B0); BAR; SCHED;
;       LDB(B1, 1, 1); STAGE(SB(1, 0), Bt, ldb, bcol, t + 3);
	ds_read_b128 v[70:73], v228 offset:16384
	ds_read_b128 v[140:143], v228 offset:17408
	ds_read_b128 v[144:147], v229 offset:18432
	ds_read_b128 v[148:151], v229 offset:19456
	ds_read_b128 v[152:155], v229 offset:20480
	ds_read_b128 v[156:159], v229 offset:21504
	ds_read_b128 v[160:163], v229 offset:22528
	ds_read_b128 v[164:167], v229 offset:23552
	global_load_lds_dwordx4 v[16:17], off
	s_nop 1
	v_lshl_add_u64 v[16:17], v[10:11], 0, s[38:39]
	s_mov_b32 m0, s48
	s_nop 0
	global_load_lds_dwordx4 v[16:17], off
	s_barrier
	s_waitcnt lgkmcnt(0)
	s_waitcnt lgkmcnt(0)
	v_mfma_f32_16x16x32_bf16 v[168:171], v[70:73], v[26:29], 0
	v_mfma_f32_16x16x32_bf16 v[172:175], v[70:73], v[34:37], 0
	v_mfma_f32_16x16x32_bf16 v[176:179], v[144:147], v[26:29], 0
	v_mfma_f32_16x16x32_bf16 v[180:183], v[144:147], v[34:37], 0
	v_mfma_f32_16x16x32_bf16 v[184:187], v[152:155], v[26:29], 0
	v_mfma_f32_16x16x32_bf16 v[188:191], v[152:155], v[34:37], 0
	v_mfma_f32_16x16x32_bf16 v[24:27], v[160:163], v[26:29], 0
	v_mfma_f32_16x16x32_bf16 v[34:37], v[160:163], v[34:37], 0
	v_mfma_f32_16x16x32_bf16 v[168:171], v[140:143], v[30:33], v[168:171]
	v_mfma_f32_16x16x32_bf16 v[176:179], v[148:151], v[30:33], v[176:179]
	v_mfma_f32_16x16x32_bf16 v[184:187], v[156:159], v[30:33], v[184:187]
	v_mfma_f32_16x16x32_bf16 v[24:27], v[164:167], v[30:33], v[24:27]
	v_mfma_f32_16x16x32_bf16 v[28:31], v[164:167], v[38:41], v[34:37]
	v_mfma_f32_16x16x32_bf16 v[172:175], v[140:143], v[38:41], v[172:175]
	v_mfma_f32_16x16x32_bf16 v[180:183], v[148:151], v[38:41], v[180:183]
	v_mfma_f32_16x16x32_bf16 v[188:191], v[156:159], v[38:41], v[188:191]
	s_barrier
	v_readfirstlane_b32 s48, v22
	v_add_u32_e32 v20, 0x2000, v22
	v_lshl_add_u64 v[16:17], v[2:3], 0, s[38:39]
	s_mov_b32 m0, s48
	v_readfirstlane_b32 s48, v20
	global_load_lds_dwordx4 v[16:17], off
	s_nop 1
	v_lshl_add_u64 v[16:17], v[0:1], 0, s[38:39]
	s_mov_b32 m0, s48
	s_nop 0
	global_load_lds_dwordx4 v[16:17], off
	s_waitcnt vmcnt(6)
	s_barrier
	v_mfma_f32_16x16x32_bf16 v[20:23], v[70:73], v[106:109], 0
	v_mfma_f32_16x16x32_bf16 v[32:35], v[70:73], v[114:117], 0
	v_mfma_f32_16x16x32_bf16 v[36:39], v[144:147], v[106:109], 0
	v_mfma_f32_16x16x32_bf16 v[70:73], v[144:147], v[114:117], 0
	v_mfma_f32_16x16x32_bf16 v[144:147], v[152:155], v[106:109], 0
	v_mfma_f32_16x16x32_bf16 v[152:155], v[152:155], v[114:117], 0
	v_mfma_f32_16x16x32_bf16 v[106:109], v[160:163], v[106:109], 0
	v_mfma_f32_16x16x32_bf16 v[114:117], v[160:163], v[114:117], 0
	v_mfma_f32_16x16x32_bf16 v[20:23], v[140:143], v[110:113], v[20:23]
	v_mfma_f32_16x16x32_bf16 v[32:35], v[140:143], v[118:121], v[32:35]
	v_mfma_f32_16x16x32_bf16 v[36:39], v[148:151], v[110:113], v[36:39]
	v_mfma_f32_16x16x32_bf16 v[70:73], v[148:151], v[118:121], v[70:73]
	v_mfma_f32_16x16x32_bf16 v[140:143], v[156:159], v[110:113], v[144:147]
	v_mfma_f32_16x16x32_bf16 v[106:109], v[164:167], v[110:113], v[106:109]
	v_mfma_f32_16x16x32_bf16 v[110:113], v[164:167], v[118:121], v[114:117]
	v_mfma_f32_16x16x32_bf16 v[144:147], v[156:159], v[118:121], v[152:155]
	v_add3_u32 v225, s58, v127, v126
	s_barrier
	ds_read_b128 v[114:117], v225
	ds_read_b128 v[118:121], v225 offset:1024
	ds_read_b128 v[148:151], v225 offset:2048
	ds_read_b128 v[152:155], v225 offset:3072
	v_readfirstlane_b32 s48, v18
	v_lshl_add_u64 v[16:17], v[6:7], 0, s[38:39]
	s_mov_b32 m0, s48
	v_readfirstlane_b32 s48, v19
	ds_read_b128 v[156:159], v228 offset:32768
	ds_read_b128 v[160:163], v228 offset:33792
	ds_read_b128 v[164:167], v229 offset:34816
	ds_read_b128 v[192:195], v229 offset:35840
	ds_read_b128 v[196:199], v229 offset:36864
	ds_read_b128 v[200:203], v229 offset:37888
	ds_read_b128 v[204:207], v229 offset:38912
	ds_read_b128 v[208:211], v229 offset:39936
	global_load_lds_dwordx4 v[16:17], off
	s_nop 1
	v_lshl_add_u64 v[16:17], v[4:5], 0, s[38:39]
	s_mov_b32 m0, s48
	s_nop 0
	global_load_lds_dwordx4 v[16:17], off
	s_waitcnt lgkmcnt(8)
	s_barrier
	s_waitcnt lgkmcnt(0)
	s_waitcnt lgkmcnt(0)
	v_mfma_f32_16x16x32_bf16 v[16:19], v[156:159], v[114:117], v[74:77]
	v_mfma_f32_16x16x32_bf16 v[74:77], v[156:159], v[148:151], v[78:81]
	v_mfma_f32_16x16x32_bf16 v[78:81], v[164:167], v[114:117], v[82:85]
	v_mfma_f32_16x16x32_bf16 v[82:85], v[164:167], v[148:151], v[86:89]
	v_mfma_f32_16x16x32_bf16 v[86:89], v[196:199], v[114:117], v[90:93]
	v_mfma_f32_16x16x32_bf16 v[90:93], v[196:199], v[148:151], v[94:97]
	v_mfma_f32_16x16x32_bf16 v[94:97], v[204:207], v[114:117], v[98:101]
	v_mfma_f32_16x16x32_bf16 v[98:101], v[204:207], v[148:151], v[102:105]
	v_mfma_f32_16x16x32_bf16 v[16:19], v[160:163], v[118:121], v[16:19]
	v_mfma_f32_16x16x32_bf16 v[74:77], v[160:163], v[152:155], v[74:77]
	v_mfma_f32_16x16x32_bf16 v[78:81], v[192:195], v[118:121], v[78:81]
	v_mfma_f32_16x16x32_bf16 v[82:85], v[192:195], v[152:155], v[82:85]
	v_mfma_f32_16x16x32_bf16 v[86:89], v[200:203], v[118:121], v[86:89]
	v_mfma_f32_16x16x32_bf16 v[90:93], v[200:203], v[152:155], v[90:93]
	v_mfma_f32_16x16x32_bf16 v[94:97], v[208:211], v[118:121], v[94:97]
	v_mfma_f32_16x16x32_bf16 v[98:101], v[208:211], v[152:155], v[98:101]
	s_barrier
	s_mov_b32 m0, s53
	v_add3_u32 v226, s59, v127, v126
	v_lshl_add_u64 v[12:13], v[12:13], 0, s[40:41]
	ds_read_b128 v[102:105], v226
	ds_read_b128 v[212:215], v226 offset:1024
	ds_read_b128 v[216:219], v226 offset:2048
	ds_read_b128 v[220:223], v226 offset:3072
	global_load_lds_dwordx4 v[12:13], off
	s_nop 1
	v_lshl_add_u64 v[12:13], v[14:15], 0, s[40:41]
	s_mov_b32 m0, s52
	s_nop 0
	global_load_lds_dwordx4 v[12:13], off
	s_barrier
; #define STAGE(P, BASE, LD, br, kt) do { const char* _g = (const char*)((BASE) + (size_t)(br) * (LD) + (size_t)(kt) * 64); \
;     for (int _i = 0; _i < 2; ++_i) { int _b = tidx * 16 + _i * 8192; int _r, _c; stage_rc(_b, _r, _c); \
;       __builtin_amdgcn_global_load_lds((const unsigned*)(_g + (unsigned)((_r * (LD) + _c) * 2)), (unsigned*)((char*)(P) + _b), 16, 0, 0); } } while (0)
; #define LDA(dst, b, h) for (int m = 0; m < 4; ++m) for (int k = 0; k < 2; ++k) \
;     dst[m][k] = *reinterpret_cast<const bf16x8*>((char*)SA(b, h) + lds_byte(wr * 64 + m * 16 + fr, k * 32 + fq * 8))
; #define LDB(dst, b, h) for (int n = 0; n < 2; ++n) for (int k = 0; k < 2; ++k) \
;     dst[n][k] = *reinterpret_cast<const bf16x8*>((char*)SB(b, h) + lds_byte(wc * 32 + n * 16 + fr, k * 32 + fq * 8))
; #define MMA(ai, bj, At_, Bt_) do { __builtin_amdgcn_s_setprio(1); \
;     for (int k = 0; k < 2; ++k) for (int m = 0; m < 4; ++m) for (int n = 0; n < 2; ++n) \
;       acc[ai][bj][m][n] = __builtin_amdgcn_mfma_f32_16x16x32_bf16(At_[m][k], Bt_[n][k], acc[ai][bj][m][n], 0, 0, 0); \
;     __builtin_amdgcn_s_setprio(0); } while (0)
; #define WAIT_V(n) asm volatile("s_waitcnt vmcnt(" #n ")" ::: "memory")
; #define WAIT_L(n) asm volatile("s_waitcnt lgkmcnt(" #n ")" ::: "memory")
; #define BAR __builtin_amdgcn_s_barrier()
; #define SCHED __builtin_amdgcn_sched_barrier(0)
; template <int EPI, int lda, int ldb, int N, int K>
; __device__ __forceinline__ void gemm_phase(const u16* __restrict__ A, const u16* __restrict__ Bt, const GemmEpi ep, int wv) {
;     ...
;       BAR; WAIT_L(0); MMA(0, 1, At, B1); BAR;
;       LDA(At, 1, 1); STAGE(SA(1, 0), Ab, lda, brow, t + 3);
;       BAR; WAIT_L(0); MMA(1, 0, At, B0); BAR; SCHED;
;       STAGE(SB(1, 1), Bt, ldb, bcol + HALF, t + 3);
;       WAIT_V(6); BAR; MMA(1, 1, At, B1); BAR;
;     }
;     { LDB(B0, 0, 0); LDA(At, 0, 0); STAGE(SA(1, 1), Ab, lda, brow + HALF, nt - 1);
;       BAR; WAIT_L(0); MMA(0, 0, At, B0); BAR;
	s_waitcnt lgkmcnt(0)
	s_waitcnt lgkmcnt(0)
	v_mfma_f32_16x16x32_bf16 v[12:15], v[156:159], v[102:105], v[122:125]
	v_mfma_f32_16x16x32_bf16 v[40:43], v[156:159], v[216:219], v[42:45]
	v_mfma_f32_16x16x32_bf16 v[44:47], v[164:167], v[102:105], v[46:49]
	v_mfma_f32_16x16x32_bf16 v[48:51], v[164:167], v[216:219], v[50:53]
	v_mfma_f32_16x16x32_bf16 v[52:55], v[196:199], v[102:105], v[54:57]
	v_mfma_f32_16x16x32_bf16 v[56:59], v[196:199], v[216:219], v[58:61]
	v_mfma_f32_16x16x32_bf16 v[60:63], v[204:207], v[102:105], v[62:65]
	v_mfma_f32_16x16x32_bf16 v[64:67], v[204:207], v[216:219], v[66:69]
	v_mfma_f32_16x16x32_bf16 v[12:15], v[160:163], v[212:215], v[12:15]
	v_mfma_f32_16x16x32_bf16 v[40:43], v[160:163], v[220:223], v[40:43]
	v_mfma_f32_16x16x32_bf16 v[44:47], v[192:195], v[212:215], v[44:47]
	v_mfma_f32_16x16x32_bf16 v[48:51], v[192:195], v[220:223], v[48:51]
	v_mfma_f32_16x16x32_bf16 v[52:55], v[200:203], v[212:215], v[52:55]
	v_mfma_f32_16x16x32_bf16 v[56:59], v[200:203], v[220:223], v[56:59]
	v_mfma_f32_16x16x32_bf16 v[60:63], v[208:211], v[212:215], v[60:63]
	v_mfma_f32_16x16x32_bf16 v[64:67], v[208:211], v[220:223], v[64:67]
	s_mov_b32 m0, s51
	v_lshl_add_u64 v[8:9], v[8:9], 0, s[40:41]
	s_barrier
	ds_read_b128 v[122:125], v228 offset:49152
	ds_read_b128 v[156:159], v228 offset:50176
	ds_read_b128 v[160:163], v229 offset:51200
	ds_read_b128 v[164:167], v229 offset:52224
	ds_read_b128 v[192:195], v229 offset:53248
	ds_read_b128 v[196:199], v229 offset:54272
	ds_read_b128 v[200:203], v229 offset:55296
	ds_read_b128 v[204:207], v229 offset:56320
	global_load_lds_dwordx4 v[8:9], off
	s_nop 1
	v_lshl_add_u64 v[8:9], v[10:11], 0, s[40:41]
	s_mov_b32 m0, s50
	s_nop 0
	global_load_lds_dwordx4 v[8:9], off
	s_barrier
	s_waitcnt lgkmcnt(0)
	s_waitcnt lgkmcnt(0)
	v_mfma_f32_16x16x32_bf16 v[8:11], v[122:125], v[114:117], v[168:171]
	v_mfma_f32_16x16x32_bf16 v[168:171], v[122:125], v[148:151], v[172:175]
	v_mfma_f32_16x16x32_bf16 v[24:27], v[200:203], v[114:117], v[24:27]
	v_mfma_f32_16x16x32_bf16 v[28:31], v[200:203], v[148:151], v[28:31]
	v_mfma_f32_16x16x32_bf16 v[172:175], v[160:163], v[114:117], v[176:179]
	v_mfma_f32_16x16x32_bf16 v[176:179], v[160:163], v[148:151], v[180:183]
	v_mfma_f32_16x16x32_bf16 v[180:183], v[192:195], v[114:117], v[184:187]
	v_mfma_f32_16x16x32_bf16 v[184:187], v[192:195], v[148:151], v[188:191]
	v_mfma_f32_16x16x32_bf16 v[8:11], v[156:159], v[118:121], v[8:11]
	v_mfma_f32_16x16x32_bf16 v[114:117], v[156:159], v[152:155], v[168:171]
	v_mfma_f32_16x16x32_bf16 v[24:27], v[204:207], v[118:121], v[24:27]
	v_mfma_f32_16x16x32_bf16 v[28:31], v[204:207], v[152:155], v[28:31]
	v_mfma_f32_16x16x32_bf16 v[148:151], v[164:167], v[118:121], v[172:175]
	v_mfma_f32_16x16x32_bf16 v[168:171], v[164:167], v[152:155], v[176:179]
	v_mfma_f32_16x16x32_bf16 v[172:175], v[196:199], v[118:121], v[180:183]
	v_mfma_f32_16x16x32_bf16 v[176:179], v[196:199], v[152:155], v[184:187]
	s_barrier
	s_mov_b32 m0, s11
	v_lshl_add_u64 v[2:3], v[2:3], 0, s[40:41]
	global_load_lds_dwordx4 v[2:3], off
	s_nop 1
	v_lshl_add_u64 v[0:1], v[0:1], 0, s[40:41]
	s_mov_b32 m0, s5
	s_nop 0
	global_load_lds_dwordx4 v[0:1], off
	s_waitcnt vmcnt(6)
	s_barrier
	v_mfma_f32_16x16x32_bf16 v[0:3], v[122:125], v[102:105], v[20:23]
	v_mfma_f32_16x16x32_bf16 v[20:23], v[122:125], v[216:219], v[32:35]
	v_mfma_f32_16x16x32_bf16 v[32:35], v[160:163], v[102:105], v[36:39]
	v_mfma_f32_16x16x32_bf16 v[36:39], v[160:163], v[216:219], v[70:73]
	v_mfma_f32_16x16x32_bf16 v[68:71], v[192:195], v[102:105], v[140:143]
	v_mfma_f32_16x16x32_bf16 v[118:121], v[192:195], v[216:219], v[144:147]
	v_mfma_f32_16x16x32_bf16 v[102:105], v[200:203], v[102:105], v[106:109]
	v_mfma_f32_16x16x32_bf16 v[106:109], v[200:203], v[216:219], v[110:113]
	v_mfma_f32_16x16x32_bf16 v[0:3], v[156:159], v[212:215], v[0:3]
	v_mfma_f32_16x16x32_bf16 v[20:23], v[156:159], v[220:223], v[20:23]
	v_mfma_f32_16x16x32_bf16 v[32:35], v[164:167], v[212:215], v[32:35]
	v_mfma_f32_16x16x32_bf16 v[36:39], v[164:167], v[220:223], v[36:39]
	v_mfma_f32_16x16x32_bf16 v[68:71], v[196:199], v[212:215], v[68:71]
	v_mfma_f32_16x16x32_bf16 v[110:113], v[196:199], v[220:223], v[118:121]
	v_mfma_f32_16x16x32_bf16 v[102:105], v[204:207], v[212:215], v[102:105]
	v_mfma_f32_16x16x32_bf16 v[106:109], v[204:207], v[220:223], v[106:109]
	s_mov_b32 m0, s47
	v_lshl_add_u64 v[6:7], v[6:7], 0, s[40:41]
	s_barrier
	ds_read_b128 v[118:121], v133
	ds_read_b128 v[122:125], v133 offset:1024
	ds_read_b128 v[140:143], v133 offset:2048
	ds_read_b128 v[144:147], v133 offset:3072
	ds_read_b128 v[152:155], v228
	ds_read_b128 v[156:159], v228 offset:1024
	ds_read_b128 v[160:163], v229 offset:2048
	ds_read_b128 v[164:167], v229 offset:3072
	ds_read_b128 v[180:183], v229 offset:4096
	ds_read_b128 v[184:187], v229 offset:5120
	ds_read_b128 v[188:191], v229 offset:6144
	ds_read_b128 v[192:195], v229 offset:7168
	global_load_lds_dwordx4 v[6:7], off
	v_lshl_add_u64 v[4:5], v[4:5], 0, s[40:41]
	s_mov_b32 m0, s46
	s_nop 0
	global_load_lds_dwordx4 v[4:5], off
	s_barrier
	s_waitcnt lgkmcnt(0)
	s_waitcnt lgkmcnt(0)
	v_mfma_f32_16x16x32_bf16 v[4:7], v[152:155], v[118:121], v[16:19]
	v_mfma_f32_16x16x32_bf16 v[16:19], v[152:155], v[140:143], v[74:77]
	v_mfma_f32_16x16x32_bf16 v[72:75], v[160:163], v[118:121], v[78:81]
	v_mfma_f32_16x16x32_bf16 v[76:79], v[160:163], v[140:143], v[82:85]
	v_mfma_f32_16x16x32_bf16 v[80:83], v[180:183], v[118:121], v[86:89]
	v_mfma_f32_16x16x32_bf16 v[84:87], v[180:183], v[140:143], v[90:93]
	v_mfma_f32_16x16x32_bf16 v[88:91], v[188:191], v[118:121], v[94:97]
	v_mfma_f32_16x16x32_bf16 v[92:95], v[188:191], v[140:143], v[98:101]
	v_mfma_f32_16x16x32_bf16 v[4:7], v[156:159], v[122:125], v[4:7]
	v_mfma_f32_16x16x32_bf16 v[16:19], v[156:159], v[144:147], v[16:19]
	v_mfma_f32_16x16x32_bf16 v[72:75], v[164:167], v[122:125], v[72:75]
	v_mfma_f32_16x16x32_bf16 v[76:79], v[164:167], v[144:147], v[76:79]
	v_mfma_f32_16x16x32_bf16 v[80:83], v[184:187], v[122:125], v[80:83]
	v_mfma_f32_16x16x32_bf16 v[84:87], v[184:187], v[144:147], v[84:87]
	v_mfma_f32_16x16x32_bf16 v[88:91], v[192:195], v[122:125], v[88:91]
	v_mfma_f32_16x16x32_bf16 v[92:95], v[192:195], v[144:147], v[92:95]
	s_barrier
; #define LDA(dst, b, h) for (int m = 0; m < 4; ++m) for (int k = 0; k < 2; ++k) \
;     dst[m][k] = *reinterpret_cast<const bf16x8*>((char*)SA(b, h) + lds_byte(wr * 64 + m * 16 + fr, k * 32 + fq * 8))
; #define LDB(dst, b, h) for (int n = 0; n < 2; ++n) for (int k = 0; k < 2; ++k) \
;     dst[n][k] = *reinterpret_cast<const bf16x8*>((char*)SB(b, h) + lds_byte(wc * 32 + n * 16 + fr, k * 32 + fq * 8))
; #define MMA(ai, bj, At_, Bt_) do { __builtin_amdgcn_s_setprio(1); \
;     for (int k = 0; k < 2; ++k) for (int m = 0; m < 4; ++m) for (int n = 0; n < 2; ++n) \
;       acc[ai][bj][m][n] = __builtin_amdgcn_mfma_f32_16x16x32_bf16(At_[m][k], Bt_[n][k], acc[ai][bj][m][n], 0, 0, 0); \
;     __builtin_amdgcn_s_setprio(0); } while (0)
; #define WAIT_V(n) asm volatile("s_waitcnt vmcnt(" #n ")" ::: "memory")
; #define WAIT_L(n) asm volatile("s_waitcnt lgkmcnt(" #n ")" ::: "memory")
; #define BAR __builtin_amdgcn_s_barrier()
; template <int EPI, int lda, int ldb, int N, int K>
; __device__ __forceinline__ void gemm_phase(const u16* __restrict__ A, const u16* __restrict__ Bt, const GemmEpi ep, int wv) {
;     ...
;       LDB(B1, 0, 1); BAR; WAIT_L(0); MMA(0, 1, At, B1); BAR;
;       LDA(At, 0, 1); WAIT_V(4); BAR; WAIT_L(0); MMA(1, 0, At, B0); MMA(1, 1, At, B1); BAR; }
;     { LDB(B0, 1, 0); LDA(At, 1, 0); WAIT_V(2); BAR; WAIT_L(0); MMA(0, 0, At, B0); BAR;
	ds_read_b128 v[96:99], v224
	ds_read_b128 v[196:199], v224 offset:1024
	ds_read_b128 v[200:203], v224 offset:2048
	ds_read_b128 v[204:207], v224 offset:3072
	s_barrier
	s_waitcnt lgkmcnt(0)
	s_waitcnt lgkmcnt(0)
	v_mfma_f32_16x16x32_bf16 v[12:15], v[152:155], v[96:99], v[12:15]
	v_mfma_f32_16x16x32_bf16 v[40:43], v[152:155], v[200:203], v[40:43]
	v_mfma_f32_16x16x32_bf16 v[52:55], v[180:183], v[96:99], v[52:55]
	v_mfma_f32_16x16x32_bf16 v[56:59], v[180:183], v[200:203], v[56:59]
	v_mfma_f32_16x16x32_bf16 v[64:67], v[188:191], v[200:203], v[64:67]
	v_mfma_f32_16x16x32_bf16 v[44:47], v[160:163], v[96:99], v[44:47]
	v_mfma_f32_16x16x32_bf16 v[48:51], v[160:163], v[200:203], v[48:51]
	v_mfma_f32_16x16x32_bf16 v[60:63], v[188:191], v[96:99], v[60:63]
	v_mfma_f32_16x16x32_bf16 v[12:15], v[156:159], v[196:199], v[12:15]
	v_mfma_f32_16x16x32_bf16 v[40:43], v[156:159], v[204:207], v[40:43]
	v_mfma_f32_16x16x32_bf16 v[52:55], v[184:187], v[196:199], v[52:55]
	v_mfma_f32_16x16x32_bf16 v[56:59], v[184:187], v[204:207], v[56:59]
	v_mfma_f32_16x16x32_bf16 v[64:67], v[192:195], v[204:207], v[64:67]
	v_mfma_f32_16x16x32_bf16 v[152:155], v[164:167], v[196:199], v[44:47]
	v_mfma_f32_16x16x32_bf16 v[156:159], v[164:167], v[204:207], v[48:51]
	v_mfma_f32_16x16x32_bf16 v[160:163], v[192:195], v[196:199], v[60:63]
	s_barrier
	ds_read_b128 v[44:47], v228 offset:16384
	ds_read_b128 v[48:51], v228 offset:17408
	ds_read_b128 v[60:63], v229 offset:18432
	ds_read_b128 v[164:167], v229 offset:19456
	ds_read_b128 v[180:183], v229 offset:20480
	ds_read_b128 v[184:187], v229 offset:21504
	ds_read_b128 v[188:191], v229 offset:22528
	ds_read_b128 v[192:195], v229 offset:23552
	s_waitcnt vmcnt(4)
	s_barrier
	s_waitcnt lgkmcnt(0)
	s_waitcnt lgkmcnt(0)
	v_mfma_f32_16x16x32_bf16 v[8:11], v[44:47], v[118:121], v[8:11]
	v_mfma_f32_16x16x32_bf16 v[24:27], v[188:191], v[118:121], v[24:27]
	v_mfma_f32_16x16x32_bf16 v[28:31], v[188:191], v[140:143], v[28:31]
	v_mfma_f32_16x16x32_bf16 v[114:117], v[44:47], v[140:143], v[114:117]
	v_mfma_f32_16x16x32_bf16 v[148:151], v[60:63], v[118:121], v[148:151]
	v_mfma_f32_16x16x32_bf16 v[168:171], v[60:63], v[140:143], v[168:171]
	v_mfma_f32_16x16x32_bf16 v[172:175], v[180:183], v[118:121], v[172:175]
	v_mfma_f32_16x16x32_bf16 v[176:179], v[180:183], v[140:143], v[176:179]
	v_mfma_f32_16x16x32_bf16 v[8:11], v[48:51], v[122:125], v[8:11]
	v_mfma_f32_16x16x32_bf16 v[24:27], v[192:195], v[122:125], v[24:27]
	v_mfma_f32_16x16x32_bf16 v[28:31], v[192:195], v[144:147], v[28:31]
	v_mfma_f32_16x16x32_bf16 v[140:143], v[48:51], v[144:147], v[114:117]
	v_mfma_f32_16x16x32_bf16 v[148:151], v[164:167], v[122:125], v[148:151]
	v_mfma_f32_16x16x32_bf16 v[168:171], v[164:167], v[144:147], v[168:171]
	v_mfma_f32_16x16x32_bf16 v[172:175], v[184:187], v[122:125], v[172:175]
	v_mfma_f32_16x16x32_bf16 v[176:179], v[184:187], v[144:147], v[176:179]
	v_mfma_f32_16x16x32_bf16 v[0:3], v[44:47], v[96:99], v[0:3]
	v_mfma_f32_16x16x32_bf16 v[20:23], v[44:47], v[200:203], v[20:23]
	v_mfma_f32_16x16x32_bf16 v[44:47], v[180:183], v[96:99], v[68:71]
	v_mfma_f32_16x16x32_bf16 v[68:71], v[188:191], v[96:99], v[102:105]
	v_mfma_f32_16x16x32_bf16 v[32:35], v[60:63], v[96:99], v[32:35]
	v_mfma_f32_16x16x32_bf16 v[36:39], v[60:63], v[200:203], v[36:39]
	v_mfma_f32_16x16x32_bf16 v[60:63], v[180:183], v[200:203], v[110:113]
	v_mfma_f32_16x16x32_bf16 v[96:99], v[188:191], v[200:203], v[106:109]
	v_mfma_f32_16x16x32_bf16 v[20:23], v[48:51], v[204:207], v[20:23]
	v_mfma_f32_16x16x32_bf16 v[68:71], v[192:195], v[196:199], v[68:71]
	v_mfma_f32_16x16x32_bf16 v[144:147], v[48:51], v[196:199], v[0:3]
	v_mfma_f32_16x16x32_bf16 v[180:183], v[164:167], v[196:199], v[32:35]
	v_mfma_f32_16x16x32_bf16 v[164:167], v[164:167], v[204:207], v[36:39]
	v_mfma_f32_16x16x32_bf16 v[188:191], v[184:187], v[196:199], v[44:47]
	v_mfma_f32_16x16x32_bf16 v[184:187], v[184:187], v[204:207], v[60:63]
	v_mfma_f32_16x16x32_bf16 v[192:195], v[192:195], v[204:207], v[96:99]
	s_barrier
	ds_read_b128 v[0:3], v225
	ds_read_b128 v[196:199], v225 offset:1024
	ds_read_b128 v[200:203], v225 offset:2048
	ds_read_b128 v[204:207], v225 offset:3072
	ds_read_b128 v[36:39], v228 offset:32768
	ds_read_b128 v[100:103], v228 offset:33792
	ds_read_b128 v[108:111], v229 offset:34816
	ds_read_b128 v[208:211], v229 offset:35840
	ds_read_b128 v[116:119], v229 offset:36864
	ds_read_b128 v[212:215], v229 offset:37888
	ds_read_b128 v[124:127], v229 offset:38912
	ds_read_b128 v[216:219], v229 offset:39936
	s_waitcnt vmcnt(2)
	s_barrier
; #define LDA(dst, b, h) for (int m = 0; m < 4; ++m) for (int k = 0; k < 2; ++k) \
;     dst[m][k] = *reinterpret_cast<const bf16x8*>((char*)SA(b, h) + lds_byte(wr * 64 + m * 16 + fr, k * 32 + fq * 8))
; #define LDB(dst, b, h) for (int n = 0; n < 2; ++n) for (int k = 0; k < 2; ++k) \
;     dst[n][k] = *reinterpret_cast<const bf16x8*>((char*)SB(b, h) + lds_byte(wc * 32 + n * 16 + fr, k * 32 + fq * 8))
; #define MMA(ai, bj, At_, Bt_) do { __builtin_amdgcn_s_setprio(1); \
;     for (int k = 0; k < 2; ++k) for (int m = 0; m < 4; ++m) for (int n = 0; n < 2; ++n) \
;       acc[ai][bj][m][n] = __builtin_amdgcn_mfma_f32_16x16x32_bf16(At_[m][k], Bt_[n][k], acc[ai][bj][m][n], 0, 0, 0); \
;     __builtin_amdgcn_s_setprio(0); } while (0)
; #define WAIT_V(n) asm volatile("s_waitcnt vmcnt(" #n ")" ::: "memory")
; #define WAIT_L(n) asm volatile("s_waitcnt lgkmcnt(" #n ")" ::: "memory")
; #define BAR __builtin_amdgcn_s_barrier()
; template <int EPI, int lda, int ldb, int N, int K>
; __device__ __forceinline__ void gemm_phase(const u16* __restrict__ A, const u16* __restrict__ Bt, const GemmEpi ep, int wv) {
;     ...
;     { LDB(B0, 1, 0); LDA(At, 1, 0); WAIT_V(2); BAR; WAIT_L(0); MMA(0, 0, At, B0); BAR;
;       LDB(B1, 1, 1); WAIT_V(0); BAR; WAIT_L(0); MMA(0, 1, At, B1); BAR;
;       LDA(At, 1, 1); BAR; WAIT_L(0); MMA(1, 0, At, B0); MMA(1, 1, At, B1); BAR; }
;     if (wr == 0) BAR;
	s_waitcnt lgkmcnt(0)
	s_waitcnt lgkmcnt(0)
	v_mfma_f32_16x16x32_bf16 v[4:7], v[36:39], v[0:3], v[4:7]
	v_mfma_f32_16x16x32_bf16 v[16:19], v[36:39], v[200:203], v[16:19]
	v_mfma_f32_16x16x32_bf16 v[32:35], v[108:111], v[0:3], v[72:75]
	v_mfma_f32_16x16x32_bf16 v[44:47], v[108:111], v[200:203], v[76:79]
	v_mfma_f32_16x16x32_bf16 v[72:75], v[116:119], v[0:3], v[80:83]
	v_mfma_f32_16x16x32_bf16 v[76:79], v[116:119], v[200:203], v[84:87]
	v_mfma_f32_16x16x32_bf16 v[80:83], v[124:127], v[0:3], v[88:91]
	v_mfma_f32_16x16x32_bf16 v[84:87], v[124:127], v[200:203], v[92:95]
	v_mfma_f32_16x16x32_bf16 v[120:123], v[100:103], v[196:199], v[4:7]
	v_mfma_f32_16x16x32_bf16 v[60:63], v[100:103], v[204:207], v[16:19]
	v_mfma_f32_16x16x32_bf16 v[112:115], v[208:211], v[196:199], v[32:35]
	v_mfma_f32_16x16x32_bf16 v[48:51], v[208:211], v[204:207], v[44:47]
	v_mfma_f32_16x16x32_bf16 v[104:107], v[212:215], v[196:199], v[72:75]
	v_mfma_f32_16x16x32_bf16 v[44:47], v[212:215], v[204:207], v[76:79]
	v_mfma_f32_16x16x32_bf16 v[96:99], v[216:219], v[196:199], v[80:83]
	v_mfma_f32_16x16x32_bf16 v[32:35], v[216:219], v[204:207], v[84:87]
	s_barrier
	ds_read_b128 v[4:7], v226
	ds_read_b128 v[220:223], v226 offset:1024
	ds_read_b128 v[76:79], v226 offset:2048
	ds_read_b128 v[224:227], v226 offset:3072
	s_waitcnt vmcnt(0)
	s_barrier
	s_waitcnt lgkmcnt(0)
	s_waitcnt lgkmcnt(0)
	v_mfma_f32_16x16x32_bf16 v[12:15], v[36:39], v[4:7], v[12:15]
	v_mfma_f32_16x16x32_bf16 v[16:19], v[36:39], v[76:79], v[40:43]
	v_mfma_f32_16x16x32_bf16 v[36:39], v[108:111], v[4:7], v[152:155]
	v_mfma_f32_16x16x32_bf16 v[40:43], v[108:111], v[76:79], v[156:159]
	v_mfma_f32_16x16x32_bf16 v[72:75], v[116:119], v[4:7], v[52:55]
	v_mfma_f32_16x16x32_bf16 v[80:83], v[116:119], v[76:79], v[56:59]
	v_mfma_f32_16x16x32_bf16 v[84:87], v[124:127], v[4:7], v[160:163]
	v_mfma_f32_16x16x32_bf16 v[64:67], v[124:127], v[76:79], v[64:67]
	v_mfma_f32_16x16x32_bf16 v[124:127], v[100:103], v[220:223], v[12:15]
	v_mfma_f32_16x16x32_bf16 v[56:59], v[100:103], v[224:227], v[16:19]
	v_mfma_f32_16x16x32_bf16 v[116:119], v[208:211], v[220:223], v[36:39]
	v_mfma_f32_16x16x32_bf16 v[52:55], v[208:211], v[224:227], v[40:43]
	v_mfma_f32_16x16x32_bf16 v[108:111], v[212:215], v[220:223], v[72:75]
	v_mfma_f32_16x16x32_bf16 v[40:43], v[212:215], v[224:227], v[80:83]
	v_mfma_f32_16x16x32_bf16 v[100:103], v[216:219], v[220:223], v[84:87]
	v_mfma_f32_16x16x32_bf16 v[36:39], v[216:219], v[224:227], v[64:67]
	s_barrier
	ds_read_b128 v[84:87], v228 offset:49152
	ds_read_b128 v[152:155], v228 offset:50176
	ds_read_b128 v[92:95], v229 offset:51200
	ds_read_b128 v[156:159], v229 offset:52224
	ds_read_b128 v[160:163], v229 offset:53248
	ds_read_b128 v[208:211], v229 offset:54272
	ds_read_b128 v[212:215], v229 offset:55296
	ds_read_b128 v[216:219], v229 offset:56320
	s_barrier
	s_waitcnt lgkmcnt(0)
	s_waitcnt lgkmcnt(0)
	v_mfma_f32_16x16x32_bf16 v[8:11], v[84:87], v[0:3], v[8:11]
	v_mfma_f32_16x16x32_bf16 v[12:15], v[84:87], v[200:203], v[140:143]
	v_mfma_f32_16x16x32_bf16 v[16:19], v[92:95], v[0:3], v[148:151]
	v_mfma_f32_16x16x32_bf16 v[64:67], v[92:95], v[200:203], v[168:171]
	v_mfma_f32_16x16x32_bf16 v[72:75], v[160:163], v[0:3], v[172:175]
	v_mfma_f32_16x16x32_bf16 v[140:143], v[160:163], v[200:203], v[176:179]
	v_mfma_f32_16x16x32_bf16 v[0:3], v[212:215], v[0:3], v[24:27]
	v_mfma_f32_16x16x32_bf16 v[24:27], v[212:215], v[200:203], v[28:31]
	v_mfma_f32_16x16x32_bf16 v[88:91], v[152:155], v[196:199], v[8:11]
	v_mfma_f32_16x16x32_bf16 v[28:31], v[152:155], v[204:207], v[12:15]
	v_mfma_f32_16x16x32_bf16 v[80:83], v[156:159], v[196:199], v[16:19]
	v_mfma_f32_16x16x32_bf16 v[16:19], v[156:159], v[204:207], v[64:67]
	v_mfma_f32_16x16x32_bf16 v[72:75], v[208:211], v[196:199], v[72:75]
	v_mfma_f32_16x16x32_bf16 v[12:15], v[208:211], v[204:207], v[140:143]
	v_mfma_f32_16x16x32_bf16 v[64:67], v[216:219], v[196:199], v[0:3]
	v_mfma_f32_16x16x32_bf16 v[0:3], v[216:219], v[204:207], v[24:27]
	v_mfma_f32_16x16x32_bf16 v[8:11], v[84:87], v[4:7], v[144:147]
	v_mfma_f32_16x16x32_bf16 v[20:23], v[84:87], v[76:79], v[20:23]
	v_mfma_f32_16x16x32_bf16 v[84:87], v[92:95], v[4:7], v[180:183]
	v_mfma_f32_16x16x32_bf16 v[140:143], v[92:95], v[76:79], v[164:167]
	v_mfma_f32_16x16x32_bf16 v[144:147], v[160:163], v[4:7], v[188:191]
	v_mfma_f32_16x16x32_bf16 v[148:151], v[160:163], v[76:79], v[184:187]
	v_mfma_f32_16x16x32_bf16 v[4:7], v[212:215], v[4:7], v[68:71]
	v_mfma_f32_16x16x32_bf16 v[160:163], v[212:215], v[76:79], v[192:195]
	v_mfma_f32_16x16x32_bf16 v[92:95], v[152:155], v[220:223], v[8:11]
	v_mfma_f32_16x16x32_bf16 v[24:27], v[152:155], v[224:227], v[20:23]
	v_mfma_f32_16x16x32_bf16 v[84:87], v[156:159], v[220:223], v[84:87]
	v_mfma_f32_16x16x32_bf16 v[20:23], v[156:159], v[224:227], v[140:143]
	v_mfma_f32_16x16x32_bf16 v[76:79], v[208:211], v[220:223], v[144:147]
	v_mfma_f32_16x16x32_bf16 v[8:11], v[208:211], v[224:227], v[148:151]
	v_mfma_f32_16x16x32_bf16 v[68:71], v[216:219], v[220:223], v[4:7]
	v_mfma_f32_16x16x32_bf16 v[4:7], v[216:219], v[224:227], v[160:163]
	v_cmp_gt_u32_e32 vcc, s60, v130
	s_barrier
	s_and_saveexec_b64 s[46:47], vcc
	s_cbranch_execz .LBB0_1346
	s_barrier
	s_branch .LBB0_1346

; #define STAGE(P, BASE, LD, br, kt) do { const char* _g = (const char*)((BASE) + (size_t)(br) * (LD) + (size_t)(kt) * 64); \
;     for (int _i = 0; _i < 2; ++_i) { int _b = tidx * 16 + _i * 8192; int _r, _c; stage_rc(_b, _r, _c); \
;       __builtin_amdgcn_global_load_lds((const unsigned*)(_g + (unsigned)((_r * (LD) + _c) * 2)), (unsigned*)((char*)(P) + _b), 16, 0, 0); } } while (0)
; #define LDA(dst, b, h) for (int m = 0; m < 4; ++m) for (int k = 0; k < 2; ++k) \
;     dst[m][k] = *reinterpret_cast<const bf16x8*>((char*)SA(b, h) + lds_byte(wr * 64 + m * 16 + fr, k * 32 + fq * 8))
; #define LDB(dst, b, h) for (int n = 0; n < 2; ++n) for (int k = 0; k < 2; ++k) \
;     dst[n][k] = *reinterpret_cast<const bf16x8*>((char*)SB(b, h) + lds_byte(wc * 32 + n * 16 + fr, k * 32 + fq * 8))
; #define MMA(ai, bj, At_, Bt_) do { __builtin_amdgcn_s_setprio(1); \
;     for (int k = 0; k < 2; ++k) for (int m = 0; m < 4; ++m) for (int n = 0; n < 2; ++n) \
;       acc[ai][bj][m][n] = __builtin_amdgcn_mfma_f32_16x16x32_bf16(At_[m][k], Bt_[n][k], acc[ai][bj][m][n], 0, 0, 0); \
;     __builtin_amdgcn_s_setprio(0); } while (0)
; #define WAIT_L(n) asm volatile("s_waitcnt lgkmcnt(" #n ")" ::: "memory")
; #define BAR __builtin_amdgcn_s_barrier()
; #define SCHED __builtin_amdgcn_sched_barrier(0)
; template <int EPI, int lda, int ldb, int N, int K>
; __device__ __forceinline__ void gemm_phase(const u16* __restrict__ A, const u16* __restrict__ Bt, const GemmEpi ep, int wv) {
;     ...
;     for (int t = 0; t < nt - 2; t += 2) {
;       LDB(B0, 0, 0); SCHED; LDA(At, 0, 0); STAGE(SA(1, 1), Ab, lda, brow + HALF, t + 1);
;       WAIT_L(8); BAR; WAIT_L(0); MMA(0, 0, At, B0); BAR; SCHED;
;       LDB(B1, 0, 1); STAGE(SB(0, 0), Bt, ldb, bcol, t + 2);
;       BAR; WAIT_L(0); MMA(0, 1, At, B1); BAR;
;       LDA(At, 0, 1); STAGE(SA(0, 0), Ab, lda, brow, t + 2);
;       BAR; WAIT_L(0); MMA(1, 0, At, B0); BAR; SCHED;
.LBB0_1448:
	ds_read_b128 v[164:167], v160
	ds_read_b128 v[170:173], v160 offset:1024
	ds_read_b128 v[174:177], v160 offset:2048
	ds_read_b128 v[178:181], v160 offset:3072
	v_add_u32_e32 v168, 0xc000, v143
	v_lshl_add_u64 v[234:235], v[138:139], 0, s[44:45]
	v_readfirstlane_b32 s47, v168
	v_add_u32_e32 v169, 0xe000, v143
	v_lshl_add_u64 v[162:163], v[234:235], 0, s[20:21]
	s_mov_b32 m0, s47
	v_lshl_add_u64 v[236:237], v[140:141], 0, s[44:45]
	v_readfirstlane_b32 s47, v169
	ds_read_b128 v[182:185], v151
	ds_read_b128 v[186:189], v151 offset:1024
	ds_read_b128 v[190:193], v150
	ds_read_b128 v[194:197], v150 offset:1024
	ds_read_b128 v[198:201], v149
	ds_read_b128 v[202:205], v149 offset:1024
	ds_read_b128 v[206:209], v148
	ds_read_b128 v[210:213], v148 offset:1024
	global_load_lds_dwordx4 v[162:163], off
	s_nop 1
	v_lshl_add_u64 v[162:163], v[236:237], 0, s[20:21]
	s_mov_b32 m0, s47
	s_nop 0
	global_load_lds_dwordx4 v[162:163], off
	s_waitcnt lgkmcnt(8)
	s_barrier
	s_waitcnt lgkmcnt(0)
	s_waitcnt lgkmcnt(0)
	v_mfma_f32_16x16x32_bf16 v[124:127], v[164:167], v[182:185], v[124:127]
	v_mfma_f32_16x16x32_bf16 v[120:123], v[174:177], v[182:185], v[120:123]
	v_mfma_f32_16x16x32_bf16 v[116:119], v[164:167], v[190:193], v[116:119]
	v_mfma_f32_16x16x32_bf16 v[112:115], v[174:177], v[190:193], v[112:115]
	v_mfma_f32_16x16x32_bf16 v[108:111], v[164:167], v[198:201], v[108:111]
	v_mfma_f32_16x16x32_bf16 v[104:107], v[174:177], v[198:201], v[104:107]
	v_mfma_f32_16x16x32_bf16 v[100:103], v[164:167], v[206:209], v[100:103]
	v_mfma_f32_16x16x32_bf16 v[96:99], v[174:177], v[206:209], v[96:99]
	v_mfma_f32_16x16x32_bf16 v[124:127], v[170:173], v[186:189], v[124:127]
	v_mfma_f32_16x16x32_bf16 v[120:123], v[178:181], v[186:189], v[120:123]
	v_mfma_f32_16x16x32_bf16 v[116:119], v[170:173], v[194:197], v[116:119]
	v_mfma_f32_16x16x32_bf16 v[112:115], v[178:181], v[194:197], v[112:115]
	v_mfma_f32_16x16x32_bf16 v[108:111], v[170:173], v[202:205], v[108:111]
	v_mfma_f32_16x16x32_bf16 v[104:107], v[178:181], v[202:205], v[104:107]
	v_mfma_f32_16x16x32_bf16 v[100:103], v[170:173], v[210:213], v[100:103]
	v_mfma_f32_16x16x32_bf16 v[96:99], v[178:181], v[210:213], v[96:99]
	s_barrier
	v_add_u32_e32 v161, s55, v153
	v_lshl_add_u64 v[238:239], v[134:135], 0, s[44:45]
	v_readfirstlane_b32 s47, v161
	v_lshl_add_u64 v[162:163], v[238:239], 0, s[22:23]
	s_mov_b32 m0, s47
	ds_read_b128 v[214:217], v159
	ds_read_b128 v[218:221], v159 offset:1024
	ds_read_b128 v[222:225], v159 offset:2048
	ds_read_b128 v[226:229], v159 offset:3072
	global_load_lds_dwordx4 v[162:163], off
	s_nop 1
	v_add_u32_e32 v162, 0x2000, v161
	v_lshl_add_u64 v[240:241], v[136:137], 0, s[44:45]
	v_readfirstlane_b32 s47, v162
	v_lshl_add_u64 v[230:231], v[240:241], 0, s[22:23]
	s_mov_b32 m0, s47
	s_nop 0
	global_load_lds_dwordx4 v[230:231], off
	s_barrier
	s_waitcnt lgkmcnt(0)
	s_waitcnt lgkmcnt(0)
	v_mfma_f32_16x16x32_bf16 v[92:95], v[214:217], v[182:185], v[92:95]
	v_mfma_f32_16x16x32_bf16 v[88:91], v[222:225], v[182:185], v[88:91]
	v_mfma_f32_16x16x32_bf16 v[84:87], v[214:217], v[190:193], v[84:87]
	v_mfma_f32_16x16x32_bf16 v[80:83], v[222:225], v[190:193], v[80:83]
	v_mfma_f32_16x16x32_bf16 v[76:79], v[214:217], v[198:201], v[76:79]
	v_mfma_f32_16x16x32_bf16 v[72:75], v[222:225], v[198:201], v[72:75]
	v_mfma_f32_16x16x32_bf16 v[68:71], v[214:217], v[206:209], v[68:71]
	v_mfma_f32_16x16x32_bf16 v[64:67], v[222:225], v[206:209], v[64:67]
	v_mfma_f32_16x16x32_bf16 v[92:95], v[218:221], v[186:189], v[92:95]
	v_mfma_f32_16x16x32_bf16 v[88:91], v[226:229], v[186:189], v[88:91]
	v_mfma_f32_16x16x32_bf16 v[84:87], v[218:221], v[194:197], v[84:87]
	v_mfma_f32_16x16x32_bf16 v[80:83], v[226:229], v[194:197], v[80:83]
	v_mfma_f32_16x16x32_bf16 v[76:79], v[218:221], v[202:205], v[76:79]
	v_mfma_f32_16x16x32_bf16 v[72:75], v[226:229], v[202:205], v[72:75]
	v_mfma_f32_16x16x32_bf16 v[68:71], v[218:221], v[210:213], v[68:71]
	v_mfma_f32_16x16x32_bf16 v[64:67], v[226:229], v[210:213], v[64:67]
	v_readfirstlane_b32 s47, v143
	v_add_u32_e32 v163, 0x2000, v143
	v_lshl_add_u64 v[230:231], v[234:235], 0, s[24:25]
	s_mov_b32 m0, s47
	v_readfirstlane_b32 s47, v163
	s_barrier
	ds_read_b128 v[182:185], v151 offset:16384
	ds_read_b128 v[186:189], v151 offset:17408
	ds_read_b128 v[190:193], v150 offset:16384
	ds_read_b128 v[194:197], v150 offset:17408
	ds_read_b128 v[198:201], v149 offset:16384
	ds_read_b128 v[202:205], v149 offset:17408
	ds_read_b128 v[206:209], v148 offset:16384
	ds_read_b128 v[210:213], v148 offset:17408
	global_load_lds_dwordx4 v[230:231], off
	s_nop 1
	v_lshl_add_u64 v[230:231], v[236:237], 0, s[24:25]
	s_mov_b32 m0, s47
	s_nop 0
	global_load_lds_dwordx4 v[230:231], off
	s_barrier
	s_waitcnt lgkmcnt(0)
	s_waitcnt lgkmcnt(0)
	v_mfma_f32_16x16x32_bf16 v[60:63], v[164:167], v[182:185], v[60:63]
	v_mfma_f32_16x16x32_bf16 v[56:59], v[174:177], v[182:185], v[56:59]
	v_mfma_f32_16x16x32_bf16 v[52:55], v[164:167], v[190:193], v[52:55]
	v_mfma_f32_16x16x32_bf16 v[48:51], v[174:177], v[190:193], v[48:51]
	v_mfma_f32_16x16x32_bf16 v[44:47], v[164:167], v[198:201], v[44:47]
	v_mfma_f32_16x16x32_bf16 v[40:43], v[174:177], v[198:201], v[40:43]
	v_mfma_f32_16x16x32_bf16 v[36:39], v[164:167], v[206:209], v[36:39]
	v_mfma_f32_16x16x32_bf16 v[32:35], v[174:177], v[206:209], v[32:35]
	v_mfma_f32_16x16x32_bf16 v[60:63], v[170:173], v[186:189], v[60:63]
	v_mfma_f32_16x16x32_bf16 v[56:59], v[178:181], v[186:189], v[56:59]
	v_mfma_f32_16x16x32_bf16 v[52:55], v[170:173], v[194:197], v[52:55]
	v_mfma_f32_16x16x32_bf16 v[48:51], v[178:181], v[194:197], v[48:51]
	v_mfma_f32_16x16x32_bf16 v[44:47], v[170:173], v[202:205], v[44:47]
	v_mfma_f32_16x16x32_bf16 v[40:43], v[178:181], v[202:205], v[40:43]
	v_mfma_f32_16x16x32_bf16 v[36:39], v[170:173], v[210:213], v[36:39]
	v_mfma_f32_16x16x32_bf16 v[32:35], v[178:181], v[210:213], v[32:35]
	s_barrier
; #define STAGE(P, BASE, LD, br, kt) do { const char* _g = (const char*)((BASE) + (size_t)(br) * (LD) + (size_t)(kt) * 64); \
;     for (int _i = 0; _i < 2; ++_i) { int _b = tidx * 16 + _i * 8192; int _r, _c; stage_rc(_b, _r, _c); \
;       __builtin_amdgcn_global_load_lds((const unsigned*)(_g + (unsigned)((_r * (LD) + _c) * 2)), (unsigned*)((char*)(P) + _b), 16, 0, 0); } } while (0)
; #define LDA(dst, b, h) for (int m = 0; m < 4; ++m) for (int k = 0; k < 2; ++k) \
;     dst[m][k] = *reinterpret_cast<const bf16x8*>((char*)SA(b, h) + lds_byte(wr * 64 + m * 16 + fr, k * 32 + fq * 8))
; #define LDB(dst, b, h) for (int n = 0; n < 2; ++n) for (int k = 0; k < 2; ++k) \
;     dst[n][k] = *reinterpret_cast<const bf16x8*>((char*)SB(b, h) + lds_byte(wc * 32 + n * 16 + fr, k * 32 + fq * 8))
; #define MMA(ai, bj, At_, Bt_) do { __builtin_amdgcn_s_setprio(1); \
;     for (int k = 0; k < 2; ++k) for (int m = 0; m < 4; ++m) for (int n = 0; n < 2; ++n) \
;       acc[ai][bj][m][n] = __builtin_amdgcn_mfma_f32_16x16x32_bf16(At_[m][k], Bt_[n][k], acc[ai][bj][m][n], 0, 0, 0); \
;     __builtin_amdgcn_s_setprio(0); } while (0)
; #define WAIT_V(n) asm volatile("s_waitcnt vmcnt(" #n ")" ::: "memory")
; #define WAIT_L(n) asm volatile("s_waitcnt lgkmcnt(" #n ")" ::: "memory")
; #define BAR __builtin_amdgcn_s_barrier()
; #define SCHED __builtin_amdgcn_sched_barrier(0)
; template <int EPI, int lda, int ldb, int N, int K>
; __device__ __forceinline__ void gemm_phase(const u16* __restrict__ A, const u16* __restrict__ Bt, const GemmEpi ep, int wv) {
;     ...
;       STAGE(SB(0, 1), Bt, ldb, bcol + HALF, t + 2);
;       WAIT_V(6); BAR; MMA(1, 1, At, B1); BAR;
;       LDB(B0, 1, 0); SCHED; LDA(At, 1, 0); STAGE(SA(0, 1), Ab, lda, brow + HALF, t + 2);
;       WAIT_L(8); BAR; WAIT_L(0); MMA(0, 0, At, B0); BAR; SCHED;
;       LDB(B1, 1, 1); STAGE(SB(1, 0), Bt, ldb, bcol, t + 3);
;       BAR; WAIT_L(0); MMA(0, 1, At, B1); BAR;
	v_add_u32_e32 v164, s56, v153
	v_add_u32_e32 v165, 0x2000, v164
	v_readfirstlane_b32 s47, v164
	v_lshl_add_u64 v[166:167], v[238:239], 0, s[26:27]
	s_mov_b32 m0, s47
	v_readfirstlane_b32 s47, v165
	global_load_lds_dwordx4 v[166:167], off
	s_nop 1
	v_lshl_add_u64 v[166:167], v[240:241], 0, s[26:27]
	s_mov_b32 m0, s47
	s_nop 0
	global_load_lds_dwordx4 v[166:167], off
	s_waitcnt vmcnt(6)
	s_barrier
	v_mfma_f32_16x16x32_bf16 v[28:31], v[214:217], v[182:185], v[28:31]
	v_mfma_f32_16x16x32_bf16 v[24:27], v[222:225], v[182:185], v[24:27]
	v_mfma_f32_16x16x32_bf16 v[20:23], v[214:217], v[190:193], v[20:23]
	v_mfma_f32_16x16x32_bf16 v[16:19], v[222:225], v[190:193], v[16:19]
	v_mfma_f32_16x16x32_bf16 v[12:15], v[214:217], v[198:201], v[12:15]
	v_mfma_f32_16x16x32_bf16 v[8:11], v[222:225], v[198:201], v[8:11]
	v_mfma_f32_16x16x32_bf16 v[4:7], v[214:217], v[206:209], v[4:7]
	v_mfma_f32_16x16x32_bf16 v[0:3], v[222:225], v[206:209], v[0:3]
	v_mfma_f32_16x16x32_bf16 v[28:31], v[218:221], v[186:189], v[28:31]
	v_mfma_f32_16x16x32_bf16 v[24:27], v[226:229], v[186:189], v[24:27]
	v_mfma_f32_16x16x32_bf16 v[20:23], v[218:221], v[194:197], v[20:23]
	v_mfma_f32_16x16x32_bf16 v[16:19], v[226:229], v[194:197], v[16:19]
	v_mfma_f32_16x16x32_bf16 v[12:15], v[218:221], v[202:205], v[12:15]
	v_mfma_f32_16x16x32_bf16 v[8:11], v[226:229], v[202:205], v[8:11]
	v_mfma_f32_16x16x32_bf16 v[4:7], v[218:221], v[210:213], v[4:7]
	v_mfma_f32_16x16x32_bf16 v[0:3], v[226:229], v[210:213], v[0:3]
	s_barrier
	ds_read_b128 v[170:173], v154
	ds_read_b128 v[174:177], v154 offset:1024
	ds_read_b128 v[178:181], v154 offset:2048
	ds_read_b128 v[182:185], v154 offset:3072
	v_add_u32_e32 v166, 0x4000, v143
	v_add_u32_e32 v167, 0x6000, v143
	v_readfirstlane_b32 s47, v166
	v_lshl_add_u64 v[218:219], v[234:235], 0, s[34:35]
	s_mov_b32 m0, s47
	v_readfirstlane_b32 s47, v167
	ds_read_b128 v[186:189], v151 offset:32768
	ds_read_b128 v[190:193], v151 offset:33792
	ds_read_b128 v[194:197], v150 offset:32768
	ds_read_b128 v[198:201], v150 offset:33792
	ds_read_b128 v[202:205], v149 offset:32768
	ds_read_b128 v[206:209], v149 offset:33792
	ds_read_b128 v[210:213], v148 offset:32768
	ds_read_b128 v[214:217], v148 offset:33792
	global_load_lds_dwordx4 v[218:219], off
	s_nop 1
	v_lshl_add_u64 v[218:219], v[236:237], 0, s[34:35]
	s_mov_b32 m0, s47
	s_nop 0
	global_load_lds_dwordx4 v[218:219], off
	s_waitcnt lgkmcnt(8)
	s_barrier
	s_waitcnt lgkmcnt(0)
	s_waitcnt lgkmcnt(0)
	v_mfma_f32_16x16x32_bf16 v[124:127], v[170:173], v[186:189], v[124:127]
	v_mfma_f32_16x16x32_bf16 v[120:123], v[178:181], v[186:189], v[120:123]
	v_mfma_f32_16x16x32_bf16 v[116:119], v[170:173], v[194:197], v[116:119]
	v_mfma_f32_16x16x32_bf16 v[112:115], v[178:181], v[194:197], v[112:115]
	v_mfma_f32_16x16x32_bf16 v[108:111], v[170:173], v[202:205], v[108:111]
	v_mfma_f32_16x16x32_bf16 v[104:107], v[178:181], v[202:205], v[104:107]
	v_mfma_f32_16x16x32_bf16 v[100:103], v[170:173], v[210:213], v[100:103]
	v_mfma_f32_16x16x32_bf16 v[96:99], v[178:181], v[210:213], v[96:99]
	v_mfma_f32_16x16x32_bf16 v[124:127], v[174:177], v[190:193], v[124:127]
	v_mfma_f32_16x16x32_bf16 v[120:123], v[182:185], v[190:193], v[120:123]
	v_mfma_f32_16x16x32_bf16 v[116:119], v[174:177], v[198:201], v[116:119]
	v_mfma_f32_16x16x32_bf16 v[112:115], v[182:185], v[198:201], v[112:115]
	v_mfma_f32_16x16x32_bf16 v[108:111], v[174:177], v[206:209], v[108:111]
	v_mfma_f32_16x16x32_bf16 v[104:107], v[182:185], v[206:209], v[104:107]
	v_mfma_f32_16x16x32_bf16 v[100:103], v[174:177], v[214:217], v[100:103]
	v_mfma_f32_16x16x32_bf16 v[96:99], v[182:185], v[214:217], v[96:99]
	s_barrier
	v_readfirstlane_b32 s47, v155
	v_add_u32_e32 v244, 0x2000, v155
	v_lshl_add_u64 v[242:243], v[238:239], 0, s[36:37]
	s_mov_b32 m0, s47
	v_readfirstlane_b32 s47, v244
	ds_read_b128 v[218:221], v152
	ds_read_b128 v[222:225], v152 offset:1024
	ds_read_b128 v[226:229], v152 offset:2048
	ds_read_b128 v[230:233], v152 offset:3072
	global_load_lds_dwordx4 v[242:243], off
	s_nop 1
	v_lshl_add_u64 v[242:243], v[240:241], 0, s[36:37]
	s_mov_b32 m0, s47
	s_nop 0
	global_load_lds_dwordx4 v[242:243], off
	s_barrier
	s_waitcnt lgkmcnt(0)
	s_waitcnt lgkmcnt(0)
	v_mfma_f32_16x16x32_bf16 v[92:95], v[218:221], v[186:189], v[92:95]
	v_mfma_f32_16x16x32_bf16 v[88:91], v[226:229], v[186:189], v[88:91]
	v_mfma_f32_16x16x32_bf16 v[84:87], v[218:221], v[194:197], v[84:87]
	v_mfma_f32_16x16x32_bf16 v[80:83], v[226:229], v[194:197], v[80:83]
	v_mfma_f32_16x16x32_bf16 v[76:79], v[218:221], v[202:205], v[76:79]
	v_mfma_f32_16x16x32_bf16 v[72:75], v[226:229], v[202:205], v[72:75]
	v_mfma_f32_16x16x32_bf16 v[68:71], v[218:221], v[210:213], v[68:71]
	v_mfma_f32_16x16x32_bf16 v[64:67], v[226:229], v[210:213], v[64:67]
	v_mfma_f32_16x16x32_bf16 v[92:95], v[222:225], v[190:193], v[92:95]
	v_mfma_f32_16x16x32_bf16 v[88:91], v[230:233], v[190:193], v[88:91]
	v_mfma_f32_16x16x32_bf16 v[84:87], v[222:225], v[198:201], v[84:87]
	v_mfma_f32_16x16x32_bf16 v[80:83], v[230:233], v[198:201], v[80:83]
	v_mfma_f32_16x16x32_bf16 v[76:79], v[222:225], v[206:209], v[76:79]
	v_mfma_f32_16x16x32_bf16 v[72:75], v[230:233], v[206:209], v[72:75]
	v_mfma_f32_16x16x32_bf16 v[68:71], v[222:225], v[214:217], v[68:71]
	v_mfma_f32_16x16x32_bf16 v[64:67], v[230:233], v[214:217], v[64:67]
	v_readfirstlane_b32 s47, v156
	v_lshl_add_u64 v[234:235], v[234:235], 0, s[38:39]
	s_mov_b32 m0, s47
	v_readfirstlane_b32 s47, v157
	s_barrier
; #define STAGE(P, BASE, LD, br, kt) do { const char* _g = (const char*)((BASE) + (size_t)(br) * (LD) + (size_t)(kt) * 64); \
;     for (int _i = 0; _i < 2; ++_i) { int _b = tidx * 16 + _i * 8192; int _r, _c; stage_rc(_b, _r, _c); \
;       __builtin_amdgcn_global_load_lds((const unsigned*)(_g + (unsigned)((_r * (LD) + _c) * 2)), (unsigned*)((char*)(P) + _b), 16, 0, 0); } } while (0)
; #define LDA(dst, b, h) for (int m = 0; m < 4; ++m) for (int k = 0; k < 2; ++k) \
;     dst[m][k] = *reinterpret_cast<const bf16x8*>((char*)SA(b, h) + lds_byte(wr * 64 + m * 16 + fr, k * 32 + fq * 8))
; #define LDB(dst, b, h) for (int n = 0; n < 2; ++n) for (int k = 0; k < 2; ++k) \
;     dst[n][k] = *reinterpret_cast<const bf16x8*>((char*)SB(b, h) + lds_byte(wc * 32 + n * 16 + fr, k * 32 + fq * 8))
; #define MMA(ai, bj, At_, Bt_) do { __builtin_amdgcn_s_setprio(1); \
;     for (int k = 0; k < 2; ++k) for (int m = 0; m < 4; ++m) for (int n = 0; n < 2; ++n) \
;       acc[ai][bj][m][n] = __builtin_amdgcn_mfma_f32_16x16x32_bf16(At_[m][k], Bt_[n][k], acc[ai][bj][m][n], 0, 0, 0); \
;     __builtin_amdgcn_s_setprio(0); } while (0)
; #define WAIT_V(n) asm volatile("s_waitcnt vmcnt(" #n ")" ::: "memory")
; #define WAIT_L(n) asm volatile("s_waitcnt lgkmcnt(" #n ")" ::: "memory")
; #define BAR __builtin_amdgcn_s_barrier()
; #define SCHED __builtin_amdgcn_sched_barrier(0)
; template <int EPI, int lda, int ldb, int N, int K>
; __device__ __forceinline__ void gemm_phase(const u16* __restrict__ A, const u16* __restrict__ Bt, const GemmEpi ep, int wv) {
;     ...
;       LDA(At, 1, 1); STAGE(SA(1, 0), Ab, lda, brow, t + 3);
;       BAR; WAIT_L(0); MMA(1, 0, At, B0); BAR; SCHED;
;       STAGE(SB(1, 1), Bt, ldb, bcol + HALF, t + 3);
;       WAIT_V(6); BAR; MMA(1, 1, At, B1); BAR;
;     }
;     { LDB(B0, 0, 0); LDA(At, 0, 0); STAGE(SA(1, 1), Ab, lda, brow + HALF, nt - 1);
;       BAR; WAIT_L(0); MMA(0, 0, At, B0); BAR;
;       LDB(B1, 0, 1); BAR; WAIT_L(0); MMA(0, 1, At, B1); BAR;
	ds_read_b128 v[186:189], v151 offset:49152
	ds_read_b128 v[190:193], v151 offset:50176
	ds_read_b128 v[194:197], v150 offset:49152
	ds_read_b128 v[198:201], v150 offset:50176
	ds_read_b128 v[202:205], v149 offset:49152
	ds_read_b128 v[206:209], v149 offset:50176
	ds_read_b128 v[210:213], v148 offset:49152
	ds_read_b128 v[214:217], v148 offset:50176
	global_load_lds_dwordx4 v[234:235], off
	s_nop 1
	v_lshl_add_u64 v[234:235], v[236:237], 0, s[38:39]
	s_mov_b32 m0, s47
	s_nop 0
	global_load_lds_dwordx4 v[234:235], off
	s_barrier
	s_waitcnt lgkmcnt(0)
	s_waitcnt lgkmcnt(0)
	v_mfma_f32_16x16x32_bf16 v[60:63], v[170:173], v[186:189], v[60:63]
	v_mfma_f32_16x16x32_bf16 v[56:59], v[178:181], v[186:189], v[56:59]
	v_mfma_f32_16x16x32_bf16 v[52:55], v[170:173], v[194:197], v[52:55]
	v_mfma_f32_16x16x32_bf16 v[48:51], v[178:181], v[194:197], v[48:51]
	v_mfma_f32_16x16x32_bf16 v[44:47], v[170:173], v[202:205], v[44:47]
	v_mfma_f32_16x16x32_bf16 v[40:43], v[178:181], v[202:205], v[40:43]
	v_mfma_f32_16x16x32_bf16 v[36:39], v[170:173], v[210:213], v[36:39]
	v_mfma_f32_16x16x32_bf16 v[32:35], v[178:181], v[210:213], v[32:35]
	v_mfma_f32_16x16x32_bf16 v[60:63], v[174:177], v[190:193], v[60:63]
	v_mfma_f32_16x16x32_bf16 v[56:59], v[182:185], v[190:193], v[56:59]
	v_mfma_f32_16x16x32_bf16 v[52:55], v[174:177], v[198:201], v[52:55]
	v_mfma_f32_16x16x32_bf16 v[48:51], v[182:185], v[198:201], v[48:51]
	v_mfma_f32_16x16x32_bf16 v[44:47], v[174:177], v[206:209], v[44:47]
	v_mfma_f32_16x16x32_bf16 v[40:43], v[182:185], v[206:209], v[40:43]
	v_mfma_f32_16x16x32_bf16 v[36:39], v[174:177], v[214:217], v[36:39]
	v_mfma_f32_16x16x32_bf16 v[32:35], v[182:185], v[214:217], v[32:35]
	s_barrier
	v_readfirstlane_b32 s47, v158
	v_add_u32_e32 v172, 0x2000, v158
	v_lshl_add_u64 v[170:171], v[238:239], 0, s[40:41]
	s_mov_b32 m0, s47
	v_readfirstlane_b32 s47, v172
	global_load_lds_dwordx4 v[170:171], off
	s_nop 1
	v_lshl_add_u64 v[170:171], v[240:241], 0, s[40:41]
	s_mov_b32 m0, s47
	s_nop 0
	global_load_lds_dwordx4 v[170:171], off
	s_waitcnt vmcnt(6)
	s_barrier
	v_mfma_f32_16x16x32_bf16 v[28:31], v[218:221], v[186:189], v[28:31]
	v_mfma_f32_16x16x32_bf16 v[24:27], v[226:229], v[186:189], v[24:27]
	v_mfma_f32_16x16x32_bf16 v[20:23], v[218:221], v[194:197], v[20:23]
	v_mfma_f32_16x16x32_bf16 v[16:19], v[226:229], v[194:197], v[16:19]
	v_mfma_f32_16x16x32_bf16 v[12:15], v[218:221], v[202:205], v[12:15]
	v_mfma_f32_16x16x32_bf16 v[8:11], v[226:229], v[202:205], v[8:11]
	v_mfma_f32_16x16x32_bf16 v[4:7], v[218:221], v[210:213], v[4:7]
	v_mfma_f32_16x16x32_bf16 v[0:3], v[226:229], v[210:213], v[0:3]
	v_mfma_f32_16x16x32_bf16 v[28:31], v[222:225], v[190:193], v[28:31]
	v_mfma_f32_16x16x32_bf16 v[24:27], v[230:233], v[190:193], v[24:27]
	v_mfma_f32_16x16x32_bf16 v[20:23], v[222:225], v[198:201], v[20:23]
	v_mfma_f32_16x16x32_bf16 v[16:19], v[230:233], v[198:201], v[16:19]
	v_mfma_f32_16x16x32_bf16 v[12:15], v[222:225], v[206:209], v[12:15]
	v_mfma_f32_16x16x32_bf16 v[8:11], v[230:233], v[206:209], v[8:11]
	v_mfma_f32_16x16x32_bf16 v[4:7], v[222:225], v[214:217], v[4:7]
	v_mfma_f32_16x16x32_bf16 v[0:3], v[230:233], v[214:217], v[0:3]
	s_add_i32 s46, s46, 2
	s_add_u32 s44, s44, 0x100
	s_addc_u32 s45, s45, 0
	s_cmp_gt_u32 s46, 27
	s_barrier
	s_cbranch_scc0 .LBB0_1448
	s_lshl_b64 s[44:45], s[16:17], 12
	s_add_u32 s44, s14, s44
	s_addc_u32 s45, s15, s45
	s_add_u32 s44, s44, 0x80000
	s_addc_u32 s45, s45, 0
	v_lshl_add_u64 v[156:157], s[44:45], 0, v[128:129]
	v_readfirstlane_b32 s46, v168
	v_lshl_add_u64 v[156:157], v[156:157], 0, s[42:43]
	s_mov_b32 m0, s46
	ds_read_b128 v[134:137], v160
	ds_read_b128 v[138:141], v160 offset:1024
	ds_read_b128 v[170:173], v160 offset:2048
	ds_read_b128 v[174:177], v160 offset:3072
	ds_read_b128 v[178:181], v151
	ds_read_b128 v[182:185], v151 offset:1024
	ds_read_b128 v[186:189], v150
	ds_read_b128 v[190:193], v150 offset:1024
	ds_read_b128 v[194:197], v149
	ds_read_b128 v[198:201], v149 offset:1024
	ds_read_b128 v[202:205], v148
	ds_read_b128 v[206:209], v148 offset:1024
	global_load_lds_dwordx4 v[156:157], off
	v_lshl_add_u64 v[156:157], s[44:45], 0, v[132:133]
	v_readfirstlane_b32 s44, v169
	v_lshl_add_u64 v[156:157], v[156:157], 0, s[42:43]
	s_mov_b32 m0, s44
	s_nop 0
	global_load_lds_dwordx4 v[156:157], off
	s_barrier
	s_waitcnt lgkmcnt(0)
	s_waitcnt lgkmcnt(0)
	v_mfma_f32_16x16x32_bf16 v[124:127], v[134:137], v[178:181], v[124:127]
	v_mfma_f32_16x16x32_bf16 v[120:123], v[170:173], v[178:181], v[120:123]
	v_mfma_f32_16x16x32_bf16 v[116:119], v[134:137], v[186:189], v[116:119]
	v_mfma_f32_16x16x32_bf16 v[112:115], v[170:173], v[186:189], v[112:115]
	v_mfma_f32_16x16x32_bf16 v[108:111], v[134:137], v[194:197], v[108:111]
	v_mfma_f32_16x16x32_bf16 v[104:107], v[170:173], v[194:197], v[104:107]
	v_mfma_f32_16x16x32_bf16 v[100:103], v[134:137], v[202:205], v[100:103]
	v_mfma_f32_16x16x32_bf16 v[96:99], v[170:173], v[202:205], v[96:99]
	v_mfma_f32_16x16x32_bf16 v[124:127], v[138:141], v[182:185], v[124:127]
	v_mfma_f32_16x16x32_bf16 v[120:123], v[174:177], v[182:185], v[120:123]
	v_mfma_f32_16x16x32_bf16 v[116:119], v[138:141], v[190:193], v[116:119]
	v_mfma_f32_16x16x32_bf16 v[112:115], v[174:177], v[190:193], v[112:115]
	v_mfma_f32_16x16x32_bf16 v[108:111], v[138:141], v[198:201], v[108:111]
	v_mfma_f32_16x16x32_bf16 v[104:107], v[174:177], v[198:201], v[104:107]
	v_mfma_f32_16x16x32_bf16 v[100:103], v[138:141], v[206:209], v[100:103]
	v_mfma_f32_16x16x32_bf16 v[96:99], v[174:177], v[206:209], v[96:99]
	s_barrier
	ds_read_b128 v[210:213], v159
	ds_read_b128 v[214:217], v159 offset:1024
	ds_read_b128 v[218:221], v159 offset:2048
	ds_read_b128 v[156:159], v159 offset:3072
	s_barrier
; #define LDA(dst, b, h) for (int m = 0; m < 4; ++m) for (int k = 0; k < 2; ++k) \
;     dst[m][k] = *reinterpret_cast<const bf16x8*>((char*)SA(b, h) + lds_byte(wr * 64 + m * 16 + fr, k * 32 + fq * 8))
; #define LDB(dst, b, h) for (int n = 0; n < 2; ++n) for (int k = 0; k < 2; ++k) \
;     dst[n][k] = *reinterpret_cast<const bf16x8*>((char*)SB(b, h) + lds_byte(wc * 32 + n * 16 + fr, k * 32 + fq * 8))
; #define MMA(ai, bj, At_, Bt_) do { __builtin_amdgcn_s_setprio(1); \
;     for (int k = 0; k < 2; ++k) for (int m = 0; m < 4; ++m) for (int n = 0; n < 2; ++n) \
;       acc[ai][bj][m][n] = __builtin_amdgcn_mfma_f32_16x16x32_bf16(At_[m][k], Bt_[n][k], acc[ai][bj][m][n], 0, 0, 0); \
;     __builtin_amdgcn_s_setprio(0); } while (0)
; #define WAIT_V(n) asm volatile("s_waitcnt vmcnt(" #n ")" ::: "memory")
; #define WAIT_L(n) asm volatile("s_waitcnt lgkmcnt(" #n ")" ::: "memory")
; #define BAR __builtin_amdgcn_s_barrier()
; template <int EPI, int lda, int ldb, int N, int K>
; __device__ __forceinline__ void gemm_phase(const u16* __restrict__ A, const u16* __restrict__ Bt, const GemmEpi ep, int wv) {
;     ...
;       LDB(B1, 0, 1); BAR; WAIT_L(0); MMA(0, 1, At, B1); BAR;
;       LDA(At, 0, 1); WAIT_V(4); BAR; WAIT_L(0); MMA(1, 0, At, B0); MMA(1, 1, At, B1); BAR; }
;     { LDB(B0, 1, 0); LDA(At, 1, 0); WAIT_V(2); BAR; WAIT_L(0); MMA(0, 0, At, B0); BAR;
	s_waitcnt lgkmcnt(0)
	s_waitcnt lgkmcnt(0)
	v_mfma_f32_16x16x32_bf16 v[92:95], v[210:213], v[178:181], v[92:95]
	v_mfma_f32_16x16x32_bf16 v[88:91], v[218:221], v[178:181], v[88:91]
	v_mfma_f32_16x16x32_bf16 v[76:79], v[210:213], v[194:197], v[76:79]
	v_mfma_f32_16x16x32_bf16 v[72:75], v[218:221], v[194:197], v[72:75]
	v_mfma_f32_16x16x32_bf16 v[84:87], v[210:213], v[186:189], v[84:87]
	v_mfma_f32_16x16x32_bf16 v[80:83], v[218:221], v[186:189], v[80:83]
	v_mfma_f32_16x16x32_bf16 v[68:71], v[210:213], v[202:205], v[68:71]
	v_mfma_f32_16x16x32_bf16 v[64:67], v[218:221], v[202:205], v[64:67]
	v_mfma_f32_16x16x32_bf16 v[92:95], v[214:217], v[182:185], v[92:95]
	v_mfma_f32_16x16x32_bf16 v[88:91], v[156:159], v[182:185], v[88:91]
	v_mfma_f32_16x16x32_bf16 v[76:79], v[214:217], v[198:201], v[76:79]
	v_mfma_f32_16x16x32_bf16 v[72:75], v[156:159], v[198:201], v[72:75]
	v_mfma_f32_16x16x32_bf16 v[178:181], v[214:217], v[190:193], v[84:87]
	v_mfma_f32_16x16x32_bf16 v[182:185], v[156:159], v[190:193], v[80:83]
	v_mfma_f32_16x16x32_bf16 v[186:189], v[214:217], v[206:209], v[68:71]
	v_mfma_f32_16x16x32_bf16 v[190:193], v[156:159], v[206:209], v[64:67]
	s_barrier
	s_nop 0
	ds_read_b128 v[64:67], v151 offset:16384
	ds_read_b128 v[68:71], v151 offset:17408
	ds_read_b128 v[80:83], v150 offset:16384
	ds_read_b128 v[84:87], v150 offset:17408
	ds_read_b128 v[194:197], v149 offset:16384
	ds_read_b128 v[198:201], v149 offset:17408
	ds_read_b128 v[202:205], v148 offset:16384
	ds_read_b128 v[206:209], v148 offset:17408
	s_waitcnt vmcnt(4)
	s_barrier
	s_waitcnt lgkmcnt(0)
	s_waitcnt lgkmcnt(0)
	v_mfma_f32_16x16x32_bf16 v[60:63], v[134:137], v[64:67], v[60:63]
	v_mfma_f32_16x16x32_bf16 v[56:59], v[170:173], v[64:67], v[56:59]
	v_mfma_f32_16x16x32_bf16 v[52:55], v[134:137], v[80:83], v[52:55]
	v_mfma_f32_16x16x32_bf16 v[48:51], v[170:173], v[80:83], v[48:51]
	v_mfma_f32_16x16x32_bf16 v[44:47], v[134:137], v[194:197], v[44:47]
	v_mfma_f32_16x16x32_bf16 v[40:43], v[170:173], v[194:197], v[40:43]
	v_mfma_f32_16x16x32_bf16 v[36:39], v[134:137], v[202:205], v[36:39]
	v_mfma_f32_16x16x32_bf16 v[32:35], v[170:173], v[202:205], v[32:35]
	v_mfma_f32_16x16x32_bf16 v[60:63], v[138:141], v[68:71], v[60:63]
	v_mfma_f32_16x16x32_bf16 v[56:59], v[174:177], v[68:71], v[56:59]
	v_mfma_f32_16x16x32_bf16 v[52:55], v[138:141], v[84:87], v[52:55]
	v_mfma_f32_16x16x32_bf16 v[48:51], v[174:177], v[84:87], v[48:51]
	v_mfma_f32_16x16x32_bf16 v[44:47], v[138:141], v[198:201], v[44:47]
	v_mfma_f32_16x16x32_bf16 v[40:43], v[174:177], v[198:201], v[40:43]
	v_mfma_f32_16x16x32_bf16 v[36:39], v[138:141], v[206:209], v[36:39]
	v_mfma_f32_16x16x32_bf16 v[32:35], v[174:177], v[206:209], v[32:35]
	v_mfma_f32_16x16x32_bf16 v[28:31], v[210:213], v[64:67], v[28:31]
	v_mfma_f32_16x16x32_bf16 v[20:23], v[210:213], v[80:83], v[20:23]
	v_mfma_f32_16x16x32_bf16 v[12:15], v[210:213], v[194:197], v[12:15]
	v_mfma_f32_16x16x32_bf16 v[4:7], v[210:213], v[202:205], v[4:7]
	v_mfma_f32_16x16x32_bf16 v[24:27], v[218:221], v[64:67], v[24:27]
	v_mfma_f32_16x16x32_bf16 v[16:19], v[218:221], v[80:83], v[16:19]
	v_mfma_f32_16x16x32_bf16 v[8:11], v[218:221], v[194:197], v[8:11]
	v_mfma_f32_16x16x32_bf16 v[0:3], v[218:221], v[202:205], v[0:3]
	v_mfma_f32_16x16x32_bf16 v[28:31], v[214:217], v[68:71], v[28:31]
	v_mfma_f32_16x16x32_bf16 v[20:23], v[214:217], v[84:87], v[20:23]
	v_mfma_f32_16x16x32_bf16 v[12:15], v[214:217], v[198:201], v[12:15]
	v_mfma_f32_16x16x32_bf16 v[4:7], v[214:217], v[206:209], v[4:7]
	v_mfma_f32_16x16x32_bf16 v[134:137], v[156:159], v[68:71], v[24:27]
	v_mfma_f32_16x16x32_bf16 v[138:141], v[156:159], v[84:87], v[16:19]
	v_mfma_f32_16x16x32_bf16 v[168:171], v[156:159], v[198:201], v[8:11]
	v_mfma_f32_16x16x32_bf16 v[156:159], v[156:159], v[206:209], v[0:3]
	s_barrier
	s_nop 0
	ds_read_b128 v[0:3], v154
	ds_read_b128 v[8:11], v154 offset:1024
	ds_read_b128 v[16:19], v154 offset:2048
	ds_read_b128 v[172:175], v154 offset:3072
	ds_read_b128 v[24:27], v151 offset:32768
	ds_read_b128 v[194:197], v151 offset:33792
	ds_read_b128 v[198:201], v150 offset:32768
	ds_read_b128 v[202:205], v150 offset:33792
	ds_read_b128 v[206:209], v149 offset:32768
	ds_read_b128 v[210:213], v149 offset:33792
	ds_read_b128 v[214:217], v148 offset:32768
	ds_read_b128 v[218:221], v148 offset:33792
	s_waitcnt vmcnt(2)
	s_barrier
; #define LDA(dst, b, h) for (int m = 0; m < 4; ++m) for (int k = 0; k < 2; ++k) \
;     dst[m][k] = *reinterpret_cast<const bf16x8*>((char*)SA(b, h) + lds_byte(wr * 64 + m * 16 + fr, k * 32 + fq * 8))
; #define LDB(dst, b, h) for (int n = 0; n < 2; ++n) for (int k = 0; k < 2; ++k) \
;     dst[n][k] = *reinterpret_cast<const bf16x8*>((char*)SB(b, h) + lds_byte(wc * 32 + n * 16 + fr, k * 32 + fq * 8))
; #define MMA(ai, bj, At_, Bt_) do { __builtin_amdgcn_s_setprio(1); \
;     for (int k = 0; k < 2; ++k) for (int m = 0; m < 4; ++m) for (int n = 0; n < 2; ++n) \
;       acc[ai][bj][m][n] = __builtin_amdgcn_mfma_f32_16x16x32_bf16(At_[m][k], Bt_[n][k], acc[ai][bj][m][n], 0, 0, 0); \
;     __builtin_amdgcn_s_setprio(0); } while (0)
; #define WAIT_V(n) asm volatile("s_waitcnt vmcnt(" #n ")" ::: "memory")
; #define WAIT_L(n) asm volatile("s_waitcnt lgkmcnt(" #n ")" ::: "memory")
; #define BAR __builtin_amdgcn_s_barrier()
; template <int EPI, int lda, int ldb, int N, int K>
; __device__ __forceinline__ void gemm_phase(const u16* __restrict__ A, const u16* __restrict__ Bt, const GemmEpi ep, int wv) {
;     ...
;     { LDB(B0, 1, 0); LDA(At, 1, 0); WAIT_V(2); BAR; WAIT_L(0); MMA(0, 0, At, B0); BAR;
;       LDB(B1, 1, 1); WAIT_V(0); BAR; WAIT_L(0); MMA(0, 1, At, B1); BAR;
;       LDA(At, 1, 1); BAR; WAIT_L(0); MMA(1, 0, At, B0); MMA(1, 1, At, B1); BAR; }
;     if (wr == 0) BAR;
	s_waitcnt lgkmcnt(0)
	s_waitcnt lgkmcnt(0)
	v_mfma_f32_16x16x32_bf16 v[64:67], v[0:3], v[24:27], v[124:127]
	v_mfma_f32_16x16x32_bf16 v[68:71], v[16:19], v[24:27], v[120:123]
	v_mfma_f32_16x16x32_bf16 v[80:83], v[0:3], v[198:201], v[116:119]
	v_mfma_f32_16x16x32_bf16 v[84:87], v[16:19], v[198:201], v[112:115]
	v_mfma_f32_16x16x32_bf16 v[108:111], v[0:3], v[206:209], v[108:111]
	v_mfma_f32_16x16x32_bf16 v[104:107], v[16:19], v[206:209], v[104:107]
	v_mfma_f32_16x16x32_bf16 v[120:123], v[0:3], v[214:217], v[100:103]
	v_mfma_f32_16x16x32_bf16 v[124:127], v[16:19], v[214:217], v[96:99]
	v_mfma_f32_16x16x32_bf16 v[116:119], v[8:11], v[194:197], v[64:67]
	v_mfma_f32_16x16x32_bf16 v[112:115], v[172:175], v[194:197], v[68:71]
	v_mfma_f32_16x16x32_bf16 v[100:103], v[8:11], v[202:205], v[80:83]
	v_mfma_f32_16x16x32_bf16 v[96:99], v[172:175], v[202:205], v[84:87]
	v_mfma_f32_16x16x32_bf16 v[84:87], v[8:11], v[210:213], v[108:111]
	v_mfma_f32_16x16x32_bf16 v[80:83], v[172:175], v[210:213], v[104:107]
	v_mfma_f32_16x16x32_bf16 v[68:71], v[8:11], v[218:221], v[120:123]
	v_mfma_f32_16x16x32_bf16 v[64:67], v[172:175], v[218:221], v[124:127]
	s_barrier
	ds_read_b128 v[222:225], v152
	ds_read_b128 v[226:229], v152 offset:1024
	ds_read_b128 v[230:233], v152 offset:2048
	ds_read_b128 v[152:155], v152 offset:3072
	s_waitcnt vmcnt(0)
	s_barrier
	s_waitcnt lgkmcnt(0)
	s_waitcnt lgkmcnt(0)
	v_mfma_f32_16x16x32_bf16 v[92:95], v[222:225], v[24:27], v[92:95]
	v_mfma_f32_16x16x32_bf16 v[24:27], v[230:233], v[24:27], v[88:91]
	v_mfma_f32_16x16x32_bf16 v[88:91], v[222:225], v[198:201], v[178:181]
	v_mfma_f32_16x16x32_bf16 v[104:107], v[230:233], v[198:201], v[182:185]
	v_mfma_f32_16x16x32_bf16 v[76:79], v[222:225], v[206:209], v[76:79]
	v_mfma_f32_16x16x32_bf16 v[72:75], v[230:233], v[206:209], v[72:75]
	v_mfma_f32_16x16x32_bf16 v[176:179], v[222:225], v[214:217], v[186:189]
	v_mfma_f32_16x16x32_bf16 v[180:183], v[230:233], v[214:217], v[190:193]
	v_mfma_f32_16x16x32_bf16 v[124:127], v[226:229], v[194:197], v[92:95]
	v_mfma_f32_16x16x32_bf16 v[120:123], v[152:155], v[194:197], v[24:27]
	v_mfma_f32_16x16x32_bf16 v[108:111], v[226:229], v[202:205], v[88:91]
	v_mfma_f32_16x16x32_bf16 v[104:107], v[152:155], v[202:205], v[104:107]
	v_mfma_f32_16x16x32_bf16 v[92:95], v[226:229], v[210:213], v[76:79]
	v_mfma_f32_16x16x32_bf16 v[88:91], v[152:155], v[210:213], v[72:75]
	v_mfma_f32_16x16x32_bf16 v[76:79], v[226:229], v[218:221], v[176:179]
	v_mfma_f32_16x16x32_bf16 v[72:75], v[152:155], v[218:221], v[180:183]
	s_barrier
	ds_read_b128 v[176:179], v151 offset:49152
	ds_read_b128 v[180:183], v151 offset:50176
	ds_read_b128 v[184:187], v150 offset:49152
	ds_read_b128 v[188:191], v150 offset:50176
	ds_read_b128 v[192:195], v149 offset:49152
	ds_read_b128 v[196:199], v149 offset:50176
	ds_read_b128 v[200:203], v148 offset:49152
	ds_read_b128 v[148:151], v148 offset:50176
	s_barrier
	s_waitcnt lgkmcnt(0)
	s_waitcnt lgkmcnt(0)
	v_mfma_f32_16x16x32_bf16 v[24:27], v[0:3], v[176:179], v[60:63]
	v_mfma_f32_16x16x32_bf16 v[60:63], v[16:19], v[176:179], v[56:59]
	v_mfma_f32_16x16x32_bf16 v[52:55], v[0:3], v[184:187], v[52:55]
	v_mfma_f32_16x16x32_bf16 v[204:207], v[16:19], v[184:187], v[48:51]
	v_mfma_f32_16x16x32_bf16 v[44:47], v[0:3], v[192:195], v[44:47]
	v_mfma_f32_16x16x32_bf16 v[208:211], v[16:19], v[192:195], v[40:43]
	v_mfma_f32_16x16x32_bf16 v[0:3], v[0:3], v[200:203], v[36:39]
	v_mfma_f32_16x16x32_bf16 v[36:39], v[16:19], v[200:203], v[32:35]
	v_mfma_f32_16x16x32_bf16 v[56:59], v[8:11], v[180:183], v[24:27]
	v_mfma_f32_16x16x32_bf16 v[48:51], v[172:175], v[180:183], v[60:63]
	v_mfma_f32_16x16x32_bf16 v[40:43], v[8:11], v[188:191], v[52:55]
	v_mfma_f32_16x16x32_bf16 v[32:35], v[172:175], v[188:191], v[204:207]
	v_mfma_f32_16x16x32_bf16 v[24:27], v[8:11], v[196:199], v[44:47]
	v_mfma_f32_16x16x32_bf16 v[16:19], v[172:175], v[196:199], v[208:211]
	v_mfma_f32_16x16x32_bf16 v[8:11], v[8:11], v[148:151], v[0:3]
	v_mfma_f32_16x16x32_bf16 v[0:3], v[172:175], v[148:151], v[36:39]
	v_mfma_f32_16x16x32_bf16 v[28:31], v[222:225], v[176:179], v[28:31]
	v_mfma_f32_16x16x32_bf16 v[36:39], v[230:233], v[176:179], v[134:137]
	v_mfma_f32_16x16x32_bf16 v[20:23], v[222:225], v[184:187], v[20:23]
	v_mfma_f32_16x16x32_bf16 v[134:137], v[230:233], v[184:187], v[138:141]
	v_mfma_f32_16x16x32_bf16 v[12:15], v[222:225], v[192:195], v[12:15]
	v_mfma_f32_16x16x32_bf16 v[138:141], v[230:233], v[192:195], v[168:171]
	v_mfma_f32_16x16x32_bf16 v[4:7], v[222:225], v[200:203], v[4:7]
	v_mfma_f32_16x16x32_bf16 v[156:159], v[230:233], v[200:203], v[156:159]
	v_mfma_f32_16x16x32_bf16 v[60:63], v[226:229], v[180:183], v[28:31]
	v_mfma_f32_16x16x32_bf16 v[52:55], v[152:155], v[180:183], v[36:39]
	v_mfma_f32_16x16x32_bf16 v[44:47], v[226:229], v[188:191], v[20:23]
	v_mfma_f32_16x16x32_bf16 v[36:39], v[152:155], v[188:191], v[134:137]
	v_mfma_f32_16x16x32_bf16 v[28:31], v[226:229], v[196:199], v[12:15]
	v_mfma_f32_16x16x32_bf16 v[20:23], v[152:155], v[196:199], v[138:141]
	v_mfma_f32_16x16x32_bf16 v[12:15], v[226:229], v[148:151], v[4:7]
	v_mfma_f32_16x16x32_bf16 v[4:7], v[152:155], v[148:151], v[156:159]
	v_cmp_gt_u32_e32 vcc, s60, v130
	s_barrier
	s_and_saveexec_b64 s[44:45], vcc
	s_cbranch_execz .LBB0_1451
	s_barrier

; #define STAGE(P, BASE, LD, br, kt) do { const char* _g = (const char*)((BASE) + (size_t)(br) * (LD) + (size_t)(kt) * 64); \
;     for (int _i = 0; _i < 2; ++_i) { int _b = tidx * 16 + _i * 8192; int _r, _c; stage_rc(_b, _r, _c); \
;       __builtin_amdgcn_global_load_lds((const unsigned*)(_g + (unsigned)((_r * (LD) + _c) * 2)), (unsigned*)((char*)(P) + _b), 16, 0, 0); } } while (0)
; #define LDA(dst, b, h) for (int m = 0; m < 4; ++m) for (int k = 0; k < 2; ++k) \
;     dst[m][k] = *reinterpret_cast<const bf16x8*>((char*)SA(b, h) + lds_byte(wr * 64 + m * 16 + fr, k * 32 + fq * 8))
; #define LDB(dst, b, h) for (int n = 0; n < 2; ++n) for (int k = 0; k < 2; ++k) \
;     dst[n][k] = *reinterpret_cast<const bf16x8*>((char*)SB(b, h) + lds_byte(wc * 32 + n * 16 + fr, k * 32 + fq * 8))
; #define MMA(ai, bj, At_, Bt_) do { __builtin_amdgcn_s_setprio(1); \
;     for (int k = 0; k < 2; ++k) for (int m = 0; m < 4; ++m) for (int n = 0; n < 2; ++n) \
;       acc[ai][bj][m][n] = __builtin_amdgcn_mfma_f32_16x16x32_bf16(At_[m][k], Bt_[n][k], acc[ai][bj][m][n], 0, 0, 0); \
;     __builtin_amdgcn_s_setprio(0); } while (0)
; #define WAIT_L(n) asm volatile("s_waitcnt lgkmcnt(" #n ")" ::: "memory")
; #define BAR __builtin_amdgcn_s_barrier()
; #define SCHED __builtin_amdgcn_sched_barrier(0)
; template <int EPI, int lda, int ldb, int N, int K>
; __device__ __forceinline__ void gemm_phase(const u16* __restrict__ A, const u16* __restrict__ Bt, const GemmEpi ep, int wv) {
;     ...
;     for (int t = 0; t < nt - 2; t += 2) {
;       LDB(B0, 0, 0); SCHED; LDA(At, 0, 0); STAGE(SA(1, 1), Ab, lda, brow + HALF, t + 1);
;       WAIT_L(8); BAR; WAIT_L(0); MMA(0, 0, At, B0); BAR; SCHED;
;       LDB(B1, 0, 1); STAGE(SB(0, 0), Bt, ldb, bcol, t + 2);
;       BAR; WAIT_L(0); MMA(0, 1, At, B1); BAR;
;       LDA(At, 0, 1); STAGE(SA(0, 0), Ab, lda, brow, t + 2);
;       BAR; WAIT_L(0); MMA(1, 0, At, B0); BAR; SCHED;
.LBB0_1564:
	ds_read_b128 v[172:175], v161
	ds_read_b128 v[176:179], v161 offset:1024
	ds_read_b128 v[180:183], v161 offset:2048
	ds_read_b128 v[184:187], v161 offset:3072
	v_add_u32_e32 v169, 0xc000, v148
	v_lshl_add_u64 v[236:237], v[136:137], 0, s[40:41]
	v_readfirstlane_b32 s43, v169
	v_add_u32_e32 v170, 0xe000, v148
	v_lshl_add_u64 v[162:163], v[236:237], 0, s[14:15]
	s_mov_b32 m0, s43
	v_lshl_add_u64 v[238:239], v[134:135], 0, s[40:41]
	v_readfirstlane_b32 s43, v170
	ds_read_b128 v[164:167], v152
	ds_read_b128 v[188:191], v152 offset:1024
	ds_read_b128 v[192:195], v151
	ds_read_b128 v[196:199], v151 offset:1024
	ds_read_b128 v[200:203], v150
	ds_read_b128 v[204:207], v150 offset:1024
	ds_read_b128 v[208:211], v149
	ds_read_b128 v[212:215], v149 offset:1024
	global_load_lds_dwordx4 v[162:163], off
	s_nop 1
	v_lshl_add_u64 v[162:163], v[238:239], 0, s[14:15]
	s_mov_b32 m0, s43
	s_nop 0
	global_load_lds_dwordx4 v[162:163], off
	s_waitcnt lgkmcnt(8)
	s_barrier
	s_waitcnt lgkmcnt(0)
	s_waitcnt lgkmcnt(0)
	v_mfma_f32_16x16x32_bf16 v[124:127], v[172:175], v[164:167], v[124:127]
	v_mfma_f32_16x16x32_bf16 v[120:123], v[180:183], v[164:167], v[120:123]
	v_mfma_f32_16x16x32_bf16 v[116:119], v[172:175], v[192:195], v[116:119]
	v_mfma_f32_16x16x32_bf16 v[112:115], v[180:183], v[192:195], v[112:115]
	v_mfma_f32_16x16x32_bf16 v[108:111], v[172:175], v[200:203], v[108:111]
	v_mfma_f32_16x16x32_bf16 v[104:107], v[180:183], v[200:203], v[104:107]
	v_mfma_f32_16x16x32_bf16 v[100:103], v[172:175], v[208:211], v[100:103]
	v_mfma_f32_16x16x32_bf16 v[96:99], v[180:183], v[208:211], v[96:99]
	v_mfma_f32_16x16x32_bf16 v[124:127], v[176:179], v[188:191], v[124:127]
	v_mfma_f32_16x16x32_bf16 v[120:123], v[184:187], v[188:191], v[120:123]
	v_mfma_f32_16x16x32_bf16 v[116:119], v[176:179], v[196:199], v[116:119]
	v_mfma_f32_16x16x32_bf16 v[112:115], v[184:187], v[196:199], v[112:115]
	v_mfma_f32_16x16x32_bf16 v[108:111], v[176:179], v[204:207], v[108:111]
	v_mfma_f32_16x16x32_bf16 v[104:107], v[184:187], v[204:207], v[104:107]
	v_mfma_f32_16x16x32_bf16 v[100:103], v[176:179], v[212:215], v[100:103]
	v_mfma_f32_16x16x32_bf16 v[96:99], v[184:187], v[212:215], v[96:99]
	s_barrier
	v_add_u32_e32 v162, s52, v153
	v_lshl_add_u64 v[240:241], v[140:141], 0, s[40:41]
	v_readfirstlane_b32 s43, v162
	v_add_u32_e32 v163, 0x2000, v162
	v_lshl_add_u64 v[232:233], v[240:241], 0, s[16:17]
	s_mov_b32 m0, s43
	v_lshl_add_u64 v[242:243], v[138:139], 0, s[40:41]
	v_readfirstlane_b32 s43, v163
	ds_read_b128 v[216:219], v160
	ds_read_b128 v[220:223], v160 offset:1024
	ds_read_b128 v[224:227], v160 offset:2048
	ds_read_b128 v[228:231], v160 offset:3072
	global_load_lds_dwordx4 v[232:233], off
	s_nop 1
	v_lshl_add_u64 v[232:233], v[242:243], 0, s[16:17]
	s_mov_b32 m0, s43
	s_nop 0
	global_load_lds_dwordx4 v[232:233], off
	s_barrier
	s_waitcnt lgkmcnt(0)
	s_waitcnt lgkmcnt(0)
	v_mfma_f32_16x16x32_bf16 v[92:95], v[216:219], v[164:167], v[92:95]
	v_mfma_f32_16x16x32_bf16 v[88:91], v[224:227], v[164:167], v[88:91]
	v_mfma_f32_16x16x32_bf16 v[84:87], v[216:219], v[192:195], v[84:87]
	v_mfma_f32_16x16x32_bf16 v[80:83], v[224:227], v[192:195], v[80:83]
	v_mfma_f32_16x16x32_bf16 v[76:79], v[216:219], v[200:203], v[76:79]
	v_mfma_f32_16x16x32_bf16 v[72:75], v[224:227], v[200:203], v[72:75]
	v_mfma_f32_16x16x32_bf16 v[68:71], v[216:219], v[208:211], v[68:71]
	v_mfma_f32_16x16x32_bf16 v[64:67], v[224:227], v[208:211], v[64:67]
	v_mfma_f32_16x16x32_bf16 v[92:95], v[220:223], v[188:191], v[92:95]
	v_mfma_f32_16x16x32_bf16 v[88:91], v[228:231], v[188:191], v[88:91]
	v_mfma_f32_16x16x32_bf16 v[84:87], v[220:223], v[196:199], v[84:87]
	v_mfma_f32_16x16x32_bf16 v[80:83], v[228:231], v[196:199], v[80:83]
	v_mfma_f32_16x16x32_bf16 v[76:79], v[220:223], v[204:207], v[76:79]
	v_mfma_f32_16x16x32_bf16 v[72:75], v[228:231], v[204:207], v[72:75]
	v_mfma_f32_16x16x32_bf16 v[68:71], v[220:223], v[212:215], v[68:71]
	v_mfma_f32_16x16x32_bf16 v[64:67], v[228:231], v[212:215], v[64:67]
	v_readfirstlane_b32 s43, v148
	v_lshl_add_u64 v[164:165], v[236:237], 0, s[18:19]
	s_mov_b32 m0, s43
	s_barrier
	ds_read_b128 v[188:191], v152 offset:16384
	ds_read_b128 v[192:195], v152 offset:17408
	ds_read_b128 v[196:199], v151 offset:16384
	ds_read_b128 v[200:203], v151 offset:17408
	ds_read_b128 v[204:207], v150 offset:16384
	ds_read_b128 v[208:211], v150 offset:17408
	ds_read_b128 v[212:215], v149 offset:16384
	ds_read_b128 v[232:235], v149 offset:17408
	global_load_lds_dwordx4 v[164:165], off
	s_nop 1
	v_add_u32_e32 v164, 0x2000, v148
	v_lshl_add_u64 v[166:167], v[238:239], 0, s[18:19]
	v_readfirstlane_b32 s43, v164
	s_mov_b32 m0, s43
	s_nop 0
	global_load_lds_dwordx4 v[166:167], off
	s_barrier
	s_waitcnt lgkmcnt(0)
	s_waitcnt lgkmcnt(0)
	v_mfma_f32_16x16x32_bf16 v[60:63], v[172:175], v[188:191], v[60:63]
	v_mfma_f32_16x16x32_bf16 v[56:59], v[180:183], v[188:191], v[56:59]
	v_mfma_f32_16x16x32_bf16 v[52:55], v[172:175], v[196:199], v[52:55]
	v_mfma_f32_16x16x32_bf16 v[48:51], v[180:183], v[196:199], v[48:51]
	v_mfma_f32_16x16x32_bf16 v[44:47], v[172:175], v[204:207], v[44:47]
	v_mfma_f32_16x16x32_bf16 v[40:43], v[180:183], v[204:207], v[40:43]
	v_mfma_f32_16x16x32_bf16 v[36:39], v[172:175], v[212:215], v[36:39]
	v_mfma_f32_16x16x32_bf16 v[32:35], v[180:183], v[212:215], v[32:35]
	v_mfma_f32_16x16x32_bf16 v[60:63], v[176:179], v[192:195], v[60:63]
	v_mfma_f32_16x16x32_bf16 v[56:59], v[184:187], v[192:195], v[56:59]
	v_mfma_f32_16x16x32_bf16 v[52:55], v[176:179], v[200:203], v[52:55]
	v_mfma_f32_16x16x32_bf16 v[48:51], v[184:187], v[200:203], v[48:51]
	v_mfma_f32_16x16x32_bf16 v[44:47], v[176:179], v[208:211], v[44:47]
	v_mfma_f32_16x16x32_bf16 v[40:43], v[184:187], v[208:211], v[40:43]
	v_mfma_f32_16x16x32_bf16 v[36:39], v[176:179], v[232:235], v[36:39]
	v_mfma_f32_16x16x32_bf16 v[32:35], v[184:187], v[232:235], v[32:35]
	s_barrier
; #define STAGE(P, BASE, LD, br, kt) do { const char* _g = (const char*)((BASE) + (size_t)(br) * (LD) + (size_t)(kt) * 64); \
;     for (int _i = 0; _i < 2; ++_i) { int _b = tidx * 16 + _i * 8192; int _r, _c; stage_rc(_b, _r, _c); \
;       __builtin_amdgcn_global_load_lds((const unsigned*)(_g + (unsigned)((_r * (LD) + _c) * 2)), (unsigned*)((char*)(P) + _b), 16, 0, 0); } } while (0)
; #define LDA(dst, b, h) for (int m = 0; m < 4; ++m) for (int k = 0; k < 2; ++k) \
;     dst[m][k] = *reinterpret_cast<const bf16x8*>((char*)SA(b, h) + lds_byte(wr * 64 + m * 16 + fr, k * 32 + fq * 8))
; #define LDB(dst, b, h) for (int n = 0; n < 2; ++n) for (int k = 0; k < 2; ++k) \
;     dst[n][k] = *reinterpret_cast<const bf16x8*>((char*)SB(b, h) + lds_byte(wc * 32 + n * 16 + fr, k * 32 + fq * 8))
; #define MMA(ai, bj, At_, Bt_) do { __builtin_amdgcn_s_setprio(1); \
;     for (int k = 0; k < 2; ++k) for (int m = 0; m < 4; ++m) for (int n = 0; n < 2; ++n) \
;       acc[ai][bj][m][n] = __builtin_amdgcn_mfma_f32_16x16x32_bf16(At_[m][k], Bt_[n][k], acc[ai][bj][m][n], 0, 0, 0); \
;     __builtin_amdgcn_s_setprio(0); } while (0)
; #define WAIT_V(n) asm volatile("s_waitcnt vmcnt(" #n ")" ::: "memory")
; #define WAIT_L(n) asm volatile("s_waitcnt lgkmcnt(" #n ")" ::: "memory")
; #define BAR __builtin_amdgcn_s_barrier()
; #define SCHED __builtin_amdgcn_sched_barrier(0)
; template <int EPI, int lda, int ldb, int N, int K>
; __device__ __forceinline__ void gemm_phase(const u16* __restrict__ A, const u16* __restrict__ Bt, const GemmEpi ep, int wv) {
;     ...
;       STAGE(SB(0, 1), Bt, ldb, bcol + HALF, t + 2);
;       WAIT_V(6); BAR; MMA(1, 1, At, B1); BAR;
;       LDB(B0, 1, 0); SCHED; LDA(At, 1, 0); STAGE(SA(0, 1), Ab, lda, brow + HALF, t + 2);
;       WAIT_L(8); BAR; WAIT_L(0); MMA(0, 0, At, B0); BAR; SCHED;
;       LDB(B1, 1, 1); STAGE(SB(1, 0), Bt, ldb, bcol, t + 3);
;       BAR; WAIT_L(0); MMA(0, 1, At, B1); BAR;
	v_add_u32_e32 v165, s53, v153
	v_lshl_add_u64 v[166:167], v[240:241], 0, s[20:21]
	v_readfirstlane_b32 s43, v165
	s_mov_b32 m0, s43
	v_lshl_add_u64 v[172:173], v[242:243], 0, s[20:21]
	global_load_lds_dwordx4 v[166:167], off
	s_nop 1
	v_add_u32_e32 v166, 0x2000, v165
	s_nop 0
	v_readfirstlane_b32 s43, v166
	s_mov_b32 m0, s43
	s_nop 0
	global_load_lds_dwordx4 v[172:173], off
	s_waitcnt vmcnt(6)
	s_barrier
	v_mfma_f32_16x16x32_bf16 v[28:31], v[216:219], v[188:191], v[28:31]
	v_mfma_f32_16x16x32_bf16 v[24:27], v[224:227], v[188:191], v[24:27]
	v_mfma_f32_16x16x32_bf16 v[20:23], v[216:219], v[196:199], v[20:23]
	v_mfma_f32_16x16x32_bf16 v[16:19], v[224:227], v[196:199], v[16:19]
	v_mfma_f32_16x16x32_bf16 v[12:15], v[216:219], v[204:207], v[12:15]
	v_mfma_f32_16x16x32_bf16 v[8:11], v[224:227], v[204:207], v[8:11]
	v_mfma_f32_16x16x32_bf16 v[4:7], v[216:219], v[212:215], v[4:7]
	v_mfma_f32_16x16x32_bf16 v[0:3], v[224:227], v[212:215], v[0:3]
	v_mfma_f32_16x16x32_bf16 v[28:31], v[220:223], v[192:195], v[28:31]
	v_mfma_f32_16x16x32_bf16 v[24:27], v[228:231], v[192:195], v[24:27]
	v_mfma_f32_16x16x32_bf16 v[20:23], v[220:223], v[200:203], v[20:23]
	v_mfma_f32_16x16x32_bf16 v[16:19], v[228:231], v[200:203], v[16:19]
	v_mfma_f32_16x16x32_bf16 v[12:15], v[220:223], v[208:211], v[12:15]
	v_mfma_f32_16x16x32_bf16 v[8:11], v[228:231], v[208:211], v[8:11]
	v_mfma_f32_16x16x32_bf16 v[4:7], v[220:223], v[232:235], v[4:7]
	v_mfma_f32_16x16x32_bf16 v[0:3], v[228:231], v[232:235], v[0:3]
	s_barrier
	ds_read_b128 v[172:175], v156
	ds_read_b128 v[176:179], v156 offset:1024
	ds_read_b128 v[180:183], v156 offset:2048
	ds_read_b128 v[184:187], v156 offset:3072
	v_add_u32_e32 v167, 0x4000, v148
	v_add_u32_e32 v168, 0x6000, v148
	v_readfirstlane_b32 s43, v167
	v_lshl_add_u64 v[220:221], v[236:237], 0, s[22:23]
	s_mov_b32 m0, s43
	v_readfirstlane_b32 s43, v168
	ds_read_b128 v[188:191], v152 offset:32768
	ds_read_b128 v[192:195], v152 offset:33792
	ds_read_b128 v[196:199], v151 offset:32768
	ds_read_b128 v[200:203], v151 offset:33792
	ds_read_b128 v[204:207], v150 offset:32768
	ds_read_b128 v[208:211], v150 offset:33792
	ds_read_b128 v[212:215], v149 offset:32768
	ds_read_b128 v[216:219], v149 offset:33792
	global_load_lds_dwordx4 v[220:221], off
	s_nop 1
	v_lshl_add_u64 v[220:221], v[238:239], 0, s[22:23]
	s_mov_b32 m0, s43
	s_nop 0
	global_load_lds_dwordx4 v[220:221], off
	s_waitcnt lgkmcnt(8)
	s_barrier
	s_waitcnt lgkmcnt(0)
	s_waitcnt lgkmcnt(0)
	v_mfma_f32_16x16x32_bf16 v[124:127], v[172:175], v[188:191], v[124:127]
	v_mfma_f32_16x16x32_bf16 v[120:123], v[180:183], v[188:191], v[120:123]
	v_mfma_f32_16x16x32_bf16 v[116:119], v[172:175], v[196:199], v[116:119]
	v_mfma_f32_16x16x32_bf16 v[112:115], v[180:183], v[196:199], v[112:115]
	v_mfma_f32_16x16x32_bf16 v[108:111], v[172:175], v[204:207], v[108:111]
	v_mfma_f32_16x16x32_bf16 v[104:107], v[180:183], v[204:207], v[104:107]
	v_mfma_f32_16x16x32_bf16 v[100:103], v[172:175], v[212:215], v[100:103]
	v_mfma_f32_16x16x32_bf16 v[96:99], v[180:183], v[212:215], v[96:99]
	v_mfma_f32_16x16x32_bf16 v[124:127], v[176:179], v[192:195], v[124:127]
	v_mfma_f32_16x16x32_bf16 v[120:123], v[184:187], v[192:195], v[120:123]
	v_mfma_f32_16x16x32_bf16 v[116:119], v[176:179], v[200:203], v[116:119]
	v_mfma_f32_16x16x32_bf16 v[112:115], v[184:187], v[200:203], v[112:115]
	v_mfma_f32_16x16x32_bf16 v[108:111], v[176:179], v[208:211], v[108:111]
	v_mfma_f32_16x16x32_bf16 v[104:107], v[184:187], v[208:211], v[104:107]
	v_mfma_f32_16x16x32_bf16 v[100:103], v[176:179], v[216:219], v[100:103]
	v_mfma_f32_16x16x32_bf16 v[96:99], v[184:187], v[216:219], v[96:99]
	s_barrier
	v_readfirstlane_b32 s43, v155
	v_add_u32_e32 v171, 0x2000, v155
	v_lshl_add_u64 v[244:245], v[240:241], 0, s[24:25]
	s_mov_b32 m0, s43
	v_readfirstlane_b32 s43, v171
	ds_read_b128 v[220:223], v154
	ds_read_b128 v[224:227], v154 offset:1024
	ds_read_b128 v[228:231], v154 offset:2048
	ds_read_b128 v[232:235], v154 offset:3072
	global_load_lds_dwordx4 v[244:245], off
	s_nop 1
	v_lshl_add_u64 v[244:245], v[242:243], 0, s[24:25]
	s_mov_b32 m0, s43
	s_nop 0
	global_load_lds_dwordx4 v[244:245], off
	s_barrier
	s_waitcnt lgkmcnt(0)
	s_waitcnt lgkmcnt(0)
	v_mfma_f32_16x16x32_bf16 v[92:95], v[220:223], v[188:191], v[92:95]
	v_mfma_f32_16x16x32_bf16 v[88:91], v[228:231], v[188:191], v[88:91]
	v_mfma_f32_16x16x32_bf16 v[84:87], v[220:223], v[196:199], v[84:87]
	v_mfma_f32_16x16x32_bf16 v[80:83], v[228:231], v[196:199], v[80:83]
	v_mfma_f32_16x16x32_bf16 v[76:79], v[220:223], v[204:207], v[76:79]
	v_mfma_f32_16x16x32_bf16 v[72:75], v[228:231], v[204:207], v[72:75]
	v_mfma_f32_16x16x32_bf16 v[68:71], v[220:223], v[212:215], v[68:71]
	v_mfma_f32_16x16x32_bf16 v[64:67], v[228:231], v[212:215], v[64:67]
	v_mfma_f32_16x16x32_bf16 v[92:95], v[224:227], v[192:195], v[92:95]
	v_mfma_f32_16x16x32_bf16 v[88:91], v[232:235], v[192:195], v[88:91]
	v_mfma_f32_16x16x32_bf16 v[84:87], v[224:227], v[200:203], v[84:87]
	v_mfma_f32_16x16x32_bf16 v[80:83], v[232:235], v[200:203], v[80:83]
	v_mfma_f32_16x16x32_bf16 v[76:79], v[224:227], v[208:211], v[76:79]
	v_mfma_f32_16x16x32_bf16 v[72:75], v[232:235], v[208:211], v[72:75]
	v_mfma_f32_16x16x32_bf16 v[68:71], v[224:227], v[216:219], v[68:71]
	v_mfma_f32_16x16x32_bf16 v[64:67], v[232:235], v[216:219], v[64:67]
	v_readfirstlane_b32 s43, v157
	v_lshl_add_u64 v[236:237], v[236:237], 0, s[26:27]
	s_mov_b32 m0, s43
	v_readfirstlane_b32 s43, v158
	s_barrier
; #define STAGE(P, BASE, LD, br, kt) do { const char* _g = (const char*)((BASE) + (size_t)(br) * (LD) + (size_t)(kt) * 64); \
;     for (int _i = 0; _i < 2; ++_i) { int _b = tidx * 16 + _i * 8192; int _r, _c; stage_rc(_b, _r, _c); \
;       __builtin_amdgcn_global_load_lds((const unsigned*)(_g + (unsigned)((_r * (LD) + _c) * 2)), (unsigned*)((char*)(P) + _b), 16, 0, 0); } } while (0)
; #define LDA(dst, b, h) for (int m = 0; m < 4; ++m) for (int k = 0; k < 2; ++k) \
;     dst[m][k] = *reinterpret_cast<const bf16x8*>((char*)SA(b, h) + lds_byte(wr * 64 + m * 16 + fr, k * 32 + fq * 8))
; #define LDB(dst, b, h) for (int n = 0; n < 2; ++n) for (int k = 0; k < 2; ++k) \
;     dst[n][k] = *reinterpret_cast<const bf16x8*>((char*)SB(b, h) + lds_byte(wc * 32 + n * 16 + fr, k * 32 + fq * 8))
; #define MMA(ai, bj, At_, Bt_) do { __builtin_amdgcn_s_setprio(1); \
;     for (int k = 0; k < 2; ++k) for (int m = 0; m < 4; ++m) for (int n = 0; n < 2; ++n) \
;       acc[ai][bj][m][n] = __builtin_amdgcn_mfma_f32_16x16x32_bf16(At_[m][k], Bt_[n][k], acc[ai][bj][m][n], 0, 0, 0); \
;     __builtin_amdgcn_s_setprio(0); } while (0)
; #define WAIT_V(n) asm volatile("s_waitcnt vmcnt(" #n ")" ::: "memory")
; #define WAIT_L(n) asm volatile("s_waitcnt lgkmcnt(" #n ")" ::: "memory")
; #define BAR __builtin_amdgcn_s_barrier()
; #define SCHED __builtin_amdgcn_sched_barrier(0)
; template <int EPI, int lda, int ldb, int N, int K>
; __device__ __forceinline__ void gemm_phase(const u16* __restrict__ A, const u16* __restrict__ Bt, const GemmEpi ep, int wv) {
;     ...
;       LDA(At, 1, 1); STAGE(SA(1, 0), Ab, lda, brow, t + 3);
;       BAR; WAIT_L(0); MMA(1, 0, At, B0); BAR; SCHED;
;       STAGE(SB(1, 1), Bt, ldb, bcol + HALF, t + 3);
;       WAIT_V(6); BAR; MMA(1, 1, At, B1); BAR;
;     }
;     { LDB(B0, 0, 0); LDA(At, 0, 0); STAGE(SA(1, 1), Ab, lda, brow + HALF, nt - 1);
;       BAR; WAIT_L(0); MMA(0, 0, At, B0); BAR;
;       LDB(B1, 0, 1); BAR; WAIT_L(0); MMA(0, 1, At, B1); BAR;
	ds_read_b128 v[188:191], v152 offset:49152
	ds_read_b128 v[192:195], v152 offset:50176
	ds_read_b128 v[196:199], v151 offset:49152
	ds_read_b128 v[200:203], v151 offset:50176
	ds_read_b128 v[204:207], v150 offset:49152
	ds_read_b128 v[208:211], v150 offset:50176
	ds_read_b128 v[212:215], v149 offset:49152
	ds_read_b128 v[216:219], v149 offset:50176
	global_load_lds_dwordx4 v[236:237], off
	s_nop 1
	v_lshl_add_u64 v[236:237], v[238:239], 0, s[26:27]
	s_mov_b32 m0, s43
	s_nop 0
	global_load_lds_dwordx4 v[236:237], off
	s_barrier
	s_waitcnt lgkmcnt(0)
	s_waitcnt lgkmcnt(0)
	v_mfma_f32_16x16x32_bf16 v[60:63], v[172:175], v[188:191], v[60:63]
	v_mfma_f32_16x16x32_bf16 v[56:59], v[180:183], v[188:191], v[56:59]
	v_mfma_f32_16x16x32_bf16 v[52:55], v[172:175], v[196:199], v[52:55]
	v_mfma_f32_16x16x32_bf16 v[48:51], v[180:183], v[196:199], v[48:51]
	v_mfma_f32_16x16x32_bf16 v[44:47], v[172:175], v[204:207], v[44:47]
	v_mfma_f32_16x16x32_bf16 v[40:43], v[180:183], v[204:207], v[40:43]
	v_mfma_f32_16x16x32_bf16 v[36:39], v[172:175], v[212:215], v[36:39]
	v_mfma_f32_16x16x32_bf16 v[32:35], v[180:183], v[212:215], v[32:35]
	v_mfma_f32_16x16x32_bf16 v[60:63], v[176:179], v[192:195], v[60:63]
	v_mfma_f32_16x16x32_bf16 v[56:59], v[184:187], v[192:195], v[56:59]
	v_mfma_f32_16x16x32_bf16 v[52:55], v[176:179], v[200:203], v[52:55]
	v_mfma_f32_16x16x32_bf16 v[48:51], v[184:187], v[200:203], v[48:51]
	v_mfma_f32_16x16x32_bf16 v[44:47], v[176:179], v[208:211], v[44:47]
	v_mfma_f32_16x16x32_bf16 v[40:43], v[184:187], v[208:211], v[40:43]
	v_mfma_f32_16x16x32_bf16 v[36:39], v[176:179], v[216:219], v[36:39]
	v_mfma_f32_16x16x32_bf16 v[32:35], v[184:187], v[216:219], v[32:35]
	s_barrier
	v_readfirstlane_b32 s43, v159
	v_add_u32_e32 v171, 0x2000, v159
	v_lshl_add_u64 v[172:173], v[240:241], 0, s[34:35]
	s_mov_b32 m0, s43
	v_readfirstlane_b32 s43, v171
	global_load_lds_dwordx4 v[172:173], off
	s_nop 1
	v_lshl_add_u64 v[172:173], v[242:243], 0, s[34:35]
	s_mov_b32 m0, s43
	s_nop 0
	global_load_lds_dwordx4 v[172:173], off
	s_waitcnt vmcnt(6)
	s_barrier
	v_mfma_f32_16x16x32_bf16 v[28:31], v[220:223], v[188:191], v[28:31]
	v_mfma_f32_16x16x32_bf16 v[24:27], v[228:231], v[188:191], v[24:27]
	v_mfma_f32_16x16x32_bf16 v[20:23], v[220:223], v[196:199], v[20:23]
	v_mfma_f32_16x16x32_bf16 v[16:19], v[228:231], v[196:199], v[16:19]
	v_mfma_f32_16x16x32_bf16 v[12:15], v[220:223], v[204:207], v[12:15]
	v_mfma_f32_16x16x32_bf16 v[8:11], v[228:231], v[204:207], v[8:11]
	v_mfma_f32_16x16x32_bf16 v[4:7], v[220:223], v[212:215], v[4:7]
	v_mfma_f32_16x16x32_bf16 v[0:3], v[228:231], v[212:215], v[0:3]
	v_mfma_f32_16x16x32_bf16 v[28:31], v[224:227], v[192:195], v[28:31]
	v_mfma_f32_16x16x32_bf16 v[24:27], v[232:235], v[192:195], v[24:27]
	v_mfma_f32_16x16x32_bf16 v[20:23], v[224:227], v[200:203], v[20:23]
	v_mfma_f32_16x16x32_bf16 v[16:19], v[232:235], v[200:203], v[16:19]
	v_mfma_f32_16x16x32_bf16 v[12:15], v[224:227], v[208:211], v[12:15]
	v_mfma_f32_16x16x32_bf16 v[8:11], v[232:235], v[208:211], v[8:11]
	v_mfma_f32_16x16x32_bf16 v[4:7], v[224:227], v[216:219], v[4:7]
	v_mfma_f32_16x16x32_bf16 v[0:3], v[232:235], v[216:219], v[0:3]
	s_add_i32 s42, s42, 2
	s_add_u32 s40, s40, 0x100
	s_addc_u32 s41, s41, 0
	s_cmp_gt_u32 s42, 27
	s_barrier
	s_cbranch_scc0 .LBB0_1564
	s_add_i32 s40, s38, 0x80
	s_mul_hi_i32 s41, s40, 0x1080
	s_mulk_i32 s40, 0x1080
	s_add_u32 s40, s49, s40
	s_addc_u32 s41, s50, s41
	v_lshl_add_u64 v[158:159], s[40:41], 0, v[128:129]
	v_readfirstlane_b32 s42, v169
	v_lshl_add_u64 v[158:159], v[158:159], 0, s[36:37]
	s_mov_b32 m0, s42
	ds_read_b128 v[134:137], v161
	ds_read_b128 v[138:141], v161 offset:1024
	ds_read_b128 v[172:175], v161 offset:2048
	ds_read_b128 v[176:179], v161 offset:3072
	ds_read_b128 v[180:183], v152
	ds_read_b128 v[184:187], v152 offset:1024
	ds_read_b128 v[188:191], v151
	ds_read_b128 v[192:195], v151 offset:1024
	ds_read_b128 v[196:199], v150
	ds_read_b128 v[200:203], v150 offset:1024
	ds_read_b128 v[204:207], v149
	ds_read_b128 v[208:211], v149 offset:1024
	global_load_lds_dwordx4 v[158:159], off
	v_lshl_add_u64 v[158:159], s[40:41], 0, v[132:133]
	v_readfirstlane_b32 s40, v170
	v_lshl_add_u64 v[158:159], v[158:159], 0, s[36:37]
	s_mov_b32 m0, s40
	s_nop 0
	global_load_lds_dwordx4 v[158:159], off
	s_barrier
	s_waitcnt lgkmcnt(0)
	s_waitcnt lgkmcnt(0)
	v_mfma_f32_16x16x32_bf16 v[124:127], v[134:137], v[180:183], v[124:127]
	v_mfma_f32_16x16x32_bf16 v[120:123], v[172:175], v[180:183], v[120:123]
	v_mfma_f32_16x16x32_bf16 v[116:119], v[134:137], v[188:191], v[116:119]
	v_mfma_f32_16x16x32_bf16 v[112:115], v[172:175], v[188:191], v[112:115]
	v_mfma_f32_16x16x32_bf16 v[108:111], v[134:137], v[196:199], v[108:111]
	v_mfma_f32_16x16x32_bf16 v[104:107], v[172:175], v[196:199], v[104:107]
	v_mfma_f32_16x16x32_bf16 v[100:103], v[134:137], v[204:207], v[100:103]
	v_mfma_f32_16x16x32_bf16 v[96:99], v[172:175], v[204:207], v[96:99]
	v_mfma_f32_16x16x32_bf16 v[124:127], v[138:141], v[184:187], v[124:127]
	v_mfma_f32_16x16x32_bf16 v[120:123], v[176:179], v[184:187], v[120:123]
	v_mfma_f32_16x16x32_bf16 v[116:119], v[138:141], v[192:195], v[116:119]
	v_mfma_f32_16x16x32_bf16 v[112:115], v[176:179], v[192:195], v[112:115]
	v_mfma_f32_16x16x32_bf16 v[108:111], v[138:141], v[200:203], v[108:111]
	v_mfma_f32_16x16x32_bf16 v[104:107], v[176:179], v[200:203], v[104:107]
	v_mfma_f32_16x16x32_bf16 v[100:103], v[138:141], v[208:211], v[100:103]
	v_mfma_f32_16x16x32_bf16 v[96:99], v[176:179], v[208:211], v[96:99]
	s_barrier
	ds_read_b128 v[212:215], v160
	ds_read_b128 v[216:219], v160 offset:1024
	ds_read_b128 v[220:223], v160 offset:2048
	ds_read_b128 v[158:161], v160 offset:3072
	s_barrier
; #define LDA(dst, b, h) for (int m = 0; m < 4; ++m) for (int k = 0; k < 2; ++k) \
;     dst[m][k] = *reinterpret_cast<const bf16x8*>((char*)SA(b, h) + lds_byte(wr * 64 + m * 16 + fr, k * 32 + fq * 8))
; #define LDB(dst, b, h) for (int n = 0; n < 2; ++n) for (int k = 0; k < 2; ++k) \
;     dst[n][k] = *reinterpret_cast<const bf16x8*>((char*)SB(b, h) + lds_byte(wc * 32 + n * 16 + fr, k * 32 + fq * 8))
; #define MMA(ai, bj, At_, Bt_) do { __builtin_amdgcn_s_setprio(1); \
;     for (int k = 0; k < 2; ++k) for (int m = 0; m < 4; ++m) for (int n = 0; n < 2; ++n) \
;       acc[ai][bj][m][n] = __builtin_amdgcn_mfma_f32_16x16x32_bf16(At_[m][k], Bt_[n][k], acc[ai][bj][m][n], 0, 0, 0); \
;     __builtin_amdgcn_s_setprio(0); } while (0)
; #define WAIT_V(n) asm volatile("s_waitcnt vmcnt(" #n ")" ::: "memory")
; #define WAIT_L(n) asm volatile("s_waitcnt lgkmcnt(" #n ")" ::: "memory")
; #define BAR __builtin_amdgcn_s_barrier()
; template <int EPI, int lda, int ldb, int N, int K>
; __device__ __forceinline__ void gemm_phase(const u16* __restrict__ A, const u16* __restrict__ Bt, const GemmEpi ep, int wv) {
;     ...
;       LDB(B1, 0, 1); BAR; WAIT_L(0); MMA(0, 1, At, B1); BAR;
;       LDA(At, 0, 1); WAIT_V(4); BAR; WAIT_L(0); MMA(1, 0, At, B0); MMA(1, 1, At, B1); BAR; }
;     { LDB(B0, 1, 0); LDA(At, 1, 0); WAIT_V(2); BAR; WAIT_L(0); MMA(0, 0, At, B0); BAR;
	s_waitcnt lgkmcnt(0)
	s_waitcnt lgkmcnt(0)
	v_mfma_f32_16x16x32_bf16 v[92:95], v[212:215], v[180:183], v[92:95]
	v_mfma_f32_16x16x32_bf16 v[88:91], v[220:223], v[180:183], v[88:91]
	v_mfma_f32_16x16x32_bf16 v[76:79], v[212:215], v[196:199], v[76:79]
	v_mfma_f32_16x16x32_bf16 v[72:75], v[220:223], v[196:199], v[72:75]
	v_mfma_f32_16x16x32_bf16 v[84:87], v[212:215], v[188:191], v[84:87]
	v_mfma_f32_16x16x32_bf16 v[80:83], v[220:223], v[188:191], v[80:83]
	v_mfma_f32_16x16x32_bf16 v[68:71], v[212:215], v[204:207], v[68:71]
	v_mfma_f32_16x16x32_bf16 v[64:67], v[220:223], v[204:207], v[64:67]
	v_mfma_f32_16x16x32_bf16 v[92:95], v[216:219], v[184:187], v[92:95]
	v_mfma_f32_16x16x32_bf16 v[88:91], v[158:161], v[184:187], v[88:91]
	v_mfma_f32_16x16x32_bf16 v[76:79], v[216:219], v[200:203], v[76:79]
	v_mfma_f32_16x16x32_bf16 v[72:75], v[158:161], v[200:203], v[72:75]
	v_mfma_f32_16x16x32_bf16 v[180:183], v[216:219], v[192:195], v[84:87]
	v_mfma_f32_16x16x32_bf16 v[184:187], v[158:161], v[192:195], v[80:83]
	v_mfma_f32_16x16x32_bf16 v[188:191], v[216:219], v[208:211], v[68:71]
	v_mfma_f32_16x16x32_bf16 v[192:195], v[158:161], v[208:211], v[64:67]
	s_barrier
	s_nop 0
	ds_read_b128 v[64:67], v152 offset:16384
	ds_read_b128 v[68:71], v152 offset:17408
	ds_read_b128 v[80:83], v151 offset:16384
	ds_read_b128 v[84:87], v151 offset:17408
	ds_read_b128 v[196:199], v150 offset:16384
	ds_read_b128 v[200:203], v150 offset:17408
	ds_read_b128 v[204:207], v149 offset:16384
	ds_read_b128 v[208:211], v149 offset:17408
	s_waitcnt vmcnt(4)
	s_barrier
	s_waitcnt lgkmcnt(0)
	s_waitcnt lgkmcnt(0)
	v_mfma_f32_16x16x32_bf16 v[60:63], v[134:137], v[64:67], v[60:63]
	v_mfma_f32_16x16x32_bf16 v[56:59], v[172:175], v[64:67], v[56:59]
	v_mfma_f32_16x16x32_bf16 v[52:55], v[134:137], v[80:83], v[52:55]
	v_mfma_f32_16x16x32_bf16 v[48:51], v[172:175], v[80:83], v[48:51]
	v_mfma_f32_16x16x32_bf16 v[44:47], v[134:137], v[196:199], v[44:47]
	v_mfma_f32_16x16x32_bf16 v[40:43], v[172:175], v[196:199], v[40:43]
	v_mfma_f32_16x16x32_bf16 v[36:39], v[134:137], v[204:207], v[36:39]
	v_mfma_f32_16x16x32_bf16 v[32:35], v[172:175], v[204:207], v[32:35]
	v_mfma_f32_16x16x32_bf16 v[60:63], v[138:141], v[68:71], v[60:63]
	v_mfma_f32_16x16x32_bf16 v[56:59], v[176:179], v[68:71], v[56:59]
	v_mfma_f32_16x16x32_bf16 v[52:55], v[138:141], v[84:87], v[52:55]
	v_mfma_f32_16x16x32_bf16 v[48:51], v[176:179], v[84:87], v[48:51]
	v_mfma_f32_16x16x32_bf16 v[44:47], v[138:141], v[200:203], v[44:47]
	v_mfma_f32_16x16x32_bf16 v[40:43], v[176:179], v[200:203], v[40:43]
	v_mfma_f32_16x16x32_bf16 v[36:39], v[138:141], v[208:211], v[36:39]
	v_mfma_f32_16x16x32_bf16 v[32:35], v[176:179], v[208:211], v[32:35]
	v_mfma_f32_16x16x32_bf16 v[28:31], v[212:215], v[64:67], v[28:31]
	v_mfma_f32_16x16x32_bf16 v[24:27], v[220:223], v[64:67], v[24:27]
	v_mfma_f32_16x16x32_bf16 v[12:15], v[212:215], v[196:199], v[12:15]
	v_mfma_f32_16x16x32_bf16 v[8:11], v[220:223], v[196:199], v[8:11]
	v_mfma_f32_16x16x32_bf16 v[20:23], v[212:215], v[80:83], v[20:23]
	v_mfma_f32_16x16x32_bf16 v[16:19], v[220:223], v[80:83], v[16:19]
	v_mfma_f32_16x16x32_bf16 v[4:7], v[212:215], v[204:207], v[4:7]
	v_mfma_f32_16x16x32_bf16 v[0:3], v[220:223], v[204:207], v[0:3]
	v_mfma_f32_16x16x32_bf16 v[28:31], v[216:219], v[68:71], v[28:31]
	v_mfma_f32_16x16x32_bf16 v[24:27], v[158:161], v[68:71], v[24:27]
	v_mfma_f32_16x16x32_bf16 v[12:15], v[216:219], v[200:203], v[12:15]
	v_mfma_f32_16x16x32_bf16 v[8:11], v[158:161], v[200:203], v[8:11]
	v_mfma_f32_16x16x32_bf16 v[134:137], v[216:219], v[84:87], v[20:23]
	v_mfma_f32_16x16x32_bf16 v[138:141], v[158:161], v[84:87], v[16:19]
	v_mfma_f32_16x16x32_bf16 v[170:173], v[216:219], v[208:211], v[4:7]
	v_mfma_f32_16x16x32_bf16 v[158:161], v[158:161], v[208:211], v[0:3]
	s_barrier
	s_nop 0
	ds_read_b128 v[0:3], v156
	ds_read_b128 v[4:7], v156 offset:1024
	ds_read_b128 v[16:19], v156 offset:2048
	ds_read_b128 v[174:177], v156 offset:3072
	ds_read_b128 v[20:23], v152 offset:32768
	ds_read_b128 v[196:199], v152 offset:33792
	ds_read_b128 v[200:203], v151 offset:32768
	ds_read_b128 v[204:207], v151 offset:33792
	ds_read_b128 v[208:211], v150 offset:32768
	ds_read_b128 v[212:215], v150 offset:33792
	ds_read_b128 v[216:219], v149 offset:32768
	ds_read_b128 v[220:223], v149 offset:33792
	s_waitcnt vmcnt(2)
	s_barrier
; #define LDA(dst, b, h) for (int m = 0; m < 4; ++m) for (int k = 0; k < 2; ++k) \
;     dst[m][k] = *reinterpret_cast<const bf16x8*>((char*)SA(b, h) + lds_byte(wr * 64 + m * 16 + fr, k * 32 + fq * 8))
; #define LDB(dst, b, h) for (int n = 0; n < 2; ++n) for (int k = 0; k < 2; ++k) \
;     dst[n][k] = *reinterpret_cast<const bf16x8*>((char*)SB(b, h) + lds_byte(wc * 32 + n * 16 + fr, k * 32 + fq * 8))
; #define MMA(ai, bj, At_, Bt_) do { __builtin_amdgcn_s_setprio(1); \
;     for (int k = 0; k < 2; ++k) for (int m = 0; m < 4; ++m) for (int n = 0; n < 2; ++n) \
;       acc[ai][bj][m][n] = __builtin_amdgcn_mfma_f32_16x16x32_bf16(At_[m][k], Bt_[n][k], acc[ai][bj][m][n], 0, 0, 0); \
;     __builtin_amdgcn_s_setprio(0); } while (0)
; #define WAIT_V(n) asm volatile("s_waitcnt vmcnt(" #n ")" ::: "memory")
; #define WAIT_L(n) asm volatile("s_waitcnt lgkmcnt(" #n ")" ::: "memory")
; #define BAR __builtin_amdgcn_s_barrier()
; template <int EPI, int lda, int ldb, int N, int K>
; __device__ __forceinline__ void gemm_phase(const u16* __restrict__ A, const u16* __restrict__ Bt, const GemmEpi ep, int wv) {
;     ...
;     { LDB(B0, 1, 0); LDA(At, 1, 0); WAIT_V(2); BAR; WAIT_L(0); MMA(0, 0, At, B0); BAR;
;       LDB(B1, 1, 1); WAIT_V(0); BAR; WAIT_L(0); MMA(0, 1, At, B1); BAR;
;       LDA(At, 1, 1); BAR; WAIT_L(0); MMA(1, 0, At, B0); MMA(1, 1, At, B1); BAR; }
;     if (wr == 0) BAR;
	s_waitcnt lgkmcnt(0)
	s_waitcnt lgkmcnt(0)
	v_mfma_f32_16x16x32_bf16 v[64:67], v[0:3], v[20:23], v[124:127]
	v_mfma_f32_16x16x32_bf16 v[68:71], v[16:19], v[20:23], v[120:123]
	v_mfma_f32_16x16x32_bf16 v[80:83], v[0:3], v[200:203], v[116:119]
	v_mfma_f32_16x16x32_bf16 v[84:87], v[16:19], v[200:203], v[112:115]
	v_mfma_f32_16x16x32_bf16 v[108:111], v[0:3], v[208:211], v[108:111]
	v_mfma_f32_16x16x32_bf16 v[104:107], v[16:19], v[208:211], v[104:107]
	v_mfma_f32_16x16x32_bf16 v[120:123], v[0:3], v[216:219], v[100:103]
	v_mfma_f32_16x16x32_bf16 v[124:127], v[16:19], v[216:219], v[96:99]
	v_mfma_f32_16x16x32_bf16 v[116:119], v[4:7], v[196:199], v[64:67]
	v_mfma_f32_16x16x32_bf16 v[112:115], v[174:177], v[196:199], v[68:71]
	v_mfma_f32_16x16x32_bf16 v[100:103], v[4:7], v[204:207], v[80:83]
	v_mfma_f32_16x16x32_bf16 v[96:99], v[174:177], v[204:207], v[84:87]
	v_mfma_f32_16x16x32_bf16 v[84:87], v[4:7], v[212:215], v[108:111]
	v_mfma_f32_16x16x32_bf16 v[80:83], v[174:177], v[212:215], v[104:107]
	v_mfma_f32_16x16x32_bf16 v[68:71], v[4:7], v[220:223], v[120:123]
	v_mfma_f32_16x16x32_bf16 v[64:67], v[174:177], v[220:223], v[124:127]
	s_barrier
	ds_read_b128 v[224:227], v154
	ds_read_b128 v[228:231], v154 offset:1024
	ds_read_b128 v[232:235], v154 offset:2048
	ds_read_b128 v[154:157], v154 offset:3072
	s_waitcnt vmcnt(0)
	s_barrier
	s_waitcnt lgkmcnt(0)
	s_waitcnt lgkmcnt(0)
	v_mfma_f32_16x16x32_bf16 v[92:95], v[224:227], v[20:23], v[92:95]
	v_mfma_f32_16x16x32_bf16 v[20:23], v[232:235], v[20:23], v[88:91]
	v_mfma_f32_16x16x32_bf16 v[88:91], v[224:227], v[200:203], v[180:183]
	v_mfma_f32_16x16x32_bf16 v[104:107], v[232:235], v[200:203], v[184:187]
	v_mfma_f32_16x16x32_bf16 v[76:79], v[224:227], v[208:211], v[76:79]
	v_mfma_f32_16x16x32_bf16 v[72:75], v[232:235], v[208:211], v[72:75]
	v_mfma_f32_16x16x32_bf16 v[178:181], v[224:227], v[216:219], v[188:191]
	v_mfma_f32_16x16x32_bf16 v[182:185], v[232:235], v[216:219], v[192:195]
	v_mfma_f32_16x16x32_bf16 v[124:127], v[228:231], v[196:199], v[92:95]
	v_mfma_f32_16x16x32_bf16 v[120:123], v[154:157], v[196:199], v[20:23]
	v_mfma_f32_16x16x32_bf16 v[108:111], v[228:231], v[204:207], v[88:91]
	v_mfma_f32_16x16x32_bf16 v[104:107], v[154:157], v[204:207], v[104:107]
	v_mfma_f32_16x16x32_bf16 v[92:95], v[228:231], v[212:215], v[76:79]
	v_mfma_f32_16x16x32_bf16 v[88:91], v[154:157], v[212:215], v[72:75]
	v_mfma_f32_16x16x32_bf16 v[76:79], v[228:231], v[220:223], v[178:181]
	v_mfma_f32_16x16x32_bf16 v[72:75], v[154:157], v[220:223], v[182:185]
	s_barrier
	ds_read_b128 v[178:181], v152 offset:49152
	ds_read_b128 v[182:185], v152 offset:50176
	ds_read_b128 v[186:189], v151 offset:49152
	ds_read_b128 v[190:193], v151 offset:50176
	ds_read_b128 v[194:197], v150 offset:49152
	ds_read_b128 v[150:153], v150 offset:50176
	ds_read_b128 v[198:201], v149 offset:49152
	ds_read_b128 v[202:205], v149 offset:50176
	s_barrier
	s_waitcnt lgkmcnt(0)
	s_waitcnt lgkmcnt(0)
	v_mfma_f32_16x16x32_bf16 v[20:23], v[0:3], v[178:181], v[60:63]
	v_mfma_f32_16x16x32_bf16 v[56:59], v[16:19], v[178:181], v[56:59]
	v_mfma_f32_16x16x32_bf16 v[60:63], v[0:3], v[186:189], v[52:55]
	v_mfma_f32_16x16x32_bf16 v[206:209], v[16:19], v[186:189], v[48:51]
	v_mfma_f32_16x16x32_bf16 v[44:47], v[0:3], v[194:197], v[44:47]
	v_mfma_f32_16x16x32_bf16 v[40:43], v[16:19], v[194:197], v[40:43]
	v_mfma_f32_16x16x32_bf16 v[0:3], v[0:3], v[198:201], v[36:39]
	v_mfma_f32_16x16x32_bf16 v[210:213], v[16:19], v[198:201], v[32:35]
	v_mfma_f32_16x16x32_bf16 v[52:55], v[4:7], v[182:185], v[20:23]
	v_mfma_f32_16x16x32_bf16 v[48:51], v[174:177], v[182:185], v[56:59]
	v_mfma_f32_16x16x32_bf16 v[36:39], v[4:7], v[190:193], v[60:63]
	v_mfma_f32_16x16x32_bf16 v[32:35], v[174:177], v[190:193], v[206:209]
	v_mfma_f32_16x16x32_bf16 v[20:23], v[4:7], v[150:153], v[44:47]
	v_mfma_f32_16x16x32_bf16 v[16:19], v[174:177], v[150:153], v[40:43]
	v_mfma_f32_16x16x32_bf16 v[4:7], v[4:7], v[202:205], v[0:3]
	v_mfma_f32_16x16x32_bf16 v[0:3], v[174:177], v[202:205], v[210:213]
	v_mfma_f32_16x16x32_bf16 v[28:31], v[224:227], v[178:181], v[28:31]
	v_mfma_f32_16x16x32_bf16 v[24:27], v[232:235], v[178:181], v[24:27]
	v_mfma_f32_16x16x32_bf16 v[40:43], v[224:227], v[186:189], v[134:137]
	v_mfma_f32_16x16x32_bf16 v[134:137], v[232:235], v[186:189], v[138:141]
	v_mfma_f32_16x16x32_bf16 v[12:15], v[224:227], v[194:197], v[12:15]
	v_mfma_f32_16x16x32_bf16 v[8:11], v[232:235], v[194:197], v[8:11]
	v_mfma_f32_16x16x32_bf16 v[138:141], v[224:227], v[198:201], v[170:173]
	v_mfma_f32_16x16x32_bf16 v[158:161], v[232:235], v[198:201], v[158:161]
	v_mfma_f32_16x16x32_bf16 v[60:63], v[228:231], v[182:185], v[28:31]
	v_mfma_f32_16x16x32_bf16 v[56:59], v[154:157], v[182:185], v[24:27]
	v_mfma_f32_16x16x32_bf16 v[44:47], v[228:231], v[190:193], v[40:43]
	v_mfma_f32_16x16x32_bf16 v[40:43], v[154:157], v[190:193], v[134:137]
	v_mfma_f32_16x16x32_bf16 v[28:31], v[228:231], v[150:153], v[12:15]
	v_mfma_f32_16x16x32_bf16 v[24:27], v[154:157], v[150:153], v[8:11]
	v_mfma_f32_16x16x32_bf16 v[12:15], v[228:231], v[202:205], v[138:141]
	v_mfma_f32_16x16x32_bf16 v[8:11], v[154:157], v[202:205], v[158:161]
	v_cmp_gt_u32_e32 vcc, s54, v130
	s_barrier
	s_and_saveexec_b64 s[40:41], vcc
	s_cbranch_execz .LBB0_1567
	s_barrier

; #define STAGE(P, BASE, LD, br, kt) do { const char* _g = (const char*)((BASE) + (size_t)(br) * (LD) + (size_t)(kt) * 64); \
;     for (int _i = 0; _i < 2; ++_i) { int _b = tidx * 16 + _i * 8192; int _r, _c; stage_rc(_b, _r, _c); \
;       __builtin_amdgcn_global_load_lds((const unsigned*)(_g + (unsigned)((_r * (LD) + _c) * 2)), (unsigned*)((char*)(P) + _b), 16, 0, 0); } } while (0)
; #define LDA(dst, b, h) for (int m = 0; m < 4; ++m) for (int k = 0; k < 2; ++k) \
;     dst[m][k] = *reinterpret_cast<const bf16x8*>((char*)SA(b, h) + lds_byte(wr * 64 + m * 16 + fr, k * 32 + fq * 8))
; #define LDB(dst, b, h) for (int n = 0; n < 2; ++n) for (int k = 0; k < 2; ++k) \
;     dst[n][k] = *reinterpret_cast<const bf16x8*>((char*)SB(b, h) + lds_byte(wc * 32 + n * 16 + fr, k * 32 + fq * 8))
; #define MMA(ai, bj, At_, Bt_) do { __builtin_amdgcn_s_setprio(1); \
;     for (int k = 0; k < 2; ++k) for (int m = 0; m < 4; ++m) for (int n = 0; n < 2; ++n) \
;       acc[ai][bj][m][n] = __builtin_amdgcn_mfma_f32_16x16x32_bf16(At_[m][k], Bt_[n][k], acc[ai][bj][m][n], 0, 0, 0); \
;     __builtin_amdgcn_s_setprio(0); } while (0)
; #define WAIT_L(n) asm volatile("s_waitcnt lgkmcnt(" #n ")" ::: "memory")
; #define BAR __builtin_amdgcn_s_barrier()
; #define SCHED __builtin_amdgcn_sched_barrier(0)
; template <int EPI, int lda, int ldb, int N, int K>
; __device__ __forceinline__ void gemm_phase(const u16* __restrict__ A, const u16* __restrict__ Bt, const GemmEpi ep, int wv) {
;     ...
;     for (int t = 0; t < nt - 2; t += 2) {
;       LDB(B0, 0, 0); SCHED; LDA(At, 0, 0); STAGE(SA(1, 1), Ab, lda, brow + HALF, t + 1);
;       WAIT_L(8); BAR; WAIT_L(0); MMA(0, 0, At, B0); BAR; SCHED;
;       LDB(B1, 0, 1); STAGE(SB(0, 0), Bt, ldb, bcol, t + 2);
;       BAR; WAIT_L(0); MMA(0, 1, At, B1); BAR;
;       LDA(At, 0, 1); STAGE(SA(0, 0), Ab, lda, brow, t + 2);
;       BAR; WAIT_L(0); MMA(1, 0, At, B0); BAR; SCHED;
.LBB0_1624:
	ds_read_b128 v[174:177], v163
	ds_read_b128 v[178:181], v163 offset:1024
	ds_read_b128 v[182:185], v163 offset:2048
	ds_read_b128 v[186:189], v163 offset:3072
	v_add_u32_e32 v171, 0xc000, v149
	v_lshl_add_u64 v[238:239], v[134:135], 0, s[28:29]
	v_readfirstlane_b32 s50, v171
	v_add_u32_e32 v172, 0xe000, v149
	v_lshl_add_u64 v[164:165], v[238:239], 0, s[10:11]
	s_mov_b32 m0, s50
	v_lshl_add_u64 v[240:241], v[132:133], 0, s[28:29]
	v_readfirstlane_b32 s50, v172
	ds_read_b128 v[166:169], v154
	ds_read_b128 v[190:193], v154 offset:1024
	ds_read_b128 v[194:197], v153
	ds_read_b128 v[198:201], v153 offset:1024
	ds_read_b128 v[202:205], v151
	ds_read_b128 v[206:209], v151 offset:1024
	ds_read_b128 v[210:213], v150
	ds_read_b128 v[214:217], v150 offset:1024
	global_load_lds_dwordx4 v[164:165], off
	s_nop 1
	v_lshl_add_u64 v[164:165], v[240:241], 0, s[10:11]
	s_mov_b32 m0, s50
	s_nop 0
	global_load_lds_dwordx4 v[164:165], off
	s_waitcnt lgkmcnt(8)
	s_barrier
	s_waitcnt lgkmcnt(0)
	s_waitcnt lgkmcnt(0)
	v_mfma_f32_16x16x32_bf16 v[124:127], v[166:169], v[174:177], v[124:127]
	v_mfma_f32_16x16x32_bf16 v[120:123], v[166:169], v[182:185], v[120:123]
	v_mfma_f32_16x16x32_bf16 v[116:119], v[194:197], v[174:177], v[116:119]
	v_mfma_f32_16x16x32_bf16 v[112:115], v[194:197], v[182:185], v[112:115]
	v_mfma_f32_16x16x32_bf16 v[108:111], v[202:205], v[174:177], v[108:111]
	v_mfma_f32_16x16x32_bf16 v[104:107], v[202:205], v[182:185], v[104:107]
	v_mfma_f32_16x16x32_bf16 v[100:103], v[210:213], v[174:177], v[100:103]
	v_mfma_f32_16x16x32_bf16 v[96:99], v[210:213], v[182:185], v[96:99]
	v_mfma_f32_16x16x32_bf16 v[124:127], v[190:193], v[178:181], v[124:127]
	v_mfma_f32_16x16x32_bf16 v[120:123], v[190:193], v[186:189], v[120:123]
	v_mfma_f32_16x16x32_bf16 v[116:119], v[198:201], v[178:181], v[116:119]
	v_mfma_f32_16x16x32_bf16 v[112:115], v[198:201], v[186:189], v[112:115]
	v_mfma_f32_16x16x32_bf16 v[108:111], v[206:209], v[178:181], v[108:111]
	v_mfma_f32_16x16x32_bf16 v[104:107], v[206:209], v[186:189], v[104:107]
	v_mfma_f32_16x16x32_bf16 v[100:103], v[214:217], v[178:181], v[100:103]
	v_mfma_f32_16x16x32_bf16 v[96:99], v[214:217], v[186:189], v[96:99]
	s_barrier
	v_add_u32_e32 v164, s40, v155
	v_lshl_add_u64 v[242:243], v[142:143], 0, s[28:29]
	v_readfirstlane_b32 s50, v164
	v_add_u32_e32 v165, 0x2000, v164
	v_lshl_add_u64 v[234:235], v[242:243], 0, s[12:13]
	s_mov_b32 m0, s50
	v_lshl_add_u64 v[244:245], v[140:141], 0, s[28:29]
	v_readfirstlane_b32 s50, v165
	ds_read_b128 v[218:221], v162
	ds_read_b128 v[222:225], v162 offset:1024
	ds_read_b128 v[226:229], v162 offset:2048
	ds_read_b128 v[230:233], v162 offset:3072
	global_load_lds_dwordx4 v[234:235], off
	s_nop 1
	v_lshl_add_u64 v[234:235], v[244:245], 0, s[12:13]
	s_mov_b32 m0, s50
	s_nop 0
	global_load_lds_dwordx4 v[234:235], off
	s_barrier
	s_waitcnt lgkmcnt(0)
	s_waitcnt lgkmcnt(0)
	v_mfma_f32_16x16x32_bf16 v[92:95], v[166:169], v[218:221], v[92:95]
	v_mfma_f32_16x16x32_bf16 v[88:91], v[166:169], v[226:229], v[88:91]
	v_mfma_f32_16x16x32_bf16 v[84:87], v[194:197], v[218:221], v[84:87]
	v_mfma_f32_16x16x32_bf16 v[80:83], v[194:197], v[226:229], v[80:83]
	v_mfma_f32_16x16x32_bf16 v[76:79], v[202:205], v[218:221], v[76:79]
	v_mfma_f32_16x16x32_bf16 v[72:75], v[202:205], v[226:229], v[72:75]
	v_mfma_f32_16x16x32_bf16 v[68:71], v[210:213], v[218:221], v[68:71]
	v_mfma_f32_16x16x32_bf16 v[64:67], v[210:213], v[226:229], v[64:67]
	v_mfma_f32_16x16x32_bf16 v[92:95], v[190:193], v[222:225], v[92:95]
	v_mfma_f32_16x16x32_bf16 v[88:91], v[190:193], v[230:233], v[88:91]
	v_mfma_f32_16x16x32_bf16 v[84:87], v[198:201], v[222:225], v[84:87]
	v_mfma_f32_16x16x32_bf16 v[80:83], v[198:201], v[230:233], v[80:83]
	v_mfma_f32_16x16x32_bf16 v[76:79], v[206:209], v[222:225], v[76:79]
	v_mfma_f32_16x16x32_bf16 v[72:75], v[206:209], v[230:233], v[72:75]
	v_mfma_f32_16x16x32_bf16 v[68:71], v[214:217], v[222:225], v[68:71]
	v_mfma_f32_16x16x32_bf16 v[64:67], v[214:217], v[230:233], v[64:67]
	v_readfirstlane_b32 s50, v149
	v_lshl_add_u64 v[166:167], v[238:239], 0, s[14:15]
	s_mov_b32 m0, s50
	s_barrier
	ds_read_b128 v[190:193], v154 offset:16384
	ds_read_b128 v[194:197], v154 offset:17408
	ds_read_b128 v[198:201], v153 offset:16384
	ds_read_b128 v[202:205], v153 offset:17408
	ds_read_b128 v[206:209], v151 offset:16384
	ds_read_b128 v[210:213], v151 offset:17408
	ds_read_b128 v[214:217], v150 offset:16384
	ds_read_b128 v[234:237], v150 offset:17408
	global_load_lds_dwordx4 v[166:167], off
	s_nop 1
	v_add_u32_e32 v166, 0x2000, v149
	v_lshl_add_u64 v[168:169], v[240:241], 0, s[14:15]
	v_readfirstlane_b32 s50, v166
	s_mov_b32 m0, s50
	s_nop 0
	global_load_lds_dwordx4 v[168:169], off
	s_barrier
	s_waitcnt lgkmcnt(0)
	s_waitcnt lgkmcnt(0)
	v_mfma_f32_16x16x32_bf16 v[60:63], v[190:193], v[174:177], v[60:63]
	v_mfma_f32_16x16x32_bf16 v[56:59], v[190:193], v[182:185], v[56:59]
	v_mfma_f32_16x16x32_bf16 v[52:55], v[198:201], v[174:177], v[52:55]
	v_mfma_f32_16x16x32_bf16 v[48:51], v[198:201], v[182:185], v[48:51]
	v_mfma_f32_16x16x32_bf16 v[44:47], v[206:209], v[174:177], v[44:47]
	v_mfma_f32_16x16x32_bf16 v[40:43], v[206:209], v[182:185], v[40:43]
	v_mfma_f32_16x16x32_bf16 v[36:39], v[214:217], v[174:177], v[36:39]
	v_mfma_f32_16x16x32_bf16 v[32:35], v[214:217], v[182:185], v[32:35]
	v_mfma_f32_16x16x32_bf16 v[60:63], v[194:197], v[178:181], v[60:63]
	v_mfma_f32_16x16x32_bf16 v[56:59], v[194:197], v[186:189], v[56:59]
	v_mfma_f32_16x16x32_bf16 v[52:55], v[202:205], v[178:181], v[52:55]
	v_mfma_f32_16x16x32_bf16 v[48:51], v[202:205], v[186:189], v[48:51]
	v_mfma_f32_16x16x32_bf16 v[44:47], v[210:213], v[178:181], v[44:47]
	v_mfma_f32_16x16x32_bf16 v[40:43], v[210:213], v[186:189], v[40:43]
	v_mfma_f32_16x16x32_bf16 v[36:39], v[234:237], v[178:181], v[36:39]
	v_mfma_f32_16x16x32_bf16 v[32:35], v[234:237], v[186:189], v[32:35]
	s_barrier
; #define STAGE(P, BASE, LD, br, kt) do { const char* _g = (const char*)((BASE) + (size_t)(br) * (LD) + (size_t)(kt) * 64); \
;     for (int _i = 0; _i < 2; ++_i) { int _b = tidx * 16 + _i * 8192; int _r, _c; stage_rc(_b, _r, _c); \
;       __builtin_amdgcn_global_load_lds((const unsigned*)(_g + (unsigned)((_r * (LD) + _c) * 2)), (unsigned*)((char*)(P) + _b), 16, 0, 0); } } while (0)
; #define LDA(dst, b, h) for (int m = 0; m < 4; ++m) for (int k = 0; k < 2; ++k) \
;     dst[m][k] = *reinterpret_cast<const bf16x8*>((char*)SA(b, h) + lds_byte(wr * 64 + m * 16 + fr, k * 32 + fq * 8))
; #define LDB(dst, b, h) for (int n = 0; n < 2; ++n) for (int k = 0; k < 2; ++k) \
;     dst[n][k] = *reinterpret_cast<const bf16x8*>((char*)SB(b, h) + lds_byte(wc * 32 + n * 16 + fr, k * 32 + fq * 8))
; #define MMA(ai, bj, At_, Bt_) do { __builtin_amdgcn_s_setprio(1); \
;     for (int k = 0; k < 2; ++k) for (int m = 0; m < 4; ++m) for (int n = 0; n < 2; ++n) \
;       acc[ai][bj][m][n] = __builtin_amdgcn_mfma_f32_16x16x32_bf16(At_[m][k], Bt_[n][k], acc[ai][bj][m][n], 0, 0, 0); \
;     __builtin_amdgcn_s_setprio(0); } while (0)
; #define WAIT_V(n) asm volatile("s_waitcnt vmcnt(" #n ")" ::: "memory")
; #define WAIT_L(n) asm volatile("s_waitcnt lgkmcnt(" #n ")" ::: "memory")
; #define BAR __builtin_amdgcn_s_barrier()
; #define SCHED __builtin_amdgcn_sched_barrier(0)
; template <int EPI, int lda, int ldb, int N, int K>
; __device__ __forceinline__ void gemm_phase(const u16* __restrict__ A, const u16* __restrict__ Bt, const GemmEpi ep, int wv) {
;     ...
;       STAGE(SB(0, 1), Bt, ldb, bcol + HALF, t + 2);
;       WAIT_V(6); BAR; MMA(1, 1, At, B1); BAR;
;       LDB(B0, 1, 0); SCHED; LDA(At, 1, 0); STAGE(SA(0, 1), Ab, lda, brow + HALF, t + 2);
;       WAIT_L(8); BAR; WAIT_L(0); MMA(0, 0, At, B0); BAR; SCHED;
;       LDB(B1, 1, 1); STAGE(SB(1, 0), Bt, ldb, bcol, t + 3);
;       BAR; WAIT_L(0); MMA(0, 1, At, B1); BAR;
	v_add_u32_e32 v167, s41, v155
	v_lshl_add_u64 v[246:247], v[138:139], 0, s[28:29]
	v_readfirstlane_b32 s50, v167
	v_lshl_add_u64 v[168:169], v[246:247], 0, s[16:17]
	s_mov_b32 m0, s50
	v_lshl_add_u64 v[248:249], v[136:137], 0, s[28:29]
	global_load_lds_dwordx4 v[168:169], off
	s_nop 1
	v_add_u32_e32 v168, 0x2000, v167
	v_lshl_add_u64 v[174:175], v[248:249], 0, s[16:17]
	v_readfirstlane_b32 s50, v168
	s_mov_b32 m0, s50
	s_nop 0
	global_load_lds_dwordx4 v[174:175], off
	s_waitcnt vmcnt(6)
	s_barrier
	v_mfma_f32_16x16x32_bf16 v[28:31], v[190:193], v[218:221], v[28:31]
	v_mfma_f32_16x16x32_bf16 v[24:27], v[190:193], v[226:229], v[24:27]
	v_mfma_f32_16x16x32_bf16 v[20:23], v[198:201], v[218:221], v[20:23]
	v_mfma_f32_16x16x32_bf16 v[16:19], v[198:201], v[226:229], v[16:19]
	v_mfma_f32_16x16x32_bf16 v[12:15], v[206:209], v[218:221], v[12:15]
	v_mfma_f32_16x16x32_bf16 v[8:11], v[206:209], v[226:229], v[8:11]
	v_mfma_f32_16x16x32_bf16 v[4:7], v[214:217], v[218:221], v[4:7]
	v_mfma_f32_16x16x32_bf16 v[0:3], v[214:217], v[226:229], v[0:3]
	v_mfma_f32_16x16x32_bf16 v[28:31], v[194:197], v[222:225], v[28:31]
	v_mfma_f32_16x16x32_bf16 v[24:27], v[194:197], v[230:233], v[24:27]
	v_mfma_f32_16x16x32_bf16 v[20:23], v[202:205], v[222:225], v[20:23]
	v_mfma_f32_16x16x32_bf16 v[16:19], v[202:205], v[230:233], v[16:19]
	v_mfma_f32_16x16x32_bf16 v[12:15], v[210:213], v[222:225], v[12:15]
	v_mfma_f32_16x16x32_bf16 v[8:11], v[210:213], v[230:233], v[8:11]
	v_mfma_f32_16x16x32_bf16 v[4:7], v[234:237], v[222:225], v[4:7]
	v_mfma_f32_16x16x32_bf16 v[0:3], v[234:237], v[230:233], v[0:3]
	s_barrier
	ds_read_b128 v[174:177], v158
	ds_read_b128 v[178:181], v158 offset:1024
	ds_read_b128 v[182:185], v158 offset:2048
	ds_read_b128 v[186:189], v158 offset:3072
	v_add_u32_e32 v169, 0x4000, v149
	v_add_u32_e32 v170, 0x6000, v149
	v_readfirstlane_b32 s50, v169
	v_lshl_add_u64 v[222:223], v[238:239], 0, s[18:19]
	s_mov_b32 m0, s50
	v_readfirstlane_b32 s50, v170
	ds_read_b128 v[190:193], v154 offset:32768
	ds_read_b128 v[194:197], v154 offset:33792
	ds_read_b128 v[198:201], v153 offset:32768
	ds_read_b128 v[202:205], v153 offset:33792
	ds_read_b128 v[206:209], v151 offset:32768
	ds_read_b128 v[210:213], v151 offset:33792
	ds_read_b128 v[214:217], v150 offset:32768
	ds_read_b128 v[218:221], v150 offset:33792
	global_load_lds_dwordx4 v[222:223], off
	s_nop 1
	v_lshl_add_u64 v[222:223], v[240:241], 0, s[18:19]
	s_mov_b32 m0, s50
	s_nop 0
	global_load_lds_dwordx4 v[222:223], off
	s_waitcnt lgkmcnt(8)
	s_barrier
	s_waitcnt lgkmcnt(0)
	s_waitcnt lgkmcnt(0)
	v_mfma_f32_16x16x32_bf16 v[124:127], v[190:193], v[174:177], v[124:127]
	v_mfma_f32_16x16x32_bf16 v[120:123], v[190:193], v[182:185], v[120:123]
	v_mfma_f32_16x16x32_bf16 v[116:119], v[198:201], v[174:177], v[116:119]
	v_mfma_f32_16x16x32_bf16 v[112:115], v[198:201], v[182:185], v[112:115]
	v_mfma_f32_16x16x32_bf16 v[108:111], v[206:209], v[174:177], v[108:111]
	v_mfma_f32_16x16x32_bf16 v[104:107], v[206:209], v[182:185], v[104:107]
	v_mfma_f32_16x16x32_bf16 v[100:103], v[214:217], v[174:177], v[100:103]
	v_mfma_f32_16x16x32_bf16 v[96:99], v[214:217], v[182:185], v[96:99]
	v_mfma_f32_16x16x32_bf16 v[124:127], v[194:197], v[178:181], v[124:127]
	v_mfma_f32_16x16x32_bf16 v[120:123], v[194:197], v[186:189], v[120:123]
	v_mfma_f32_16x16x32_bf16 v[116:119], v[202:205], v[178:181], v[116:119]
	v_mfma_f32_16x16x32_bf16 v[112:115], v[202:205], v[186:189], v[112:115]
	v_mfma_f32_16x16x32_bf16 v[108:111], v[210:213], v[178:181], v[108:111]
	v_mfma_f32_16x16x32_bf16 v[104:107], v[210:213], v[186:189], v[104:107]
	v_mfma_f32_16x16x32_bf16 v[100:103], v[218:221], v[178:181], v[100:103]
	v_mfma_f32_16x16x32_bf16 v[96:99], v[218:221], v[186:189], v[96:99]
	s_barrier
	v_readfirstlane_b32 s50, v157
	v_add_u32_e32 v173, 0x2000, v157
	v_lshl_add_u64 v[242:243], v[242:243], 0, s[20:21]
	s_mov_b32 m0, s50
	v_readfirstlane_b32 s50, v173
	ds_read_b128 v[222:225], v156
	ds_read_b128 v[226:229], v156 offset:1024
	ds_read_b128 v[230:233], v156 offset:2048
	ds_read_b128 v[234:237], v156 offset:3072
	global_load_lds_dwordx4 v[242:243], off
	s_nop 1
	v_lshl_add_u64 v[242:243], v[244:245], 0, s[20:21]
	s_mov_b32 m0, s50
	s_nop 0
	global_load_lds_dwordx4 v[242:243], off
	s_barrier
	s_waitcnt lgkmcnt(0)
	s_waitcnt lgkmcnt(0)
	v_mfma_f32_16x16x32_bf16 v[92:95], v[190:193], v[222:225], v[92:95]
	v_mfma_f32_16x16x32_bf16 v[88:91], v[190:193], v[230:233], v[88:91]
	v_mfma_f32_16x16x32_bf16 v[84:87], v[198:201], v[222:225], v[84:87]
	v_mfma_f32_16x16x32_bf16 v[80:83], v[198:201], v[230:233], v[80:83]
	v_mfma_f32_16x16x32_bf16 v[76:79], v[206:209], v[222:225], v[76:79]
	v_mfma_f32_16x16x32_bf16 v[72:75], v[206:209], v[230:233], v[72:75]
	v_mfma_f32_16x16x32_bf16 v[68:71], v[214:217], v[222:225], v[68:71]
	v_mfma_f32_16x16x32_bf16 v[64:67], v[214:217], v[230:233], v[64:67]
	v_mfma_f32_16x16x32_bf16 v[92:95], v[194:197], v[226:229], v[92:95]
	v_mfma_f32_16x16x32_bf16 v[88:91], v[194:197], v[234:237], v[88:91]
	v_mfma_f32_16x16x32_bf16 v[84:87], v[202:205], v[226:229], v[84:87]
	v_mfma_f32_16x16x32_bf16 v[80:83], v[202:205], v[234:237], v[80:83]
	v_mfma_f32_16x16x32_bf16 v[76:79], v[210:213], v[226:229], v[76:79]
	v_mfma_f32_16x16x32_bf16 v[72:75], v[210:213], v[234:237], v[72:75]
	v_mfma_f32_16x16x32_bf16 v[68:71], v[218:221], v[226:229], v[68:71]
	v_mfma_f32_16x16x32_bf16 v[64:67], v[218:221], v[234:237], v[64:67]
	v_readfirstlane_b32 s50, v159
	v_lshl_add_u64 v[238:239], v[238:239], 0, s[22:23]
	s_mov_b32 m0, s50
	v_readfirstlane_b32 s50, v160
	s_barrier
; #define STAGE(P, BASE, LD, br, kt) do { const char* _g = (const char*)((BASE) + (size_t)(br) * (LD) + (size_t)(kt) * 64); \
;     for (int _i = 0; _i < 2; ++_i) { int _b = tidx * 16 + _i * 8192; int _r, _c; stage_rc(_b, _r, _c); \
;       __builtin_amdgcn_global_load_lds((const unsigned*)(_g + (unsigned)((_r * (LD) + _c) * 2)), (unsigned*)((char*)(P) + _b), 16, 0, 0); } } while (0)
; #define LDA(dst, b, h) for (int m = 0; m < 4; ++m) for (int k = 0; k < 2; ++k) \
;     dst[m][k] = *reinterpret_cast<const bf16x8*>((char*)SA(b, h) + lds_byte(wr * 64 + m * 16 + fr, k * 32 + fq * 8))
; #define LDB(dst, b, h) for (int n = 0; n < 2; ++n) for (int k = 0; k < 2; ++k) \
;     dst[n][k] = *reinterpret_cast<const bf16x8*>((char*)SB(b, h) + lds_byte(wc * 32 + n * 16 + fr, k * 32 + fq * 8))
; #define MMA(ai, bj, At_, Bt_) do { __builtin_amdgcn_s_setprio(1); \
;     for (int k = 0; k < 2; ++k) for (int m = 0; m < 4; ++m) for (int n = 0; n < 2; ++n) \
;       acc[ai][bj][m][n] = __builtin_amdgcn_mfma_f32_16x16x32_bf16(At_[m][k], Bt_[n][k], acc[ai][bj][m][n], 0, 0, 0); \
;     __builtin_amdgcn_s_setprio(0); } while (0)
; #define WAIT_V(n) asm volatile("s_waitcnt vmcnt(" #n ")" ::: "memory")
; #define WAIT_L(n) asm volatile("s_waitcnt lgkmcnt(" #n ")" ::: "memory")
; #define BAR __builtin_amdgcn_s_barrier()
; #define SCHED __builtin_amdgcn_sched_barrier(0)
; template <int EPI, int lda, int ldb, int N, int K>
; __device__ __forceinline__ void gemm_phase(const u16* __restrict__ A, const u16* __restrict__ Bt, const GemmEpi ep, int wv) {
;     ...
;       LDA(At, 1, 1); STAGE(SA(1, 0), Ab, lda, brow, t + 3);
;       BAR; WAIT_L(0); MMA(1, 0, At, B0); BAR; SCHED;
;       STAGE(SB(1, 1), Bt, ldb, bcol + HALF, t + 3);
;       WAIT_V(6); BAR; MMA(1, 1, At, B1); BAR;
;     }
;     { LDB(B0, 0, 0); LDA(At, 0, 0); STAGE(SA(1, 1), Ab, lda, brow + HALF, nt - 1);
	ds_read_b128 v[190:193], v154 offset:49152
	ds_read_b128 v[194:197], v154 offset:50176
	ds_read_b128 v[198:201], v153 offset:49152
	ds_read_b128 v[202:205], v153 offset:50176
	ds_read_b128 v[206:209], v151 offset:49152
	ds_read_b128 v[210:213], v151 offset:50176
	ds_read_b128 v[214:217], v150 offset:49152
	ds_read_b128 v[218:221], v150 offset:50176
	global_load_lds_dwordx4 v[238:239], off
	s_nop 1
	v_lshl_add_u64 v[238:239], v[240:241], 0, s[22:23]
	s_mov_b32 m0, s50
	s_nop 0
	global_load_lds_dwordx4 v[238:239], off
	s_barrier
	s_waitcnt lgkmcnt(0)
	s_waitcnt lgkmcnt(0)
	v_mfma_f32_16x16x32_bf16 v[60:63], v[190:193], v[174:177], v[60:63]
	v_mfma_f32_16x16x32_bf16 v[56:59], v[190:193], v[182:185], v[56:59]
	v_mfma_f32_16x16x32_bf16 v[52:55], v[198:201], v[174:177], v[52:55]
	v_mfma_f32_16x16x32_bf16 v[48:51], v[198:201], v[182:185], v[48:51]
	v_mfma_f32_16x16x32_bf16 v[44:47], v[206:209], v[174:177], v[44:47]
	v_mfma_f32_16x16x32_bf16 v[40:43], v[206:209], v[182:185], v[40:43]
	v_mfma_f32_16x16x32_bf16 v[36:39], v[214:217], v[174:177], v[36:39]
	v_mfma_f32_16x16x32_bf16 v[32:35], v[214:217], v[182:185], v[32:35]
	v_mfma_f32_16x16x32_bf16 v[60:63], v[194:197], v[178:181], v[60:63]
	v_mfma_f32_16x16x32_bf16 v[56:59], v[194:197], v[186:189], v[56:59]
	v_mfma_f32_16x16x32_bf16 v[52:55], v[202:205], v[178:181], v[52:55]
	v_mfma_f32_16x16x32_bf16 v[48:51], v[202:205], v[186:189], v[48:51]
	v_mfma_f32_16x16x32_bf16 v[44:47], v[210:213], v[178:181], v[44:47]
	v_mfma_f32_16x16x32_bf16 v[40:43], v[210:213], v[186:189], v[40:43]
	v_mfma_f32_16x16x32_bf16 v[36:39], v[218:221], v[178:181], v[36:39]
	v_mfma_f32_16x16x32_bf16 v[32:35], v[218:221], v[186:189], v[32:35]
	s_barrier
	v_readfirstlane_b32 s50, v161
	v_add_u32_e32 v173, 0x2000, v161
	v_lshl_add_u64 v[174:175], v[246:247], 0, s[24:25]
	s_mov_b32 m0, s50
	v_readfirstlane_b32 s50, v173
	global_load_lds_dwordx4 v[174:175], off
	s_nop 1
	v_lshl_add_u64 v[174:175], v[248:249], 0, s[24:25]
	s_mov_b32 m0, s50
	s_nop 0
	global_load_lds_dwordx4 v[174:175], off
	s_waitcnt vmcnt(6)
	s_barrier
	v_mfma_f32_16x16x32_bf16 v[28:31], v[190:193], v[222:225], v[28:31]
	v_mfma_f32_16x16x32_bf16 v[24:27], v[190:193], v[230:233], v[24:27]
	v_mfma_f32_16x16x32_bf16 v[20:23], v[198:201], v[222:225], v[20:23]
	v_mfma_f32_16x16x32_bf16 v[16:19], v[198:201], v[230:233], v[16:19]
	v_mfma_f32_16x16x32_bf16 v[12:15], v[206:209], v[222:225], v[12:15]
	v_mfma_f32_16x16x32_bf16 v[8:11], v[206:209], v[230:233], v[8:11]
	v_mfma_f32_16x16x32_bf16 v[4:7], v[214:217], v[222:225], v[4:7]
	v_mfma_f32_16x16x32_bf16 v[0:3], v[214:217], v[230:233], v[0:3]
	v_mfma_f32_16x16x32_bf16 v[28:31], v[194:197], v[226:229], v[28:31]
	v_mfma_f32_16x16x32_bf16 v[24:27], v[194:197], v[234:237], v[24:27]
	v_mfma_f32_16x16x32_bf16 v[20:23], v[202:205], v[226:229], v[20:23]
	v_mfma_f32_16x16x32_bf16 v[16:19], v[202:205], v[234:237], v[16:19]
	v_mfma_f32_16x16x32_bf16 v[12:15], v[210:213], v[226:229], v[12:15]
	v_mfma_f32_16x16x32_bf16 v[8:11], v[210:213], v[234:237], v[8:11]
	v_mfma_f32_16x16x32_bf16 v[4:7], v[218:221], v[226:229], v[4:7]
	v_mfma_f32_16x16x32_bf16 v[0:3], v[218:221], v[234:237], v[0:3]
	s_add_i32 s49, s49, 2
	s_add_u32 s28, s28, 0x100
	s_addc_u32 s29, s29, 0
	s_cmpk_gt_u32 s49, 0x51
	s_barrier
	s_cbranch_scc0 .LBB0_1624
	s_add_i32 s28, s48, 0x80
	s_mul_hi_i32 s29, s28, 0x2b00
	s_mulk_i32 s28, 0x2b00
	s_add_u32 s28, s34, s28
	s_addc_u32 s29, s35, s29
	s_add_u32 s28, s28, 0x2a80
	s_addc_u32 s29, s29, 0
	v_readfirstlane_b32 s49, v171
	v_lshl_add_u64 v[160:161], s[28:29], 0, v[128:129]
	s_mov_b32 m0, s49
	ds_read_b128 v[132:135], v163
	ds_read_b128 v[136:139], v163 offset:1024
	ds_read_b128 v[140:143], v163 offset:2048
	ds_read_b128 v[174:177], v163 offset:3072
	ds_read_b128 v[178:181], v154
	ds_read_b128 v[182:185], v154 offset:1024
	ds_read_b128 v[186:189], v153
	ds_read_b128 v[190:193], v153 offset:1024
	ds_read_b128 v[194:197], v151
	ds_read_b128 v[198:201], v151 offset:1024
	ds_read_b128 v[202:205], v150
	ds_read_b128 v[206:209], v150 offset:1024
	global_load_lds_dwordx4 v[160:161], off
	v_lshl_add_u64 v[160:161], s[28:29], 0, v[130:131]
	v_readfirstlane_b32 s28, v172
	s_mov_b32 m0, s28
	s_nop 0
	global_load_lds_dwordx4 v[160:161], off
	s_barrier
	s_waitcnt lgkmcnt(0)
	s_waitcnt lgkmcnt(0)
	v_mfma_f32_16x16x32_bf16 v[124:127], v[178:181], v[132:135], v[124:127]
	v_mfma_f32_16x16x32_bf16 v[120:123], v[178:181], v[140:143], v[120:123]
	v_mfma_f32_16x16x32_bf16 v[116:119], v[186:189], v[132:135], v[116:119]
	v_mfma_f32_16x16x32_bf16 v[112:115], v[186:189], v[140:143], v[112:115]
	v_mfma_f32_16x16x32_bf16 v[108:111], v[194:197], v[132:135], v[108:111]
	v_mfma_f32_16x16x32_bf16 v[104:107], v[194:197], v[140:143], v[104:107]
	v_mfma_f32_16x16x32_bf16 v[100:103], v[202:205], v[132:135], v[100:103]
	v_mfma_f32_16x16x32_bf16 v[96:99], v[202:205], v[140:143], v[96:99]
	v_mfma_f32_16x16x32_bf16 v[124:127], v[182:185], v[136:139], v[124:127]
	v_mfma_f32_16x16x32_bf16 v[120:123], v[182:185], v[174:177], v[120:123]
	v_mfma_f32_16x16x32_bf16 v[116:119], v[190:193], v[136:139], v[116:119]
	v_mfma_f32_16x16x32_bf16 v[112:115], v[190:193], v[174:177], v[112:115]
	v_mfma_f32_16x16x32_bf16 v[108:111], v[198:201], v[136:139], v[108:111]
	v_mfma_f32_16x16x32_bf16 v[104:107], v[198:201], v[174:177], v[104:107]
	v_mfma_f32_16x16x32_bf16 v[100:103], v[206:209], v[136:139], v[100:103]
	v_mfma_f32_16x16x32_bf16 v[96:99], v[206:209], v[174:177], v[96:99]
	s_barrier
	ds_read_b128 v[210:213], v162
	ds_read_b128 v[214:217], v162 offset:1024
	ds_read_b128 v[218:221], v162 offset:2048
	ds_read_b128 v[160:163], v162 offset:3072
	s_barrier
; #define LDA(dst, b, h) for (int m = 0; m < 4; ++m) for (int k = 0; k < 2; ++k) \
;     dst[m][k] = *reinterpret_cast<const bf16x8*>((char*)SA(b, h) + lds_byte(wr * 64 + m * 16 + fr, k * 32 + fq * 8))
; #define LDB(dst, b, h) for (int n = 0; n < 2; ++n) for (int k = 0; k < 2; ++k) \
;     dst[n][k] = *reinterpret_cast<const bf16x8*>((char*)SB(b, h) + lds_byte(wc * 32 + n * 16 + fr, k * 32 + fq * 8))
; #define MMA(ai, bj, At_, Bt_) do { __builtin_amdgcn_s_setprio(1); \
;     for (int k = 0; k < 2; ++k) for (int m = 0; m < 4; ++m) for (int n = 0; n < 2; ++n) \
;       acc[ai][bj][m][n] = __builtin_amdgcn_mfma_f32_16x16x32_bf16(At_[m][k], Bt_[n][k], acc[ai][bj][m][n], 0, 0, 0); \
;     __builtin_amdgcn_s_setprio(0); } while (0)
; #define WAIT_V(n) asm volatile("s_waitcnt vmcnt(" #n ")" ::: "memory")
; #define WAIT_L(n) asm volatile("s_waitcnt lgkmcnt(" #n ")" ::: "memory")
; #define BAR __builtin_amdgcn_s_barrier()
; template <int EPI, int lda, int ldb, int N, int K>
; __device__ __forceinline__ void gemm_phase(const u16* __restrict__ A, const u16* __restrict__ Bt, const GemmEpi ep, int wv) {
;     ...
;       BAR; WAIT_L(0); MMA(0, 0, At, B0); BAR;
;       LDB(B1, 0, 1); BAR; WAIT_L(0); MMA(0, 1, At, B1); BAR;
;       LDA(At, 0, 1); WAIT_V(4); BAR; WAIT_L(0); MMA(1, 0, At, B0); MMA(1, 1, At, B1); BAR; }
;     { LDB(B0, 1, 0); LDA(At, 1, 0); WAIT_V(2); BAR; WAIT_L(0); MMA(0, 0, At, B0); BAR;
	s_waitcnt lgkmcnt(0)
	s_waitcnt lgkmcnt(0)
	v_mfma_f32_16x16x32_bf16 v[92:95], v[178:181], v[210:213], v[92:95]
	v_mfma_f32_16x16x32_bf16 v[88:91], v[178:181], v[218:221], v[88:91]
	v_mfma_f32_16x16x32_bf16 v[72:75], v[194:197], v[218:221], v[72:75]
	v_mfma_f32_16x16x32_bf16 v[68:71], v[202:205], v[210:213], v[68:71]
	v_mfma_f32_16x16x32_bf16 v[84:87], v[186:189], v[210:213], v[84:87]
	v_mfma_f32_16x16x32_bf16 v[80:83], v[186:189], v[218:221], v[80:83]
	v_mfma_f32_16x16x32_bf16 v[76:79], v[194:197], v[210:213], v[76:79]
	v_mfma_f32_16x16x32_bf16 v[64:67], v[202:205], v[218:221], v[64:67]
	v_mfma_f32_16x16x32_bf16 v[92:95], v[182:185], v[214:217], v[92:95]
	v_mfma_f32_16x16x32_bf16 v[88:91], v[182:185], v[160:163], v[88:91]
	v_mfma_f32_16x16x32_bf16 v[72:75], v[198:201], v[160:163], v[72:75]
	v_mfma_f32_16x16x32_bf16 v[68:71], v[206:209], v[214:217], v[68:71]
	v_mfma_f32_16x16x32_bf16 v[178:181], v[190:193], v[214:217], v[84:87]
	v_mfma_f32_16x16x32_bf16 v[182:185], v[190:193], v[160:163], v[80:83]
	v_mfma_f32_16x16x32_bf16 v[186:189], v[198:201], v[214:217], v[76:79]
	v_mfma_f32_16x16x32_bf16 v[190:193], v[206:209], v[160:163], v[64:67]
	s_barrier
	s_nop 0
	ds_read_b128 v[64:67], v154 offset:16384
	ds_read_b128 v[76:79], v154 offset:17408
	ds_read_b128 v[80:83], v153 offset:16384
	ds_read_b128 v[84:87], v153 offset:17408
	ds_read_b128 v[194:197], v151 offset:16384
	ds_read_b128 v[198:201], v151 offset:17408
	ds_read_b128 v[202:205], v150 offset:16384
	ds_read_b128 v[206:209], v150 offset:17408
	s_waitcnt vmcnt(4)
	s_barrier
	s_waitcnt lgkmcnt(0)
	s_waitcnt lgkmcnt(0)
	v_mfma_f32_16x16x32_bf16 v[60:63], v[64:67], v[132:135], v[60:63]
	v_mfma_f32_16x16x32_bf16 v[56:59], v[64:67], v[140:143], v[56:59]
	v_mfma_f32_16x16x32_bf16 v[52:55], v[80:83], v[132:135], v[52:55]
	v_mfma_f32_16x16x32_bf16 v[48:51], v[80:83], v[140:143], v[48:51]
	v_mfma_f32_16x16x32_bf16 v[44:47], v[194:197], v[132:135], v[44:47]
	v_mfma_f32_16x16x32_bf16 v[40:43], v[194:197], v[140:143], v[40:43]
	v_mfma_f32_16x16x32_bf16 v[36:39], v[202:205], v[132:135], v[36:39]
	v_mfma_f32_16x16x32_bf16 v[32:35], v[202:205], v[140:143], v[32:35]
	v_mfma_f32_16x16x32_bf16 v[60:63], v[76:79], v[136:139], v[60:63]
	v_mfma_f32_16x16x32_bf16 v[56:59], v[76:79], v[174:177], v[56:59]
	v_mfma_f32_16x16x32_bf16 v[52:55], v[84:87], v[136:139], v[52:55]
	v_mfma_f32_16x16x32_bf16 v[48:51], v[84:87], v[174:177], v[48:51]
	v_mfma_f32_16x16x32_bf16 v[44:47], v[198:201], v[136:139], v[44:47]
	v_mfma_f32_16x16x32_bf16 v[40:43], v[198:201], v[174:177], v[40:43]
	v_mfma_f32_16x16x32_bf16 v[36:39], v[206:209], v[136:139], v[36:39]
	v_mfma_f32_16x16x32_bf16 v[32:35], v[206:209], v[174:177], v[32:35]
	v_mfma_f32_16x16x32_bf16 v[28:31], v[64:67], v[210:213], v[28:31]
	v_mfma_f32_16x16x32_bf16 v[24:27], v[64:67], v[218:221], v[24:27]
	v_mfma_f32_16x16x32_bf16 v[12:15], v[194:197], v[210:213], v[12:15]
	v_mfma_f32_16x16x32_bf16 v[8:11], v[194:197], v[218:221], v[8:11]
	v_mfma_f32_16x16x32_bf16 v[20:23], v[80:83], v[210:213], v[20:23]
	v_mfma_f32_16x16x32_bf16 v[16:19], v[80:83], v[218:221], v[16:19]
	v_mfma_f32_16x16x32_bf16 v[4:7], v[202:205], v[210:213], v[4:7]
	v_mfma_f32_16x16x32_bf16 v[0:3], v[202:205], v[218:221], v[0:3]
	v_mfma_f32_16x16x32_bf16 v[28:31], v[76:79], v[214:217], v[28:31]
	v_mfma_f32_16x16x32_bf16 v[24:27], v[76:79], v[160:163], v[24:27]
	v_mfma_f32_16x16x32_bf16 v[12:15], v[198:201], v[214:217], v[12:15]
	v_mfma_f32_16x16x32_bf16 v[8:11], v[198:201], v[160:163], v[8:11]
	v_mfma_f32_16x16x32_bf16 v[132:135], v[84:87], v[214:217], v[20:23]
	v_mfma_f32_16x16x32_bf16 v[136:139], v[84:87], v[160:163], v[16:19]
	v_mfma_f32_16x16x32_bf16 v[140:143], v[206:209], v[214:217], v[4:7]
	v_mfma_f32_16x16x32_bf16 v[160:163], v[206:209], v[160:163], v[0:3]
	s_barrier
	s_nop 0
	ds_read_b128 v[0:3], v158
	ds_read_b128 v[4:7], v158 offset:1024
	ds_read_b128 v[16:19], v158 offset:2048
	ds_read_b128 v[172:175], v158 offset:3072
	ds_read_b128 v[20:23], v154 offset:32768
	ds_read_b128 v[194:197], v154 offset:33792
	ds_read_b128 v[198:201], v153 offset:32768
	ds_read_b128 v[202:205], v153 offset:33792
	ds_read_b128 v[206:209], v151 offset:32768
	ds_read_b128 v[210:213], v151 offset:33792
	ds_read_b128 v[214:217], v150 offset:32768
	ds_read_b128 v[218:221], v150 offset:33792
	s_waitcnt vmcnt(2)
	s_barrier
; #define LDA(dst, b, h) for (int m = 0; m < 4; ++m) for (int k = 0; k < 2; ++k) \
;     dst[m][k] = *reinterpret_cast<const bf16x8*>((char*)SA(b, h) + lds_byte(wr * 64 + m * 16 + fr, k * 32 + fq * 8))
; #define LDB(dst, b, h) for (int n = 0; n < 2; ++n) for (int k = 0; k < 2; ++k) \
;     dst[n][k] = *reinterpret_cast<const bf16x8*>((char*)SB(b, h) + lds_byte(wc * 32 + n * 16 + fr, k * 32 + fq * 8))
; #define MMA(ai, bj, At_, Bt_) do { __builtin_amdgcn_s_setprio(1); \
;     for (int k = 0; k < 2; ++k) for (int m = 0; m < 4; ++m) for (int n = 0; n < 2; ++n) \
;       acc[ai][bj][m][n] = __builtin_amdgcn_mfma_f32_16x16x32_bf16(At_[m][k], Bt_[n][k], acc[ai][bj][m][n], 0, 0, 0); \
;     __builtin_amdgcn_s_setprio(0); } while (0)
; #define WAIT_V(n) asm volatile("s_waitcnt vmcnt(" #n ")" ::: "memory")
; #define WAIT_L(n) asm volatile("s_waitcnt lgkmcnt(" #n ")" ::: "memory")
; #define BAR __builtin_amdgcn_s_barrier()
; template <int EPI, int lda, int ldb, int N, int K>
; __device__ __forceinline__ void gemm_phase(const u16* __restrict__ A, const u16* __restrict__ Bt, const GemmEpi ep, int wv) {
;     ...
;     { LDB(B0, 1, 0); LDA(At, 1, 0); WAIT_V(2); BAR; WAIT_L(0); MMA(0, 0, At, B0); BAR;
;       LDB(B1, 1, 1); WAIT_V(0); BAR; WAIT_L(0); MMA(0, 1, At, B1); BAR;
;       LDA(At, 1, 1); BAR; WAIT_L(0); MMA(1, 0, At, B0); MMA(1, 1, At, B1); BAR; }
;     if (wr == 0) BAR;
	s_waitcnt lgkmcnt(0)
	s_waitcnt lgkmcnt(0)
	v_mfma_f32_16x16x32_bf16 v[64:67], v[20:23], v[0:3], v[124:127]
	v_mfma_f32_16x16x32_bf16 v[76:79], v[20:23], v[16:19], v[120:123]
	v_mfma_f32_16x16x32_bf16 v[80:83], v[198:201], v[0:3], v[116:119]
	v_mfma_f32_16x16x32_bf16 v[84:87], v[198:201], v[16:19], v[112:115]
	v_mfma_f32_16x16x32_bf16 v[108:111], v[206:209], v[0:3], v[108:111]
	v_mfma_f32_16x16x32_bf16 v[104:107], v[206:209], v[16:19], v[104:107]
	v_mfma_f32_16x16x32_bf16 v[120:123], v[214:217], v[0:3], v[100:103]
	v_mfma_f32_16x16x32_bf16 v[124:127], v[214:217], v[16:19], v[96:99]
	v_mfma_f32_16x16x32_bf16 v[116:119], v[194:197], v[4:7], v[64:67]
	v_mfma_f32_16x16x32_bf16 v[112:115], v[194:197], v[172:175], v[76:79]
	v_mfma_f32_16x16x32_bf16 v[100:103], v[202:205], v[4:7], v[80:83]
	v_mfma_f32_16x16x32_bf16 v[96:99], v[202:205], v[172:175], v[84:87]
	v_mfma_f32_16x16x32_bf16 v[84:87], v[210:213], v[4:7], v[108:111]
	v_mfma_f32_16x16x32_bf16 v[80:83], v[210:213], v[172:175], v[104:107]
	v_mfma_f32_16x16x32_bf16 v[76:79], v[218:221], v[4:7], v[120:123]
	v_mfma_f32_16x16x32_bf16 v[64:67], v[218:221], v[172:175], v[124:127]
	s_barrier
	ds_read_b128 v[222:225], v156
	ds_read_b128 v[226:229], v156 offset:1024
	ds_read_b128 v[230:233], v156 offset:2048
	ds_read_b128 v[156:159], v156 offset:3072
	s_waitcnt vmcnt(0)
	s_barrier
	s_waitcnt lgkmcnt(0)
	s_waitcnt lgkmcnt(0)
	v_mfma_f32_16x16x32_bf16 v[92:95], v[20:23], v[222:225], v[92:95]
	v_mfma_f32_16x16x32_bf16 v[20:23], v[20:23], v[230:233], v[88:91]
	v_mfma_f32_16x16x32_bf16 v[88:91], v[198:201], v[222:225], v[178:181]
	v_mfma_f32_16x16x32_bf16 v[104:107], v[198:201], v[230:233], v[182:185]
	v_mfma_f32_16x16x32_bf16 v[176:179], v[206:209], v[222:225], v[186:189]
	v_mfma_f32_16x16x32_bf16 v[72:75], v[206:209], v[230:233], v[72:75]
	v_mfma_f32_16x16x32_bf16 v[68:71], v[214:217], v[222:225], v[68:71]
	v_mfma_f32_16x16x32_bf16 v[180:183], v[214:217], v[230:233], v[190:193]
	v_mfma_f32_16x16x32_bf16 v[124:127], v[194:197], v[226:229], v[92:95]
	v_mfma_f32_16x16x32_bf16 v[120:123], v[194:197], v[156:159], v[20:23]
	v_mfma_f32_16x16x32_bf16 v[108:111], v[202:205], v[226:229], v[88:91]
	v_mfma_f32_16x16x32_bf16 v[104:107], v[202:205], v[156:159], v[104:107]
	v_mfma_f32_16x16x32_bf16 v[92:95], v[210:213], v[226:229], v[176:179]
	v_mfma_f32_16x16x32_bf16 v[88:91], v[210:213], v[156:159], v[72:75]
	v_mfma_f32_16x16x32_bf16 v[72:75], v[218:221], v[226:229], v[68:71]
	v_mfma_f32_16x16x32_bf16 v[68:71], v[218:221], v[156:159], v[180:183]
	s_barrier
	ds_read_b128 v[176:179], v154 offset:49152
	ds_read_b128 v[180:183], v154 offset:50176
	ds_read_b128 v[184:187], v153 offset:49152
	ds_read_b128 v[188:191], v153 offset:50176
	ds_read_b128 v[192:195], v151 offset:49152
	ds_read_b128 v[196:199], v151 offset:50176
	ds_read_b128 v[200:203], v150 offset:49152
	ds_read_b128 v[204:207], v150 offset:50176
	s_barrier
	s_waitcnt lgkmcnt(0)
	s_waitcnt lgkmcnt(0)
	v_mfma_f32_16x16x32_bf16 v[20:23], v[176:179], v[0:3], v[60:63]
	v_mfma_f32_16x16x32_bf16 v[56:59], v[176:179], v[16:19], v[56:59]
	v_mfma_f32_16x16x32_bf16 v[60:63], v[184:187], v[0:3], v[52:55]
	v_mfma_f32_16x16x32_bf16 v[208:211], v[184:187], v[16:19], v[48:51]
	v_mfma_f32_16x16x32_bf16 v[44:47], v[192:195], v[0:3], v[44:47]
	v_mfma_f32_16x16x32_bf16 v[40:43], v[192:195], v[16:19], v[40:43]
	v_mfma_f32_16x16x32_bf16 v[0:3], v[200:203], v[0:3], v[36:39]
	v_mfma_f32_16x16x32_bf16 v[212:215], v[200:203], v[16:19], v[32:35]
	v_mfma_f32_16x16x32_bf16 v[52:55], v[180:183], v[4:7], v[20:23]
	v_mfma_f32_16x16x32_bf16 v[48:51], v[180:183], v[172:175], v[56:59]
	v_mfma_f32_16x16x32_bf16 v[36:39], v[188:191], v[4:7], v[60:63]
	v_mfma_f32_16x16x32_bf16 v[32:35], v[188:191], v[172:175], v[208:211]
	v_mfma_f32_16x16x32_bf16 v[20:23], v[196:199], v[4:7], v[44:47]
	v_mfma_f32_16x16x32_bf16 v[16:19], v[196:199], v[172:175], v[40:43]
	v_mfma_f32_16x16x32_bf16 v[4:7], v[204:207], v[4:7], v[0:3]
	v_mfma_f32_16x16x32_bf16 v[0:3], v[204:207], v[172:175], v[212:215]
	v_mfma_f32_16x16x32_bf16 v[28:31], v[176:179], v[222:225], v[28:31]
	v_mfma_f32_16x16x32_bf16 v[24:27], v[176:179], v[230:233], v[24:27]
	v_mfma_f32_16x16x32_bf16 v[40:43], v[184:187], v[222:225], v[132:135]
	v_mfma_f32_16x16x32_bf16 v[132:135], v[184:187], v[230:233], v[136:139]
	v_mfma_f32_16x16x32_bf16 v[12:15], v[192:195], v[222:225], v[12:15]
	v_mfma_f32_16x16x32_bf16 v[8:11], v[192:195], v[230:233], v[8:11]
	v_mfma_f32_16x16x32_bf16 v[136:139], v[200:203], v[222:225], v[140:143]
	v_mfma_f32_16x16x32_bf16 v[140:143], v[200:203], v[230:233], v[160:163]
	v_mfma_f32_16x16x32_bf16 v[60:63], v[180:183], v[226:229], v[28:31]
	v_mfma_f32_16x16x32_bf16 v[56:59], v[180:183], v[156:159], v[24:27]
	v_mfma_f32_16x16x32_bf16 v[44:47], v[188:191], v[226:229], v[40:43]
	v_mfma_f32_16x16x32_bf16 v[40:43], v[188:191], v[156:159], v[132:135]
	v_mfma_f32_16x16x32_bf16 v[28:31], v[196:199], v[226:229], v[12:15]
	v_mfma_f32_16x16x32_bf16 v[24:27], v[196:199], v[156:159], v[8:11]
	v_mfma_f32_16x16x32_bf16 v[12:15], v[204:207], v[226:229], v[136:139]
	v_mfma_f32_16x16x32_bf16 v[8:11], v[204:207], v[156:159], v[140:143]
	v_cmp_gt_u32_e32 vcc, s46, v147
	s_barrier
	s_and_saveexec_b64 s[28:29], vcc
	s_cbranch_execz .LBB0_1627
	s_barrier
